# v56 + removed 117 s_nop pads that followed inline-asm pk_fma blocks (no hardware hazard for VOP3P producers)
# speedup vs baseline: 1.0173x; 1.0012x over previous
; #define SYNC() __syncthreads()
; #define OPAQUE_I(x) asm volatile("" : "+v"(x))
; DEV void filt_channel_unit2(int c, const bf16_t* h2b, const float* w3, unsigned* KF, LAS unsigned char* lds, int tid) {
;     ...
;     SYNC();
;     float tt[4] = {0.f, 0.f, 0.f, 0.f};
; #pragma unroll
;     for (int w = 0; w < 8; ++w)
; #pragma unroll
;         for (int q = 0; q < 4; ++q) tt[q] += red[w * 4 + q];
;     const cf in0 = cf{1.0f / tt[0], 1.0f / tt[1]}, in1 = cf{1.0f / tt[2], 1.0f / tt[3]};
;     {
;         OPAQUE_I(tid);
;         cf v[16], u[16];
; #pragma unroll
;         for (int q = 0; q < 16; ++q) { v[q] = buf0[PADI(tid + 512 * q)] * in0; u[q] = buf1[PADI(tid + 512 * q)] * in1; }
.LBB0_205:
	s_or_b64 exec, exec, s[2:3]
	v_add_u32_e32 v0, 0x800, v107
	s_waitcnt lgkmcnt(0)
	s_barrier
	v_add_u32_e32 v2, 0x810, v107
	ds_read2_b32 v[0:1], v0 offset1:1
	ds_read2_b32 v[2:3], v2 offset1:1
	v_add_u32_e32 v6, 0x820, v107
	v_add_u32_e32 v8, 0x830, v107
	v_add_u32_e32 v10, 0x840, v107
	s_waitcnt lgkmcnt(1)
	v_pk_add_f32 v[0:1], v[0:1], 0 op_sel_hi:[1,0]
	v_add_u32_e32 v12, 0x850, v107
	s_waitcnt lgkmcnt(0)
	v_pk_add_f32 v[0:1], v[0:1], v[2:3]
	ds_read2_b32 v[2:3], v6 offset1:1
	v_add_u32_e32 v14, 0x860, v107
	v_add_u32_e32 v16, 0x870, v107
	v_add_u32_e32 v4, 0x808, v107
	v_add_u32_e32 v5, 0x818, v107
	s_waitcnt lgkmcnt(0)
	v_pk_add_f32 v[0:1], v[0:1], v[2:3]
	ds_read2_b32 v[2:3], v8 offset1:1
	v_add_u32_e32 v7, 0x828, v107
	v_add_u32_e32 v9, 0x838, v107
	v_add_u32_e32 v11, 0x848, v107
	v_add_u32_e32 v13, 0x858, v107
	s_waitcnt lgkmcnt(0)
	v_pk_add_f32 v[0:1], v[0:1], v[2:3]
	ds_read2_b32 v[2:3], v10 offset1:1
	v_add_u32_e32 v15, 0x868, v107
	v_add_u32_e32 v17, 0x878, v107
	s_mov_b32 s22, s85
	s_mov_b32 s24, s85
	s_waitcnt lgkmcnt(0)
	v_pk_add_f32 v[0:1], v[0:1], v[2:3]
	ds_read2_b32 v[2:3], v12 offset1:1
	s_mov_b32 s25, s0
	s_mov_b32 s28, s85
	s_mov_b32 s29, s84
	s_mov_b32 s26, s84
	s_waitcnt lgkmcnt(0)
	v_pk_add_f32 v[0:1], v[0:1], v[2:3]
	ds_read2_b32 v[2:3], v14 offset1:1
	s_mov_b32 s27, s88
	s_mov_b32 s6, s97
	s_mov_b32 s7, s96
	v_mov_b32_e32 v138, s33
	s_waitcnt lgkmcnt(0)
	v_pk_add_f32 v[0:1], v[0:1], v[2:3]
	ds_read2_b32 v[2:3], v16 offset1:1
	s_mov_b32 s8, s95
	s_mov_b32 s10, s87
	s_mov_b32 s30, s11
	s_mov_b32 s31, s87
	s_waitcnt lgkmcnt(0)
	v_pk_add_f32 v[0:1], v[0:1], v[2:3]
	s_ashr_i32 s21, s20, 31
	v_div_scale_f32 v2, s[2:3], v1, v1, 1.0
	v_rcp_f32_e32 v3, v2
	s_nop 0
	v_fma_f32 v6, -v2, v3, 1.0
	v_fmac_f32_e32 v3, v6, v3
	v_div_scale_f32 v6, vcc, 1.0, v1, 1.0
	v_mul_f32_e32 v8, v6, v3
	v_fma_f32 v10, -v2, v8, v6
	v_fmac_f32_e32 v8, v10, v3
	v_fma_f32 v2, -v2, v8, v6
	v_div_fmas_f32 v2, v2, v3, v8
	v_div_fixup_f32 v3, v2, v1, 1.0
	v_div_scale_f32 v1, s[2:3], v0, v0, 1.0
	v_rcp_f32_e32 v2, v1
	s_nop 0
	v_fma_f32 v6, -v1, v2, 1.0
	v_fmac_f32_e32 v2, v6, v2
	v_div_scale_f32 v6, vcc, 1.0, v0, 1.0
	v_mul_f32_e32 v8, v6, v2
	v_fma_f32 v10, -v1, v8, v6
	v_fmac_f32_e32 v8, v10, v2
	v_fma_f32 v1, -v1, v8, v6
	v_div_fmas_f32 v1, v1, v2, v8
	v_div_fixup_f32 v2, v1, v0, 1.0
	ds_read2_b32 v[0:1], v4 offset1:1
	ds_read2_b32 v[4:5], v5 offset1:1
	s_waitcnt lgkmcnt(1)
	v_pk_add_f32 v[0:1], v[0:1], 0 op_sel_hi:[1,0]
	s_waitcnt lgkmcnt(0)
	v_pk_add_f32 v[0:1], v[0:1], v[4:5]
	ds_read2_b32 v[4:5], v7 offset1:1
	s_waitcnt lgkmcnt(0)
	v_pk_add_f32 v[0:1], v[0:1], v[4:5]
	ds_read2_b32 v[4:5], v9 offset1:1
	s_waitcnt lgkmcnt(0)
	v_pk_add_f32 v[0:1], v[0:1], v[4:5]
	ds_read2_b32 v[4:5], v11 offset1:1
	s_waitcnt lgkmcnt(0)
	v_pk_add_f32 v[0:1], v[0:1], v[4:5]
	ds_read2_b32 v[4:5], v13 offset1:1
	s_waitcnt lgkmcnt(0)
	v_pk_add_f32 v[0:1], v[0:1], v[4:5]
	ds_read2_b32 v[4:5], v15 offset1:1
	s_waitcnt lgkmcnt(0)
	v_pk_add_f32 v[0:1], v[0:1], v[4:5]
	ds_read2_b32 v[4:5], v17 offset1:1
	s_waitcnt lgkmcnt(0)
	v_pk_add_f32 v[0:1], v[0:1], v[4:5]
	s_nop 0
	v_div_scale_f32 v4, s[2:3], v1, v1, 1.0
	v_rcp_f32_e32 v5, v4
	s_nop 0
	v_fma_f32 v6, -v4, v5, 1.0
	v_fmac_f32_e32 v5, v6, v5
	v_div_scale_f32 v6, vcc, 1.0, v1, 1.0
	v_mul_f32_e32 v7, v6, v5
	v_fma_f32 v8, -v4, v7, v6
	v_fmac_f32_e32 v7, v8, v5
	v_fma_f32 v4, -v4, v7, v6
	v_div_fmas_f32 v4, v4, v5, v7
	v_div_fixup_f32 v5, v4, v1, 1.0
	v_div_scale_f32 v1, s[2:3], v0, v0, 1.0
	v_rcp_f32_e32 v4, v1
	s_mov_b32 s2, s97
	v_fma_f32 v6, -v1, v4, 1.0
	v_fmac_f32_e32 v4, v6, v4
	v_div_scale_f32 v6, vcc, 1.0, v0, 1.0
	v_mul_f32_e32 v7, v6, v4
	v_fma_f32 v8, -v1, v7, v6
	v_fmac_f32_e32 v7, v8, v4
	v_fma_f32 v1, -v1, v7, v6
	v_div_fmas_f32 v1, v1, v4, v7
	v_div_fixup_f32 v4, v1, v0, 1.0
	v_mov_b32_e32 v0, v88
	s_nop 0
	v_add_u32_e32 v118, 0xe00, v0
	v_ashrrev_i32_e32 v21, 4, v118
	v_add_u32_e32 v22, v21, v118
	v_add_u32_e32 v21, v21, v0
	v_add_u32_e32 v115, 0x1000, v0
	v_lshl_add_u32 v117, v21, 3, 0
	v_ashrrev_i32_e32 v21, 4, v115
	v_add_u32_e32 v26, v21, v115
	v_add_u32_e32 v21, v21, v0
	v_add_u32_e32 v112, 0x1200, v0
	v_lshl_add_u32 v113, v21, 3, 0
	v_ashrrev_i32_e32 v21, 4, v112
	v_add_u32_e32 v28, v21, v112
	v_add_u32_e32 v21, v21, v0
	v_add_u32_e32 v109, 0x1400, v0
	v_lshl_add_u32 v111, v21, 3, 0
	v_ashrrev_i32_e32 v21, 4, v109
	v_add_u32_e32 v34, v21, v109
	v_add_u32_e32 v21, v21, v0
	v_add_u32_e32 v87, 0x1600, v0
	v_lshl_add_u32 v107, v21, 3, 0
	v_ashrrev_i32_e32 v21, 4, v87
	v_add_u32_e32 v40, v21, v87
	v_add_u32_e32 v21, v21, v0
	v_lshl_add_u32 v86, v21, 3, 0
	v_add_u32_e32 v84, 0x1800, v0
	ds_read_b64 v[50:51], v117 offset:28672
	v_lshl_add_u32 v114, v26, 3, s33
	ds_read_b64 v[26:27], v111 offset:36864
	v_lshl_add_u32 v108, v34, 3, s33
	ds_read_b64 v[34:35], v86 offset:45056
	v_ashrrev_i32_e32 v21, 4, v84
	v_add_u32_e32 v124, 0xa00, v0
	v_add_u32_e32 v121, 0xc00, v0
	v_add_u32_e32 v46, v21, v84
	v_add_u32_e32 v21, v21, v0
	v_add_u32_e32 v79, 0x1a00, v0
	v_ashrrev_i32_e32 v16, 4, v124
	v_ashrrev_i32_e32 v18, 4, v121
	v_lshl_add_u32 v80, v21, 3, 0
	v_ashrrev_i32_e32 v21, 4, v79
	v_ashrrev_i32_e32 v1, 4, v0
	v_add_u32_e32 v17, v16, v124
	v_add_u32_e32 v19, v18, v121
	v_add_u32_e32 v56, v21, v79
	v_add_u32_e32 v21, v21, v0
	v_add_lshl_u32 v1, v1, v0, 3
	v_add_u32_e32 v16, v16, v0
	v_lshl_add_u32 v122, v17, 3, s33
	v_add_u32_e32 v18, v18, v0
	v_lshl_add_u32 v119, v19, 3, s33
	v_lshl_add_u32 v116, v22, 3, s33
	v_lshl_add_u32 v110, v28, 3, s33
	v_lshl_add_u32 v85, v40, 3, s33
	v_lshl_add_u32 v78, v21, 3, 0
	v_add_u32_e32 v137, 0, v1
	v_add_u32_e32 v136, 0x200, v0
	v_lshl_add_u32 v123, v16, 3, 0
	ds_read_b64 v[16:17], v122
	ds_read_b64 v[24:25], v113 offset:32768
	v_lshl_add_u32 v120, v18, 3, 0
	ds_read_b64 v[18:19], v119
	ds_read_b64 v[22:23], v116
	ds_read_b64 v[28:29], v107 offset:40960
	s_waitcnt lgkmcnt(6)
; template <int R, bool INV> DEV void dft_regs(cf (&v)[R]) {
; #pragma unroll
;     for (int s = R; s >= 2; s >>= 1) {
;         const int h = s >> 1;
; #pragma unroll
;         for (int b = 0; b < R; b += s) {
; #pragma unroll
;             for (int k = 0; k < h; ++k) {
;                 const cf a = v[b + k], c = v[b + k + h];
;                 v[b + k] = a + c;
;                 const cf d = a - c;
;                 const int m = k * (32 / s);
;                 const float wr = tw_cos(m), wi = INV ? tw_sin(m) : -tw_sin(m);
;                 v[b + k + h] = cf{d.x * wr - d.y * wi, d.x * wi + d.y * wr};
;             }
;         }
;     }
; DEV void filt_channel_unit2(int c, const bf16_t* h2b, const float* w3, unsigned* KF, LAS unsigned char* lds, int tid) {
;     ...
;         for (int q = 0; q < 16; ++q) { v[q] = buf0[PADI(tid + 512 * q)] * in0; u[q] = buf1[PADI(tid + 512 * q)] * in1; }
;         dft_regs<16, false>(v); dft_regs<16, false>(u);
	v_pk_mul_f32 v[54:55], v[2:3], v[26:27]
	ds_read_b64 v[26:27], v110
	ds_read_b64 v[40:41], v80 offset:49152
	s_waitcnt lgkmcnt(7)
	v_pk_mul_f32 v[60:61], v[2:3], v[34:35]
	ds_read_b64 v[34:35], v85
	v_lshl_add_u32 v81, v46, 3, s33
	ds_read_b64 v[46:47], v78 offset:53248
	ds_read_b64 v[30:31], v137
	v_ashrrev_i32_e32 v8, 4, v136
	v_add_u32_e32 v9, v8, v136
	v_add_u32_e32 v8, v8, v0
	v_lshl_add_u32 v135, v8, 3, 0
	v_add_u32_e32 v133, 0x400, v0
	ds_read_b64 v[32:33], v135 offset:4096
	v_ashrrev_i32_e32 v10, 4, v133
	v_lshl_add_u32 v77, v56, 3, s33
	v_add_u32_e32 v11, v10, v133
	v_add_u32_e32 v10, v10, v0
	v_add_u32_e32 v130, 0x600, v0
	s_waitcnt lgkmcnt(2)
	v_pk_mul_f32 v[64:65], v[2:3], v[46:47]
	ds_read_b64 v[46:47], v77
	v_pk_mul_f32 v[62:63], v[2:3], v[40:41]
	ds_read_b64 v[40:41], v81
	v_pk_mul_f32 v[58:59], v[2:3], v[28:29]
	ds_read_b64 v[28:29], v108
	v_pk_mul_f32 v[52:53], v[2:3], v[24:25]
	v_lshl_add_u32 v134, v9, 3, s33
	v_lshl_add_u32 v132, v10, 3, 0
	v_ashrrev_i32_e32 v12, 4, v130
	s_waitcnt lgkmcnt(4)
	v_pk_fma_f32 v[140:141], v[2:3], v[30:31], v[52:53]
	v_pk_fma_f32 v[30:31], v[2:3], v[30:31], v[52:53] neg_lo:[0,0,1] neg_hi:[0,0,1]
	ds_read_b64 v[8:9], v134
	ds_read_b64 v[36:37], v132 offset:8192
	v_add_u32_e32 v13, v12, v130
	v_add_u32_e32 v12, v12, v0
	v_pk_mul_f32 v[52:53], v[30:31], 0 op_sel_hi:[1,0]
	v_lshl_add_u32 v131, v11, 3, s33
	v_lshl_add_u32 v129, v12, 3, 0
	v_add_u32_e32 v127, 0x800, v0
	v_pk_add_f32 v[142:143], v[30:31], v[52:53] op_sel:[0,1] op_sel_hi:[1,0] neg_lo:[0,1] neg_hi:[0,1]
	v_pk_add_f32 v[30:31], v[30:31], v[52:53] op_sel:[0,1] op_sel_hi:[1,0]
	ds_read_b64 v[10:11], v131
	ds_read_b64 v[38:39], v129 offset:12288
	v_ashrrev_i32_e32 v14, 4, v127
	v_add_u32_e32 v76, 0x1c00, v0
	v_mov_b32_e32 v143, v31
	s_waitcnt lgkmcnt(7)
	v_pk_fma_f32 v[30:31], v[2:3], v[32:33], v[54:55]
	v_pk_fma_f32 v[32:33], v[2:3], v[32:33], v[54:55] neg_lo:[0,0,1] neg_hi:[0,0,1]
	v_add_u32_e32 v15, v14, v127
	v_add_u32_e32 v14, v14, v0
	v_ashrrev_i32_e32 v21, 4, v76
	v_pk_mul_f32 v[52:53], v[32:33], s[84:85] op_sel_hi:[1,0]
	v_lshl_add_u32 v128, v13, 3, s33
	v_lshl_add_u32 v126, v14, 3, 0
	v_add_u32_e32 v68, v21, v76
	v_add_u32_e32 v21, v21, v0
	v_add_u32_e32 v73, 0x1e00, v0
	v_pk_fma_f32 v[54:55], v[32:33], s[22:23], v[52:53] op_sel:[0,0,1] op_sel_hi:[1,0,0]
	v_pk_fma_f32 v[32:33], v[32:33], s[22:23], v[52:53] op_sel:[0,0,1] op_sel_hi:[1,0,0] neg_lo:[0,0,1] neg_hi:[0,0,1]
	ds_read_b64 v[12:13], v128
	ds_read_b64 v[42:43], v126 offset:16384
	v_lshl_add_u32 v74, v21, 3, 0
	v_ashrrev_i32_e32 v21, 4, v73
	v_mov_b32_e32 v55, v33
	s_waitcnt lgkmcnt(4)
	v_pk_fma_f32 v[32:33], v[2:3], v[36:37], v[58:59]
	v_pk_fma_f32 v[36:37], v[2:3], v[36:37], v[58:59] neg_lo:[0,0,1] neg_hi:[0,0,1]
	v_lshl_add_u32 v125, v15, 3, s33
	v_add_u32_e32 v70, v21, v73
	v_add_u32_e32 v21, v21, v0
	v_pk_mul_f32 v[52:53], v[36:37], s[2:3] op_sel_hi:[1,0]
	ds_read_b64 v[14:15], v125
	ds_read_b64 v[44:45], v123 offset:20480
	ds_read_b64 v[48:49], v120 offset:24576
	ds_read_b64 v[24:25], v114
	v_lshl_add_u32 v72, v21, 3, 0
	v_pk_fma_f32 v[58:59], v[36:37], s[2:3], v[52:53] op_sel:[0,0,1] op_sel_hi:[1,0,0]
	v_pk_fma_f32 v[36:37], v[36:37], s[2:3], v[52:53] op_sel_hi:[1,0,0] neg_lo:[0,0,1] neg_hi:[0,0,1]
	s_waitcnt lgkmcnt(6)
	v_pk_fma_f32 v[52:53], v[2:3], v[38:39], v[60:61]
	v_pk_fma_f32 v[38:39], v[2:3], v[38:39], v[60:61] neg_lo:[0,0,1] neg_hi:[0,0,1]
	ds_read_b64 v[56:57], v74 offset:57344
	v_lshl_add_u32 v75, v68, 3, s33
	ds_read_b64 v[68:69], v72 offset:61440
	v_pk_mul_f32 v[60:61], v[38:39], s[22:23] op_sel_hi:[1,0]
	v_add_u32_e32 v1, s33, v1
	v_pk_fma_f32 v[144:145], v[38:39], s[84:85], v[60:61] op_sel:[0,0,1] op_sel_hi:[1,0,0]
	v_pk_fma_f32 v[38:39], v[38:39], s[84:85], v[60:61] op_sel:[0,0,1] op_sel_hi:[1,0,0] neg_lo:[0,0,1] neg_hi:[0,0,1]
	v_lshl_add_u32 v21, v70, 3, s33
	v_mov_b32_e32 v145, v39
	s_waitcnt lgkmcnt(6)
	v_pk_fma_f32 v[38:39], v[2:3], v[42:43], v[62:63]
	v_pk_fma_f32 v[42:43], v[2:3], v[42:43], v[62:63] neg_lo:[0,0,1] neg_hi:[0,0,1]
	ds_read_b64 v[6:7], v1
	ds_read_b64 v[70:71], v21
	v_pk_fma_f32 v[60:61], v[42:43], 0, v[42:43] op_sel:[0,0,1] op_sel_hi:[1,0,0]
	v_pk_fma_f32 v[42:43], v[42:43], 0, v[42:43] op_sel:[0,0,1] op_sel_hi:[1,0,0] neg_lo:[0,0,1] neg_hi:[0,0,1]
	s_waitcnt lgkmcnt(3)
	v_pk_mul_f32 v[66:67], v[2:3], v[56:57]
	v_mov_b32_e32 v61, v43
	v_pk_fma_f32 v[42:43], v[2:3], v[44:45], v[64:65]
	v_pk_fma_f32 v[44:45], v[2:3], v[44:45], v[64:65] neg_lo:[0,0,1] neg_hi:[0,0,1]
	s_waitcnt lgkmcnt(2)
; template <int R, bool INV> DEV void dft_regs(cf (&v)[R]) {
; #pragma unroll
;     for (int s = R; s >= 2; s >>= 1) {
;         const int h = s >> 1;
; #pragma unroll
;         for (int b = 0; b < R; b += s) {
; #pragma unroll
;             for (int k = 0; k < h; ++k) {
;                 const cf a = v[b + k], c = v[b + k + h];
;                 v[b + k] = a + c;
;                 const cf d = a - c;
;                 const int m = k * (32 / s);
;                 const float wr = tw_cos(m), wi = INV ? tw_sin(m) : -tw_sin(m);
;                 v[b + k + h] = cf{d.x * wr - d.y * wi, d.x * wi + d.y * wr};
;             }
;         }
;     }
	v_pk_mul_f32 v[68:69], v[2:3], v[68:69]
	v_pk_mul_f32 v[62:63], v[44:45], s[84:85] op_sel_hi:[0,1]
	v_pk_fma_f32 v[44:45], v[44:45], s[24:25], v[62:63] op_sel:[1,0,0] neg_lo:[0,0,1] neg_hi:[0,0,1]
	v_pk_fma_f32 v[62:63], v[2:3], v[48:49], v[66:67]
	v_pk_fma_f32 v[48:49], v[2:3], v[48:49], v[66:67] neg_lo:[0,0,1] neg_hi:[0,0,1]
	v_pk_fma_f32 v[64:65], v[2:3], v[50:51], v[68:69]
	v_pk_fma_f32 v[2:3], v[2:3], v[50:51], v[68:69] neg_lo:[0,0,1] neg_hi:[0,0,1]
	v_mul_f32_e32 v36, 0x3f3504f3, v48
	v_pk_mul_f32 v[50:51], v[2:3], s[28:29] op_sel_hi:[0,1]
	v_pk_fma_f32 v[2:3], v[2:3], s[26:27], v[50:51] op_sel:[1,0,0] neg_lo:[0,0,1] neg_hi:[0,0,1]
	v_pk_add_f32 v[50:51], v[140:141], v[38:39]
	v_pk_add_f32 v[38:39], v[140:141], v[38:39] neg_lo:[0,1] neg_hi:[0,1]
	v_pk_fma_f32 v[48:49], v[48:49], s[6:7], v[36:37] op_sel:[1,0,0] op_sel_hi:[1,1,0] neg_lo:[0,0,1] neg_hi:[0,0,1]
	v_pk_mul_f32 v[66:67], v[38:39], 0 op_sel_hi:[1,0]
	v_mov_b32_e32 v59, v37
	v_pk_add_f32 v[68:69], v[38:39], v[66:67] op_sel:[0,1] op_sel_hi:[1,0] neg_lo:[0,1] neg_hi:[0,1]
	v_pk_add_f32 v[38:39], v[38:39], v[66:67] op_sel:[0,1] op_sel_hi:[1,0]
	v_pk_add_f32 v[36:37], v[58:59], v[48:49]
	v_mov_b32_e32 v69, v39
	v_pk_add_f32 v[38:39], v[30:31], v[42:43]
	v_pk_add_f32 v[30:31], v[30:31], v[42:43] neg_lo:[0,1] neg_hi:[0,1]
	v_pk_mul_f32 v[24:25], v[4:5], v[24:25]
	v_pk_mul_f32 v[42:43], v[30:31], s[2:3] op_sel_hi:[1,0]
	v_pk_mul_f32 v[26:27], v[4:5], v[26:27]
	v_pk_fma_f32 v[66:67], v[30:31], s[2:3], v[42:43] op_sel:[0,0,1] op_sel_hi:[1,0,0]
	v_pk_fma_f32 v[30:31], v[30:31], s[2:3], v[42:43] op_sel_hi:[1,0,0] neg_lo:[0,0,1] neg_hi:[0,0,1]
	v_pk_add_f32 v[42:43], v[32:33], v[62:63]
	v_pk_add_f32 v[32:33], v[32:33], v[62:63] neg_lo:[0,1] neg_hi:[0,1]
	v_mov_b32_e32 v67, v31
	v_pk_fma_f32 v[62:63], v[32:33], 0, v[32:33] op_sel:[0,0,1] op_sel_hi:[1,0,0]
	v_pk_fma_f32 v[32:33], v[32:33], 0, v[32:33] op_sel:[0,0,1] op_sel_hi:[1,0,0] neg_lo:[0,0,1] neg_hi:[0,0,1]
	v_pk_mul_f32 v[28:29], v[4:5], v[28:29]
	v_mov_b32_e32 v63, v33
	v_pk_add_f32 v[32:33], v[52:53], v[64:65]
	v_pk_add_f32 v[52:53], v[52:53], v[64:65] neg_lo:[0,1] neg_hi:[0,1]
	v_pk_add_f32 v[64:65], v[142:143], v[60:61]
	v_pk_add_f32 v[60:61], v[142:143], v[60:61] neg_lo:[0,1] neg_hi:[0,1]
	v_mul_f32_e32 v30, 0x3f3504f3, v52
	v_pk_mul_f32 v[140:141], v[60:61], 0 op_sel_hi:[1,0]
	v_pk_fma_f32 v[52:53], v[52:53], s[6:7], v[30:31] op_sel:[1,0,0] op_sel_hi:[1,1,0] neg_lo:[0,0,1] neg_hi:[0,0,1]
	v_pk_add_f32 v[142:143], v[60:61], v[140:141] op_sel:[0,1] op_sel_hi:[1,0] neg_lo:[0,1] neg_hi:[0,1]
	v_pk_add_f32 v[60:61], v[60:61], v[140:141] op_sel:[0,1] op_sel_hi:[1,0]
	v_pk_mul_f32 v[34:35], v[4:5], v[34:35]
	v_mov_b32_e32 v143, v61
	v_pk_add_f32 v[60:61], v[54:55], v[44:45]
	v_pk_add_f32 v[44:45], v[54:55], v[44:45] neg_lo:[0,1] neg_hi:[0,1]
	ds_read_b64 v[56:57], v75
	v_pk_mul_f32 v[54:55], v[44:45], s[2:3] op_sel_hi:[1,0]
	v_pk_mul_f32 v[40:41], v[4:5], v[40:41]
	v_pk_fma_f32 v[140:141], v[44:45], s[2:3], v[54:55] op_sel:[0,0,1] op_sel_hi:[1,0,0]
	v_pk_fma_f32 v[44:45], v[44:45], s[2:3], v[54:55] op_sel_hi:[1,0,0] neg_lo:[0,0,1] neg_hi:[0,0,1]
	v_pk_add_f32 v[54:55], v[50:51], v[42:43]
	v_mov_b32_e32 v141, v45
	v_pk_add_f32 v[44:45], v[58:59], v[48:49] neg_lo:[0,1] neg_hi:[0,1]
	v_pk_add_f32 v[42:43], v[50:51], v[42:43] neg_lo:[0,1] neg_hi:[0,1]
	v_pk_fma_f32 v[48:49], v[44:45], 0, v[44:45] op_sel:[0,0,1] op_sel_hi:[1,0,0]
	v_pk_fma_f32 v[44:45], v[44:45], 0, v[44:45] op_sel:[0,0,1] op_sel_hi:[1,0,0] neg_lo:[0,0,1] neg_hi:[0,0,1]
	v_pk_mul_f32 v[50:51], v[42:43], 0 op_sel_hi:[1,0]
	v_mov_b32_e32 v49, v45
	v_pk_add_f32 v[44:45], v[144:145], v[2:3]
	v_pk_add_f32 v[2:3], v[144:145], v[2:3] neg_lo:[0,1] neg_hi:[0,1]
	v_pk_add_f32 v[144:145], v[42:43], v[50:51] op_sel:[0,1] op_sel_hi:[1,0] neg_lo:[0,1] neg_hi:[0,1]
	v_pk_add_f32 v[42:43], v[42:43], v[50:51] op_sel:[0,1] op_sel_hi:[1,0]
	v_pk_add_f32 v[50:51], v[68:69], v[62:63] neg_lo:[0,1] neg_hi:[0,1]
	v_mov_b32_e32 v145, v43
	v_pk_add_f32 v[42:43], v[38:39], v[32:33]
	v_pk_add_f32 v[32:33], v[38:39], v[32:33] neg_lo:[0,1] neg_hi:[0,1]
	v_mul_f32_e32 v30, 0x3f3504f3, v2
	v_pk_fma_f32 v[38:39], v[32:33], 0, v[32:33] op_sel:[0,0,1] op_sel_hi:[1,0,0]
	v_pk_fma_f32 v[32:33], v[32:33], 0, v[32:33] op_sel:[0,0,1] op_sel_hi:[1,0,0] neg_lo:[0,0,1] neg_hi:[0,0,1]
	v_pk_mul_f32 v[58:59], v[50:51], 0 op_sel_hi:[1,0]
	v_pk_fma_f32 v[2:3], v[2:3], s[6:7], v[30:31] op_sel:[1,0,0] op_sel_hi:[1,1,0] neg_lo:[0,0,1] neg_hi:[0,0,1]
	v_mov_b32_e32 v39, v33
	v_pk_add_f32 v[32:33], v[68:69], v[62:63]
	v_pk_add_f32 v[62:63], v[50:51], v[58:59] op_sel:[0,1] op_sel_hi:[1,0] neg_lo:[0,1] neg_hi:[0,1]
	v_pk_add_f32 v[50:51], v[50:51], v[58:59] op_sel:[0,1] op_sel_hi:[1,0]
	v_pk_add_f32 v[30:31], v[66:67], v[52:53] neg_lo:[0,1] neg_hi:[0,1]
	v_mov_b32_e32 v63, v51
	v_pk_add_f32 v[50:51], v[66:67], v[52:53]
	v_pk_fma_f32 v[66:67], v[30:31], 0, v[30:31] op_sel:[0,0,1] op_sel_hi:[1,0,0]
	v_pk_fma_f32 v[30:31], v[30:31], 0, v[30:31] op_sel:[0,0,1] op_sel_hi:[1,0,0] neg_lo:[0,0,1] neg_hi:[0,0,1]
	v_pk_add_f32 v[68:69], v[64:65], v[36:37]
	v_mov_b32_e32 v67, v31
	v_pk_add_f32 v[30:31], v[64:65], v[36:37] neg_lo:[0,1] neg_hi:[0,1]
	v_pk_add_f32 v[146:147], v[60:61], v[44:45]
	v_pk_mul_f32 v[36:37], v[30:31], 0 op_sel_hi:[1,0]
	v_pk_add_f32 v[150:151], v[140:141], v[2:3]
	v_pk_add_f32 v[64:65], v[30:31], v[36:37] op_sel:[0,1] op_sel_hi:[1,0] neg_lo:[0,1] neg_hi:[0,1]
	v_pk_add_f32 v[30:31], v[30:31], v[36:37] op_sel:[0,1] op_sel_hi:[1,0]
	v_pk_add_f32 v[2:3], v[140:141], v[2:3] neg_lo:[0,1] neg_hi:[0,1]
	v_mov_b32_e32 v65, v31
	v_pk_add_f32 v[30:31], v[60:61], v[44:45] neg_lo:[0,1] neg_hi:[0,1]
; template <int R, bool INV> DEV void dft_regs(cf (&v)[R]) {
; #pragma unroll
;     for (int s = R; s >= 2; s >>= 1) {
;         const int h = s >> 1;
; #pragma unroll
;         for (int b = 0; b < R; b += s) {
; #pragma unroll
;             for (int k = 0; k < h; ++k) {
;                 const cf a = v[b + k], c = v[b + k + h];
;                 v[b + k] = a + c;
;                 const cf d = a - c;
;                 const int m = k * (32 / s);
;                 const float wr = tw_cos(m), wi = INV ? tw_sin(m) : -tw_sin(m);
;                 v[b + k + h] = cf{d.x * wr - d.y * wi, d.x * wi + d.y * wr};
;             }
;         }
;     }
; DEV void filt_channel_unit2(int c, const bf16_t* h2b, const float* w3, unsigned* KF, LAS unsigned char* lds, int tid) {
;     ...
;         for (int q = 0; q < 16; ++q) { v[q] = buf0[PADI(tid + 512 * q)] * in0; u[q] = buf1[PADI(tid + 512 * q)] * in1; }
;         dft_regs<16, false>(v); dft_regs<16, false>(u);
	v_pk_fma_f32 v[140:141], v[2:3], 0, v[2:3] op_sel:[0,0,1] op_sel_hi:[1,0,0]
	v_pk_fma_f32 v[44:45], v[30:31], 0, v[30:31] op_sel:[0,0,1] op_sel_hi:[1,0,0]
	v_pk_fma_f32 v[30:31], v[30:31], 0, v[30:31] op_sel:[0,0,1] op_sel_hi:[1,0,0] neg_lo:[0,0,1] neg_hi:[0,0,1]
	v_pk_fma_f32 v[2:3], v[2:3], 0, v[2:3] op_sel:[0,0,1] op_sel_hi:[1,0,0] neg_lo:[0,0,1] neg_hi:[0,0,1]
	v_mov_b32_e32 v45, v31
	v_pk_add_f32 v[30:31], v[142:143], v[48:49] neg_lo:[0,1] neg_hi:[0,1]
	v_pk_add_f32 v[148:149], v[142:143], v[48:49]
	v_pk_mul_f32 v[36:37], v[30:31], 0 op_sel_hi:[1,0]
	v_mov_b32_e32 v141, v3
	v_pk_add_f32 v[142:143], v[30:31], v[36:37] op_sel:[0,1] op_sel_hi:[1,0] neg_lo:[0,1] neg_hi:[0,1]
	v_pk_add_f32 v[30:31], v[30:31], v[36:37] op_sel:[0,1] op_sel_hi:[1,0]
	v_pk_add_f32 v[2:3], v[54:55], v[42:43] neg_lo:[0,1] neg_hi:[0,1]
	v_mov_b32_e32 v143, v31
	v_pk_mul_f32 v[30:31], v[2:3], 0 op_sel_hi:[1,0]
	v_pk_add_f32 v[52:53], v[144:145], v[38:39]
	v_pk_add_f32 v[36:37], v[2:3], v[30:31] op_sel:[0,1] op_sel_hi:[1,0] neg_lo:[0,1] neg_hi:[0,1]
	v_pk_add_f32 v[2:3], v[2:3], v[30:31] op_sel:[0,1] op_sel_hi:[1,0]
	v_pk_add_f32 v[60:61], v[32:33], v[50:51]
	v_mov_b32_e32 v37, v3
	v_pk_add_f32 v[2:3], v[144:145], v[38:39] neg_lo:[0,1] neg_hi:[0,1]
	v_pk_add_f32 v[58:59], v[54:55], v[42:43]
	v_pk_mul_f32 v[38:39], v[2:3], 0 op_sel_hi:[1,0]
	v_pk_add_f32 v[54:55], v[62:63], v[66:67]
	v_pk_add_f32 v[30:31], v[2:3], v[38:39] op_sel:[0,1] op_sel_hi:[1,0] neg_lo:[0,1] neg_hi:[0,1]
	v_pk_add_f32 v[2:3], v[2:3], v[38:39] op_sel:[0,1] op_sel_hi:[1,0]
	v_pk_mul_f32 v[46:47], v[4:5], v[46:47]
	v_mov_b32_e32 v31, v3
	v_pk_add_f32 v[2:3], v[32:33], v[50:51] neg_lo:[0,1] neg_hi:[0,1]
	s_waitcnt lgkmcnt(0)
	v_pk_mul_f32 v[56:57], v[4:5], v[56:57]
	v_pk_mul_f32 v[32:33], v[2:3], 0 op_sel_hi:[1,0]
	v_pk_mul_f32 v[70:71], v[4:5], v[70:71]
	v_pk_add_f32 v[38:39], v[2:3], v[32:33] op_sel:[0,1] op_sel_hi:[1,0] neg_lo:[0,1] neg_hi:[0,1]
	v_pk_add_f32 v[2:3], v[2:3], v[32:33] op_sel:[0,1] op_sel_hi:[1,0]
	s_nop 0
	v_mov_b32_e32 v39, v3
	v_pk_add_f32 v[2:3], v[62:63], v[66:67] neg_lo:[0,1] neg_hi:[0,1]
	v_pk_add_f32 v[62:63], v[64:65], v[44:45]
	v_pk_mul_f32 v[42:43], v[2:3], 0 op_sel_hi:[1,0]
	v_pk_add_f32 v[66:67], v[68:69], v[146:147]
	v_pk_add_f32 v[32:33], v[2:3], v[42:43] op_sel:[0,1] op_sel_hi:[1,0] neg_lo:[0,1] neg_hi:[0,1]
	v_pk_add_f32 v[2:3], v[2:3], v[42:43] op_sel:[0,1] op_sel_hi:[1,0]
	s_nop 0
	v_mov_b32_e32 v33, v3
	v_pk_add_f32 v[2:3], v[68:69], v[146:147] neg_lo:[0,1] neg_hi:[0,1]
	v_pk_add_f32 v[68:69], v[148:149], v[150:151]
	v_pk_mul_f32 v[42:43], v[2:3], 0 op_sel_hi:[1,0]
	s_nop 0
	v_pk_add_f32 v[48:49], v[2:3], v[42:43] op_sel:[0,1] op_sel_hi:[1,0] neg_lo:[0,1] neg_hi:[0,1]
	v_pk_add_f32 v[2:3], v[2:3], v[42:43] op_sel:[0,1] op_sel_hi:[1,0]
	s_nop 0
	v_mov_b32_e32 v49, v3
	v_pk_add_f32 v[2:3], v[64:65], v[44:45] neg_lo:[0,1] neg_hi:[0,1]
	v_pk_add_f32 v[64:65], v[142:143], v[140:141]
	v_pk_mul_f32 v[44:45], v[2:3], 0 op_sel_hi:[1,0]
	s_nop 0
	v_pk_add_f32 v[42:43], v[2:3], v[44:45] op_sel:[0,1] op_sel_hi:[1,0] neg_lo:[0,1] neg_hi:[0,1]
	v_pk_add_f32 v[2:3], v[2:3], v[44:45] op_sel:[0,1] op_sel_hi:[1,0]
	s_nop 0
	v_mov_b32_e32 v43, v3
	v_pk_add_f32 v[2:3], v[148:149], v[150:151] neg_lo:[0,1] neg_hi:[0,1]
	s_nop 0
	v_pk_mul_f32 v[44:45], v[2:3], 0 op_sel_hi:[1,0]
	s_nop 0
	v_pk_add_f32 v[50:51], v[2:3], v[44:45] op_sel:[0,1] op_sel_hi:[1,0] neg_lo:[0,1] neg_hi:[0,1]
	v_pk_add_f32 v[2:3], v[2:3], v[44:45] op_sel:[0,1] op_sel_hi:[1,0]
	s_nop 0
	v_mov_b32_e32 v51, v3
	v_pk_add_f32 v[2:3], v[142:143], v[140:141] neg_lo:[0,1] neg_hi:[0,1]
	s_nop 0
	v_pk_mul_f32 v[140:141], v[2:3], 0 op_sel_hi:[1,0]
	s_nop 0
	v_pk_add_f32 v[44:45], v[2:3], v[140:141] op_sel:[0,1] op_sel_hi:[1,0] neg_lo:[0,1] neg_hi:[0,1]
	v_pk_add_f32 v[2:3], v[2:3], v[140:141] op_sel:[0,1] op_sel_hi:[1,0]
	s_nop 0
	v_mov_b32_e32 v45, v3
	v_pk_fma_f32 v[2:3], v[4:5], v[6:7], v[24:25]
	v_pk_fma_f32 v[6:7], v[4:5], v[6:7], v[24:25] neg_lo:[0,0,1] neg_hi:[0,0,1]
	s_nop 0
	v_pk_mul_f32 v[24:25], v[6:7], 0 op_sel_hi:[1,0]
	s_nop 0
	v_pk_add_f32 v[140:141], v[6:7], v[24:25] op_sel:[0,1] op_sel_hi:[1,0] neg_lo:[0,1] neg_hi:[0,1]
	v_pk_add_f32 v[6:7], v[6:7], v[24:25] op_sel:[0,1] op_sel_hi:[1,0]
	s_nop 0
	v_mov_b32_e32 v141, v7
	v_pk_fma_f32 v[6:7], v[4:5], v[8:9], v[26:27]
	v_pk_fma_f32 v[8:9], v[4:5], v[8:9], v[26:27] neg_lo:[0,0,1] neg_hi:[0,0,1]
	s_nop 0
	v_pk_mul_f32 v[24:25], v[8:9], s[84:85] op_sel_hi:[1,0]
	s_nop 0
	v_pk_fma_f32 v[26:27], v[8:9], s[22:23], v[24:25] op_sel:[0,0,1] op_sel_hi:[1,0,0]
	v_pk_fma_f32 v[8:9], v[8:9], s[22:23], v[24:25] op_sel:[0,0,1] op_sel_hi:[1,0,0] neg_lo:[0,0,1] neg_hi:[0,0,1]
	s_nop 0
	v_mov_b32_e32 v27, v9
	v_pk_fma_f32 v[8:9], v[4:5], v[10:11], v[28:29]
	v_pk_fma_f32 v[10:11], v[4:5], v[10:11], v[28:29] neg_lo:[0,0,1] neg_hi:[0,0,1]
	s_nop 0
	v_pk_mul_f32 v[24:25], v[10:11], s[2:3] op_sel_hi:[1,0]
	s_nop 0
	v_pk_fma_f32 v[28:29], v[10:11], s[2:3], v[24:25] op_sel:[0,0,1] op_sel_hi:[1,0,0]
	v_pk_fma_f32 v[10:11], v[10:11], s[2:3], v[24:25] op_sel_hi:[1,0,0] neg_lo:[0,0,1] neg_hi:[0,0,1]
	s_nop 0
	v_mov_b32_e32 v29, v11
	v_pk_fma_f32 v[10:11], v[4:5], v[12:13], v[34:35]
	v_pk_fma_f32 v[12:13], v[4:5], v[12:13], v[34:35] neg_lo:[0,0,1] neg_hi:[0,0,1]
	s_nop 0
	v_pk_mul_f32 v[24:25], v[12:13], s[22:23] op_sel_hi:[1,0]
	s_nop 0
	v_pk_fma_f32 v[34:35], v[12:13], s[84:85], v[24:25] op_sel:[0,0,1] op_sel_hi:[1,0,0]
	v_pk_fma_f32 v[12:13], v[12:13], s[84:85], v[24:25] op_sel:[0,0,1] op_sel_hi:[1,0,0] neg_lo:[0,0,1] neg_hi:[0,0,1]
	s_nop 0
	v_mov_b32_e32 v35, v13
	v_pk_fma_f32 v[12:13], v[4:5], v[14:15], v[40:41]
	v_pk_fma_f32 v[14:15], v[4:5], v[14:15], v[40:41] neg_lo:[0,0,1] neg_hi:[0,0,1]
; template <int R, bool INV> DEV void dft_regs(cf (&v)[R]) {
; #pragma unroll
;     for (int s = R; s >= 2; s >>= 1) {
;         const int h = s >> 1;
; #pragma unroll
;         for (int b = 0; b < R; b += s) {
; #pragma unroll
;             for (int k = 0; k < h; ++k) {
;                 const cf a = v[b + k], c = v[b + k + h];
;                 v[b + k] = a + c;
;                 const cf d = a - c;
;                 const int m = k * (32 / s);
;                 const float wr = tw_cos(m), wi = INV ? tw_sin(m) : -tw_sin(m);
;                 v[b + k + h] = cf{d.x * wr - d.y * wi, d.x * wi + d.y * wr};
;             }
;         }
;     }
	s_nop 0
	v_pk_fma_f32 v[24:25], v[14:15], 0, v[14:15] op_sel:[0,0,1] op_sel_hi:[1,0,0]
	v_pk_fma_f32 v[14:15], v[14:15], 0, v[14:15] op_sel:[0,0,1] op_sel_hi:[1,0,0] neg_lo:[0,0,1] neg_hi:[0,0,1]
	s_nop 0
	v_mov_b32_e32 v25, v15
	v_pk_fma_f32 v[14:15], v[4:5], v[16:17], v[46:47]
	v_pk_fma_f32 v[16:17], v[4:5], v[16:17], v[46:47] neg_lo:[0,0,1] neg_hi:[0,0,1]
	s_nop 0
	v_pk_mul_f32 v[40:41], v[16:17], s[84:85] op_sel_hi:[0,1]
	v_pk_fma_f32 v[16:17], v[16:17], s[24:25], v[40:41] op_sel:[1,0,0] neg_lo:[0,0,1] neg_hi:[0,0,1]
	v_pk_fma_f32 v[40:41], v[4:5], v[18:19], v[56:57]
	v_pk_fma_f32 v[18:19], v[4:5], v[18:19], v[56:57] neg_lo:[0,0,1] neg_hi:[0,0,1]
	s_nop 0
	v_mul_f32_e32 v46, 0x3f3504f3, v18
	v_pk_fma_f32 v[18:19], v[18:19], s[6:7], v[46:47] op_sel:[1,0,0] op_sel_hi:[1,1,0] neg_lo:[0,0,1] neg_hi:[0,0,1]
	v_pk_fma_f32 v[46:47], v[4:5], v[22:23], v[70:71]
	v_pk_fma_f32 v[4:5], v[4:5], v[22:23], v[70:71] neg_lo:[0,0,1] neg_hi:[0,0,1]
	s_nop 0
	v_pk_mul_f32 v[22:23], v[4:5], s[28:29] op_sel_hi:[0,1]
	v_pk_fma_f32 v[4:5], v[4:5], s[26:27], v[22:23] op_sel:[1,0,0] neg_lo:[0,0,1] neg_hi:[0,0,1]
	v_pk_add_f32 v[22:23], v[2:3], v[12:13]
	v_pk_add_f32 v[2:3], v[2:3], v[12:13] neg_lo:[0,1] neg_hi:[0,1]
	s_nop 0
	v_pk_mul_f32 v[12:13], v[2:3], 0 op_sel_hi:[1,0]
	s_nop 0
	v_pk_add_f32 v[56:57], v[2:3], v[12:13] op_sel:[0,1] op_sel_hi:[1,0] neg_lo:[0,1] neg_hi:[0,1]
	v_pk_add_f32 v[2:3], v[2:3], v[12:13] op_sel:[0,1] op_sel_hi:[1,0]
	s_nop 0
	v_mov_b32_e32 v57, v3
	v_pk_add_f32 v[2:3], v[6:7], v[14:15]
	v_pk_add_f32 v[6:7], v[6:7], v[14:15] neg_lo:[0,1] neg_hi:[0,1]
	s_nop 0
	v_pk_mul_f32 v[12:13], v[6:7], s[2:3] op_sel_hi:[1,0]
	s_nop 0
	v_pk_fma_f32 v[14:15], v[6:7], s[2:3], v[12:13] op_sel:[0,0,1] op_sel_hi:[1,0,0]
	v_pk_fma_f32 v[6:7], v[6:7], s[2:3], v[12:13] op_sel_hi:[1,0,0] neg_lo:[0,0,1] neg_hi:[0,0,1]
	s_nop 0
	v_mov_b32_e32 v15, v7
	v_pk_add_f32 v[6:7], v[8:9], v[40:41]
	v_pk_add_f32 v[8:9], v[8:9], v[40:41] neg_lo:[0,1] neg_hi:[0,1]
	s_nop 0
	v_pk_fma_f32 v[12:13], v[8:9], 0, v[8:9] op_sel:[0,0,1] op_sel_hi:[1,0,0]
	v_pk_fma_f32 v[8:9], v[8:9], 0, v[8:9] op_sel:[0,0,1] op_sel_hi:[1,0,0] neg_lo:[0,0,1] neg_hi:[0,0,1]
	s_nop 0
	v_mov_b32_e32 v13, v9
	v_pk_add_f32 v[8:9], v[10:11], v[46:47]
	v_pk_add_f32 v[10:11], v[10:11], v[46:47] neg_lo:[0,1] neg_hi:[0,1]
	s_nop 0
	v_mul_f32_e32 v40, 0x3f3504f3, v10
	v_pk_fma_f32 v[10:11], v[10:11], s[6:7], v[40:41] op_sel:[1,0,0] op_sel_hi:[1,1,0] neg_lo:[0,0,1] neg_hi:[0,0,1]
	v_pk_add_f32 v[40:41], v[140:141], v[24:25]
	v_pk_add_f32 v[24:25], v[140:141], v[24:25] neg_lo:[0,1] neg_hi:[0,1]
	s_nop 0
	v_pk_mul_f32 v[46:47], v[24:25], 0 op_sel_hi:[1,0]
	s_nop 0
	v_pk_add_f32 v[70:71], v[24:25], v[46:47] op_sel:[0,1] op_sel_hi:[1,0] neg_lo:[0,1] neg_hi:[0,1]
	v_pk_add_f32 v[24:25], v[24:25], v[46:47] op_sel:[0,1] op_sel_hi:[1,0]
	s_nop 0
	v_mov_b32_e32 v71, v25
	v_pk_add_f32 v[24:25], v[26:27], v[16:17]
	v_pk_add_f32 v[16:17], v[26:27], v[16:17] neg_lo:[0,1] neg_hi:[0,1]
	s_nop 0
	v_pk_mul_f32 v[26:27], v[16:17], s[2:3] op_sel_hi:[1,0]
	s_nop 0
	v_pk_fma_f32 v[46:47], v[16:17], s[2:3], v[26:27] op_sel:[0,0,1] op_sel_hi:[1,0,0]
	v_pk_fma_f32 v[16:17], v[16:17], s[2:3], v[26:27] op_sel_hi:[1,0,0] neg_lo:[0,0,1] neg_hi:[0,0,1]
	s_movk_i32 s3, 0x100
	v_mov_b32_e32 v47, v17
	v_pk_add_f32 v[16:17], v[28:29], v[18:19]
	v_pk_add_f32 v[18:19], v[28:29], v[18:19] neg_lo:[0,1] neg_hi:[0,1]
	v_cmp_gt_u32_e32 vcc, s3, v0
	v_pk_fma_f32 v[26:27], v[18:19], 0, v[18:19] op_sel:[0,0,1] op_sel_hi:[1,0,0]
	v_pk_fma_f32 v[18:19], v[18:19], 0, v[18:19] op_sel:[0,0,1] op_sel_hi:[1,0,0] neg_lo:[0,0,1] neg_hi:[0,0,1]
	s_nop 0
	v_mov_b32_e32 v27, v19
	v_pk_add_f32 v[18:19], v[34:35], v[4:5]
	v_pk_add_f32 v[4:5], v[34:35], v[4:5] neg_lo:[0,1] neg_hi:[0,1]
	s_nop 0
	v_mul_f32_e32 v28, 0x3f3504f3, v4
	v_pk_fma_f32 v[4:5], v[4:5], s[6:7], v[28:29] op_sel:[1,0,0] op_sel_hi:[1,1,0] neg_lo:[0,0,1] neg_hi:[0,0,1]
	v_pk_add_f32 v[28:29], v[22:23], v[6:7]
	v_pk_add_f32 v[6:7], v[22:23], v[6:7] neg_lo:[0,1] neg_hi:[0,1]
	s_nop 0
	v_pk_mul_f32 v[22:23], v[6:7], 0 op_sel_hi:[1,0]
	s_nop 0
	v_pk_add_f32 v[34:35], v[6:7], v[22:23] op_sel:[0,1] op_sel_hi:[1,0] neg_lo:[0,1] neg_hi:[0,1]
	v_pk_add_f32 v[6:7], v[6:7], v[22:23] op_sel:[0,1] op_sel_hi:[1,0]
	s_nop 0
	v_mov_b32_e32 v35, v7
	v_pk_add_f32 v[6:7], v[2:3], v[8:9]
	v_pk_add_f32 v[2:3], v[2:3], v[8:9] neg_lo:[0,1] neg_hi:[0,1]
	s_nop 0
	v_pk_fma_f32 v[8:9], v[2:3], 0, v[2:3] op_sel:[0,0,1] op_sel_hi:[1,0,0]
	v_pk_fma_f32 v[2:3], v[2:3], 0, v[2:3] op_sel:[0,0,1] op_sel_hi:[1,0,0] neg_lo:[0,0,1] neg_hi:[0,0,1]
	s_nop 0
	v_mov_b32_e32 v9, v3
	v_pk_add_f32 v[2:3], v[56:57], v[12:13]
	v_pk_add_f32 v[12:13], v[56:57], v[12:13] neg_lo:[0,1] neg_hi:[0,1]
	s_nop 0
	v_pk_mul_f32 v[22:23], v[12:13], 0 op_sel_hi:[1,0]
	s_nop 0
	v_pk_add_f32 v[56:57], v[12:13], v[22:23] op_sel:[0,1] op_sel_hi:[1,0] neg_lo:[0,1] neg_hi:[0,1]
	v_pk_add_f32 v[12:13], v[12:13], v[22:23] op_sel:[0,1] op_sel_hi:[1,0]
	s_nop 0
	v_mov_b32_e32 v57, v13
	v_pk_add_f32 v[12:13], v[14:15], v[10:11]
	v_pk_add_f32 v[10:11], v[14:15], v[10:11] neg_lo:[0,1] neg_hi:[0,1]
	s_nop 0
	v_pk_fma_f32 v[14:15], v[10:11], 0, v[10:11] op_sel:[0,0,1] op_sel_hi:[1,0,0]
	v_pk_fma_f32 v[10:11], v[10:11], 0, v[10:11] op_sel:[0,0,1] op_sel_hi:[1,0,0] neg_lo:[0,0,1] neg_hi:[0,0,1]
	s_nop 0
	v_mov_b32_e32 v15, v11
	v_pk_add_f32 v[10:11], v[40:41], v[16:17]
	v_pk_add_f32 v[16:17], v[40:41], v[16:17] neg_lo:[0,1] neg_hi:[0,1]
	s_nop 0
	v_pk_mul_f32 v[22:23], v[16:17], 0 op_sel_hi:[1,0]
	s_nop 0
	v_pk_add_f32 v[40:41], v[16:17], v[22:23] op_sel:[0,1] op_sel_hi:[1,0] neg_lo:[0,1] neg_hi:[0,1]
	v_pk_add_f32 v[16:17], v[16:17], v[22:23] op_sel:[0,1] op_sel_hi:[1,0]
; #define SINCOSPI(x, s, c) do { const float hx_ = 0.5f * (x); *(s) = __builtin_amdgcn_sinf(hx_); *(c) = __builtin_amdgcn_cosf(hx_); } while (0)
; template <int R, bool INV> DEV void dft_regs(cf (&v)[R]) {
; #pragma unroll
;     for (int s = R; s >= 2; s >>= 1) {
;         const int h = s >> 1;
; #pragma unroll
;         for (int b = 0; b < R; b += s) {
; #pragma unroll
;             for (int k = 0; k < h; ++k) {
;                 const cf a = v[b + k], c = v[b + k + h];
;                 v[b + k] = a + c;
;                 const cf d = a - c;
;                 const int m = k * (32 / s);
;                 const float wr = tw_cos(m), wi = INV ? tw_sin(m) : -tw_sin(m);
;                 v[b + k + h] = cf{d.x * wr - d.y * wi, d.x * wi + d.y * wr};
;             }
;         }
;     }
; DEV void filt_channel_unit2(int c, const bf16_t* h2b, const float* w3, unsigned* KF, LAS unsigned char* lds, int tid) {
;     ...
;         dft_regs<16, false>(v); dft_regs<16, false>(u);
;         float sn, cs; SINCOSPI(-(float)tid * (2.0f / 8192.0f), &sn, &cs);
;         const cf w = cf{cs, sn}; cf wp = cf{1.f, 0.f};
; #pragma unroll
;         for (int p = 0; p < 16; ++p) { buf0[PADI(tid + 512 * p)] = cmul(v[BR16[p]], wp); buf1[PADI(tid + 512 * p)] = cmul(u[BR16[p]], wp); wp = cmul(wp, w); }
	s_nop 0
	v_mov_b32_e32 v41, v17
	v_pk_add_f32 v[16:17], v[24:25], v[18:19]
	v_pk_add_f32 v[18:19], v[24:25], v[18:19] neg_lo:[0,1] neg_hi:[0,1]
	v_pk_add_f32 v[24:25], v[70:71], v[26:27] neg_lo:[0,1] neg_hi:[0,1]
	v_pk_fma_f32 v[22:23], v[18:19], 0, v[18:19] op_sel:[0,0,1] op_sel_hi:[1,0,0]
	v_pk_fma_f32 v[18:19], v[18:19], 0, v[18:19] op_sel:[0,0,1] op_sel_hi:[1,0,0] neg_lo:[0,0,1] neg_hi:[0,0,1]
	s_nop 0
	v_mov_b32_e32 v23, v19
	v_pk_add_f32 v[18:19], v[70:71], v[26:27]
	v_pk_mul_f32 v[26:27], v[24:25], 0 op_sel_hi:[1,0]
	s_nop 0
	v_pk_add_f32 v[70:71], v[24:25], v[26:27] op_sel:[0,1] op_sel_hi:[1,0] neg_lo:[0,1] neg_hi:[0,1]
	v_pk_add_f32 v[24:25], v[24:25], v[26:27] op_sel:[0,1] op_sel_hi:[1,0]
	s_nop 0
	v_mov_b32_e32 v71, v25
	v_pk_add_f32 v[24:25], v[46:47], v[4:5]
	v_pk_add_f32 v[4:5], v[46:47], v[4:5] neg_lo:[0,1] neg_hi:[0,1]
	s_nop 0
	v_pk_fma_f32 v[26:27], v[4:5], 0, v[4:5] op_sel:[0,0,1] op_sel_hi:[1,0,0]
	v_pk_fma_f32 v[4:5], v[4:5], 0, v[4:5] op_sel:[0,0,1] op_sel_hi:[1,0,0] neg_lo:[0,0,1] neg_hi:[0,0,1]
	s_nop 0
	v_mov_b32_e32 v27, v5
	v_pk_add_f32 v[4:5], v[28:29], v[6:7]
	v_pk_add_f32 v[6:7], v[28:29], v[6:7] neg_lo:[0,1] neg_hi:[0,1]
	s_nop 0
	v_pk_mul_f32 v[28:29], v[6:7], 0 op_sel_hi:[1,0]
	s_nop 0
	v_pk_add_f32 v[46:47], v[6:7], v[28:29] op_sel:[0,1] op_sel_hi:[1,0] neg_lo:[0,1] neg_hi:[0,1]
	v_pk_add_f32 v[6:7], v[6:7], v[28:29] op_sel:[0,1] op_sel_hi:[1,0]
	s_nop 0
	v_mov_b32_e32 v47, v7
	v_pk_add_f32 v[6:7], v[34:35], v[8:9]
	v_pk_add_f32 v[8:9], v[34:35], v[8:9] neg_lo:[0,1] neg_hi:[0,1]
	s_nop 0
	v_pk_mul_f32 v[28:29], v[8:9], 0 op_sel_hi:[1,0]
	s_nop 0
	v_pk_add_f32 v[34:35], v[8:9], v[28:29] op_sel:[0,1] op_sel_hi:[1,0] neg_lo:[0,1] neg_hi:[0,1]
	v_pk_add_f32 v[8:9], v[8:9], v[28:29] op_sel:[0,1] op_sel_hi:[1,0]
	s_nop 0
	v_mov_b32_e32 v35, v9
	v_pk_add_f32 v[8:9], v[2:3], v[12:13]
	v_pk_add_f32 v[2:3], v[2:3], v[12:13] neg_lo:[0,1] neg_hi:[0,1]
	s_nop 0
	v_pk_mul_f32 v[12:13], v[2:3], 0 op_sel_hi:[1,0]
	s_nop 0
	v_pk_add_f32 v[28:29], v[2:3], v[12:13] op_sel:[0,1] op_sel_hi:[1,0] neg_lo:[0,1] neg_hi:[0,1]
	v_pk_add_f32 v[2:3], v[2:3], v[12:13] op_sel:[0,1] op_sel_hi:[1,0]
	v_pk_add_f32 v[12:13], v[56:57], v[14:15]
	v_mov_b32_e32 v29, v3
	v_pk_add_f32 v[2:3], v[56:57], v[14:15] neg_lo:[0,1] neg_hi:[0,1]
	s_nop 0
	v_pk_mul_f32 v[14:15], v[2:3], 0 op_sel_hi:[1,0]
	s_nop 0
	v_pk_add_f32 v[56:57], v[2:3], v[14:15] op_sel:[0,1] op_sel_hi:[1,0] neg_lo:[0,1] neg_hi:[0,1]
	v_pk_add_f32 v[2:3], v[2:3], v[14:15] op_sel:[0,1] op_sel_hi:[1,0]
	v_pk_add_f32 v[14:15], v[10:11], v[16:17]
	v_mov_b32_e32 v57, v3
	v_pk_add_f32 v[2:3], v[10:11], v[16:17] neg_lo:[0,1] neg_hi:[0,1]
	s_nop 0
	v_pk_mul_f32 v[10:11], v[2:3], 0 op_sel_hi:[1,0]
	s_nop 0
	v_pk_add_f32 v[16:17], v[2:3], v[10:11] op_sel:[0,1] op_sel_hi:[1,0] neg_lo:[0,1] neg_hi:[0,1]
	v_pk_add_f32 v[2:3], v[2:3], v[10:11] op_sel:[0,1] op_sel_hi:[1,0]
	v_pk_add_f32 v[10:11], v[40:41], v[22:23]
	v_mov_b32_e32 v17, v3
	v_pk_add_f32 v[2:3], v[40:41], v[22:23] neg_lo:[0,1] neg_hi:[0,1]
	s_nop 0
	v_pk_mul_f32 v[22:23], v[2:3], 0 op_sel_hi:[1,0]
	s_nop 0
	v_pk_add_f32 v[40:41], v[2:3], v[22:23] op_sel:[0,1] op_sel_hi:[1,0] neg_lo:[0,1] neg_hi:[0,1]
	v_pk_add_f32 v[2:3], v[2:3], v[22:23] op_sel:[0,1] op_sel_hi:[1,0]
	v_pk_add_f32 v[22:23], v[18:19], v[24:25]
	v_mov_b32_e32 v41, v3
	v_pk_add_f32 v[2:3], v[18:19], v[24:25] neg_lo:[0,1] neg_hi:[0,1]
	s_nop 0
	v_pk_mul_f32 v[18:19], v[2:3], 0 op_sel_hi:[1,0]
	s_nop 0
	v_pk_add_f32 v[24:25], v[2:3], v[18:19] op_sel:[0,1] op_sel_hi:[1,0] neg_lo:[0,1] neg_hi:[0,1]
	v_pk_add_f32 v[2:3], v[2:3], v[18:19] op_sel:[0,1] op_sel_hi:[1,0]
	v_pk_add_f32 v[18:19], v[70:71], v[26:27]
	v_mov_b32_e32 v25, v3
	v_pk_add_f32 v[2:3], v[70:71], v[26:27] neg_lo:[0,1] neg_hi:[0,1]
	s_nop 0
	v_pk_mul_f32 v[26:27], v[2:3], 0 op_sel_hi:[1,0]
	s_nop 0
	v_pk_add_f32 v[70:71], v[2:3], v[26:27] op_sel:[0,1] op_sel_hi:[1,0] neg_lo:[0,1] neg_hi:[0,1]
	v_pk_add_f32 v[2:3], v[2:3], v[26:27] op_sel:[0,1] op_sel_hi:[1,0]
	s_nop 0
	v_cvt_f32_i32_e32 v2, v0
	v_mov_b32_e32 v71, v3
	v_mul_f32_e32 v2, 0xb9800000, v2
	v_mul_f32_e32 v2, 0.5, v2
	v_sin_f32_e32 v27, v2
	v_cos_f32_e32 v26, v2
	v_mov_b64_e32 v[2:3], s[90:91]
	v_pk_mul_f32 v[140:141], v[58:59], v[2:3] op_sel:[1,1] op_sel_hi:[1,0] neg_lo:[1,0]
	v_pk_fma_f32 v[58:59], v[58:59], v[2:3], v[140:141] op_sel_hi:[0,1,1]
	ds_write_b64 v137, v[58:59]
	v_pk_mul_f32 v[58:59], v[4:5], v[2:3] op_sel:[1,1] op_sel_hi:[1,0] neg_lo:[1,0]
	v_pk_fma_f32 v[4:5], v[4:5], v[2:3], v[58:59] op_sel_hi:[0,1,1]
	ds_write_b64 v1, v[4:5]
	v_pk_mul_f32 v[4:5], v[2:3], v[26:27] op_sel:[1,1] op_sel_hi:[1,0] neg_lo:[1,0]
	v_pk_fma_f32 v[58:59], v[2:3], v[26:27], v[4:5] op_sel_hi:[0,1,1]
	v_pk_mul_f32 v[140:141], v[66:67], v[58:59] op_sel:[1,1] op_sel_hi:[1,0] neg_lo:[1,0]
	v_pk_fma_f32 v[4:5], v[66:67], v[58:59], v[140:141] op_sel_hi:[0,1,1]
	ds_write_b64 v135, v[4:5] offset:4096
	v_pk_mul_f32 v[66:67], v[14:15], v[58:59] op_sel:[1,1] op_sel_hi:[1,0] neg_lo:[1,0]
	v_pk_fma_f32 v[4:5], v[14:15], v[58:59], v[66:67] op_sel_hi:[0,1,1]
	ds_write_b64 v134, v[4:5]
	v_pk_mul_f32 v[4:5], v[58:59], v[26:27] op_sel:[1,1] op_sel_hi:[1,0] neg_lo:[1,0]
	v_pk_fma_f32 v[14:15], v[58:59], v[26:27], v[4:5] op_sel_hi:[0,1,1]
	v_pk_mul_f32 v[58:59], v[60:61], v[14:15] op_sel:[1,1] op_sel_hi:[1,0] neg_lo:[1,0]
	v_pk_fma_f32 v[4:5], v[60:61], v[14:15], v[58:59] op_sel_hi:[0,1,1]
	ds_write_b64 v132, v[4:5] offset:8192
	v_pk_mul_f32 v[58:59], v[8:9], v[14:15] op_sel:[1,1] op_sel_hi:[1,0] neg_lo:[1,0]
	v_pk_fma_f32 v[4:5], v[8:9], v[14:15], v[58:59] op_sel_hi:[0,1,1]
	ds_write_b64 v131, v[4:5]
	v_pk_mul_f32 v[4:5], v[14:15], v[26:27] op_sel:[1,1] op_sel_hi:[1,0] neg_lo:[1,0]
; #define SINCOSPI(x, s, c) do { const float hx_ = 0.5f * (x); *(s) = __builtin_amdgcn_sinf(hx_); *(c) = __builtin_amdgcn_cosf(hx_); } while (0)
; DEV void filt_channel_unit2(int c, const bf16_t* h2b, const float* w3, unsigned* KF, LAS unsigned char* lds, int tid) {
;     ...
;         float sn, cs; SINCOSPI(-(float)tid * (2.0f / 8192.0f), &sn, &cs);
;         const cf w = cf{cs, sn}; cf wp = cf{1.f, 0.f};
; #pragma unroll
;         for (int p = 0; p < 16; ++p) { buf0[PADI(tid + 512 * p)] = cmul(v[BR16[p]], wp); buf1[PADI(tid + 512 * p)] = cmul(u[BR16[p]], wp); wp = cmul(wp, w); }
	v_pk_fma_f32 v[8:9], v[14:15], v[26:27], v[4:5] op_sel_hi:[0,1,1]
	v_pk_mul_f32 v[14:15], v[68:69], v[8:9] op_sel:[1,1] op_sel_hi:[1,0] neg_lo:[1,0]
	v_pk_fma_f32 v[4:5], v[68:69], v[8:9], v[14:15] op_sel_hi:[0,1,1]
	ds_write_b64 v129, v[4:5] offset:12288
	v_pk_mul_f32 v[14:15], v[22:23], v[8:9] op_sel:[1,1] op_sel_hi:[1,0] neg_lo:[1,0]
	v_pk_fma_f32 v[4:5], v[22:23], v[8:9], v[14:15] op_sel_hi:[0,1,1]
	ds_write_b64 v128, v[4:5]
	v_pk_mul_f32 v[4:5], v[8:9], v[26:27] op_sel:[1,1] op_sel_hi:[1,0] neg_lo:[1,0]
	v_pk_fma_f32 v[8:9], v[8:9], v[26:27], v[4:5] op_sel_hi:[0,1,1]
	v_pk_mul_f32 v[14:15], v[52:53], v[8:9] op_sel:[1,1] op_sel_hi:[1,0] neg_lo:[1,0]
	v_pk_fma_f32 v[4:5], v[52:53], v[8:9], v[14:15] op_sel_hi:[0,1,1]
	ds_write_b64 v126, v[4:5] offset:16384
	v_pk_mul_f32 v[14:15], v[6:7], v[8:9] op_sel:[1,1] op_sel_hi:[1,0] neg_lo:[1,0]
	v_pk_fma_f32 v[4:5], v[6:7], v[8:9], v[14:15] op_sel_hi:[0,1,1]
	ds_write_b64 v125, v[4:5]
	v_pk_mul_f32 v[4:5], v[8:9], v[26:27] op_sel:[1,1] op_sel_hi:[1,0] neg_lo:[1,0]
	v_pk_fma_f32 v[6:7], v[8:9], v[26:27], v[4:5] op_sel_hi:[0,1,1]
	v_pk_mul_f32 v[8:9], v[62:63], v[6:7] op_sel:[1,1] op_sel_hi:[1,0] neg_lo:[1,0]
	v_pk_fma_f32 v[4:5], v[62:63], v[6:7], v[8:9] op_sel_hi:[0,1,1]
	ds_write_b64 v123, v[4:5] offset:20480
	v_pk_mul_f32 v[8:9], v[10:11], v[6:7] op_sel:[1,1] op_sel_hi:[1,0] neg_lo:[1,0]
	v_pk_fma_f32 v[4:5], v[10:11], v[6:7], v[8:9] op_sel_hi:[0,1,1]
	ds_write_b64 v122, v[4:5]
	v_pk_mul_f32 v[4:5], v[6:7], v[26:27] op_sel:[1,1] op_sel_hi:[1,0] neg_lo:[1,0]
	v_pk_fma_f32 v[6:7], v[6:7], v[26:27], v[4:5] op_sel_hi:[0,1,1]
	v_pk_mul_f32 v[8:9], v[54:55], v[6:7] op_sel:[1,1] op_sel_hi:[1,0] neg_lo:[1,0]
	v_pk_fma_f32 v[4:5], v[54:55], v[6:7], v[8:9] op_sel_hi:[0,1,1]
	ds_write_b64 v120, v[4:5] offset:24576
	v_pk_mul_f32 v[8:9], v[12:13], v[6:7] op_sel:[1,1] op_sel_hi:[1,0] neg_lo:[1,0]
	v_pk_fma_f32 v[4:5], v[12:13], v[6:7], v[8:9] op_sel_hi:[0,1,1]
	ds_write_b64 v119, v[4:5]
	v_pk_mul_f32 v[4:5], v[6:7], v[26:27] op_sel:[1,1] op_sel_hi:[1,0] neg_lo:[1,0]
	v_pk_fma_f32 v[6:7], v[6:7], v[26:27], v[4:5] op_sel_hi:[0,1,1]
	v_pk_mul_f32 v[8:9], v[64:65], v[6:7] op_sel:[1,1] op_sel_hi:[1,0] neg_lo:[1,0]
	v_pk_fma_f32 v[4:5], v[64:65], v[6:7], v[8:9] op_sel_hi:[0,1,1]
	ds_write_b64 v117, v[4:5] offset:28672
	v_pk_mul_f32 v[8:9], v[18:19], v[6:7] op_sel:[1,1] op_sel_hi:[1,0] neg_lo:[1,0]
	v_pk_fma_f32 v[4:5], v[18:19], v[6:7], v[8:9] op_sel_hi:[0,1,1]
	ds_write_b64 v116, v[4:5]
	v_pk_mul_f32 v[4:5], v[6:7], v[26:27] op_sel:[1,1] op_sel_hi:[1,0] neg_lo:[1,0]
	v_pk_fma_f32 v[6:7], v[6:7], v[26:27], v[4:5] op_sel_hi:[0,1,1]
	v_pk_mul_f32 v[8:9], v[36:37], v[6:7] op_sel:[1,1] op_sel_hi:[1,0] neg_lo:[1,0]
	v_pk_fma_f32 v[4:5], v[36:37], v[6:7], v[8:9] op_sel_hi:[0,1,1]
	ds_write_b64 v113, v[4:5] offset:32768
	v_pk_mul_f32 v[8:9], v[46:47], v[6:7] op_sel:[1,1] op_sel_hi:[1,0] neg_lo:[1,0]
	v_pk_fma_f32 v[4:5], v[46:47], v[6:7], v[8:9] op_sel_hi:[0,1,1]
	ds_write_b64 v114, v[4:5]
	v_pk_mul_f32 v[4:5], v[6:7], v[26:27] op_sel:[1,1] op_sel_hi:[1,0] neg_lo:[1,0]
	v_pk_fma_f32 v[6:7], v[6:7], v[26:27], v[4:5] op_sel_hi:[0,1,1]
	v_pk_mul_f32 v[8:9], v[48:49], v[6:7] op_sel:[1,1] op_sel_hi:[1,0] neg_lo:[1,0]
	v_pk_fma_f32 v[4:5], v[48:49], v[6:7], v[8:9] op_sel_hi:[0,1,1]
	ds_write_b64 v111, v[4:5] offset:36864
	v_pk_mul_f32 v[8:9], v[16:17], v[6:7] op_sel:[1,1] op_sel_hi:[1,0] neg_lo:[1,0]
	v_pk_fma_f32 v[4:5], v[16:17], v[6:7], v[8:9] op_sel_hi:[0,1,1]
	ds_write_b64 v110, v[4:5]
	v_pk_mul_f32 v[4:5], v[6:7], v[26:27] op_sel:[1,1] op_sel_hi:[1,0] neg_lo:[1,0]
	v_pk_fma_f32 v[6:7], v[6:7], v[26:27], v[4:5] op_sel_hi:[0,1,1]
	v_pk_mul_f32 v[8:9], v[38:39], v[6:7] op_sel:[1,1] op_sel_hi:[1,0] neg_lo:[1,0]
	v_pk_fma_f32 v[4:5], v[38:39], v[6:7], v[8:9] op_sel_hi:[0,1,1]
	ds_write_b64 v107, v[4:5] offset:40960
	v_pk_mul_f32 v[8:9], v[28:29], v[6:7] op_sel:[1,1] op_sel_hi:[1,0] neg_lo:[1,0]
	v_pk_fma_f32 v[4:5], v[28:29], v[6:7], v[8:9] op_sel_hi:[0,1,1]
	ds_write_b64 v108, v[4:5]
	v_pk_mul_f32 v[4:5], v[6:7], v[26:27] op_sel:[1,1] op_sel_hi:[1,0] neg_lo:[1,0]
	v_pk_fma_f32 v[6:7], v[6:7], v[26:27], v[4:5] op_sel_hi:[0,1,1]
	v_pk_mul_f32 v[8:9], v[50:51], v[6:7] op_sel:[1,1] op_sel_hi:[1,0] neg_lo:[1,0]
	v_pk_fma_f32 v[4:5], v[50:51], v[6:7], v[8:9] op_sel_hi:[0,1,1]
	ds_write_b64 v86, v[4:5] offset:45056
	v_pk_mul_f32 v[8:9], v[24:25], v[6:7] op_sel:[1,1] op_sel_hi:[1,0] neg_lo:[1,0]
	v_pk_fma_f32 v[4:5], v[24:25], v[6:7], v[8:9] op_sel_hi:[0,1,1]
	ds_write_b64 v85, v[4:5]
	v_pk_mul_f32 v[4:5], v[6:7], v[26:27] op_sel:[1,1] op_sel_hi:[1,0] neg_lo:[1,0]
	v_pk_fma_f32 v[6:7], v[6:7], v[26:27], v[4:5] op_sel_hi:[0,1,1]
	v_pk_mul_f32 v[8:9], v[30:31], v[6:7] op_sel:[1,1] op_sel_hi:[1,0] neg_lo:[1,0]
	v_pk_fma_f32 v[4:5], v[30:31], v[6:7], v[8:9] op_sel_hi:[0,1,1]
	ds_write_b64 v80, v[4:5] offset:49152
	v_pk_mul_f32 v[8:9], v[34:35], v[6:7] op_sel:[1,1] op_sel_hi:[1,0] neg_lo:[1,0]
	v_pk_fma_f32 v[4:5], v[34:35], v[6:7], v[8:9] op_sel_hi:[0,1,1]
	ds_write_b64 v81, v[4:5]
	v_pk_mul_f32 v[4:5], v[6:7], v[26:27] op_sel:[1,1] op_sel_hi:[1,0] neg_lo:[1,0]
	v_pk_fma_f32 v[6:7], v[6:7], v[26:27], v[4:5] op_sel_hi:[0,1,1]
	v_pk_mul_f32 v[8:9], v[42:43], v[6:7] op_sel:[1,1] op_sel_hi:[1,0] neg_lo:[1,0]
	v_pk_fma_f32 v[4:5], v[42:43], v[6:7], v[8:9] op_sel_hi:[0,1,1]
	ds_write_b64 v78, v[4:5] offset:53248
	v_pk_mul_f32 v[8:9], v[40:41], v[6:7] op_sel:[1,1] op_sel_hi:[1,0] neg_lo:[1,0]
	v_pk_fma_f32 v[4:5], v[40:41], v[6:7], v[8:9] op_sel_hi:[0,1,1]
	ds_write_b64 v77, v[4:5]
	v_pk_mul_f32 v[4:5], v[6:7], v[26:27] op_sel:[1,1] op_sel_hi:[1,0] neg_lo:[1,0]
	v_pk_fma_f32 v[6:7], v[6:7], v[26:27], v[4:5] op_sel_hi:[0,1,1]
	v_pk_mul_f32 v[8:9], v[32:33], v[6:7] op_sel:[1,1] op_sel_hi:[1,0] neg_lo:[1,0]
	v_pk_fma_f32 v[4:5], v[32:33], v[6:7], v[8:9] op_sel_hi:[0,1,1]
	ds_write_b64 v74, v[4:5] offset:57344
	v_pk_mul_f32 v[8:9], v[56:57], v[6:7] op_sel:[1,1] op_sel_hi:[1,0] neg_lo:[1,0]
	v_pk_fma_f32 v[4:5], v[56:57], v[6:7], v[8:9] op_sel_hi:[0,1,1]
	ds_write_b64 v75, v[4:5]
	v_pk_mul_f32 v[4:5], v[6:7], v[26:27] op_sel:[1,1] op_sel_hi:[1,0] neg_lo:[1,0]
	v_pk_fma_f32 v[6:7], v[6:7], v[26:27], v[4:5] op_sel_hi:[0,1,1]
	v_pk_mul_f32 v[8:9], v[44:45], v[6:7] op_sel:[1,1] op_sel_hi:[1,0] neg_lo:[1,0]
	v_pk_fma_f32 v[4:5], v[44:45], v[6:7], v[8:9] op_sel_hi:[0,1,1]
	ds_write_b64 v72, v[4:5] offset:61440
	v_pk_mul_f32 v[8:9], v[70:71], v[6:7] op_sel:[1,1] op_sel_hi:[1,0] neg_lo:[1,0]
	v_pk_fma_f32 v[4:5], v[70:71], v[6:7], v[8:9] op_sel_hi:[0,1,1]
	ds_write_b64 v21, v[4:5]
	v_and_b32_e32 v5, 0xff, v0
	s_waitcnt lgkmcnt(0)
	s_barrier
; #define LAS __attribute__((address_space(3)))
; #define SINCOSPI(x, s, c) do { const float hx_ = 0.5f * (x); *(s) = __builtin_amdgcn_sinf(hx_); *(c) = __builtin_amdgcn_cosf(hx_); } while (0)
; #define OPAQUE_I(x) asm volatile("" : "+v"(x))
; template <int R, bool INV> DEV void dft_regs(cf (&v)[R]) {
; #pragma unroll
;     for (int s = R; s >= 2; s >>= 1) {
;         const int h = s >> 1;
; #pragma unroll
;         for (int b = 0; b < R; b += s) {
; #pragma unroll
;             for (int k = 0; k < h; ++k) {
;                 const cf a = v[b + k], c = v[b + k + h];
;                 v[b + k] = a + c;
;                 const cf d = a - c;
;                 const int m = k * (32 / s);
;                 const float wr = tw_cos(m), wi = INV ? tw_sin(m) : -tw_sin(m);
;                 v[b + k + h] = cf{d.x * wr - d.y * wi, d.x * wi + d.y * wr};
; DEV void fft_f2(LAS cf* buf, int t8) {
;     OPAQUE_I(t8);
;     LAS cf* pb = buf + (t8 >> 4) * 544 + (t8 & 15);
;     cf v[32];
; #pragma unroll
;     for (int q = 0; q < 32; ++q) v[q] = pb[17 * q];
;     dft_regs<32, false>(v);
;     float sn, cs; SINCOSPI(-(float)(t8 & 15) * (2.0f / 512.0f), &sn, &cs);
	v_cndmask_b32_e64 v4, v138, 0, vcc
	v_lshrrev_b32_e32 v6, 4, v5
	v_and_b32_e32 v7, 15, v5
	v_mul_lo_u32 v6, v6, s15
	v_lshlrev_b32_e32 v5, 3, v7
	v_add3_u32 v6, v4, v6, v5
	ds_read2_b64 v[8:11], v6 offset1:17
	ds_read2_b64 v[12:15], v6 offset0:34 offset1:51
	ds_read2_b64 v[16:19], v6 offset0:68 offset1:85
	ds_read2_b64 v[22:25], v6 offset0:102 offset1:119
	ds_read2_b64 v[26:29], v6 offset0:136 offset1:153
	ds_read2_b64 v[30:33], v6 offset0:170 offset1:187
	ds_read2_b64 v[34:37], v6 offset0:204 offset1:221
	ds_read2_b64 v[38:41], v6 offset0:238 offset1:255
	v_add_u32_e32 v4, 0x800, v6
	ds_read2_b64 v[42:45], v4 offset0:16 offset1:33
	ds_read2_b64 v[46:49], v4 offset0:50 offset1:67
	ds_read2_b64 v[50:53], v4 offset0:84 offset1:101
	ds_read2_b64 v[54:57], v4 offset0:118 offset1:135
	ds_read2_b64 v[58:61], v4 offset0:152 offset1:169
	ds_read2_b64 v[62:65], v4 offset0:186 offset1:203
	ds_read2_b64 v[66:69], v4 offset0:220 offset1:237
	s_waitcnt lgkmcnt(6)
	v_pk_add_f32 v[70:71], v[8:9], v[42:43]
	v_pk_add_f32 v[8:9], v[8:9], v[42:43] neg_lo:[0,1] neg_hi:[0,1]
	v_add_u32_e32 v5, 0xc00, v6
	v_pk_mul_f32 v[42:43], v[8:9], 0 op_sel_hi:[1,0]
	ds_read2_b64 v[138:141], v5 offset0:126 offset1:143
	v_pk_add_f32 v[142:143], v[8:9], v[42:43] op_sel:[0,1] op_sel_hi:[1,0] neg_lo:[0,1] neg_hi:[0,1]
	v_pk_add_f32 v[8:9], v[8:9], v[42:43] op_sel:[0,1] op_sel_hi:[1,0]
	v_cvt_f32_ubyte0_e32 v7, v7
	v_mov_b32_e32 v143, v9
	v_pk_add_f32 v[8:9], v[10:11], v[44:45]
	v_pk_add_f32 v[10:11], v[10:11], v[44:45] neg_lo:[0,1] neg_hi:[0,1]
	v_mul_f32_e32 v7, 0xbb800000, v7
	v_pk_mul_f32 v[42:43], v[10:11], s[82:83] op_sel_hi:[1,0]
	v_mul_f32_e32 v7, 0.5, v7
	v_pk_fma_f32 v[44:45], v[10:11], s[94:95], v[42:43] op_sel:[0,0,1] op_sel_hi:[1,0,0]
	v_pk_fma_f32 v[10:11], v[10:11], s[94:95], v[42:43] op_sel:[0,0,1] op_sel_hi:[1,0,0] neg_lo:[0,0,1] neg_hi:[0,0,1]
	s_nop 0
	v_mov_b32_e32 v45, v11
	s_waitcnt lgkmcnt(6)
	v_pk_add_f32 v[10:11], v[12:13], v[46:47]
	v_pk_add_f32 v[12:13], v[12:13], v[46:47] neg_lo:[0,1] neg_hi:[0,1]
	s_nop 0
	v_pk_mul_f32 v[42:43], v[12:13], s[84:85] op_sel_hi:[1,0]
	s_nop 0
	v_pk_fma_f32 v[46:47], v[12:13], s[22:23], v[42:43] op_sel:[0,0,1] op_sel_hi:[1,0,0]
	v_pk_fma_f32 v[12:13], v[12:13], s[22:23], v[42:43] op_sel:[0,0,1] op_sel_hi:[1,0,0] neg_lo:[0,0,1] neg_hi:[0,0,1]
	s_nop 0
	v_mov_b32_e32 v47, v13
	v_pk_add_f32 v[12:13], v[14:15], v[48:49]
	v_pk_add_f32 v[14:15], v[14:15], v[48:49] neg_lo:[0,1] neg_hi:[0,1]
	s_nop 0
	v_pk_mul_f32 v[42:43], v[14:15], s[4:5] op_sel_hi:[1,0]
	s_nop 0
	v_pk_fma_f32 v[48:49], v[14:15], s[86:87], v[42:43] op_sel:[0,0,1] op_sel_hi:[1,0,0]
	v_pk_fma_f32 v[14:15], v[14:15], s[86:87], v[42:43] op_sel:[0,0,1] op_sel_hi:[1,0,0] neg_lo:[0,0,1] neg_hi:[0,0,1]
	s_nop 0
	v_mov_b32_e32 v49, v15
	s_waitcnt lgkmcnt(5)
	v_pk_add_f32 v[14:15], v[16:17], v[50:51]
	v_pk_add_f32 v[16:17], v[16:17], v[50:51] neg_lo:[0,1] neg_hi:[0,1]
	s_nop 0
	v_pk_mul_f32 v[42:43], v[16:17], s[2:3] op_sel_hi:[1,0]
	s_nop 0
	v_pk_fma_f32 v[50:51], v[16:17], s[2:3], v[42:43] op_sel:[0,0,1] op_sel_hi:[1,0,0]
	v_pk_fma_f32 v[16:17], v[16:17], s[2:3], v[42:43] op_sel_hi:[1,0,0] neg_lo:[0,0,1] neg_hi:[0,0,1]
	s_nop 0
	v_mov_b32_e32 v51, v17
	v_pk_add_f32 v[16:17], v[18:19], v[52:53]
	v_pk_add_f32 v[18:19], v[18:19], v[52:53] neg_lo:[0,1] neg_hi:[0,1]
	s_nop 0
	v_pk_mul_f32 v[42:43], v[18:19], s[86:87] op_sel_hi:[1,0]
	s_nop 0
	v_pk_fma_f32 v[52:53], v[18:19], s[4:5], v[42:43] op_sel:[0,0,1] op_sel_hi:[1,0,0]
	v_pk_fma_f32 v[18:19], v[18:19], s[4:5], v[42:43] op_sel:[0,0,1] op_sel_hi:[1,0,0] neg_lo:[0,0,1] neg_hi:[0,0,1]
	s_mov_b32 s5, s11
	v_mov_b32_e32 v53, v19
	s_waitcnt lgkmcnt(4)
	v_pk_add_f32 v[18:19], v[22:23], v[54:55]
	v_pk_add_f32 v[22:23], v[22:23], v[54:55] neg_lo:[0,1] neg_hi:[0,1]
	s_nop 0
	v_pk_mul_f32 v[42:43], v[22:23], s[22:23] op_sel_hi:[1,0]
	s_nop 0
	v_pk_fma_f32 v[54:55], v[22:23], s[84:85], v[42:43] op_sel:[0,0,1] op_sel_hi:[1,0,0]
	v_pk_fma_f32 v[22:23], v[22:23], s[84:85], v[42:43] op_sel:[0,0,1] op_sel_hi:[1,0,0] neg_lo:[0,0,1] neg_hi:[0,0,1]
	s_nop 0
	v_mov_b32_e32 v55, v23
	v_pk_add_f32 v[22:23], v[24:25], v[56:57]
	v_pk_add_f32 v[24:25], v[24:25], v[56:57] neg_lo:[0,1] neg_hi:[0,1]
	s_nop 0
	v_pk_mul_f32 v[42:43], v[24:25], s[94:95] op_sel_hi:[1,0]
	s_nop 0
	v_pk_fma_f32 v[56:57], v[24:25], s[82:83], v[42:43] op_sel:[0,0,1] op_sel_hi:[1,0,0]
	v_pk_fma_f32 v[24:25], v[24:25], s[82:83], v[42:43] op_sel:[0,0,1] op_sel_hi:[1,0,0] neg_lo:[0,0,1] neg_hi:[0,0,1]
	s_mov_b32 s83, s9
	v_mov_b32_e32 v57, v25
	s_waitcnt lgkmcnt(3)
	v_pk_add_f32 v[24:25], v[26:27], v[58:59]
	v_pk_add_f32 v[26:27], v[26:27], v[58:59] neg_lo:[0,1] neg_hi:[0,1]
	s_nop 0
	v_pk_fma_f32 v[42:43], v[26:27], 0, v[26:27] op_sel:[0,0,1] op_sel_hi:[1,0,0]
	v_pk_fma_f32 v[26:27], v[26:27], 0, v[26:27] op_sel:[0,0,1] op_sel_hi:[1,0,0] neg_lo:[0,0,1] neg_hi:[0,0,1]
	s_nop 0
	v_mov_b32_e32 v43, v27
	v_pk_add_f32 v[26:27], v[28:29], v[60:61]
	v_pk_add_f32 v[28:29], v[28:29], v[60:61] neg_lo:[0,1] neg_hi:[0,1]
	s_nop 0
	v_pk_mul_f32 v[58:59], v[28:29], s[8:9] op_sel_hi:[0,1]
	v_pk_fma_f32 v[28:29], v[28:29], s[94:95], v[58:59] op_sel:[1,0,0]
	s_waitcnt lgkmcnt(2)
	v_pk_add_f32 v[58:59], v[30:31], v[62:63]
	v_pk_add_f32 v[30:31], v[30:31], v[62:63] neg_lo:[0,1] neg_hi:[0,1]
	s_nop 0
	v_pk_mul_f32 v[60:61], v[30:31], s[84:85] op_sel_hi:[0,1]
	v_pk_fma_f32 v[30:31], v[30:31], s[24:25], v[60:61] op_sel:[1,0,0] neg_lo:[0,0,1] neg_hi:[0,0,1]
	v_pk_add_f32 v[60:61], v[32:33], v[64:65]
	v_pk_add_f32 v[32:33], v[32:33], v[64:65] neg_lo:[0,1] neg_hi:[0,1]
	s_nop 0
	v_pk_mul_f32 v[62:63], v[32:33], s[10:11] op_sel_hi:[0,1]
	v_pk_fma_f32 v[32:33], v[32:33], s[86:87], v[62:63] op_sel:[1,0,0]
	s_waitcnt lgkmcnt(1)
; template <int R, bool INV> DEV void dft_regs(cf (&v)[R]) {
; #pragma unroll
;     for (int s = R; s >= 2; s >>= 1) {
;         const int h = s >> 1;
; #pragma unroll
;         for (int b = 0; b < R; b += s) {
; #pragma unroll
;             for (int k = 0; k < h; ++k) {
;                 const cf a = v[b + k], c = v[b + k + h];
;                 v[b + k] = a + c;
;                 const cf d = a - c;
;                 const int m = k * (32 / s);
;                 const float wr = tw_cos(m), wi = INV ? tw_sin(m) : -tw_sin(m);
;                 v[b + k + h] = cf{d.x * wr - d.y * wi, d.x * wi + d.y * wr};
	v_pk_add_f32 v[62:63], v[34:35], v[66:67]
	v_pk_add_f32 v[34:35], v[34:35], v[66:67] neg_lo:[0,1] neg_hi:[0,1]
	s_nop 0
	v_mul_f32_e32 v64, 0x3f3504f3, v34
	v_pk_fma_f32 v[34:35], v[34:35], s[6:7], v[64:65] op_sel:[1,0,0] op_sel_hi:[1,1,0] neg_lo:[0,0,1] neg_hi:[0,0,1]
	v_pk_add_f32 v[64:65], v[36:37], v[68:69]
	v_pk_add_f32 v[36:37], v[36:37], v[68:69] neg_lo:[0,1] neg_hi:[0,1]
	s_nop 0
	v_pk_mul_f32 v[66:67], v[36:37], s[30:31] op_sel_hi:[0,1]
	v_pk_fma_f32 v[36:37], v[36:37], s[4:5], v[66:67] op_sel:[1,0,0]
	s_waitcnt lgkmcnt(0)
	v_pk_add_f32 v[66:67], v[38:39], v[138:139]
	v_pk_add_f32 v[38:39], v[38:39], v[138:139] neg_lo:[0,1] neg_hi:[0,1]
	s_mov_b32 s30, s9
	v_pk_mul_f32 v[68:69], v[38:39], s[28:29] op_sel_hi:[0,1]
	v_pk_fma_f32 v[38:39], v[38:39], s[26:27], v[68:69] op_sel:[1,0,0] neg_lo:[0,0,1] neg_hi:[0,0,1]
	v_pk_add_f32 v[68:69], v[40:41], v[140:141]
	v_pk_add_f32 v[40:41], v[40:41], v[140:141] neg_lo:[0,1] neg_hi:[0,1]
	s_mov_b32 s31, s95
	v_pk_mul_f32 v[138:139], v[40:41], s[30:31] op_sel_hi:[0,1]
	v_pk_fma_f32 v[40:41], v[40:41], s[82:83], v[138:139] op_sel:[1,0,0]
	v_pk_add_f32 v[138:139], v[70:71], v[24:25]
	v_pk_add_f32 v[24:25], v[70:71], v[24:25] neg_lo:[0,1] neg_hi:[0,1]
	s_nop 0
	v_pk_mul_f32 v[70:71], v[24:25], 0 op_sel_hi:[1,0]
	s_nop 0
	v_pk_add_f32 v[140:141], v[24:25], v[70:71] op_sel:[0,1] op_sel_hi:[1,0] neg_lo:[0,1] neg_hi:[0,1]
	v_pk_add_f32 v[24:25], v[24:25], v[70:71] op_sel:[0,1] op_sel_hi:[1,0]
	s_nop 0
	v_mov_b32_e32 v141, v25
	v_pk_add_f32 v[24:25], v[8:9], v[26:27]
	v_pk_add_f32 v[8:9], v[8:9], v[26:27] neg_lo:[0,1] neg_hi:[0,1]
	s_nop 0
	v_pk_mul_f32 v[26:27], v[8:9], s[84:85] op_sel_hi:[1,0]
	s_nop 0
	v_pk_fma_f32 v[70:71], v[8:9], s[22:23], v[26:27] op_sel:[0,0,1] op_sel_hi:[1,0,0]
	v_pk_fma_f32 v[8:9], v[8:9], s[22:23], v[26:27] op_sel:[0,0,1] op_sel_hi:[1,0,0] neg_lo:[0,0,1] neg_hi:[0,0,1]
	s_nop 0
	v_mov_b32_e32 v71, v9
	v_pk_add_f32 v[8:9], v[10:11], v[58:59]
	v_pk_add_f32 v[10:11], v[10:11], v[58:59] neg_lo:[0,1] neg_hi:[0,1]
	s_nop 0
	v_pk_mul_f32 v[26:27], v[10:11], s[2:3] op_sel_hi:[1,0]
	s_nop 0
	v_pk_fma_f32 v[58:59], v[10:11], s[2:3], v[26:27] op_sel:[0,0,1] op_sel_hi:[1,0,0]
	v_pk_fma_f32 v[10:11], v[10:11], s[2:3], v[26:27] op_sel_hi:[1,0,0] neg_lo:[0,0,1] neg_hi:[0,0,1]
	s_nop 0
	v_mov_b32_e32 v59, v11
	v_pk_add_f32 v[10:11], v[12:13], v[60:61]
	v_pk_add_f32 v[12:13], v[12:13], v[60:61] neg_lo:[0,1] neg_hi:[0,1]
	s_nop 0
	v_pk_mul_f32 v[26:27], v[12:13], s[22:23] op_sel_hi:[1,0]
	s_nop 0
	v_pk_fma_f32 v[60:61], v[12:13], s[84:85], v[26:27] op_sel:[0,0,1] op_sel_hi:[1,0,0]
	v_pk_fma_f32 v[12:13], v[12:13], s[84:85], v[26:27] op_sel:[0,0,1] op_sel_hi:[1,0,0] neg_lo:[0,0,1] neg_hi:[0,0,1]
	s_nop 0
	v_mov_b32_e32 v61, v13
	v_pk_add_f32 v[12:13], v[14:15], v[62:63]
	v_pk_add_f32 v[14:15], v[14:15], v[62:63] neg_lo:[0,1] neg_hi:[0,1]
	s_nop 0
	v_pk_fma_f32 v[26:27], v[14:15], 0, v[14:15] op_sel:[0,0,1] op_sel_hi:[1,0,0]
	v_pk_fma_f32 v[14:15], v[14:15], 0, v[14:15] op_sel:[0,0,1] op_sel_hi:[1,0,0] neg_lo:[0,0,1] neg_hi:[0,0,1]
	s_nop 0
	v_mov_b32_e32 v27, v15
	v_pk_add_f32 v[14:15], v[16:17], v[64:65]
	v_pk_add_f32 v[16:17], v[16:17], v[64:65] neg_lo:[0,1] neg_hi:[0,1]
	s_nop 0
	v_pk_mul_f32 v[62:63], v[16:17], s[84:85] op_sel_hi:[0,1]
	v_pk_fma_f32 v[16:17], v[16:17], s[24:25], v[62:63] op_sel:[1,0,0] neg_lo:[0,0,1] neg_hi:[0,0,1]
	v_pk_add_f32 v[62:63], v[18:19], v[66:67]
	v_pk_add_f32 v[18:19], v[18:19], v[66:67] neg_lo:[0,1] neg_hi:[0,1]
	s_nop 0
	v_mul_f32_e32 v64, 0x3f3504f3, v18
	v_pk_fma_f32 v[18:19], v[18:19], s[6:7], v[64:65] op_sel:[1,0,0] op_sel_hi:[1,1,0] neg_lo:[0,0,1] neg_hi:[0,0,1]
	v_pk_add_f32 v[64:65], v[22:23], v[68:69]
	v_pk_add_f32 v[22:23], v[22:23], v[68:69] neg_lo:[0,1] neg_hi:[0,1]
	s_nop 0
	v_pk_mul_f32 v[66:67], v[22:23], s[28:29] op_sel_hi:[0,1]
	v_pk_fma_f32 v[22:23], v[22:23], s[26:27], v[66:67] op_sel:[1,0,0] neg_lo:[0,0,1] neg_hi:[0,0,1]
	v_pk_add_f32 v[66:67], v[142:143], v[42:43]
	v_pk_add_f32 v[42:43], v[142:143], v[42:43] neg_lo:[0,1] neg_hi:[0,1]
	s_nop 0
	v_pk_mul_f32 v[68:69], v[42:43], 0 op_sel_hi:[1,0]
	s_nop 0
	v_pk_add_f32 v[142:143], v[42:43], v[68:69] op_sel:[0,1] op_sel_hi:[1,0] neg_lo:[0,1] neg_hi:[0,1]
	v_pk_add_f32 v[42:43], v[42:43], v[68:69] op_sel:[0,1] op_sel_hi:[1,0]
	s_nop 0
	v_mov_b32_e32 v143, v43
	v_pk_add_f32 v[42:43], v[44:45], v[28:29]
	v_pk_add_f32 v[28:29], v[44:45], v[28:29] neg_lo:[0,1] neg_hi:[0,1]
	s_nop 0
	v_pk_mul_f32 v[44:45], v[28:29], s[84:85] op_sel_hi:[1,0]
	s_nop 0
	v_pk_fma_f32 v[68:69], v[28:29], s[22:23], v[44:45] op_sel:[0,0,1] op_sel_hi:[1,0,0]
	v_pk_fma_f32 v[28:29], v[28:29], s[22:23], v[44:45] op_sel:[0,0,1] op_sel_hi:[1,0,0] neg_lo:[0,0,1] neg_hi:[0,0,1]
	s_nop 0
	v_mov_b32_e32 v69, v29
	v_pk_add_f32 v[28:29], v[46:47], v[30:31]
	v_pk_add_f32 v[30:31], v[46:47], v[30:31] neg_lo:[0,1] neg_hi:[0,1]
	s_nop 0
	v_pk_mul_f32 v[44:45], v[30:31], s[2:3] op_sel_hi:[1,0]
	s_nop 0
	v_pk_fma_f32 v[46:47], v[30:31], s[2:3], v[44:45] op_sel:[0,0,1] op_sel_hi:[1,0,0]
	v_pk_fma_f32 v[30:31], v[30:31], s[2:3], v[44:45] op_sel_hi:[1,0,0] neg_lo:[0,0,1] neg_hi:[0,0,1]
	s_nop 0
	v_mov_b32_e32 v47, v31
	v_pk_add_f32 v[30:31], v[48:49], v[32:33]
	v_pk_add_f32 v[32:33], v[48:49], v[32:33] neg_lo:[0,1] neg_hi:[0,1]
	s_nop 0
	v_pk_mul_f32 v[44:45], v[32:33], s[22:23] op_sel_hi:[1,0]
	s_nop 0
	v_pk_fma_f32 v[48:49], v[32:33], s[84:85], v[44:45] op_sel:[0,0,1] op_sel_hi:[1,0,0]
	v_pk_fma_f32 v[32:33], v[32:33], s[84:85], v[44:45] op_sel:[0,0,1] op_sel_hi:[1,0,0] neg_lo:[0,0,1] neg_hi:[0,0,1]
	s_nop 0
	v_mov_b32_e32 v49, v33
	v_pk_add_f32 v[32:33], v[50:51], v[34:35]
	v_pk_add_f32 v[34:35], v[50:51], v[34:35] neg_lo:[0,1] neg_hi:[0,1]
; template <int R, bool INV> DEV void dft_regs(cf (&v)[R]) {
; #pragma unroll
;     for (int s = R; s >= 2; s >>= 1) {
;         const int h = s >> 1;
; #pragma unroll
;         for (int b = 0; b < R; b += s) {
; #pragma unroll
;             for (int k = 0; k < h; ++k) {
;                 const cf a = v[b + k], c = v[b + k + h];
;                 v[b + k] = a + c;
;                 const cf d = a - c;
;                 const int m = k * (32 / s);
;                 const float wr = tw_cos(m), wi = INV ? tw_sin(m) : -tw_sin(m);
;                 v[b + k + h] = cf{d.x * wr - d.y * wi, d.x * wi + d.y * wr};
	s_nop 0
	v_pk_fma_f32 v[44:45], v[34:35], 0, v[34:35] op_sel:[0,0,1] op_sel_hi:[1,0,0]
	v_pk_fma_f32 v[34:35], v[34:35], 0, v[34:35] op_sel:[0,0,1] op_sel_hi:[1,0,0] neg_lo:[0,0,1] neg_hi:[0,0,1]
	s_nop 0
	v_mov_b32_e32 v45, v35
	v_pk_add_f32 v[34:35], v[52:53], v[36:37]
	v_pk_add_f32 v[36:37], v[52:53], v[36:37] neg_lo:[0,1] neg_hi:[0,1]
	s_nop 0
	v_pk_mul_f32 v[50:51], v[36:37], s[84:85] op_sel_hi:[0,1]
	v_pk_fma_f32 v[36:37], v[36:37], s[24:25], v[50:51] op_sel:[1,0,0] neg_lo:[0,0,1] neg_hi:[0,0,1]
	v_pk_add_f32 v[50:51], v[54:55], v[38:39]
	v_pk_add_f32 v[38:39], v[54:55], v[38:39] neg_lo:[0,1] neg_hi:[0,1]
	s_nop 0
	v_mul_f32_e32 v52, 0x3f3504f3, v38
	v_pk_fma_f32 v[38:39], v[38:39], s[6:7], v[52:53] op_sel:[1,0,0] op_sel_hi:[1,1,0] neg_lo:[0,0,1] neg_hi:[0,0,1]
	v_pk_add_f32 v[52:53], v[56:57], v[40:41]
	v_pk_add_f32 v[40:41], v[56:57], v[40:41] neg_lo:[0,1] neg_hi:[0,1]
	s_nop 0
	v_pk_mul_f32 v[54:55], v[40:41], s[28:29] op_sel_hi:[0,1]
	v_pk_fma_f32 v[40:41], v[40:41], s[26:27], v[54:55] op_sel:[1,0,0] neg_lo:[0,0,1] neg_hi:[0,0,1]
	v_pk_add_f32 v[54:55], v[138:139], v[12:13]
	v_pk_add_f32 v[12:13], v[138:139], v[12:13] neg_lo:[0,1] neg_hi:[0,1]
	s_nop 0
	v_pk_mul_f32 v[56:57], v[12:13], 0 op_sel_hi:[1,0]
	s_nop 0
	v_pk_add_f32 v[138:139], v[12:13], v[56:57] op_sel:[0,1] op_sel_hi:[1,0] neg_lo:[0,1] neg_hi:[0,1]
	v_pk_add_f32 v[12:13], v[12:13], v[56:57] op_sel:[0,1] op_sel_hi:[1,0]
	s_nop 0
	v_mov_b32_e32 v139, v13
	v_pk_add_f32 v[12:13], v[24:25], v[14:15]
	v_pk_add_f32 v[14:15], v[24:25], v[14:15] neg_lo:[0,1] neg_hi:[0,1]
	s_nop 0
	v_pk_mul_f32 v[24:25], v[14:15], s[2:3] op_sel_hi:[1,0]
	s_nop 0
	v_pk_fma_f32 v[56:57], v[14:15], s[2:3], v[24:25] op_sel:[0,0,1] op_sel_hi:[1,0,0]
	v_pk_fma_f32 v[14:15], v[14:15], s[2:3], v[24:25] op_sel_hi:[1,0,0] neg_lo:[0,0,1] neg_hi:[0,0,1]
	s_nop 0
	v_mov_b32_e32 v57, v15
	v_pk_add_f32 v[14:15], v[8:9], v[62:63]
	v_pk_add_f32 v[8:9], v[8:9], v[62:63] neg_lo:[0,1] neg_hi:[0,1]
	s_nop 0
	v_pk_fma_f32 v[24:25], v[8:9], 0, v[8:9] op_sel:[0,0,1] op_sel_hi:[1,0,0]
	v_pk_fma_f32 v[8:9], v[8:9], 0, v[8:9] op_sel:[0,0,1] op_sel_hi:[1,0,0] neg_lo:[0,0,1] neg_hi:[0,0,1]
	s_nop 0
	v_mov_b32_e32 v25, v9
	v_pk_add_f32 v[8:9], v[10:11], v[64:65]
	v_pk_add_f32 v[10:11], v[10:11], v[64:65] neg_lo:[0,1] neg_hi:[0,1]
	s_nop 0
	v_mul_f32_e32 v62, 0x3f3504f3, v10
	v_pk_fma_f32 v[10:11], v[10:11], s[6:7], v[62:63] op_sel:[1,0,0] op_sel_hi:[1,1,0] neg_lo:[0,0,1] neg_hi:[0,0,1]
	v_pk_add_f32 v[62:63], v[140:141], v[26:27]
	v_pk_add_f32 v[26:27], v[140:141], v[26:27] neg_lo:[0,1] neg_hi:[0,1]
	s_nop 0
	v_pk_mul_f32 v[64:65], v[26:27], 0 op_sel_hi:[1,0]
	s_nop 0
	v_pk_add_f32 v[140:141], v[26:27], v[64:65] op_sel:[0,1] op_sel_hi:[1,0] neg_lo:[0,1] neg_hi:[0,1]
	v_pk_add_f32 v[26:27], v[26:27], v[64:65] op_sel:[0,1] op_sel_hi:[1,0]
	s_nop 0
	v_mov_b32_e32 v141, v27
	v_pk_add_f32 v[26:27], v[70:71], v[16:17]
	v_pk_add_f32 v[16:17], v[70:71], v[16:17] neg_lo:[0,1] neg_hi:[0,1]
	s_nop 0
	v_pk_mul_f32 v[64:65], v[16:17], s[2:3] op_sel_hi:[1,0]
	s_nop 0
	v_pk_fma_f32 v[70:71], v[16:17], s[2:3], v[64:65] op_sel:[0,0,1] op_sel_hi:[1,0,0]
	v_pk_fma_f32 v[16:17], v[16:17], s[2:3], v[64:65] op_sel_hi:[1,0,0] neg_lo:[0,0,1] neg_hi:[0,0,1]
	s_nop 0
	v_mov_b32_e32 v71, v17
	v_pk_add_f32 v[16:17], v[58:59], v[18:19]
	v_pk_add_f32 v[18:19], v[58:59], v[18:19] neg_lo:[0,1] neg_hi:[0,1]
	s_nop 0
	v_pk_fma_f32 v[58:59], v[18:19], 0, v[18:19] op_sel:[0,0,1] op_sel_hi:[1,0,0]
	v_pk_fma_f32 v[18:19], v[18:19], 0, v[18:19] op_sel:[0,0,1] op_sel_hi:[1,0,0] neg_lo:[0,0,1] neg_hi:[0,0,1]
	s_nop 0
	v_mov_b32_e32 v59, v19
	v_pk_add_f32 v[18:19], v[60:61], v[22:23]
	v_pk_add_f32 v[22:23], v[60:61], v[22:23] neg_lo:[0,1] neg_hi:[0,1]
	s_nop 0
	v_mul_f32_e32 v60, 0x3f3504f3, v22
	v_pk_fma_f32 v[22:23], v[22:23], s[6:7], v[60:61] op_sel:[1,0,0] op_sel_hi:[1,1,0] neg_lo:[0,0,1] neg_hi:[0,0,1]
	v_pk_add_f32 v[60:61], v[66:67], v[32:33]
	v_pk_add_f32 v[32:33], v[66:67], v[32:33] neg_lo:[0,1] neg_hi:[0,1]
	s_nop 0
	v_pk_mul_f32 v[64:65], v[32:33], 0 op_sel_hi:[1,0]
	s_nop 0
	v_pk_add_f32 v[66:67], v[32:33], v[64:65] op_sel:[0,1] op_sel_hi:[1,0] neg_lo:[0,1] neg_hi:[0,1]
	v_pk_add_f32 v[32:33], v[32:33], v[64:65] op_sel:[0,1] op_sel_hi:[1,0]
	s_nop 0
	v_mov_b32_e32 v67, v33
	v_pk_add_f32 v[32:33], v[42:43], v[34:35]
	v_pk_add_f32 v[34:35], v[42:43], v[34:35] neg_lo:[0,1] neg_hi:[0,1]
	s_nop 0
	v_pk_mul_f32 v[42:43], v[34:35], s[2:3] op_sel_hi:[1,0]
	s_nop 0
	v_pk_fma_f32 v[64:65], v[34:35], s[2:3], v[42:43] op_sel:[0,0,1] op_sel_hi:[1,0,0]
	v_pk_fma_f32 v[34:35], v[34:35], s[2:3], v[42:43] op_sel_hi:[1,0,0] neg_lo:[0,0,1] neg_hi:[0,0,1]
	s_nop 0
	v_mov_b32_e32 v65, v35
	v_pk_add_f32 v[34:35], v[28:29], v[50:51]
	v_pk_add_f32 v[28:29], v[28:29], v[50:51] neg_lo:[0,1] neg_hi:[0,1]
	s_nop 0
	v_pk_fma_f32 v[42:43], v[28:29], 0, v[28:29] op_sel:[0,0,1] op_sel_hi:[1,0,0]
	v_pk_fma_f32 v[28:29], v[28:29], 0, v[28:29] op_sel:[0,0,1] op_sel_hi:[1,0,0] neg_lo:[0,0,1] neg_hi:[0,0,1]
	s_nop 0
	v_mov_b32_e32 v43, v29
	v_pk_add_f32 v[28:29], v[30:31], v[52:53]
	v_pk_add_f32 v[30:31], v[30:31], v[52:53] neg_lo:[0,1] neg_hi:[0,1]
	s_nop 0
	v_mul_f32_e32 v50, 0x3f3504f3, v30
	v_pk_fma_f32 v[30:31], v[30:31], s[6:7], v[50:51] op_sel:[1,0,0] op_sel_hi:[1,1,0] neg_lo:[0,0,1] neg_hi:[0,0,1]
	v_pk_add_f32 v[50:51], v[142:143], v[44:45]
	v_pk_add_f32 v[44:45], v[142:143], v[44:45] neg_lo:[0,1] neg_hi:[0,1]
	s_nop 0
	v_pk_mul_f32 v[52:53], v[44:45], 0 op_sel_hi:[1,0]
	s_nop 0
	v_pk_add_f32 v[142:143], v[44:45], v[52:53] op_sel:[0,1] op_sel_hi:[1,0] neg_lo:[0,1] neg_hi:[0,1]
	v_pk_add_f32 v[44:45], v[44:45], v[52:53] op_sel:[0,1] op_sel_hi:[1,0]
	s_nop 0
	v_mov_b32_e32 v143, v45
; template <int R, bool INV> DEV void dft_regs(cf (&v)[R]) {
; #pragma unroll
;     for (int s = R; s >= 2; s >>= 1) {
;         const int h = s >> 1;
; #pragma unroll
;         for (int b = 0; b < R; b += s) {
; #pragma unroll
;             for (int k = 0; k < h; ++k) {
;                 const cf a = v[b + k], c = v[b + k + h];
;                 v[b + k] = a + c;
;                 const cf d = a - c;
;                 const int m = k * (32 / s);
;                 const float wr = tw_cos(m), wi = INV ? tw_sin(m) : -tw_sin(m);
;                 v[b + k + h] = cf{d.x * wr - d.y * wi, d.x * wi + d.y * wr};
	v_pk_add_f32 v[44:45], v[68:69], v[36:37]
	v_pk_add_f32 v[36:37], v[68:69], v[36:37] neg_lo:[0,1] neg_hi:[0,1]
	s_nop 0
	v_pk_mul_f32 v[52:53], v[36:37], s[2:3] op_sel_hi:[1,0]
	s_nop 0
	v_pk_fma_f32 v[68:69], v[36:37], s[2:3], v[52:53] op_sel:[0,0,1] op_sel_hi:[1,0,0]
	v_pk_fma_f32 v[36:37], v[36:37], s[2:3], v[52:53] op_sel_hi:[1,0,0] neg_lo:[0,0,1] neg_hi:[0,0,1]
	s_nop 0
	v_mov_b32_e32 v69, v37
	v_pk_add_f32 v[36:37], v[46:47], v[38:39]
	v_pk_add_f32 v[38:39], v[46:47], v[38:39] neg_lo:[0,1] neg_hi:[0,1]
	s_nop 0
	v_pk_fma_f32 v[46:47], v[38:39], 0, v[38:39] op_sel:[0,0,1] op_sel_hi:[1,0,0]
	v_pk_fma_f32 v[38:39], v[38:39], 0, v[38:39] op_sel:[0,0,1] op_sel_hi:[1,0,0] neg_lo:[0,0,1] neg_hi:[0,0,1]
	s_nop 0
	v_mov_b32_e32 v47, v39
	v_pk_add_f32 v[38:39], v[48:49], v[40:41]
	v_pk_add_f32 v[40:41], v[48:49], v[40:41] neg_lo:[0,1] neg_hi:[0,1]
	s_nop 0
	v_mul_f32_e32 v48, 0x3f3504f3, v40
	v_pk_fma_f32 v[40:41], v[40:41], s[6:7], v[48:49] op_sel:[1,0,0] op_sel_hi:[1,1,0] neg_lo:[0,0,1] neg_hi:[0,0,1]
	v_pk_add_f32 v[48:49], v[54:55], v[14:15]
	v_pk_add_f32 v[14:15], v[54:55], v[14:15] neg_lo:[0,1] neg_hi:[0,1]
	s_nop 0
	v_pk_mul_f32 v[52:53], v[14:15], 0 op_sel_hi:[1,0]
	s_nop 0
	v_pk_add_f32 v[54:55], v[14:15], v[52:53] op_sel:[0,1] op_sel_hi:[1,0] neg_lo:[0,1] neg_hi:[0,1]
	v_pk_add_f32 v[14:15], v[14:15], v[52:53] op_sel:[0,1] op_sel_hi:[1,0]
	s_nop 0
	v_mov_b32_e32 v55, v15
	v_pk_add_f32 v[14:15], v[12:13], v[8:9]
	v_pk_add_f32 v[8:9], v[12:13], v[8:9] neg_lo:[0,1] neg_hi:[0,1]
	s_nop 0
	v_pk_fma_f32 v[12:13], v[8:9], 0, v[8:9] op_sel:[0,0,1] op_sel_hi:[1,0,0]
	v_pk_fma_f32 v[8:9], v[8:9], 0, v[8:9] op_sel:[0,0,1] op_sel_hi:[1,0,0] neg_lo:[0,0,1] neg_hi:[0,0,1]
	s_nop 0
	v_mov_b32_e32 v13, v9
	v_pk_add_f32 v[8:9], v[138:139], v[24:25]
	v_pk_add_f32 v[24:25], v[138:139], v[24:25] neg_lo:[0,1] neg_hi:[0,1]
	s_nop 0
	v_pk_mul_f32 v[52:53], v[24:25], 0 op_sel_hi:[1,0]
	s_nop 0
	v_pk_add_f32 v[138:139], v[24:25], v[52:53] op_sel:[0,1] op_sel_hi:[1,0] neg_lo:[0,1] neg_hi:[0,1]
	v_pk_add_f32 v[24:25], v[24:25], v[52:53] op_sel:[0,1] op_sel_hi:[1,0]
	s_nop 0
	v_mov_b32_e32 v139, v25
	v_pk_add_f32 v[24:25], v[56:57], v[10:11]
	v_pk_add_f32 v[10:11], v[56:57], v[10:11] neg_lo:[0,1] neg_hi:[0,1]
	s_nop 0
	v_pk_fma_f32 v[52:53], v[10:11], 0, v[10:11] op_sel:[0,0,1] op_sel_hi:[1,0,0]
	v_pk_fma_f32 v[10:11], v[10:11], 0, v[10:11] op_sel:[0,0,1] op_sel_hi:[1,0,0] neg_lo:[0,0,1] neg_hi:[0,0,1]
	s_nop 0
	v_mov_b32_e32 v53, v11
	v_pk_add_f32 v[10:11], v[62:63], v[16:17]
	v_pk_add_f32 v[16:17], v[62:63], v[16:17] neg_lo:[0,1] neg_hi:[0,1]
	s_nop 0
	v_pk_mul_f32 v[56:57], v[16:17], 0 op_sel_hi:[1,0]
	s_nop 0
	v_pk_add_f32 v[62:63], v[16:17], v[56:57] op_sel:[0,1] op_sel_hi:[1,0] neg_lo:[0,1] neg_hi:[0,1]
	v_pk_add_f32 v[16:17], v[16:17], v[56:57] op_sel:[0,1] op_sel_hi:[1,0]
	v_pk_add_f32 v[56:57], v[140:141], v[58:59] neg_lo:[0,1] neg_hi:[0,1]
	v_mov_b32_e32 v63, v17
	v_pk_add_f32 v[16:17], v[26:27], v[18:19]
	v_pk_add_f32 v[18:19], v[26:27], v[18:19] neg_lo:[0,1] neg_hi:[0,1]
	s_nop 0
	v_pk_fma_f32 v[26:27], v[18:19], 0, v[18:19] op_sel:[0,0,1] op_sel_hi:[1,0,0]
	v_pk_fma_f32 v[18:19], v[18:19], 0, v[18:19] op_sel:[0,0,1] op_sel_hi:[1,0,0] neg_lo:[0,0,1] neg_hi:[0,0,1]
	s_nop 0
	v_mov_b32_e32 v27, v19
	v_pk_add_f32 v[18:19], v[140:141], v[58:59]
	v_pk_mul_f32 v[58:59], v[56:57], 0 op_sel_hi:[1,0]
	s_nop 0
	v_pk_add_f32 v[140:141], v[56:57], v[58:59] op_sel:[0,1] op_sel_hi:[1,0] neg_lo:[0,1] neg_hi:[0,1]
	v_pk_add_f32 v[56:57], v[56:57], v[58:59] op_sel:[0,1] op_sel_hi:[1,0]
	s_nop 0
	v_mov_b32_e32 v141, v57
	v_pk_add_f32 v[56:57], v[70:71], v[22:23]
	v_pk_add_f32 v[22:23], v[70:71], v[22:23] neg_lo:[0,1] neg_hi:[0,1]
	s_nop 0
	v_pk_fma_f32 v[58:59], v[22:23], 0, v[22:23] op_sel:[0,0,1] op_sel_hi:[1,0,0]
	v_pk_fma_f32 v[22:23], v[22:23], 0, v[22:23] op_sel:[0,0,1] op_sel_hi:[1,0,0] neg_lo:[0,0,1] neg_hi:[0,0,1]
	s_nop 0
	v_mov_b32_e32 v59, v23
	v_pk_add_f32 v[22:23], v[60:61], v[34:35]
	v_pk_add_f32 v[34:35], v[60:61], v[34:35] neg_lo:[0,1] neg_hi:[0,1]
	s_nop 0
	v_pk_mul_f32 v[60:61], v[34:35], 0 op_sel_hi:[1,0]
	s_nop 0
	v_pk_add_f32 v[70:71], v[34:35], v[60:61] op_sel:[0,1] op_sel_hi:[1,0] neg_lo:[0,1] neg_hi:[0,1]
	v_pk_add_f32 v[34:35], v[34:35], v[60:61] op_sel:[0,1] op_sel_hi:[1,0]
	s_nop 0
	v_mov_b32_e32 v71, v35
	v_pk_add_f32 v[34:35], v[32:33], v[28:29]
	v_pk_add_f32 v[28:29], v[32:33], v[28:29] neg_lo:[0,1] neg_hi:[0,1]
	s_nop 0
	v_pk_fma_f32 v[32:33], v[28:29], 0, v[28:29] op_sel:[0,0,1] op_sel_hi:[1,0,0]
	v_pk_fma_f32 v[28:29], v[28:29], 0, v[28:29] op_sel:[0,0,1] op_sel_hi:[1,0,0] neg_lo:[0,0,1] neg_hi:[0,0,1]
	s_nop 0
	v_mov_b32_e32 v33, v29
	v_pk_add_f32 v[28:29], v[66:67], v[42:43]
	v_pk_add_f32 v[42:43], v[66:67], v[42:43] neg_lo:[0,1] neg_hi:[0,1]
	s_nop 0
	v_pk_mul_f32 v[60:61], v[42:43], 0 op_sel_hi:[1,0]
	s_nop 0
	v_pk_add_f32 v[66:67], v[42:43], v[60:61] op_sel:[0,1] op_sel_hi:[1,0] neg_lo:[0,1] neg_hi:[0,1]
	v_pk_add_f32 v[42:43], v[42:43], v[60:61] op_sel:[0,1] op_sel_hi:[1,0]
	s_nop 0
	v_mov_b32_e32 v67, v43
	v_pk_add_f32 v[42:43], v[64:65], v[30:31]
	v_pk_add_f32 v[30:31], v[64:65], v[30:31] neg_lo:[0,1] neg_hi:[0,1]
	s_nop 0
	v_pk_fma_f32 v[60:61], v[30:31], 0, v[30:31] op_sel:[0,0,1] op_sel_hi:[1,0,0]
	v_pk_fma_f32 v[30:31], v[30:31], 0, v[30:31] op_sel:[0,0,1] op_sel_hi:[1,0,0] neg_lo:[0,0,1] neg_hi:[0,0,1]
	s_nop 0
	v_mov_b32_e32 v61, v31
	v_pk_add_f32 v[30:31], v[50:51], v[36:37]
	v_pk_add_f32 v[36:37], v[50:51], v[36:37] neg_lo:[0,1] neg_hi:[0,1]
	s_nop 0
	v_pk_mul_f32 v[50:51], v[36:37], 0 op_sel_hi:[1,0]
	s_nop 0
	v_pk_add_f32 v[64:65], v[36:37], v[50:51] op_sel:[0,1] op_sel_hi:[1,0] neg_lo:[0,1] neg_hi:[0,1]
; template <int R, bool INV> DEV void dft_regs(cf (&v)[R]) {
; #pragma unroll
;     for (int s = R; s >= 2; s >>= 1) {
;         const int h = s >> 1;
; #pragma unroll
;         for (int b = 0; b < R; b += s) {
; #pragma unroll
;             for (int k = 0; k < h; ++k) {
;                 const cf a = v[b + k], c = v[b + k + h];
;                 v[b + k] = a + c;
;                 const cf d = a - c;
;                 const int m = k * (32 / s);
;                 const float wr = tw_cos(m), wi = INV ? tw_sin(m) : -tw_sin(m);
;                 v[b + k + h] = cf{d.x * wr - d.y * wi, d.x * wi + d.y * wr};
	v_pk_add_f32 v[36:37], v[36:37], v[50:51] op_sel:[0,1] op_sel_hi:[1,0]
	s_nop 0
	v_mov_b32_e32 v65, v37
	v_pk_add_f32 v[36:37], v[44:45], v[38:39]
	v_pk_add_f32 v[38:39], v[44:45], v[38:39] neg_lo:[0,1] neg_hi:[0,1]
	s_nop 0
	v_pk_fma_f32 v[44:45], v[38:39], 0, v[38:39] op_sel:[0,0,1] op_sel_hi:[1,0,0]
	v_pk_fma_f32 v[38:39], v[38:39], 0, v[38:39] op_sel:[0,0,1] op_sel_hi:[1,0,0] neg_lo:[0,0,1] neg_hi:[0,0,1]
	s_nop 0
	v_mov_b32_e32 v45, v39
	v_pk_add_f32 v[38:39], v[142:143], v[46:47]
	v_pk_add_f32 v[46:47], v[142:143], v[46:47] neg_lo:[0,1] neg_hi:[0,1]
	s_nop 0
	v_pk_mul_f32 v[50:51], v[46:47], 0 op_sel_hi:[1,0]
	s_nop 0
	v_pk_add_f32 v[142:143], v[46:47], v[50:51] op_sel:[0,1] op_sel_hi:[1,0] neg_lo:[0,1] neg_hi:[0,1]
	v_pk_add_f32 v[46:47], v[46:47], v[50:51] op_sel:[0,1] op_sel_hi:[1,0]
	s_nop 0
	v_mov_b32_e32 v143, v47
	v_pk_add_f32 v[46:47], v[68:69], v[40:41]
	v_pk_add_f32 v[40:41], v[68:69], v[40:41] neg_lo:[0,1] neg_hi:[0,1]
	s_nop 0
	v_pk_fma_f32 v[50:51], v[40:41], 0, v[40:41] op_sel:[0,0,1] op_sel_hi:[1,0,0]
	v_pk_fma_f32 v[40:41], v[40:41], 0, v[40:41] op_sel:[0,0,1] op_sel_hi:[1,0,0] neg_lo:[0,0,1] neg_hi:[0,0,1]
	s_nop 0
	v_mov_b32_e32 v51, v41
	v_pk_add_f32 v[40:41], v[48:49], v[14:15]
	v_pk_add_f32 v[14:15], v[48:49], v[14:15] neg_lo:[0,1] neg_hi:[0,1]
	s_nop 0
	v_pk_mul_f32 v[48:49], v[14:15], 0 op_sel_hi:[1,0]
	s_nop 0
	v_pk_add_f32 v[68:69], v[14:15], v[48:49] op_sel:[0,1] op_sel_hi:[1,0] neg_lo:[0,1] neg_hi:[0,1]
	v_pk_add_f32 v[14:15], v[14:15], v[48:49] op_sel:[0,1] op_sel_hi:[1,0]
	s_nop 0
	v_mov_b32_e32 v69, v15
	v_pk_add_f32 v[14:15], v[54:55], v[12:13]
	v_pk_add_f32 v[12:13], v[54:55], v[12:13] neg_lo:[0,1] neg_hi:[0,1]
	s_nop 0
	v_pk_mul_f32 v[48:49], v[12:13], 0 op_sel_hi:[1,0]
	s_nop 0
	v_pk_add_f32 v[54:55], v[12:13], v[48:49] op_sel:[0,1] op_sel_hi:[1,0] neg_lo:[0,1] neg_hi:[0,1]
	v_pk_add_f32 v[12:13], v[12:13], v[48:49] op_sel:[0,1] op_sel_hi:[1,0]
	s_nop 0
	v_mov_b32_e32 v55, v13
	v_pk_add_f32 v[12:13], v[8:9], v[24:25]
	v_pk_add_f32 v[8:9], v[8:9], v[24:25] neg_lo:[0,1] neg_hi:[0,1]
	s_nop 0
	v_pk_mul_f32 v[24:25], v[8:9], 0 op_sel_hi:[1,0]
	s_nop 0
	v_pk_add_f32 v[48:49], v[8:9], v[24:25] op_sel:[0,1] op_sel_hi:[1,0] neg_lo:[0,1] neg_hi:[0,1]
	v_pk_add_f32 v[8:9], v[8:9], v[24:25] op_sel:[0,1] op_sel_hi:[1,0]
	v_pk_add_f32 v[24:25], v[138:139], v[52:53] neg_lo:[0,1] neg_hi:[0,1]
	v_mov_b32_e32 v49, v9
	v_pk_add_f32 v[8:9], v[138:139], v[52:53]
	v_pk_mul_f32 v[52:53], v[24:25], 0 op_sel_hi:[1,0]
	s_nop 0
	v_pk_add_f32 v[138:139], v[24:25], v[52:53] op_sel:[0,1] op_sel_hi:[1,0] neg_lo:[0,1] neg_hi:[0,1]
	v_pk_add_f32 v[24:25], v[24:25], v[52:53] op_sel:[0,1] op_sel_hi:[1,0]
	s_nop 0
	v_mov_b32_e32 v139, v25
	v_pk_add_f32 v[24:25], v[10:11], v[16:17]
	v_pk_add_f32 v[10:11], v[10:11], v[16:17] neg_lo:[0,1] neg_hi:[0,1]
	s_nop 0
	v_pk_mul_f32 v[16:17], v[10:11], 0 op_sel_hi:[1,0]
	s_nop 0
	v_pk_add_f32 v[52:53], v[10:11], v[16:17] op_sel:[0,1] op_sel_hi:[1,0] neg_lo:[0,1] neg_hi:[0,1]
	v_pk_add_f32 v[10:11], v[10:11], v[16:17] op_sel:[0,1] op_sel_hi:[1,0]
	v_pk_add_f32 v[16:17], v[62:63], v[26:27] neg_lo:[0,1] neg_hi:[0,1]
	v_mov_b32_e32 v53, v11
	v_pk_add_f32 v[10:11], v[62:63], v[26:27]
	v_pk_mul_f32 v[26:27], v[16:17], 0 op_sel_hi:[1,0]
	s_nop 0
	v_pk_add_f32 v[62:63], v[16:17], v[26:27] op_sel:[0,1] op_sel_hi:[1,0] neg_lo:[0,1] neg_hi:[0,1]
	v_pk_add_f32 v[16:17], v[16:17], v[26:27] op_sel:[0,1] op_sel_hi:[1,0]
	s_nop 0
	v_mov_b32_e32 v63, v17
	v_pk_add_f32 v[16:17], v[18:19], v[56:57]
	v_pk_add_f32 v[18:19], v[18:19], v[56:57] neg_lo:[0,1] neg_hi:[0,1]
	s_nop 0
	v_pk_mul_f32 v[26:27], v[18:19], 0 op_sel_hi:[1,0]
	s_nop 0
	v_pk_add_f32 v[56:57], v[18:19], v[26:27] op_sel:[0,1] op_sel_hi:[1,0] neg_lo:[0,1] neg_hi:[0,1]
	v_pk_add_f32 v[18:19], v[18:19], v[26:27] op_sel:[0,1] op_sel_hi:[1,0]
	v_pk_add_f32 v[26:27], v[140:141], v[58:59] neg_lo:[0,1] neg_hi:[0,1]
	v_mov_b32_e32 v57, v19
	v_pk_add_f32 v[18:19], v[140:141], v[58:59]
	v_pk_mul_f32 v[58:59], v[26:27], 0 op_sel_hi:[1,0]
	s_nop 0
	v_pk_add_f32 v[140:141], v[26:27], v[58:59] op_sel:[0,1] op_sel_hi:[1,0] neg_lo:[0,1] neg_hi:[0,1]
	v_pk_add_f32 v[26:27], v[26:27], v[58:59] op_sel:[0,1] op_sel_hi:[1,0]
	s_nop 0
	v_mov_b32_e32 v141, v27
	v_pk_add_f32 v[26:27], v[22:23], v[34:35]
	v_pk_add_f32 v[22:23], v[22:23], v[34:35] neg_lo:[0,1] neg_hi:[0,1]
	s_nop 0
	v_pk_mul_f32 v[34:35], v[22:23], 0 op_sel_hi:[1,0]
	s_nop 0
	v_pk_add_f32 v[58:59], v[22:23], v[34:35] op_sel:[0,1] op_sel_hi:[1,0] neg_lo:[0,1] neg_hi:[0,1]
	v_pk_add_f32 v[22:23], v[22:23], v[34:35] op_sel:[0,1] op_sel_hi:[1,0]
	s_nop 0
	v_mov_b32_e32 v59, v23
	v_pk_add_f32 v[22:23], v[70:71], v[32:33]
	v_pk_add_f32 v[32:33], v[70:71], v[32:33] neg_lo:[0,1] neg_hi:[0,1]
	s_nop 0
	v_pk_mul_f32 v[34:35], v[32:33], 0 op_sel_hi:[1,0]
	s_nop 0
	v_pk_add_f32 v[70:71], v[32:33], v[34:35] op_sel:[0,1] op_sel_hi:[1,0] neg_lo:[0,1] neg_hi:[0,1]
	v_pk_add_f32 v[32:33], v[32:33], v[34:35] op_sel:[0,1] op_sel_hi:[1,0]
	s_nop 0
	v_mov_b32_e32 v71, v33
	v_pk_add_f32 v[32:33], v[28:29], v[42:43]
	v_pk_add_f32 v[28:29], v[28:29], v[42:43] neg_lo:[0,1] neg_hi:[0,1]
	s_nop 0
	v_pk_mul_f32 v[34:35], v[28:29], 0 op_sel_hi:[1,0]
	s_nop 0
	v_pk_add_f32 v[42:43], v[28:29], v[34:35] op_sel:[0,1] op_sel_hi:[1,0] neg_lo:[0,1] neg_hi:[0,1]
	v_pk_add_f32 v[28:29], v[28:29], v[34:35] op_sel:[0,1] op_sel_hi:[1,0]
	v_pk_add_f32 v[34:35], v[66:67], v[60:61] neg_lo:[0,1] neg_hi:[0,1]
	v_mov_b32_e32 v43, v29
	v_pk_add_f32 v[28:29], v[66:67], v[60:61]
	v_pk_mul_f32 v[60:61], v[34:35], 0 op_sel_hi:[1,0]
	s_nop 0
	v_pk_add_f32 v[66:67], v[34:35], v[60:61] op_sel:[0,1] op_sel_hi:[1,0] neg_lo:[0,1] neg_hi:[0,1]
; #define SINCOSPI(x, s, c) do { const float hx_ = 0.5f * (x); *(s) = __builtin_amdgcn_sinf(hx_); *(c) = __builtin_amdgcn_cosf(hx_); } while (0)
; DEV cf cmul(cf a, cf b) { cf r, t;
;     asm("v_pk_mul_f32 %1, %2, %3 op_sel:[1,1] op_sel_hi:[1,0] neg_lo:[1,0]\n\tv_pk_fma_f32 %0, %2, %3, %1 op_sel_hi:[0,1,1]" : "=v"(r), "=&v"(t) : "v"(a), "v"(b));
;     return r; }
; DEV void fft_f2(LAS cf* buf, int t8) {
;     ...
;     dft_regs<32, false>(v);
;     float sn, cs; SINCOSPI(-(float)(t8 & 15) * (2.0f / 512.0f), &sn, &cs);
;     const cf w = cf{cs, sn}; cf wp = cf{1.f, 0.f};
; #pragma unroll
;     for (int p = 0; p < 32; ++p) { pb[17 * p] = cmul(v[BR32[p]], wp); wp = cmul(wp, w); }
	v_pk_add_f32 v[34:35], v[34:35], v[60:61] op_sel:[0,1] op_sel_hi:[1,0]
	s_nop 0
	v_mov_b32_e32 v67, v35
	v_pk_add_f32 v[34:35], v[30:31], v[36:37]
	v_pk_add_f32 v[30:31], v[30:31], v[36:37] neg_lo:[0,1] neg_hi:[0,1]
	s_nop 0
	v_pk_mul_f32 v[36:37], v[30:31], 0 op_sel_hi:[1,0]
	s_nop 0
	v_pk_add_f32 v[60:61], v[30:31], v[36:37] op_sel:[0,1] op_sel_hi:[1,0] neg_lo:[0,1] neg_hi:[0,1]
	v_pk_add_f32 v[30:31], v[30:31], v[36:37] op_sel:[0,1] op_sel_hi:[1,0]
	v_pk_add_f32 v[36:37], v[64:65], v[44:45] neg_lo:[0,1] neg_hi:[0,1]
	v_mov_b32_e32 v61, v31
	v_pk_add_f32 v[30:31], v[64:65], v[44:45]
	v_pk_mul_f32 v[44:45], v[36:37], 0 op_sel_hi:[1,0]
	s_nop 0
	v_pk_add_f32 v[64:65], v[36:37], v[44:45] op_sel:[0,1] op_sel_hi:[1,0] neg_lo:[0,1] neg_hi:[0,1]
	v_pk_add_f32 v[36:37], v[36:37], v[44:45] op_sel:[0,1] op_sel_hi:[1,0]
	s_nop 0
	v_mov_b32_e32 v65, v37
	v_pk_add_f32 v[36:37], v[38:39], v[46:47]
	v_pk_add_f32 v[38:39], v[38:39], v[46:47] neg_lo:[0,1] neg_hi:[0,1]
	s_nop 0
	v_pk_mul_f32 v[44:45], v[38:39], 0 op_sel_hi:[1,0]
	s_nop 0
	v_pk_add_f32 v[46:47], v[38:39], v[44:45] op_sel:[0,1] op_sel_hi:[1,0] neg_lo:[0,1] neg_hi:[0,1]
	v_pk_add_f32 v[38:39], v[38:39], v[44:45] op_sel:[0,1] op_sel_hi:[1,0]
	v_pk_add_f32 v[44:45], v[142:143], v[50:51] neg_lo:[0,1] neg_hi:[0,1]
	v_mov_b32_e32 v47, v39
	v_pk_add_f32 v[38:39], v[142:143], v[50:51]
	v_pk_mul_f32 v[50:51], v[44:45], 0 op_sel_hi:[1,0]
	s_nop 0
	v_pk_add_f32 v[142:143], v[44:45], v[50:51] op_sel:[0,1] op_sel_hi:[1,0] neg_lo:[0,1] neg_hi:[0,1]
	v_pk_add_f32 v[44:45], v[44:45], v[50:51] op_sel:[0,1] op_sel_hi:[1,0]
	v_pk_mul_f32 v[50:51], v[40:41], v[2:3] op_sel:[1,1] op_sel_hi:[1,0] neg_lo:[1,0]
	v_pk_fma_f32 v[40:41], v[40:41], v[2:3], v[50:51] op_sel_hi:[0,1,1]
	v_mov_b32_e32 v143, v45
	v_sin_f32_e32 v45, v7
	v_cos_f32_e32 v44, v7
	v_pk_mul_f32 v[50:51], v[2:3], v[44:45] op_sel:[1,1] op_sel_hi:[1,0] neg_lo:[1,0]
	v_pk_fma_f32 v[2:3], v[2:3], v[44:45], v[50:51] op_sel_hi:[0,1,1]
	v_pk_mul_f32 v[50:51], v[26:27], v[2:3] op_sel:[1,1] op_sel_hi:[1,0] neg_lo:[1,0]
	v_pk_fma_f32 v[26:27], v[26:27], v[2:3], v[50:51] op_sel_hi:[0,1,1]
	ds_write2_b64 v6, v[40:41], v[26:27] offset1:17
	v_pk_mul_f32 v[26:27], v[2:3], v[44:45] op_sel:[1,1] op_sel_hi:[1,0] neg_lo:[1,0]
	v_pk_fma_f32 v[2:3], v[2:3], v[44:45], v[26:27] op_sel_hi:[0,1,1]
	v_pk_mul_f32 v[26:27], v[24:25], v[2:3] op_sel:[1,1] op_sel_hi:[1,0] neg_lo:[1,0]
	v_pk_fma_f32 v[24:25], v[24:25], v[2:3], v[26:27] op_sel_hi:[0,1,1]
	v_pk_mul_f32 v[26:27], v[2:3], v[44:45] op_sel:[1,1] op_sel_hi:[1,0] neg_lo:[1,0]
	v_pk_fma_f32 v[2:3], v[2:3], v[44:45], v[26:27] op_sel_hi:[0,1,1]
	v_pk_mul_f32 v[40:41], v[34:35], v[2:3] op_sel:[1,1] op_sel_hi:[1,0] neg_lo:[1,0]
	v_pk_fma_f32 v[26:27], v[34:35], v[2:3], v[40:41] op_sel_hi:[0,1,1]
	ds_write2_b64 v6, v[24:25], v[26:27] offset0:34 offset1:51
	v_pk_mul_f32 v[24:25], v[2:3], v[44:45] op_sel:[1,1] op_sel_hi:[1,0] neg_lo:[1,0]
	v_pk_fma_f32 v[2:3], v[2:3], v[44:45], v[24:25] op_sel_hi:[0,1,1]
	v_pk_mul_f32 v[24:25], v[12:13], v[2:3] op_sel:[1,1] op_sel_hi:[1,0] neg_lo:[1,0]
	v_pk_fma_f32 v[12:13], v[12:13], v[2:3], v[24:25] op_sel_hi:[0,1,1]
	v_pk_mul_f32 v[24:25], v[2:3], v[44:45] op_sel:[1,1] op_sel_hi:[1,0] neg_lo:[1,0]
	v_pk_fma_f32 v[2:3], v[2:3], v[44:45], v[24:25] op_sel_hi:[0,1,1]
	v_pk_mul_f32 v[26:27], v[32:33], v[2:3] op_sel:[1,1] op_sel_hi:[1,0] neg_lo:[1,0]
	v_pk_fma_f32 v[24:25], v[32:33], v[2:3], v[26:27] op_sel_hi:[0,1,1]
	ds_write2_b64 v6, v[12:13], v[24:25] offset0:68 offset1:85
	v_pk_mul_f32 v[12:13], v[2:3], v[44:45] op_sel:[1,1] op_sel_hi:[1,0] neg_lo:[1,0]
	v_pk_fma_f32 v[2:3], v[2:3], v[44:45], v[12:13] op_sel_hi:[0,1,1]
	v_pk_mul_f32 v[24:25], v[16:17], v[2:3] op_sel:[1,1] op_sel_hi:[1,0] neg_lo:[1,0]
	v_pk_fma_f32 v[12:13], v[16:17], v[2:3], v[24:25] op_sel_hi:[0,1,1]
	v_pk_mul_f32 v[16:17], v[2:3], v[44:45] op_sel:[1,1] op_sel_hi:[1,0] neg_lo:[1,0]
	v_pk_fma_f32 v[2:3], v[2:3], v[44:45], v[16:17] op_sel_hi:[0,1,1]
	v_pk_mul_f32 v[24:25], v[36:37], v[2:3] op_sel:[1,1] op_sel_hi:[1,0] neg_lo:[1,0]
	v_pk_fma_f32 v[16:17], v[36:37], v[2:3], v[24:25] op_sel_hi:[0,1,1]
	ds_write2_b64 v6, v[12:13], v[16:17] offset0:102 offset1:119
	v_pk_mul_f32 v[12:13], v[2:3], v[44:45] op_sel:[1,1] op_sel_hi:[1,0] neg_lo:[1,0]
	v_pk_fma_f32 v[2:3], v[2:3], v[44:45], v[12:13] op_sel_hi:[0,1,1]
	v_pk_mul_f32 v[16:17], v[14:15], v[2:3] op_sel:[1,1] op_sel_hi:[1,0] neg_lo:[1,0]
	v_pk_fma_f32 v[12:13], v[14:15], v[2:3], v[16:17] op_sel_hi:[0,1,1]
	v_pk_mul_f32 v[14:15], v[2:3], v[44:45] op_sel:[1,1] op_sel_hi:[1,0] neg_lo:[1,0]
	v_pk_fma_f32 v[2:3], v[2:3], v[44:45], v[14:15] op_sel_hi:[0,1,1]
	v_pk_mul_f32 v[16:17], v[22:23], v[2:3] op_sel:[1,1] op_sel_hi:[1,0] neg_lo:[1,0]
	v_pk_fma_f32 v[14:15], v[22:23], v[2:3], v[16:17] op_sel_hi:[0,1,1]
	ds_write2_b64 v6, v[12:13], v[14:15] offset0:136 offset1:153
	v_pk_mul_f32 v[12:13], v[2:3], v[44:45] op_sel:[1,1] op_sel_hi:[1,0] neg_lo:[1,0]
	v_pk_fma_f32 v[2:3], v[2:3], v[44:45], v[12:13] op_sel_hi:[0,1,1]
	v_pk_mul_f32 v[12:13], v[10:11], v[2:3] op_sel:[1,1] op_sel_hi:[1,0] neg_lo:[1,0]
	v_pk_fma_f32 v[10:11], v[10:11], v[2:3], v[12:13] op_sel_hi:[0,1,1]
	v_pk_mul_f32 v[12:13], v[2:3], v[44:45] op_sel:[1,1] op_sel_hi:[1,0] neg_lo:[1,0]
	v_pk_fma_f32 v[2:3], v[2:3], v[44:45], v[12:13] op_sel_hi:[0,1,1]
	v_pk_mul_f32 v[14:15], v[30:31], v[2:3] op_sel:[1,1] op_sel_hi:[1,0] neg_lo:[1,0]
	v_pk_fma_f32 v[12:13], v[30:31], v[2:3], v[14:15] op_sel_hi:[0,1,1]
	ds_write2_b64 v6, v[10:11], v[12:13] offset0:170 offset1:187
	v_pk_mul_f32 v[10:11], v[2:3], v[44:45] op_sel:[1,1] op_sel_hi:[1,0] neg_lo:[1,0]
	v_pk_fma_f32 v[2:3], v[2:3], v[44:45], v[10:11] op_sel_hi:[0,1,1]
; #define LAS __attribute__((address_space(3)))
; DEV cf cmul(cf a, cf b) { cf r, t;
;     asm("v_pk_mul_f32 %1, %2, %3 op_sel:[1,1] op_sel_hi:[1,0] neg_lo:[1,0]\n\tv_pk_fma_f32 %0, %2, %3, %1 op_sel_hi:[0,1,1]" : "=v"(r), "=&v"(t) : "v"(a), "v"(b));
;     return r; }
; DEV void fft_f2(LAS cf* buf, int t8) {
;     ...
;     const cf w = cf{cs, sn}; cf wp = cf{1.f, 0.f};
; #pragma unroll
;     for (int p = 0; p < 32; ++p) { pb[17 * p] = cmul(v[BR32[p]], wp); wp = cmul(wp, w); }
; template <bool MULK> DEV void fft_mid(LAS cf* buf, const unsigned* Kp, int blk) {
;     const int base = 16 * blk;
;     cf v[16];
; #pragma unroll
;     for (int q = 0; q < 16; ++q) v[q] = buf[PADI(base + q)];
	v_pk_mul_f32 v[10:11], v[8:9], v[2:3] op_sel:[1,1] op_sel_hi:[1,0] neg_lo:[1,0]
	v_pk_fma_f32 v[8:9], v[8:9], v[2:3], v[10:11] op_sel_hi:[0,1,1]
	v_pk_mul_f32 v[10:11], v[2:3], v[44:45] op_sel:[1,1] op_sel_hi:[1,0] neg_lo:[1,0]
	v_pk_fma_f32 v[2:3], v[2:3], v[44:45], v[10:11] op_sel_hi:[0,1,1]
	v_pk_mul_f32 v[12:13], v[28:29], v[2:3] op_sel:[1,1] op_sel_hi:[1,0] neg_lo:[1,0]
	v_pk_fma_f32 v[10:11], v[28:29], v[2:3], v[12:13] op_sel_hi:[0,1,1]
	ds_write2_b64 v6, v[8:9], v[10:11] offset0:204 offset1:221
	v_pk_mul_f32 v[8:9], v[2:3], v[44:45] op_sel:[1,1] op_sel_hi:[1,0] neg_lo:[1,0]
	v_pk_fma_f32 v[2:3], v[2:3], v[44:45], v[8:9] op_sel_hi:[0,1,1]
	v_pk_mul_f32 v[10:11], v[18:19], v[2:3] op_sel:[1,1] op_sel_hi:[1,0] neg_lo:[1,0]
	v_pk_fma_f32 v[8:9], v[18:19], v[2:3], v[10:11] op_sel_hi:[0,1,1]
	v_pk_mul_f32 v[10:11], v[2:3], v[44:45] op_sel:[1,1] op_sel_hi:[1,0] neg_lo:[1,0]
	v_pk_fma_f32 v[2:3], v[2:3], v[44:45], v[10:11] op_sel_hi:[0,1,1]
	v_pk_mul_f32 v[12:13], v[38:39], v[2:3] op_sel:[1,1] op_sel_hi:[1,0] neg_lo:[1,0]
	v_pk_fma_f32 v[10:11], v[38:39], v[2:3], v[12:13] op_sel_hi:[0,1,1]
	ds_write2_b64 v6, v[8:9], v[10:11] offset0:238 offset1:255
	v_pk_mul_f32 v[6:7], v[2:3], v[44:45] op_sel:[1,1] op_sel_hi:[1,0] neg_lo:[1,0]
	v_pk_fma_f32 v[2:3], v[2:3], v[44:45], v[6:7] op_sel_hi:[0,1,1]
	v_pk_mul_f32 v[8:9], v[68:69], v[2:3] op_sel:[1,1] op_sel_hi:[1,0] neg_lo:[1,0]
	v_pk_fma_f32 v[6:7], v[68:69], v[2:3], v[8:9] op_sel_hi:[0,1,1]
	v_pk_mul_f32 v[8:9], v[2:3], v[44:45] op_sel:[1,1] op_sel_hi:[1,0] neg_lo:[1,0]
	v_pk_fma_f32 v[2:3], v[2:3], v[44:45], v[8:9] op_sel_hi:[0,1,1]
	v_pk_mul_f32 v[10:11], v[58:59], v[2:3] op_sel:[1,1] op_sel_hi:[1,0] neg_lo:[1,0]
	v_pk_fma_f32 v[8:9], v[58:59], v[2:3], v[10:11] op_sel_hi:[0,1,1]
	ds_write2_b64 v4, v[6:7], v[8:9] offset0:16 offset1:33
	v_pk_mul_f32 v[6:7], v[2:3], v[44:45] op_sel:[1,1] op_sel_hi:[1,0] neg_lo:[1,0]
	v_pk_fma_f32 v[2:3], v[2:3], v[44:45], v[6:7] op_sel_hi:[0,1,1]
	v_pk_mul_f32 v[8:9], v[52:53], v[2:3] op_sel:[1,1] op_sel_hi:[1,0] neg_lo:[1,0]
	v_pk_fma_f32 v[6:7], v[52:53], v[2:3], v[8:9] op_sel_hi:[0,1,1]
	v_pk_mul_f32 v[8:9], v[2:3], v[44:45] op_sel:[1,1] op_sel_hi:[1,0] neg_lo:[1,0]
	v_pk_fma_f32 v[2:3], v[2:3], v[44:45], v[8:9] op_sel_hi:[0,1,1]
	v_pk_mul_f32 v[10:11], v[60:61], v[2:3] op_sel:[1,1] op_sel_hi:[1,0] neg_lo:[1,0]
	v_pk_fma_f32 v[8:9], v[60:61], v[2:3], v[10:11] op_sel_hi:[0,1,1]
	ds_write2_b64 v4, v[6:7], v[8:9] offset0:50 offset1:67
	v_pk_mul_f32 v[6:7], v[2:3], v[44:45] op_sel:[1,1] op_sel_hi:[1,0] neg_lo:[1,0]
	v_pk_fma_f32 v[2:3], v[2:3], v[44:45], v[6:7] op_sel_hi:[0,1,1]
	v_pk_mul_f32 v[8:9], v[48:49], v[2:3] op_sel:[1,1] op_sel_hi:[1,0] neg_lo:[1,0]
	v_pk_fma_f32 v[6:7], v[48:49], v[2:3], v[8:9] op_sel_hi:[0,1,1]
	v_pk_mul_f32 v[8:9], v[2:3], v[44:45] op_sel:[1,1] op_sel_hi:[1,0] neg_lo:[1,0]
	v_pk_fma_f32 v[2:3], v[2:3], v[44:45], v[8:9] op_sel_hi:[0,1,1]
	v_pk_mul_f32 v[10:11], v[42:43], v[2:3] op_sel:[1,1] op_sel_hi:[1,0] neg_lo:[1,0]
	v_pk_fma_f32 v[8:9], v[42:43], v[2:3], v[10:11] op_sel_hi:[0,1,1]
	ds_write2_b64 v4, v[6:7], v[8:9] offset0:84 offset1:101
	v_pk_mul_f32 v[6:7], v[2:3], v[44:45] op_sel:[1,1] op_sel_hi:[1,0] neg_lo:[1,0]
	v_pk_fma_f32 v[2:3], v[2:3], v[44:45], v[6:7] op_sel_hi:[0,1,1]
	v_pk_mul_f32 v[8:9], v[56:57], v[2:3] op_sel:[1,1] op_sel_hi:[1,0] neg_lo:[1,0]
	v_pk_fma_f32 v[6:7], v[56:57], v[2:3], v[8:9] op_sel_hi:[0,1,1]
	v_pk_mul_f32 v[8:9], v[2:3], v[44:45] op_sel:[1,1] op_sel_hi:[1,0] neg_lo:[1,0]
	v_pk_fma_f32 v[2:3], v[2:3], v[44:45], v[8:9] op_sel_hi:[0,1,1]
	v_pk_mul_f32 v[10:11], v[46:47], v[2:3] op_sel:[1,1] op_sel_hi:[1,0] neg_lo:[1,0]
	v_pk_fma_f32 v[8:9], v[46:47], v[2:3], v[10:11] op_sel_hi:[0,1,1]
	ds_write2_b64 v4, v[6:7], v[8:9] offset0:118 offset1:135
	v_pk_mul_f32 v[6:7], v[2:3], v[44:45] op_sel:[1,1] op_sel_hi:[1,0] neg_lo:[1,0]
	v_pk_fma_f32 v[2:3], v[2:3], v[44:45], v[6:7] op_sel_hi:[0,1,1]
	v_pk_mul_f32 v[8:9], v[54:55], v[2:3] op_sel:[1,1] op_sel_hi:[1,0] neg_lo:[1,0]
	v_pk_fma_f32 v[6:7], v[54:55], v[2:3], v[8:9] op_sel_hi:[0,1,1]
	v_lshlrev_b32_e32 v54, 3, v0
	v_pk_mul_f32 v[8:9], v[2:3], v[44:45] op_sel:[1,1] op_sel_hi:[1,0] neg_lo:[1,0]
	v_pk_fma_f32 v[2:3], v[2:3], v[44:45], v[8:9] op_sel_hi:[0,1,1]
	v_lshlrev_b32_e32 v55, 7, v0
	v_pk_mul_f32 v[10:11], v[70:71], v[2:3] op_sel:[1,1] op_sel_hi:[1,0] neg_lo:[1,0]
	v_pk_fma_f32 v[8:9], v[70:71], v[2:3], v[10:11] op_sel_hi:[0,1,1]
	ds_write2_b64 v4, v[6:7], v[8:9] offset0:152 offset1:169
	v_pk_mul_f32 v[6:7], v[2:3], v[44:45] op_sel:[1,1] op_sel_hi:[1,0] neg_lo:[1,0]
	v_pk_fma_f32 v[2:3], v[2:3], v[44:45], v[6:7] op_sel_hi:[0,1,1]
	v_add3_u32 v56, 0, v54, v55
	v_pk_mul_f32 v[8:9], v[62:63], v[2:3] op_sel:[1,1] op_sel_hi:[1,0] neg_lo:[1,0]
	v_pk_fma_f32 v[6:7], v[62:63], v[2:3], v[8:9] op_sel_hi:[0,1,1]
	v_add3_u32 v54, s33, v54, v55
	v_pk_mul_f32 v[8:9], v[2:3], v[44:45] op_sel:[1,1] op_sel_hi:[1,0] neg_lo:[1,0]
	v_pk_fma_f32 v[2:3], v[2:3], v[44:45], v[8:9] op_sel_hi:[0,1,1]
	v_pk_mul_f32 v[10:11], v[64:65], v[2:3] op_sel:[1,1] op_sel_hi:[1,0] neg_lo:[1,0]
	v_pk_fma_f32 v[8:9], v[64:65], v[2:3], v[10:11] op_sel_hi:[0,1,1]
	ds_write2_b64 v4, v[6:7], v[8:9] offset0:186 offset1:203
	v_pk_mul_f32 v[6:7], v[2:3], v[44:45] op_sel:[1,1] op_sel_hi:[1,0] neg_lo:[1,0]
	v_pk_fma_f32 v[2:3], v[2:3], v[44:45], v[6:7] op_sel_hi:[0,1,1]
	v_pk_mul_f32 v[8:9], v[138:139], v[2:3] op_sel:[1,1] op_sel_hi:[1,0] neg_lo:[1,0]
	v_pk_fma_f32 v[6:7], v[138:139], v[2:3], v[8:9] op_sel_hi:[0,1,1]
	v_pk_mul_f32 v[8:9], v[2:3], v[44:45] op_sel:[1,1] op_sel_hi:[1,0] neg_lo:[1,0]
	v_pk_fma_f32 v[2:3], v[2:3], v[44:45], v[8:9] op_sel_hi:[0,1,1]
	v_pk_mul_f32 v[10:11], v[66:67], v[2:3] op_sel:[1,1] op_sel_hi:[1,0] neg_lo:[1,0]
	v_pk_fma_f32 v[8:9], v[66:67], v[2:3], v[10:11] op_sel_hi:[0,1,1]
	ds_write2_b64 v4, v[6:7], v[8:9] offset0:220 offset1:237
	v_pk_mul_f32 v[6:7], v[2:3], v[44:45] op_sel:[1,1] op_sel_hi:[1,0] neg_lo:[1,0]
	v_pk_fma_f32 v[2:3], v[2:3], v[44:45], v[6:7] op_sel_hi:[0,1,1]
	v_pk_mul_f32 v[8:9], v[140:141], v[2:3] op_sel:[1,1] op_sel_hi:[1,0] neg_lo:[1,0]
	v_pk_fma_f32 v[6:7], v[140:141], v[2:3], v[8:9] op_sel_hi:[0,1,1]
	v_pk_mul_f32 v[8:9], v[2:3], v[44:45] op_sel:[1,1] op_sel_hi:[1,0] neg_lo:[1,0]
	v_pk_fma_f32 v[2:3], v[2:3], v[44:45], v[8:9] op_sel_hi:[0,1,1]
	v_pk_mul_f32 v[8:9], v[142:143], v[2:3] op_sel:[1,1] op_sel_hi:[1,0] neg_lo:[1,0]
	v_pk_fma_f32 v[2:3], v[142:143], v[2:3], v[8:9] op_sel_hi:[0,1,1]
	ds_write2_b64 v5, v[6:7], v[2:3] offset0:126 offset1:143
	s_waitcnt lgkmcnt(0)
	s_barrier
; #define LAS __attribute__((address_space(3)))
; template <int R, bool INV> DEV void dft_regs(cf (&v)[R]) {
; #pragma unroll
;     for (int s = R; s >= 2; s >>= 1) {
;         const int h = s >> 1;
; #pragma unroll
;         for (int b = 0; b < R; b += s) {
; #pragma unroll
;             for (int k = 0; k < h; ++k) {
;                 const cf a = v[b + k], c = v[b + k + h];
;                 v[b + k] = a + c;
;                 const cf d = a - c;
;                 const int m = k * (32 / s);
;                 const float wr = tw_cos(m), wi = INV ? tw_sin(m) : -tw_sin(m);
;                 v[b + k + h] = cf{d.x * wr - d.y * wi, d.x * wi + d.y * wr};
; template <bool MULK> DEV void fft_mid(LAS cf* buf, const unsigned* Kp, int blk) {
;     const int base = 16 * blk;
;     cf v[16];
; #pragma unroll
;     for (int q = 0; q < 16; ++q) v[q] = buf[PADI(base + q)];
;     dft_regs<16, false>(v);
	ds_read2_b64 v[2:5], v56 offset1:1
	ds_read2_b64 v[6:9], v56 offset0:2 offset1:3
	ds_read2_b64 v[10:13], v56 offset0:4 offset1:5
	ds_read2_b64 v[14:17], v56 offset0:6 offset1:7
	ds_read2_b64 v[22:25], v56 offset0:8 offset1:9
	ds_read2_b64 v[26:29], v56 offset0:10 offset1:11
	ds_read2_b64 v[30:33], v56 offset0:12 offset1:13
	ds_read2_b64 v[34:37], v56 offset0:14 offset1:15
	s_waitcnt lgkmcnt(3)
	v_pk_add_f32 v[18:19], v[2:3], v[22:23]
	v_pk_add_f32 v[2:3], v[2:3], v[22:23] neg_lo:[0,1] neg_hi:[0,1]
	s_nop 0
	v_pk_mul_f32 v[22:23], v[2:3], 0 op_sel_hi:[1,0]
	s_nop 0
	v_pk_add_f32 v[38:39], v[2:3], v[22:23] op_sel:[0,1] op_sel_hi:[1,0] neg_lo:[0,1] neg_hi:[0,1]
	v_pk_add_f32 v[2:3], v[2:3], v[22:23] op_sel:[0,1] op_sel_hi:[1,0]
	s_nop 0
	v_mov_b32_e32 v39, v3
	v_pk_add_f32 v[2:3], v[4:5], v[24:25]
	v_pk_add_f32 v[4:5], v[4:5], v[24:25] neg_lo:[0,1] neg_hi:[0,1]
	s_nop 0
	v_pk_mul_f32 v[22:23], v[4:5], s[84:85] op_sel_hi:[1,0]
	s_nop 0
	v_pk_fma_f32 v[24:25], v[4:5], s[22:23], v[22:23] op_sel:[0,0,1] op_sel_hi:[1,0,0]
	v_pk_fma_f32 v[4:5], v[4:5], s[22:23], v[22:23] op_sel:[0,0,1] op_sel_hi:[1,0,0] neg_lo:[0,0,1] neg_hi:[0,0,1]
	s_nop 0
	v_mov_b32_e32 v25, v5
	s_waitcnt lgkmcnt(2)
	v_pk_add_f32 v[4:5], v[6:7], v[26:27]
	v_pk_add_f32 v[6:7], v[6:7], v[26:27] neg_lo:[0,1] neg_hi:[0,1]
	s_nop 0
	v_pk_mul_f32 v[22:23], v[6:7], s[2:3] op_sel_hi:[1,0]
	s_nop 0
	v_pk_fma_f32 v[26:27], v[6:7], s[2:3], v[22:23] op_sel:[0,0,1] op_sel_hi:[1,0,0]
	v_pk_fma_f32 v[6:7], v[6:7], s[2:3], v[22:23] op_sel_hi:[1,0,0] neg_lo:[0,0,1] neg_hi:[0,0,1]
	v_pk_add_f32 v[22:23], v[8:9], v[28:29]
	v_pk_add_f32 v[8:9], v[8:9], v[28:29] neg_lo:[0,1] neg_hi:[0,1]
	v_mov_b32_e32 v27, v7
	v_pk_mul_f32 v[28:29], v[8:9], s[22:23] op_sel_hi:[1,0]
	s_nop 0
	v_pk_fma_f32 v[40:41], v[8:9], s[84:85], v[28:29] op_sel:[0,0,1] op_sel_hi:[1,0,0]
	v_pk_fma_f32 v[8:9], v[8:9], s[84:85], v[28:29] op_sel:[0,0,1] op_sel_hi:[1,0,0] neg_lo:[0,0,1] neg_hi:[0,0,1]
	s_nop 0
	v_mov_b32_e32 v41, v9
	s_waitcnt lgkmcnt(1)
	v_pk_add_f32 v[8:9], v[10:11], v[30:31]
	v_pk_add_f32 v[10:11], v[10:11], v[30:31] neg_lo:[0,1] neg_hi:[0,1]
	s_nop 0
	v_pk_fma_f32 v[28:29], v[10:11], 0, v[10:11] op_sel:[0,0,1] op_sel_hi:[1,0,0]
	v_pk_fma_f32 v[10:11], v[10:11], 0, v[10:11] op_sel:[0,0,1] op_sel_hi:[1,0,0] neg_lo:[0,0,1] neg_hi:[0,0,1]
	s_nop 0
	v_mov_b32_e32 v29, v11
	v_pk_add_f32 v[10:11], v[12:13], v[32:33]
	v_pk_add_f32 v[12:13], v[12:13], v[32:33] neg_lo:[0,1] neg_hi:[0,1]
	s_waitcnt lgkmcnt(0)
	v_pk_add_f32 v[32:33], v[16:17], v[36:37]
	v_pk_mul_f32 v[30:31], v[12:13], s[84:85] op_sel_hi:[0,1]
	v_pk_add_f32 v[16:17], v[16:17], v[36:37] neg_lo:[0,1] neg_hi:[0,1]
	v_pk_fma_f32 v[12:13], v[12:13], s[24:25], v[30:31] op_sel:[1,0,0] neg_lo:[0,0,1] neg_hi:[0,0,1]
	v_pk_add_f32 v[30:31], v[14:15], v[34:35]
	v_pk_add_f32 v[14:15], v[14:15], v[34:35] neg_lo:[0,1] neg_hi:[0,1]
	v_pk_mul_f32 v[34:35], v[16:17], s[28:29] op_sel_hi:[0,1]
	v_pk_fma_f32 v[16:17], v[16:17], s[26:27], v[34:35] op_sel:[1,0,0] neg_lo:[0,0,1] neg_hi:[0,0,1]
	v_pk_add_f32 v[34:35], v[18:19], v[8:9]
	v_pk_add_f32 v[8:9], v[18:19], v[8:9] neg_lo:[0,1] neg_hi:[0,1]
	v_mul_f32_e32 v6, 0x3f3504f3, v14
	v_pk_mul_f32 v[18:19], v[8:9], 0 op_sel_hi:[1,0]
	v_pk_fma_f32 v[14:15], v[14:15], s[6:7], v[6:7] op_sel:[1,0,0] op_sel_hi:[1,1,0] neg_lo:[0,0,1] neg_hi:[0,0,1]
	v_pk_add_f32 v[36:37], v[8:9], v[18:19] op_sel:[0,1] op_sel_hi:[1,0] neg_lo:[0,1] neg_hi:[0,1]
	v_pk_add_f32 v[8:9], v[8:9], v[18:19] op_sel:[0,1] op_sel_hi:[1,0]
	v_pk_add_f32 v[6:7], v[26:27], v[14:15]
	v_mov_b32_e32 v37, v9
	v_pk_add_f32 v[8:9], v[2:3], v[10:11]
	v_pk_add_f32 v[2:3], v[2:3], v[10:11] neg_lo:[0,1] neg_hi:[0,1]
	s_nop 0
	v_pk_mul_f32 v[10:11], v[2:3], s[2:3] op_sel_hi:[1,0]
	s_nop 0
	v_pk_fma_f32 v[18:19], v[2:3], s[2:3], v[10:11] op_sel:[0,0,1] op_sel_hi:[1,0,0]
	v_pk_fma_f32 v[2:3], v[2:3], s[2:3], v[10:11] op_sel_hi:[1,0,0] neg_lo:[0,0,1] neg_hi:[0,0,1]
	v_pk_add_f32 v[10:11], v[4:5], v[30:31]
	v_pk_add_f32 v[4:5], v[4:5], v[30:31] neg_lo:[0,1] neg_hi:[0,1]
	v_mov_b32_e32 v19, v3
	v_pk_fma_f32 v[30:31], v[4:5], 0, v[4:5] op_sel:[0,0,1] op_sel_hi:[1,0,0]
	v_pk_fma_f32 v[4:5], v[4:5], 0, v[4:5] op_sel:[0,0,1] op_sel_hi:[1,0,0] neg_lo:[0,0,1] neg_hi:[0,0,1]
	s_nop 0
	v_mov_b32_e32 v31, v5
	v_pk_add_f32 v[4:5], v[22:23], v[32:33]
	v_pk_add_f32 v[22:23], v[22:23], v[32:33] neg_lo:[0,1] neg_hi:[0,1]
	v_pk_add_f32 v[32:33], v[38:39], v[28:29]
	v_pk_add_f32 v[28:29], v[38:39], v[28:29] neg_lo:[0,1] neg_hi:[0,1]
	v_mul_f32_e32 v2, 0x3f3504f3, v22
	v_pk_mul_f32 v[38:39], v[28:29], 0 op_sel_hi:[1,0]
	v_pk_fma_f32 v[22:23], v[22:23], s[6:7], v[2:3] op_sel:[1,0,0] op_sel_hi:[1,1,0] neg_lo:[0,0,1] neg_hi:[0,0,1]
	v_pk_add_f32 v[42:43], v[28:29], v[38:39] op_sel:[0,1] op_sel_hi:[1,0] neg_lo:[0,1] neg_hi:[0,1]
	v_pk_add_f32 v[28:29], v[28:29], v[38:39] op_sel:[0,1] op_sel_hi:[1,0]
	s_nop 0
	v_mov_b32_e32 v43, v29
	v_pk_add_f32 v[28:29], v[24:25], v[12:13]
	v_pk_add_f32 v[12:13], v[24:25], v[12:13] neg_lo:[0,1] neg_hi:[0,1]
	s_nop 0
	v_pk_mul_f32 v[24:25], v[12:13], s[2:3] op_sel_hi:[1,0]
	s_nop 0
	v_pk_fma_f32 v[38:39], v[12:13], s[2:3], v[24:25] op_sel:[0,0,1] op_sel_hi:[1,0,0]
	v_pk_fma_f32 v[12:13], v[12:13], s[2:3], v[24:25] op_sel_hi:[1,0,0] neg_lo:[0,0,1] neg_hi:[0,0,1]
	v_pk_add_f32 v[24:25], v[34:35], v[10:11]
	v_mov_b32_e32 v39, v13
	v_pk_add_f32 v[12:13], v[26:27], v[14:15] neg_lo:[0,1] neg_hi:[0,1]
	v_pk_add_f32 v[10:11], v[34:35], v[10:11] neg_lo:[0,1] neg_hi:[0,1]
	v_pk_fma_f32 v[14:15], v[12:13], 0, v[12:13] op_sel:[0,0,1] op_sel_hi:[1,0,0]
	v_pk_fma_f32 v[12:13], v[12:13], 0, v[12:13] op_sel:[0,0,1] op_sel_hi:[1,0,0] neg_lo:[0,0,1] neg_hi:[0,0,1]
; #define LAS __attribute__((address_space(3)))
; DEV cf kunpack(unsigned w) { return cf{U2F(w << 16), U2F(w & 0xffff0000u)}; }
; template <bool MULK> DEV void fft_mid(LAS cf* buf, const unsigned* Kp, int blk) {
;     const int base = 16 * blk;
;     cf v[16];
; #pragma unroll
;     for (int q = 0; q < 16; ++q) v[q] = buf[PADI(base + q)];
;     dft_regs<16, false>(v);
;     if (MULK) {
;         cf w[16];
; #pragma unroll
;         for (int p = 0; p < 16; ++p) w[p] = cmul(v[BR16[p]], kunpack(Kp[base + p]));
;         dft_regs<16, true>(w);
; #pragma unroll
;         for (int q = 0; q < 16; ++q) buf[PADI(base + q)] = w[BR16[q]];
;     } else {
; #pragma unroll
;         for (int p = 0; p < 16; ++p) buf[PADI(base + p)] = v[BR16[p]];
;     }
; }
; DEV void filt_channel_unit2(int c, const bf16_t* h2b, const float* w3, unsigned* KF, LAS unsigned char* lds, int tid) {
;     ...
;     fft_mid<false>(buf0, nullptr, tid); fft_mid<false>(buf1, nullptr, tid);
	v_pk_mul_f32 v[26:27], v[10:11], 0 op_sel_hi:[1,0]
	v_mov_b32_e32 v15, v13
	v_pk_add_f32 v[12:13], v[40:41], v[16:17]
	v_pk_add_f32 v[16:17], v[40:41], v[16:17] neg_lo:[0,1] neg_hi:[0,1]
	v_pk_add_f32 v[34:35], v[10:11], v[26:27] op_sel:[0,1] op_sel_hi:[1,0] neg_lo:[0,1] neg_hi:[0,1]
	v_pk_add_f32 v[10:11], v[10:11], v[26:27] op_sel:[0,1] op_sel_hi:[1,0]
	v_mul_f32_e32 v2, 0x3f3504f3, v16
	v_mov_b32_e32 v35, v11
	v_pk_add_f32 v[10:11], v[8:9], v[4:5]
	v_pk_add_f32 v[4:5], v[8:9], v[4:5] neg_lo:[0,1] neg_hi:[0,1]
	v_pk_fma_f32 v[16:17], v[16:17], s[6:7], v[2:3] op_sel:[1,0,0] op_sel_hi:[1,1,0] neg_lo:[0,0,1] neg_hi:[0,0,1]
	v_pk_fma_f32 v[8:9], v[4:5], 0, v[4:5] op_sel:[0,0,1] op_sel_hi:[1,0,0]
	v_pk_fma_f32 v[4:5], v[4:5], 0, v[4:5] op_sel:[0,0,1] op_sel_hi:[1,0,0] neg_lo:[0,0,1] neg_hi:[0,0,1]
	v_pk_add_f32 v[26:27], v[36:37], v[30:31] neg_lo:[0,1] neg_hi:[0,1]
	v_pk_add_f32 v[2:3], v[18:19], v[22:23]
	v_pk_add_f32 v[18:19], v[18:19], v[22:23] neg_lo:[0,1] neg_hi:[0,1]
	v_mov_b32_e32 v9, v5
	v_pk_add_f32 v[4:5], v[36:37], v[30:31]
	v_pk_mul_f32 v[30:31], v[26:27], 0 op_sel_hi:[1,0]
	v_pk_fma_f32 v[22:23], v[18:19], 0, v[18:19] op_sel:[0,0,1] op_sel_hi:[1,0,0]
	v_pk_fma_f32 v[18:19], v[18:19], 0, v[18:19] op_sel:[0,0,1] op_sel_hi:[1,0,0] neg_lo:[0,0,1] neg_hi:[0,0,1]
	v_pk_add_f32 v[36:37], v[26:27], v[30:31] op_sel:[0,1] op_sel_hi:[1,0] neg_lo:[0,1] neg_hi:[0,1]
	v_pk_add_f32 v[26:27], v[26:27], v[30:31] op_sel:[0,1] op_sel_hi:[1,0]
	v_mov_b32_e32 v23, v19
	v_pk_add_f32 v[18:19], v[32:33], v[6:7]
	v_pk_add_f32 v[6:7], v[32:33], v[6:7] neg_lo:[0,1] neg_hi:[0,1]
	v_mov_b32_e32 v37, v27
	v_pk_mul_f32 v[26:27], v[6:7], 0 op_sel_hi:[1,0]
	s_nop 0
	v_pk_add_f32 v[30:31], v[6:7], v[26:27] op_sel:[0,1] op_sel_hi:[1,0] neg_lo:[0,1] neg_hi:[0,1]
	v_pk_add_f32 v[6:7], v[6:7], v[26:27] op_sel:[0,1] op_sel_hi:[1,0]
	s_nop 0
	v_mov_b32_e32 v31, v7
	v_pk_add_f32 v[6:7], v[28:29], v[12:13]
	v_pk_add_f32 v[12:13], v[28:29], v[12:13] neg_lo:[0,1] neg_hi:[0,1]
	s_nop 0
	v_pk_fma_f32 v[26:27], v[12:13], 0, v[12:13] op_sel:[0,0,1] op_sel_hi:[1,0,0]
	v_pk_fma_f32 v[12:13], v[12:13], 0, v[12:13] op_sel:[0,0,1] op_sel_hi:[1,0,0] neg_lo:[0,0,1] neg_hi:[0,0,1]
	s_nop 0
	v_mov_b32_e32 v27, v13
	v_pk_add_f32 v[12:13], v[42:43], v[14:15]
	v_pk_add_f32 v[14:15], v[42:43], v[14:15] neg_lo:[0,1] neg_hi:[0,1]
	s_nop 0
	v_pk_mul_f32 v[28:29], v[14:15], 0 op_sel_hi:[1,0]
	s_nop 0
	v_pk_add_f32 v[32:33], v[14:15], v[28:29] op_sel:[0,1] op_sel_hi:[1,0] neg_lo:[0,1] neg_hi:[0,1]
	v_pk_add_f32 v[14:15], v[14:15], v[28:29] op_sel:[0,1] op_sel_hi:[1,0]
	s_nop 0
	v_mov_b32_e32 v33, v15
	v_pk_add_f32 v[14:15], v[38:39], v[16:17]
	v_pk_add_f32 v[16:17], v[38:39], v[16:17] neg_lo:[0,1] neg_hi:[0,1]
	s_nop 0
	v_pk_fma_f32 v[28:29], v[16:17], 0, v[16:17] op_sel:[0,0,1] op_sel_hi:[1,0,0]
	v_pk_fma_f32 v[16:17], v[16:17], 0, v[16:17] op_sel:[0,0,1] op_sel_hi:[1,0,0] neg_lo:[0,0,1] neg_hi:[0,0,1]
	s_nop 0
	v_mov_b32_e32 v29, v17
	v_pk_add_f32 v[16:17], v[24:25], v[10:11]
	v_pk_add_f32 v[10:11], v[24:25], v[10:11] neg_lo:[0,1] neg_hi:[0,1]
	s_nop 0
	v_pk_mul_f32 v[24:25], v[10:11], 0 op_sel_hi:[1,0]
	s_nop 0
	v_pk_add_f32 v[38:39], v[10:11], v[24:25] op_sel:[0,1] op_sel_hi:[1,0] neg_lo:[0,1] neg_hi:[0,1]
	v_pk_add_f32 v[10:11], v[10:11], v[24:25] op_sel:[0,1] op_sel_hi:[1,0]
	v_pk_add_f32 v[24:25], v[34:35], v[8:9]
	v_pk_add_f32 v[8:9], v[34:35], v[8:9] neg_lo:[0,1] neg_hi:[0,1]
	v_mov_b32_e32 v39, v11
	v_pk_mul_f32 v[34:35], v[8:9], 0 op_sel_hi:[1,0]
	s_nop 0
	v_pk_add_f32 v[40:41], v[8:9], v[34:35] op_sel:[0,1] op_sel_hi:[1,0] neg_lo:[0,1] neg_hi:[0,1]
	v_pk_add_f32 v[8:9], v[8:9], v[34:35] op_sel:[0,1] op_sel_hi:[1,0]
	v_pk_add_f32 v[34:35], v[4:5], v[2:3]
	v_pk_add_f32 v[2:3], v[4:5], v[2:3] neg_lo:[0,1] neg_hi:[0,1]
	v_mov_b32_e32 v41, v9
	v_pk_mul_f32 v[4:5], v[2:3], 0 op_sel_hi:[1,0]
	s_nop 0
	v_pk_add_f32 v[42:43], v[2:3], v[4:5] op_sel:[0,1] op_sel_hi:[1,0] neg_lo:[0,1] neg_hi:[0,1]
	v_pk_add_f32 v[2:3], v[2:3], v[4:5] op_sel:[0,1] op_sel_hi:[1,0]
	v_pk_add_f32 v[4:5], v[36:37], v[22:23]
	v_pk_add_f32 v[22:23], v[36:37], v[22:23] neg_lo:[0,1] neg_hi:[0,1]
	v_mov_b32_e32 v43, v3
	v_pk_mul_f32 v[36:37], v[22:23], 0 op_sel_hi:[1,0]
	s_nop 0
	v_pk_add_f32 v[44:45], v[22:23], v[36:37] op_sel:[0,1] op_sel_hi:[1,0] neg_lo:[0,1] neg_hi:[0,1]
	v_pk_add_f32 v[22:23], v[22:23], v[36:37] op_sel:[0,1] op_sel_hi:[1,0]
	v_pk_add_f32 v[36:37], v[18:19], v[6:7]
	v_pk_add_f32 v[6:7], v[18:19], v[6:7] neg_lo:[0,1] neg_hi:[0,1]
	v_mov_b32_e32 v45, v23
	v_pk_mul_f32 v[18:19], v[6:7], 0 op_sel_hi:[1,0]
	s_nop 0
	v_pk_add_f32 v[46:47], v[6:7], v[18:19] op_sel:[0,1] op_sel_hi:[1,0] neg_lo:[0,1] neg_hi:[0,1]
	v_pk_add_f32 v[6:7], v[6:7], v[18:19] op_sel:[0,1] op_sel_hi:[1,0]
	v_pk_add_f32 v[18:19], v[30:31], v[26:27]
	v_pk_add_f32 v[26:27], v[30:31], v[26:27] neg_lo:[0,1] neg_hi:[0,1]
	v_mov_b32_e32 v47, v7
	v_pk_mul_f32 v[30:31], v[26:27], 0 op_sel_hi:[1,0]
	s_nop 0
	v_pk_add_f32 v[48:49], v[26:27], v[30:31] op_sel:[0,1] op_sel_hi:[1,0] neg_lo:[0,1] neg_hi:[0,1]
	v_pk_add_f32 v[26:27], v[26:27], v[30:31] op_sel:[0,1] op_sel_hi:[1,0]
	v_pk_add_f32 v[30:31], v[12:13], v[14:15]
	v_pk_add_f32 v[12:13], v[12:13], v[14:15] neg_lo:[0,1] neg_hi:[0,1]
	v_mov_b32_e32 v49, v27
	v_pk_mul_f32 v[14:15], v[12:13], 0 op_sel_hi:[1,0]
	s_nop 0
	v_pk_add_f32 v[50:51], v[12:13], v[14:15] op_sel:[0,1] op_sel_hi:[1,0] neg_lo:[0,1] neg_hi:[0,1]
	v_pk_add_f32 v[12:13], v[12:13], v[14:15] op_sel:[0,1] op_sel_hi:[1,0]
	v_pk_add_f32 v[14:15], v[32:33], v[28:29]
	v_pk_add_f32 v[28:29], v[32:33], v[28:29] neg_lo:[0,1] neg_hi:[0,1]
	v_mov_b32_e32 v51, v13
	v_pk_mul_f32 v[32:33], v[28:29], 0 op_sel_hi:[1,0]
	ds_write2_b64 v56, v[16:17], v[36:37] offset1:1
	ds_write2_b64 v56, v[34:35], v[30:31] offset0:2 offset1:3
	ds_write2_b64 v56, v[24:25], v[18:19] offset0:4 offset1:5
	ds_write2_b64 v56, v[4:5], v[14:15] offset0:6 offset1:7
	v_pk_add_f32 v[52:53], v[28:29], v[32:33] op_sel:[0,1] op_sel_hi:[1,0] neg_lo:[0,1] neg_hi:[0,1]
	v_pk_add_f32 v[28:29], v[28:29], v[32:33] op_sel:[0,1] op_sel_hi:[1,0]
	ds_write2_b64 v56, v[38:39], v[46:47] offset0:8 offset1:9
	v_mov_b32_e32 v53, v29
	ds_write2_b64 v56, v[42:43], v[50:51] offset0:10 offset1:11
	ds_write2_b64 v56, v[40:41], v[48:49] offset0:12 offset1:13
	ds_write2_b64 v56, v[44:45], v[52:53] offset0:14 offset1:15
	ds_read2_b64 v[2:5], v54 offset1:1
	ds_read2_b64 v[6:9], v54 offset0:2 offset1:3
	ds_read2_b64 v[10:13], v54 offset0:4 offset1:5
	ds_read2_b64 v[14:17], v54 offset0:6 offset1:7
	ds_read2_b64 v[22:25], v54 offset0:8 offset1:9
	ds_read2_b64 v[26:29], v54 offset0:10 offset1:11
	ds_read2_b64 v[30:33], v54 offset0:12 offset1:13
	ds_read2_b64 v[34:37], v54 offset0:14 offset1:15
	s_waitcnt lgkmcnt(3)
; template <int R, bool INV> DEV void dft_regs(cf (&v)[R]) {
; #pragma unroll
;     for (int s = R; s >= 2; s >>= 1) {
;         const int h = s >> 1;
; #pragma unroll
;         for (int b = 0; b < R; b += s) {
; #pragma unroll
;             for (int k = 0; k < h; ++k) {
;                 const cf a = v[b + k], c = v[b + k + h];
;                 v[b + k] = a + c;
;                 const cf d = a - c;
;                 const int m = k * (32 / s);
;                 const float wr = tw_cos(m), wi = INV ? tw_sin(m) : -tw_sin(m);
;                 v[b + k + h] = cf{d.x * wr - d.y * wi, d.x * wi + d.y * wr};
; template <bool MULK> DEV void fft_mid(LAS cf* buf, const unsigned* Kp, int blk) {
;     ...
;     cf v[16];
; #pragma unroll
;     for (int q = 0; q < 16; ++q) v[q] = buf[PADI(base + q)];
;     dft_regs<16, false>(v);
	v_pk_add_f32 v[18:19], v[2:3], v[22:23]
	v_pk_add_f32 v[2:3], v[2:3], v[22:23] neg_lo:[0,1] neg_hi:[0,1]
	s_nop 0
	v_pk_mul_f32 v[22:23], v[2:3], 0 op_sel_hi:[1,0]
	s_nop 0
	v_pk_add_f32 v[38:39], v[2:3], v[22:23] op_sel:[0,1] op_sel_hi:[1,0] neg_lo:[0,1] neg_hi:[0,1]
	v_pk_add_f32 v[2:3], v[2:3], v[22:23] op_sel:[0,1] op_sel_hi:[1,0]
	s_nop 0
	v_mov_b32_e32 v39, v3
	v_pk_add_f32 v[2:3], v[4:5], v[24:25]
	v_pk_add_f32 v[4:5], v[4:5], v[24:25] neg_lo:[0,1] neg_hi:[0,1]
	s_nop 0
	v_pk_mul_f32 v[22:23], v[4:5], s[84:85] op_sel_hi:[1,0]
	s_nop 0
	v_pk_fma_f32 v[24:25], v[4:5], s[22:23], v[22:23] op_sel:[0,0,1] op_sel_hi:[1,0,0]
	v_pk_fma_f32 v[4:5], v[4:5], s[22:23], v[22:23] op_sel:[0,0,1] op_sel_hi:[1,0,0] neg_lo:[0,0,1] neg_hi:[0,0,1]
	s_nop 0
	v_mov_b32_e32 v25, v5
	s_waitcnt lgkmcnt(2)
	v_pk_add_f32 v[4:5], v[6:7], v[26:27]
	v_pk_add_f32 v[6:7], v[6:7], v[26:27] neg_lo:[0,1] neg_hi:[0,1]
	s_nop 0
	v_pk_mul_f32 v[22:23], v[6:7], s[2:3] op_sel_hi:[1,0]
	s_nop 0
	v_pk_fma_f32 v[26:27], v[6:7], s[2:3], v[22:23] op_sel:[0,0,1] op_sel_hi:[1,0,0]
	v_pk_fma_f32 v[6:7], v[6:7], s[2:3], v[22:23] op_sel_hi:[1,0,0] neg_lo:[0,0,1] neg_hi:[0,0,1]
	v_pk_add_f32 v[22:23], v[8:9], v[28:29]
	v_pk_add_f32 v[8:9], v[8:9], v[28:29] neg_lo:[0,1] neg_hi:[0,1]
	v_mov_b32_e32 v27, v7
	v_pk_mul_f32 v[28:29], v[8:9], s[22:23] op_sel_hi:[1,0]
	s_nop 0
	v_pk_fma_f32 v[40:41], v[8:9], s[84:85], v[28:29] op_sel:[0,0,1] op_sel_hi:[1,0,0]
	v_pk_fma_f32 v[8:9], v[8:9], s[84:85], v[28:29] op_sel:[0,0,1] op_sel_hi:[1,0,0] neg_lo:[0,0,1] neg_hi:[0,0,1]
	s_nop 0
	v_mov_b32_e32 v41, v9
	s_waitcnt lgkmcnt(1)
	v_pk_add_f32 v[8:9], v[10:11], v[30:31]
	v_pk_add_f32 v[10:11], v[10:11], v[30:31] neg_lo:[0,1] neg_hi:[0,1]
	s_nop 0
	v_pk_fma_f32 v[28:29], v[10:11], 0, v[10:11] op_sel:[0,0,1] op_sel_hi:[1,0,0]
	v_pk_fma_f32 v[10:11], v[10:11], 0, v[10:11] op_sel:[0,0,1] op_sel_hi:[1,0,0] neg_lo:[0,0,1] neg_hi:[0,0,1]
	s_nop 0
	v_mov_b32_e32 v29, v11
	v_pk_add_f32 v[10:11], v[12:13], v[32:33]
	v_pk_add_f32 v[12:13], v[12:13], v[32:33] neg_lo:[0,1] neg_hi:[0,1]
	s_waitcnt lgkmcnt(0)
	v_pk_add_f32 v[32:33], v[16:17], v[36:37]
	v_pk_mul_f32 v[30:31], v[12:13], s[84:85] op_sel_hi:[0,1]
	v_pk_add_f32 v[16:17], v[16:17], v[36:37] neg_lo:[0,1] neg_hi:[0,1]
	v_pk_fma_f32 v[12:13], v[12:13], s[24:25], v[30:31] op_sel:[1,0,0] neg_lo:[0,0,1] neg_hi:[0,0,1]
	v_pk_add_f32 v[30:31], v[14:15], v[34:35]
	v_pk_add_f32 v[14:15], v[14:15], v[34:35] neg_lo:[0,1] neg_hi:[0,1]
	v_pk_mul_f32 v[34:35], v[16:17], s[28:29] op_sel_hi:[0,1]
	v_pk_fma_f32 v[16:17], v[16:17], s[26:27], v[34:35] op_sel:[1,0,0] neg_lo:[0,0,1] neg_hi:[0,0,1]
	v_pk_add_f32 v[34:35], v[18:19], v[8:9]
	v_pk_add_f32 v[8:9], v[18:19], v[8:9] neg_lo:[0,1] neg_hi:[0,1]
	v_mul_f32_e32 v6, 0x3f3504f3, v14
	v_pk_mul_f32 v[18:19], v[8:9], 0 op_sel_hi:[1,0]
	v_pk_fma_f32 v[14:15], v[14:15], s[6:7], v[6:7] op_sel:[1,0,0] op_sel_hi:[1,1,0] neg_lo:[0,0,1] neg_hi:[0,0,1]
	v_pk_add_f32 v[36:37], v[8:9], v[18:19] op_sel:[0,1] op_sel_hi:[1,0] neg_lo:[0,1] neg_hi:[0,1]
	v_pk_add_f32 v[8:9], v[8:9], v[18:19] op_sel:[0,1] op_sel_hi:[1,0]
	v_pk_add_f32 v[6:7], v[26:27], v[14:15]
	v_mov_b32_e32 v37, v9
	v_pk_add_f32 v[8:9], v[2:3], v[10:11]
	v_pk_add_f32 v[2:3], v[2:3], v[10:11] neg_lo:[0,1] neg_hi:[0,1]
	s_nop 0
	v_pk_mul_f32 v[10:11], v[2:3], s[2:3] op_sel_hi:[1,0]
	s_nop 0
	v_pk_fma_f32 v[18:19], v[2:3], s[2:3], v[10:11] op_sel:[0,0,1] op_sel_hi:[1,0,0]
	v_pk_fma_f32 v[2:3], v[2:3], s[2:3], v[10:11] op_sel_hi:[1,0,0] neg_lo:[0,0,1] neg_hi:[0,0,1]
	v_pk_add_f32 v[10:11], v[4:5], v[30:31]
	v_pk_add_f32 v[4:5], v[4:5], v[30:31] neg_lo:[0,1] neg_hi:[0,1]
	v_mov_b32_e32 v19, v3
	v_pk_fma_f32 v[30:31], v[4:5], 0, v[4:5] op_sel:[0,0,1] op_sel_hi:[1,0,0]
	v_pk_fma_f32 v[4:5], v[4:5], 0, v[4:5] op_sel:[0,0,1] op_sel_hi:[1,0,0] neg_lo:[0,0,1] neg_hi:[0,0,1]
	s_nop 0
	v_mov_b32_e32 v31, v5
	v_pk_add_f32 v[4:5], v[22:23], v[32:33]
	v_pk_add_f32 v[22:23], v[22:23], v[32:33] neg_lo:[0,1] neg_hi:[0,1]
	v_pk_add_f32 v[32:33], v[38:39], v[28:29]
	v_pk_add_f32 v[28:29], v[38:39], v[28:29] neg_lo:[0,1] neg_hi:[0,1]
	v_mul_f32_e32 v2, 0x3f3504f3, v22
	v_pk_mul_f32 v[38:39], v[28:29], 0 op_sel_hi:[1,0]
	v_pk_fma_f32 v[22:23], v[22:23], s[6:7], v[2:3] op_sel:[1,0,0] op_sel_hi:[1,1,0] neg_lo:[0,0,1] neg_hi:[0,0,1]
	v_pk_add_f32 v[42:43], v[28:29], v[38:39] op_sel:[0,1] op_sel_hi:[1,0] neg_lo:[0,1] neg_hi:[0,1]
	v_pk_add_f32 v[28:29], v[28:29], v[38:39] op_sel:[0,1] op_sel_hi:[1,0]
	s_nop 0
	v_mov_b32_e32 v43, v29
	v_pk_add_f32 v[28:29], v[24:25], v[12:13]
	v_pk_add_f32 v[12:13], v[24:25], v[12:13] neg_lo:[0,1] neg_hi:[0,1]
	s_nop 0
	v_pk_mul_f32 v[24:25], v[12:13], s[2:3] op_sel_hi:[1,0]
	s_nop 0
	v_pk_fma_f32 v[38:39], v[12:13], s[2:3], v[24:25] op_sel:[0,0,1] op_sel_hi:[1,0,0]
	v_pk_fma_f32 v[12:13], v[12:13], s[2:3], v[24:25] op_sel_hi:[1,0,0] neg_lo:[0,0,1] neg_hi:[0,0,1]
	v_pk_add_f32 v[24:25], v[34:35], v[10:11]
	v_mov_b32_e32 v39, v13
	v_pk_add_f32 v[12:13], v[26:27], v[14:15] neg_lo:[0,1] neg_hi:[0,1]
	v_pk_add_f32 v[10:11], v[34:35], v[10:11] neg_lo:[0,1] neg_hi:[0,1]
	v_pk_fma_f32 v[14:15], v[12:13], 0, v[12:13] op_sel:[0,0,1] op_sel_hi:[1,0,0]
	v_pk_fma_f32 v[12:13], v[12:13], 0, v[12:13] op_sel:[0,0,1] op_sel_hi:[1,0,0] neg_lo:[0,0,1] neg_hi:[0,0,1]
	v_pk_mul_f32 v[26:27], v[10:11], 0 op_sel_hi:[1,0]
	v_mov_b32_e32 v15, v13
	v_pk_add_f32 v[12:13], v[40:41], v[16:17]
	v_pk_add_f32 v[16:17], v[40:41], v[16:17] neg_lo:[0,1] neg_hi:[0,1]
	v_pk_add_f32 v[34:35], v[10:11], v[26:27] op_sel:[0,1] op_sel_hi:[1,0] neg_lo:[0,1] neg_hi:[0,1]
	v_pk_add_f32 v[10:11], v[10:11], v[26:27] op_sel:[0,1] op_sel_hi:[1,0]
	v_mul_f32_e32 v2, 0x3f3504f3, v16
	v_mov_b32_e32 v35, v11
; DEV int fpos(int k) { return ((k & 15) << 9) | (((k >> 4) & 31) << 4) | (k >> 9); }
; DEV int fnat(int p) { return (p >> 9) | (((p >> 4) & 31) << 4) | ((p & 15) << 9); }
; DEV cf kunpack(unsigned w) { return cf{U2F(w << 16), U2F(w & 0xffff0000u)}; }
; template <bool MULK> DEV void fft_mid(LAS cf* buf, const unsigned* Kp, int blk) {
;     ...
;     dft_regs<16, false>(v);
;     if (MULK) {
;         cf w[16];
; #pragma unroll
;         for (int p = 0; p < 16; ++p) w[p] = cmul(v[BR16[p]], kunpack(Kp[base + p]));
;         dft_regs<16, true>(w);
; #pragma unroll
;         for (int q = 0; q < 16; ++q) buf[PADI(base + q)] = w[BR16[q]];
;     } else {
; #pragma unroll
;         for (int p = 0; p < 16; ++p) buf[PADI(base + p)] = v[BR16[p]];
; DEV void filt_channel_unit2(int c, const bf16_t* h2b, const float* w3, unsigned* KF, LAS unsigned char* lds, int tid) {
;     ...
;     const float sc = 0.5f / 8192.0f;
; #pragma unroll
;     for (int i = 0; i < 16; ++i) {
;         const int p = tid + 512 * i, k = fnat(p), p2 = fpos((8192 - k) & 8191);
	v_pk_add_f32 v[10:11], v[8:9], v[4:5]
	v_pk_add_f32 v[4:5], v[8:9], v[4:5] neg_lo:[0,1] neg_hi:[0,1]
	v_pk_fma_f32 v[16:17], v[16:17], s[6:7], v[2:3] op_sel:[1,0,0] op_sel_hi:[1,1,0] neg_lo:[0,0,1] neg_hi:[0,0,1]
	v_pk_fma_f32 v[8:9], v[4:5], 0, v[4:5] op_sel:[0,0,1] op_sel_hi:[1,0,0]
	v_pk_fma_f32 v[4:5], v[4:5], 0, v[4:5] op_sel:[0,0,1] op_sel_hi:[1,0,0] neg_lo:[0,0,1] neg_hi:[0,0,1]
	v_pk_add_f32 v[26:27], v[36:37], v[30:31] neg_lo:[0,1] neg_hi:[0,1]
	v_pk_add_f32 v[2:3], v[18:19], v[22:23]
	v_pk_add_f32 v[18:19], v[18:19], v[22:23] neg_lo:[0,1] neg_hi:[0,1]
	v_mov_b32_e32 v9, v5
	v_pk_add_f32 v[4:5], v[36:37], v[30:31]
	v_pk_mul_f32 v[30:31], v[26:27], 0 op_sel_hi:[1,0]
	v_pk_fma_f32 v[22:23], v[18:19], 0, v[18:19] op_sel:[0,0,1] op_sel_hi:[1,0,0]
	v_pk_fma_f32 v[18:19], v[18:19], 0, v[18:19] op_sel:[0,0,1] op_sel_hi:[1,0,0] neg_lo:[0,0,1] neg_hi:[0,0,1]
	v_pk_add_f32 v[36:37], v[26:27], v[30:31] op_sel:[0,1] op_sel_hi:[1,0] neg_lo:[0,1] neg_hi:[0,1]
	v_pk_add_f32 v[26:27], v[26:27], v[30:31] op_sel:[0,1] op_sel_hi:[1,0]
	v_mov_b32_e32 v23, v19
	v_pk_add_f32 v[18:19], v[32:33], v[6:7]
	v_pk_add_f32 v[6:7], v[32:33], v[6:7] neg_lo:[0,1] neg_hi:[0,1]
	v_mov_b32_e32 v37, v27
	v_pk_mul_f32 v[26:27], v[6:7], 0 op_sel_hi:[1,0]
	s_lshl_b64 s[2:3], s[20:21], 16
	v_pk_add_f32 v[30:31], v[6:7], v[26:27] op_sel:[0,1] op_sel_hi:[1,0] neg_lo:[0,1] neg_hi:[0,1]
	v_pk_add_f32 v[6:7], v[6:7], v[26:27] op_sel:[0,1] op_sel_hi:[1,0]
	s_add_u32 s2, s19, s2
	v_mov_b32_e32 v31, v7
	v_pk_add_f32 v[6:7], v[28:29], v[12:13]
	v_pk_add_f32 v[12:13], v[28:29], v[12:13] neg_lo:[0,1] neg_hi:[0,1]
	s_mov_b32 s6, 0xffff0000
	v_pk_fma_f32 v[26:27], v[12:13], 0, v[12:13] op_sel:[0,0,1] op_sel_hi:[1,0,0]
	v_pk_fma_f32 v[12:13], v[12:13], 0, v[12:13] op_sel:[0,0,1] op_sel_hi:[1,0,0] neg_lo:[0,0,1] neg_hi:[0,0,1]
	s_addc_u32 s3, s23, s3
	v_mov_b32_e32 v27, v13
	v_pk_add_f32 v[12:13], v[42:43], v[14:15]
	v_pk_add_f32 v[14:15], v[42:43], v[14:15] neg_lo:[0,1] neg_hi:[0,1]
	s_add_i32 s1, s1, s81
	v_pk_mul_f32 v[28:29], v[14:15], 0 op_sel_hi:[1,0]
	s_cmpk_lt_i32 s1, 0x200
	v_pk_add_f32 v[32:33], v[14:15], v[28:29] op_sel:[0,1] op_sel_hi:[1,0] neg_lo:[0,1] neg_hi:[0,1]
	v_pk_add_f32 v[14:15], v[14:15], v[28:29] op_sel:[0,1] op_sel_hi:[1,0]
	s_nop 0
	v_mov_b32_e32 v33, v15
	v_pk_add_f32 v[14:15], v[38:39], v[16:17]
	v_pk_add_f32 v[16:17], v[38:39], v[16:17] neg_lo:[0,1] neg_hi:[0,1]
	s_nop 0
	v_pk_fma_f32 v[28:29], v[16:17], 0, v[16:17] op_sel:[0,0,1] op_sel_hi:[1,0,0]
	v_pk_fma_f32 v[16:17], v[16:17], 0, v[16:17] op_sel:[0,0,1] op_sel_hi:[1,0,0] neg_lo:[0,0,1] neg_hi:[0,0,1]
	s_nop 0
	v_mov_b32_e32 v29, v17
	v_pk_add_f32 v[16:17], v[24:25], v[10:11]
	v_pk_add_f32 v[10:11], v[24:25], v[10:11] neg_lo:[0,1] neg_hi:[0,1]
	s_nop 0
	v_pk_mul_f32 v[24:25], v[10:11], 0 op_sel_hi:[1,0]
	s_nop 0
	v_pk_add_f32 v[38:39], v[10:11], v[24:25] op_sel:[0,1] op_sel_hi:[1,0] neg_lo:[0,1] neg_hi:[0,1]
	v_pk_add_f32 v[10:11], v[10:11], v[24:25] op_sel:[0,1] op_sel_hi:[1,0]
	v_pk_add_f32 v[24:25], v[34:35], v[8:9]
	v_pk_add_f32 v[8:9], v[34:35], v[8:9] neg_lo:[0,1] neg_hi:[0,1]
	v_mov_b32_e32 v39, v11
	v_pk_mul_f32 v[34:35], v[8:9], 0 op_sel_hi:[1,0]
	s_nop 0
	v_pk_add_f32 v[40:41], v[8:9], v[34:35] op_sel:[0,1] op_sel_hi:[1,0] neg_lo:[0,1] neg_hi:[0,1]
	v_pk_add_f32 v[8:9], v[8:9], v[34:35] op_sel:[0,1] op_sel_hi:[1,0]
	v_pk_add_f32 v[34:35], v[4:5], v[2:3]
	v_pk_add_f32 v[2:3], v[4:5], v[2:3] neg_lo:[0,1] neg_hi:[0,1]
	v_mov_b32_e32 v41, v9
	v_pk_mul_f32 v[4:5], v[2:3], 0 op_sel_hi:[1,0]
	s_nop 0
	v_pk_add_f32 v[42:43], v[2:3], v[4:5] op_sel:[0,1] op_sel_hi:[1,0] neg_lo:[0,1] neg_hi:[0,1]
	v_pk_add_f32 v[2:3], v[2:3], v[4:5] op_sel:[0,1] op_sel_hi:[1,0]
	v_pk_add_f32 v[4:5], v[36:37], v[22:23]
	v_pk_add_f32 v[22:23], v[36:37], v[22:23] neg_lo:[0,1] neg_hi:[0,1]
	v_and_b32_e32 v2, 0x1f0, v0
	v_pk_mul_f32 v[36:37], v[22:23], 0 op_sel_hi:[1,0]
	v_mov_b32_e32 v43, v3
	v_pk_add_f32 v[44:45], v[22:23], v[36:37] op_sel:[0,1] op_sel_hi:[1,0] neg_lo:[0,1] neg_hi:[0,1]
	v_pk_add_f32 v[22:23], v[22:23], v[36:37] op_sel:[0,1] op_sel_hi:[1,0]
	v_pk_add_f32 v[36:37], v[18:19], v[6:7]
	v_pk_add_f32 v[6:7], v[18:19], v[6:7] neg_lo:[0,1] neg_hi:[0,1]
	v_mov_b32_e32 v45, v23
	v_pk_mul_f32 v[18:19], v[6:7], 0 op_sel_hi:[1,0]
	s_nop 0
	v_pk_add_f32 v[46:47], v[6:7], v[18:19] op_sel:[0,1] op_sel_hi:[1,0] neg_lo:[0,1] neg_hi:[0,1]
	v_pk_add_f32 v[6:7], v[6:7], v[18:19] op_sel:[0,1] op_sel_hi:[1,0]
	v_pk_add_f32 v[18:19], v[30:31], v[26:27]
	v_pk_add_f32 v[26:27], v[30:31], v[26:27] neg_lo:[0,1] neg_hi:[0,1]
	v_mov_b32_e32 v47, v7
	v_pk_mul_f32 v[30:31], v[26:27], 0 op_sel_hi:[1,0]
	s_nop 0
	v_pk_add_f32 v[48:49], v[26:27], v[30:31] op_sel:[0,1] op_sel_hi:[1,0] neg_lo:[0,1] neg_hi:[0,1]
	v_pk_add_f32 v[26:27], v[26:27], v[30:31] op_sel:[0,1] op_sel_hi:[1,0]
	v_pk_add_f32 v[30:31], v[12:13], v[14:15]
	v_pk_add_f32 v[12:13], v[12:13], v[14:15] neg_lo:[0,1] neg_hi:[0,1]
	v_mov_b32_e32 v49, v27
	v_pk_mul_f32 v[14:15], v[12:13], 0 op_sel_hi:[1,0]
	s_nop 0
	v_pk_add_f32 v[50:51], v[12:13], v[14:15] op_sel:[0,1] op_sel_hi:[1,0] neg_lo:[0,1] neg_hi:[0,1]
	v_pk_add_f32 v[12:13], v[12:13], v[14:15] op_sel:[0,1] op_sel_hi:[1,0]
	v_pk_add_f32 v[14:15], v[32:33], v[28:29]
	ds_write2_b64 v54, v[16:17], v[36:37] offset1:1
	ds_write2_b64 v54, v[34:35], v[30:31] offset0:2 offset1:3
	ds_write2_b64 v54, v[24:25], v[18:19] offset0:4 offset1:5
	ds_write2_b64 v54, v[4:5], v[14:15] offset0:6 offset1:7
	v_lshl_or_b32 v16, v0, 9, v2
	v_lshrrev_b32_e32 v2, 9, v0
	v_or_b32_e32 v2, v16, v2
	v_sub_u32_e32 v2, 0, v2
	v_lshlrev_b32_e32 v3, 9, v2
	v_pk_add_f32 v[28:29], v[32:33], v[28:29] neg_lo:[0,1] neg_hi:[0,1]
	v_and_b32_e32 v3, 0x1e00, v3
	v_and_b32_e32 v4, 0x1f0, v2
	v_bfe_u32 v2, v2, 9, 4
	v_pk_mul_f32 v[32:33], v[28:29], 0 op_sel_hi:[1,0]
	v_or3_b32 v4, v2, v4, v3
	v_pk_add_f32 v[52:53], v[28:29], v[32:33] op_sel:[0,1] op_sel_hi:[1,0] neg_lo:[0,1] neg_hi:[0,1]
	v_pk_add_f32 v[28:29], v[28:29], v[32:33] op_sel:[0,1] op_sel_hi:[1,0]
	v_lshrrev_b32_e32 v5, 4, v4
	v_mov_b32_e32 v51, v13
	v_mov_b32_e32 v53, v29
	v_add_lshl_u32 v6, v5, v4, 3
	ds_write2_b64 v54, v[38:39], v[46:47] offset0:8 offset1:9
	ds_write2_b64 v54, v[42:43], v[50:51] offset0:10 offset1:11
	ds_write2_b64 v54, v[40:41], v[48:49] offset0:12 offset1:13
	ds_write2_b64 v54, v[44:45], v[52:53] offset0:14 offset1:15
	s_waitcnt lgkmcnt(0)
	s_barrier
; DEV unsigned pk2(float lo, float hi) { return (unsigned)f2bf(lo) | ((unsigned)f2bf(hi) << 16); }
; DEV int fpos(int k) { return ((k & 15) << 9) | (((k >> 4) & 31) << 4) | (k >> 9); }
; DEV int fnat(int p) { return (p >> 9) | (((p >> 4) & 31) << 4) | ((p & 15) << 9); }
; DEV void filt_channel_unit2(int c, const bf16_t* h2b, const float* w3, unsigned* KF, LAS unsigned char* lds, int tid) {
;     ...
;     const float sc = 0.5f / 8192.0f;
; #pragma unroll
;     for (int i = 0; i < 16; ++i) {
;         const int p = tid + 512 * i, k = fnat(p), p2 = fpos((8192 - k) & 8191);
;         const cf a0 = buf0[PADI(p)], b0 = buf0[PADI(p2)], a1 = buf1[PADI(p)], b1 = buf1[PADI(p2)];
;         KF[((size_t)c * 2 + 0) * 8192 + p] = pk2((a0.x + b0.x) * sc, (a0.y - b0.y) * sc);
;         KF[((size_t)c * 2 + 1) * 8192 + p] = pk2((a0.y + b0.y) * sc, (b0.x - a0.x) * sc);
;         KF[((size_t)c * 2 + 2) * 8192 + p] = pk2((a1.x + b1.x) * sc, (a1.y - b1.y) * sc);
;         KF[((size_t)c * 2 + 3) * 8192 + p] = pk2((a1.y + b1.y) * sc, (b1.x - a1.x) * sc);
;     }
	ds_read_b64 v[2:3], v137
	v_add_u32_e32 v4, 0, v6
	ds_read_b64 v[4:5], v4
	ds_read_b64 v[8:9], v1
	v_add_u32_e32 v1, s33, v6
	ds_read_b64 v[12:13], v1
	s_waitcnt lgkmcnt(2)
	v_pk_add_f32 v[6:7], v[2:3], v[4:5]
	s_nop 0
	v_mul_f32_e32 v1, 0x38800000, v6
	v_sub_f32_e32 v3, v3, v5
	v_mul_f32_e32 v3, 0x38800000, v3
	v_bfe_u32 v5, v1, 16, 1
	v_add3_u32 v1, v1, v5, s17
	v_bfe_u32 v5, v3, 16, 1
	v_lshrrev_b32_e32 v1, 16, v1
	v_add3_u32 v3, v3, v5, s17
	v_and_or_b32 v3, v3, s6, v1
	v_ashrrev_i32_e32 v1, 31, v0
	v_lshl_add_u64 v[0:1], v[0:1], 2, s[2:3]
	global_store_dword v[0:1], v3, off
	v_mul_f32_e32 v3, 0x38800000, v7
	v_sub_f32_e32 v2, v4, v2
	v_mul_f32_e32 v2, 0x38800000, v2
	v_bfe_u32 v4, v3, 16, 1
	v_add3_u32 v3, v3, v4, s17
	v_bfe_u32 v4, v2, 16, 1
	s_mov_b64 s[2:3], 0x8000
	v_lshrrev_b32_e32 v3, 16, v3
	v_add3_u32 v2, v2, v4, s17
	v_lshl_add_u64 v[4:5], v[0:1], 0, s[2:3]
	s_mov_b32 s2, 0x9000
	v_and_or_b32 v6, v2, s6, v3
	v_add_co_u32_e32 v2, vcc, s2, v0
	s_waitcnt lgkmcnt(0)
	v_pk_add_f32 v[14:15], v[8:9], v[12:13]
	v_addc_co_u32_e32 v3, vcc, 0, v1, vcc
	global_store_dword v[2:3], v6, off offset:-4096
	v_mul_f32_e32 v6, 0x38800000, v14
	v_sub_f32_e32 v7, v9, v13
	v_mul_f32_e32 v7, 0x38800000, v7
	v_bfe_u32 v9, v6, 16, 1
	v_add3_u32 v6, v6, v9, s17
	v_bfe_u32 v9, v7, 16, 1
	s_mov_b64 s[2:3], 0x10000
	v_lshrrev_b32_e32 v6, 16, v6
	v_add3_u32 v7, v7, v9, s17
	v_lshl_add_u64 v[10:11], v[0:1], 0, s[2:3]
	s_mov_b32 s2, 0x11000
	v_and_or_b32 v9, v7, s6, v6
	v_add_co_u32_e32 v6, vcc, s2, v0
	v_sub_f32_e32 v8, v12, v8
	s_nop 0
	v_addc_co_u32_e32 v7, vcc, 0, v1, vcc
	global_store_dword v[6:7], v9, off offset:-4096
	v_mul_f32_e32 v9, 0x38800000, v15
	v_mul_f32_e32 v8, 0x38800000, v8
	v_bfe_u32 v12, v9, 16, 1
	v_add3_u32 v9, v9, v12, s17
	v_bfe_u32 v12, v8, 16, 1
	s_mov_b64 s[2:3], 0x18000
	v_lshrrev_b32_e32 v9, 16, v9
	v_add3_u32 v8, v8, v12, s17
	v_lshl_add_u64 v[12:13], v[0:1], 0, s[2:3]
	s_mov_b32 s2, 0x19000
	v_and_or_b32 v14, v8, s6, v9
	v_add_co_u32_e32 v8, vcc, s2, v0
	s_movk_i32 s2, 0x1000
	s_nop 0
	v_addc_co_u32_e32 v9, vcc, 0, v1, vcc
	global_store_dword v[8:9], v14, off offset:-4096
	v_lshrrev_b32_e32 v14, 9, v136
	v_or_b32_e32 v14, v16, v14
	v_sub_u32_e32 v14, 0, v14
	v_lshlrev_b32_e32 v15, 9, v14
	v_and_b32_e32 v15, 0x1e00, v15
	v_and_b32_e32 v17, 0x1f0, v14
	v_bfe_u32 v14, v14, 9, 4
	v_or3_b32 v17, v14, v17, v15
	v_lshrrev_b32_e32 v18, 4, v17
	v_add_lshl_u32 v17, v18, v17, 3
	ds_read_b64 v[14:15], v135 offset:4096
	v_add_u32_e32 v18, 0, v17
	ds_read_b64 v[18:19], v18
	ds_read_b64 v[22:23], v134
	v_add_u32_e32 v17, s33, v17
	ds_read_b64 v[24:25], v17
	s_waitcnt lgkmcnt(2)
	v_pk_add_f32 v[26:27], v[14:15], v[18:19]
	s_nop 0
	v_mul_f32_e32 v17, 0x38800000, v26
	v_sub_f32_e32 v15, v15, v19
	v_mul_f32_e32 v15, 0x38800000, v15
	v_bfe_u32 v19, v17, 16, 1
	v_add3_u32 v17, v17, v19, s17
	v_bfe_u32 v19, v15, 16, 1
	v_lshrrev_b32_e32 v17, 16, v17
	v_add3_u32 v15, v15, v19, s17
	v_and_or_b32 v15, v15, s6, v17
	global_store_dword v[0:1], v15, off offset:2048
	v_mul_f32_e32 v15, 0x38800000, v27
	v_sub_f32_e32 v14, v18, v14
	v_mul_f32_e32 v14, 0x38800000, v14
	v_bfe_u32 v17, v15, 16, 1
	v_add3_u32 v15, v15, v17, s17
	v_bfe_u32 v17, v14, 16, 1
	v_lshrrev_b32_e32 v15, 16, v15
	v_add3_u32 v14, v14, v17, s17
	v_and_or_b32 v14, v14, s6, v15
	global_store_dword v[4:5], v14, off offset:2048
	s_waitcnt lgkmcnt(0)
	v_pk_add_f32 v[4:5], v[22:23], v[24:25]
	v_sub_f32_e32 v14, v23, v25
	v_mul_f32_e32 v4, 0x38800000, v4
	v_mul_f32_e32 v14, 0x38800000, v14
	v_bfe_u32 v15, v4, 16, 1
	v_add3_u32 v4, v4, v15, s17
	v_bfe_u32 v15, v14, 16, 1
	v_lshrrev_b32_e32 v4, 16, v4
	v_add3_u32 v14, v14, v15, s17
	v_and_or_b32 v4, v14, s6, v4
	global_store_dword v[10:11], v4, off offset:2048
	v_mul_f32_e32 v4, 0x38800000, v5
	v_sub_f32_e32 v5, v24, v22
	v_mul_f32_e32 v5, 0x38800000, v5
	v_bfe_u32 v10, v4, 16, 1
	v_add3_u32 v4, v4, v10, s17
	v_bfe_u32 v10, v5, 16, 1
	v_lshrrev_b32_e32 v4, 16, v4
	v_add3_u32 v5, v5, v10, s17
	v_and_or_b32 v4, v5, s6, v4
	global_store_dword v[12:13], v4, off offset:2048
	v_lshrrev_b32_e32 v4, 9, v133
	v_or_b32_e32 v4, v16, v4
	v_sub_u32_e32 v4, 0, v4
	v_lshlrev_b32_e32 v5, 9, v4
	v_and_b32_e32 v5, 0x1e00, v5
	v_and_b32_e32 v10, 0x1f0, v4
	v_bfe_u32 v4, v4, 9, 4
	v_or3_b32 v4, v4, v10, v5
	v_lshrrev_b32_e32 v5, 4, v4
	v_add_lshl_u32 v4, v5, v4, 3
	ds_read_b64 v[12:13], v132 offset:8192
	v_add_u32_e32 v5, 0, v4
	ds_read_b64 v[14:15], v5
	ds_read_b64 v[18:19], v131
	v_add_u32_e32 v4, s33, v4
	ds_read_b64 v[22:23], v4
	s_waitcnt lgkmcnt(2)
	v_pk_add_f32 v[24:25], v[12:13], v[14:15]
	s_nop 0
	v_mul_f32_e32 v4, 0x38800000, v24
	v_sub_f32_e32 v5, v13, v15
	v_mul_f32_e32 v5, 0x38800000, v5
	v_bfe_u32 v10, v4, 16, 1
	v_add3_u32 v4, v4, v10, s17
	v_bfe_u32 v10, v5, 16, 1
	v_add3_u32 v5, v5, v10, s17
	v_add_co_u32_e32 v10, vcc, s2, v0
	v_lshrrev_b32_e32 v4, 16, v4
	s_nop 0
	v_addc_co_u32_e32 v11, vcc, 0, v1, vcc
	s_movk_i32 s2, 0x2000
	v_and_or_b32 v13, v5, s6, v4
	v_add_co_u32_e32 v4, vcc, s2, v0
	v_sub_f32_e32 v12, v14, v12
	s_nop 0
	v_addc_co_u32_e32 v5, vcc, 0, v1, vcc
	global_store_dword v[4:5], v13, off offset:-4096
	v_mul_f32_e32 v13, 0x38800000, v25
	v_mul_f32_e32 v12, 0x38800000, v12
	v_bfe_u32 v14, v13, 16, 1
	v_add3_u32 v13, v13, v14, s17
	v_bfe_u32 v14, v12, 16, 1
	v_lshrrev_b32_e32 v13, 16, v13
	v_add3_u32 v12, v12, v14, s17
	v_and_or_b32 v12, v12, s6, v13
	global_store_dword v[2:3], v12, off
	s_waitcnt lgkmcnt(0)
; DEV unsigned pk2(float lo, float hi) { return (unsigned)f2bf(lo) | ((unsigned)f2bf(hi) << 16); }
; DEV int fpos(int k) { return ((k & 15) << 9) | (((k >> 4) & 31) << 4) | (k >> 9); }
; DEV int fnat(int p) { return (p >> 9) | (((p >> 4) & 31) << 4) | ((p & 15) << 9); }
; DEV void filt_channel_unit2(int c, const bf16_t* h2b, const float* w3, unsigned* KF, LAS unsigned char* lds, int tid) {
;     ...
;     const float sc = 0.5f / 8192.0f;
; #pragma unroll
;     for (int i = 0; i < 16; ++i) {
;         const int p = tid + 512 * i, k = fnat(p), p2 = fpos((8192 - k) & 8191);
;         const cf a0 = buf0[PADI(p)], b0 = buf0[PADI(p2)], a1 = buf1[PADI(p)], b1 = buf1[PADI(p2)];
;         KF[((size_t)c * 2 + 0) * 8192 + p] = pk2((a0.x + b0.x) * sc, (a0.y - b0.y) * sc);
;         KF[((size_t)c * 2 + 1) * 8192 + p] = pk2((a0.y + b0.y) * sc, (b0.x - a0.x) * sc);
;         KF[((size_t)c * 2 + 2) * 8192 + p] = pk2((a1.x + b1.x) * sc, (a1.y - b1.y) * sc);
;         KF[((size_t)c * 2 + 3) * 8192 + p] = pk2((a1.y + b1.y) * sc, (b1.x - a1.x) * sc);
;     }
	v_pk_add_f32 v[12:13], v[18:19], v[22:23]
	v_sub_f32_e32 v14, v19, v23
	v_mul_f32_e32 v12, 0x38800000, v12
	v_mul_f32_e32 v14, 0x38800000, v14
	v_bfe_u32 v15, v12, 16, 1
	v_add3_u32 v12, v12, v15, s17
	v_bfe_u32 v15, v14, 16, 1
	v_lshrrev_b32_e32 v12, 16, v12
	v_add3_u32 v14, v14, v15, s17
	v_and_or_b32 v12, v14, s6, v12
	global_store_dword v[6:7], v12, off
	v_mul_f32_e32 v12, 0x38800000, v13
	v_sub_f32_e32 v13, v22, v18
	v_mul_f32_e32 v13, 0x38800000, v13
	v_bfe_u32 v14, v12, 16, 1
	v_add3_u32 v12, v12, v14, s17
	v_bfe_u32 v14, v13, 16, 1
	v_lshrrev_b32_e32 v12, 16, v12
	v_add3_u32 v13, v13, v14, s17
	v_and_or_b32 v12, v13, s6, v12
	global_store_dword v[8:9], v12, off
	v_lshrrev_b32_e32 v12, 9, v130
	v_or_b32_e32 v12, v16, v12
	v_sub_u32_e32 v12, 0, v12
	v_lshlrev_b32_e32 v13, 9, v12
	v_and_b32_e32 v13, 0x1e00, v13
	v_and_b32_e32 v14, 0x1f0, v12
	v_bfe_u32 v12, v12, 9, 4
	v_or3_b32 v14, v12, v14, v13
	v_lshrrev_b32_e32 v15, 4, v14
	v_add_lshl_u32 v17, v15, v14, 3
	ds_read_b64 v[12:13], v129 offset:12288
	v_add_u32_e32 v14, 0, v17
	ds_read_b64 v[14:15], v14
	ds_read_b64 v[18:19], v128
	v_add_u32_e32 v17, s33, v17
	ds_read_b64 v[22:23], v17
	s_mov_b32 s2, 0xa000
	s_waitcnt lgkmcnt(2)
	v_pk_add_f32 v[24:25], v[12:13], v[14:15]
	v_sub_f32_e32 v13, v13, v15
	v_mul_f32_e32 v17, 0x38800000, v24
	v_mul_f32_e32 v13, 0x38800000, v13
	v_bfe_u32 v15, v17, 16, 1
	v_add3_u32 v15, v17, v15, s17
	v_bfe_u32 v17, v13, 16, 1
	v_lshrrev_b32_e32 v15, 16, v15
	v_add3_u32 v13, v13, v17, s17
	v_and_or_b32 v13, v13, s6, v15
	global_store_dword v[10:11], v13, off offset:2048
	v_mul_f32_e32 v10, 0x38800000, v25
	v_sub_f32_e32 v11, v14, v12
	v_mul_f32_e32 v11, 0x38800000, v11
	v_bfe_u32 v12, v10, 16, 1
	v_add3_u32 v10, v10, v12, s17
	v_bfe_u32 v12, v11, 16, 1
	v_lshrrev_b32_e32 v10, 16, v10
	v_add3_u32 v11, v11, v12, s17
	v_and_or_b32 v10, v11, s6, v10
	global_store_dword v[2:3], v10, off offset:2048
	s_waitcnt lgkmcnt(0)
	v_pk_add_f32 v[2:3], v[18:19], v[22:23]
	v_sub_f32_e32 v10, v19, v23
	v_mul_f32_e32 v2, 0x38800000, v2
	v_mul_f32_e32 v10, 0x38800000, v10
	v_bfe_u32 v11, v2, 16, 1
	v_add3_u32 v2, v2, v11, s17
	v_bfe_u32 v11, v10, 16, 1
	v_lshrrev_b32_e32 v2, 16, v2
	v_add3_u32 v10, v10, v11, s17
	v_and_or_b32 v2, v10, s6, v2
	global_store_dword v[6:7], v2, off offset:2048
	v_mul_f32_e32 v2, 0x38800000, v3
	v_sub_f32_e32 v3, v22, v18
	v_mul_f32_e32 v3, 0x38800000, v3
	v_bfe_u32 v6, v2, 16, 1
	v_add3_u32 v2, v2, v6, s17
	v_bfe_u32 v6, v3, 16, 1
	v_lshrrev_b32_e32 v2, 16, v2
	v_add3_u32 v3, v3, v6, s17
	v_and_or_b32 v2, v3, s6, v2
	global_store_dword v[8:9], v2, off offset:2048
	v_lshrrev_b32_e32 v2, 9, v127
	v_or_b32_e32 v2, v16, v2
	v_sub_u32_e32 v2, 0, v2
	v_lshlrev_b32_e32 v3, 9, v2
	v_and_b32_e32 v3, 0x1e00, v3
	v_and_b32_e32 v6, 0x1f0, v2
	v_bfe_u32 v2, v2, 9, 4
	v_or3_b32 v6, v2, v6, v3
	v_lshrrev_b32_e32 v7, 4, v6
	v_add_lshl_u32 v10, v7, v6, 3
	ds_read_b64 v[2:3], v126 offset:16384
	v_add_u32_e32 v6, 0, v10
	ds_read_b64 v[6:7], v6
	ds_read_b64 v[8:9], v125
	v_add_u32_e32 v10, s33, v10
	ds_read_b64 v[14:15], v10
	s_waitcnt lgkmcnt(2)
	v_pk_add_f32 v[10:11], v[2:3], v[6:7]
	s_nop 0
	v_mul_f32_e32 v10, 0x38800000, v10
	v_sub_f32_e32 v3, v3, v7
	v_mul_f32_e32 v3, 0x38800000, v3
	v_bfe_u32 v7, v10, 16, 1
	v_add3_u32 v7, v10, v7, s17
	v_bfe_u32 v10, v3, 16, 1
	v_lshrrev_b32_e32 v7, 16, v7
	v_add3_u32 v3, v3, v10, s17
	v_and_or_b32 v3, v3, s6, v7
	global_store_dword v[4:5], v3, off
	v_mul_f32_e32 v3, 0x38800000, v11
	v_sub_f32_e32 v2, v6, v2
	v_mul_f32_e32 v2, 0x38800000, v2
	v_bfe_u32 v6, v3, 16, 1
	v_add3_u32 v3, v3, v6, s17
	v_bfe_u32 v6, v2, 16, 1
	v_add_co_u32_e32 v10, vcc, s2, v0
	v_lshrrev_b32_e32 v3, 16, v3
	v_add3_u32 v2, v2, v6, s17
	v_addc_co_u32_e32 v11, vcc, 0, v1, vcc
	s_mov_b32 s2, 0xb000
	v_and_or_b32 v6, v2, s6, v3
	v_add_co_u32_e32 v2, vcc, s2, v0
	s_waitcnt lgkmcnt(0)
	v_pk_add_f32 v[18:19], v[8:9], v[14:15]
	v_addc_co_u32_e32 v3, vcc, 0, v1, vcc
	global_store_dword v[2:3], v6, off offset:-4096
	v_mul_f32_e32 v6, 0x38800000, v18
	v_sub_f32_e32 v7, v9, v15
	v_mul_f32_e32 v7, 0x38800000, v7
	v_bfe_u32 v9, v6, 16, 1
	s_mov_b32 s2, 0x12000
	v_add3_u32 v6, v6, v9, s17
	v_bfe_u32 v9, v7, 16, 1
	v_add_co_u32_e32 v12, vcc, s2, v0
	v_lshrrev_b32_e32 v6, 16, v6
	v_add3_u32 v7, v7, v9, s17
	v_addc_co_u32_e32 v13, vcc, 0, v1, vcc
	s_mov_b32 s2, 0x13000
	v_and_or_b32 v9, v7, s6, v6
	v_add_co_u32_e32 v6, vcc, s2, v0
	v_sub_f32_e32 v8, v14, v8
	s_nop 0
	v_addc_co_u32_e32 v7, vcc, 0, v1, vcc
	global_store_dword v[6:7], v9, off offset:-4096
	v_mul_f32_e32 v9, 0x38800000, v19
	v_mul_f32_e32 v8, 0x38800000, v8
	v_bfe_u32 v14, v9, 16, 1
	v_add3_u32 v9, v9, v14, s17
	v_bfe_u32 v14, v8, 16, 1
	s_mov_b32 s2, 0x1a000
	v_add3_u32 v8, v8, v14, s17
	v_add_co_u32_e32 v14, vcc, s2, v0
	v_lshrrev_b32_e32 v9, 16, v9
	s_nop 0
	v_addc_co_u32_e32 v15, vcc, 0, v1, vcc
	s_mov_b32 s2, 0x1b000
	v_and_or_b32 v17, v8, s6, v9
	v_add_co_u32_e32 v8, vcc, s2, v0
	s_movk_i32 s2, 0x3000
	s_nop 0
	v_addc_co_u32_e32 v9, vcc, 0, v1, vcc
	global_store_dword v[8:9], v17, off offset:-4096
	v_lshrrev_b32_e32 v17, 9, v124
	v_or_b32_e32 v17, v16, v17
	v_sub_u32_e32 v17, 0, v17
	v_lshlrev_b32_e32 v18, 9, v17
	v_and_b32_e32 v18, 0x1e00, v18
	v_and_b32_e32 v19, 0x1f0, v17
	v_bfe_u32 v17, v17, 9, 4
	v_or3_b32 v17, v17, v19, v18
	v_lshrrev_b32_e32 v22, 4, v17
	v_add_lshl_u32 v17, v22, v17, 3
	ds_read_b64 v[18:19], v123 offset:20480
	v_add_u32_e32 v22, 0, v17
	ds_read_b64 v[22:23], v22
	ds_read_b64 v[24:25], v122
	v_add_u32_e32 v17, s33, v17
	ds_read_b64 v[26:27], v17
	s_waitcnt lgkmcnt(2)
; DEV unsigned pk2(float lo, float hi) { return (unsigned)f2bf(lo) | ((unsigned)f2bf(hi) << 16); }
; DEV int fpos(int k) { return ((k & 15) << 9) | (((k >> 4) & 31) << 4) | (k >> 9); }
; DEV int fnat(int p) { return (p >> 9) | (((p >> 4) & 31) << 4) | ((p & 15) << 9); }
; DEV void filt_channel_unit2(int c, const bf16_t* h2b, const float* w3, unsigned* KF, LAS unsigned char* lds, int tid) {
;     ...
;     const float sc = 0.5f / 8192.0f;
; #pragma unroll
;     for (int i = 0; i < 16; ++i) {
;         const int p = tid + 512 * i, k = fnat(p), p2 = fpos((8192 - k) & 8191);
;         const cf a0 = buf0[PADI(p)], b0 = buf0[PADI(p2)], a1 = buf1[PADI(p)], b1 = buf1[PADI(p2)];
;         KF[((size_t)c * 2 + 0) * 8192 + p] = pk2((a0.x + b0.x) * sc, (a0.y - b0.y) * sc);
;         KF[((size_t)c * 2 + 1) * 8192 + p] = pk2((a0.y + b0.y) * sc, (b0.x - a0.x) * sc);
;         KF[((size_t)c * 2 + 2) * 8192 + p] = pk2((a1.x + b1.x) * sc, (a1.y - b1.y) * sc);
;         KF[((size_t)c * 2 + 3) * 8192 + p] = pk2((a1.y + b1.y) * sc, (b1.x - a1.x) * sc);
;     }
	v_pk_add_f32 v[28:29], v[18:19], v[22:23]
	s_nop 0
	v_mul_f32_e32 v17, 0x38800000, v28
	v_sub_f32_e32 v19, v19, v23
	v_mul_f32_e32 v19, 0x38800000, v19
	v_bfe_u32 v23, v17, 16, 1
	v_add3_u32 v17, v17, v23, s17
	v_bfe_u32 v23, v19, 16, 1
	v_lshrrev_b32_e32 v17, 16, v17
	v_add3_u32 v19, v19, v23, s17
	v_and_or_b32 v17, v19, s6, v17
	global_store_dword v[4:5], v17, off offset:2048
	v_mul_f32_e32 v4, 0x38800000, v29
	v_sub_f32_e32 v5, v22, v18
	v_mul_f32_e32 v5, 0x38800000, v5
	v_bfe_u32 v17, v4, 16, 1
	v_add3_u32 v4, v4, v17, s17
	v_bfe_u32 v17, v5, 16, 1
	v_lshrrev_b32_e32 v4, 16, v4
	v_add3_u32 v5, v5, v17, s17
	v_and_or_b32 v4, v5, s6, v4
	global_store_dword v[10:11], v4, off offset:2048
	s_waitcnt lgkmcnt(0)
	v_pk_add_f32 v[4:5], v[24:25], v[26:27]
	v_sub_f32_e32 v10, v25, v27
	v_mul_f32_e32 v4, 0x38800000, v4
	v_mul_f32_e32 v10, 0x38800000, v10
	v_bfe_u32 v11, v4, 16, 1
	v_add3_u32 v4, v4, v11, s17
	v_bfe_u32 v11, v10, 16, 1
	v_lshrrev_b32_e32 v4, 16, v4
	v_add3_u32 v10, v10, v11, s17
	v_and_or_b32 v4, v10, s6, v4
	global_store_dword v[12:13], v4, off offset:2048
	v_mul_f32_e32 v4, 0x38800000, v5
	v_sub_f32_e32 v5, v26, v24
	v_mul_f32_e32 v5, 0x38800000, v5
	v_bfe_u32 v10, v4, 16, 1
	v_add3_u32 v4, v4, v10, s17
	v_bfe_u32 v10, v5, 16, 1
	v_lshrrev_b32_e32 v4, 16, v4
	v_add3_u32 v5, v5, v10, s17
	v_and_or_b32 v4, v5, s6, v4
	global_store_dword v[14:15], v4, off offset:2048
	v_lshrrev_b32_e32 v4, 9, v121
	v_or_b32_e32 v4, v16, v4
	v_sub_u32_e32 v4, 0, v4
	v_lshlrev_b32_e32 v5, 9, v4
	v_and_b32_e32 v5, 0x1e00, v5
	v_and_b32_e32 v10, 0x1f0, v4
	v_bfe_u32 v4, v4, 9, 4
	v_or3_b32 v4, v4, v10, v5
	v_lshrrev_b32_e32 v5, 4, v4
	v_add_lshl_u32 v4, v5, v4, 3
	ds_read_b64 v[12:13], v120 offset:24576
	v_add_u32_e32 v5, 0, v4
	ds_read_b64 v[14:15], v5
	ds_read_b64 v[18:19], v119
	v_add_u32_e32 v4, s33, v4
	ds_read_b64 v[22:23], v4
	s_waitcnt lgkmcnt(2)
	v_pk_add_f32 v[24:25], v[12:13], v[14:15]
	s_nop 0
	v_mul_f32_e32 v4, 0x38800000, v24
	v_sub_f32_e32 v5, v13, v15
	v_mul_f32_e32 v5, 0x38800000, v5
	v_bfe_u32 v10, v4, 16, 1
	v_add3_u32 v4, v4, v10, s17
	v_bfe_u32 v10, v5, 16, 1
	v_add3_u32 v5, v5, v10, s17
	v_add_co_u32_e32 v10, vcc, s2, v0
	v_lshrrev_b32_e32 v4, 16, v4
	s_nop 0
	v_addc_co_u32_e32 v11, vcc, 0, v1, vcc
	s_movk_i32 s2, 0x4000
	v_and_or_b32 v13, v5, s6, v4
	v_add_co_u32_e32 v4, vcc, s2, v0
	v_sub_f32_e32 v12, v14, v12
	s_nop 0
	v_addc_co_u32_e32 v5, vcc, 0, v1, vcc
	global_store_dword v[4:5], v13, off offset:-4096
	v_mul_f32_e32 v13, 0x38800000, v25
	v_mul_f32_e32 v12, 0x38800000, v12
	v_bfe_u32 v14, v13, 16, 1
	v_add3_u32 v13, v13, v14, s17
	v_bfe_u32 v14, v12, 16, 1
	v_lshrrev_b32_e32 v13, 16, v13
	v_add3_u32 v12, v12, v14, s17
	v_and_or_b32 v12, v12, s6, v13
	global_store_dword v[2:3], v12, off
	s_waitcnt lgkmcnt(0)
	v_pk_add_f32 v[12:13], v[18:19], v[22:23]
	v_sub_f32_e32 v14, v19, v23
	v_mul_f32_e32 v12, 0x38800000, v12
	v_mul_f32_e32 v14, 0x38800000, v14
	v_bfe_u32 v15, v12, 16, 1
	v_add3_u32 v12, v12, v15, s17
	v_bfe_u32 v15, v14, 16, 1
	v_lshrrev_b32_e32 v12, 16, v12
	v_add3_u32 v14, v14, v15, s17
	v_and_or_b32 v12, v14, s6, v12
	global_store_dword v[6:7], v12, off
	v_mul_f32_e32 v12, 0x38800000, v13
	v_sub_f32_e32 v13, v22, v18
	v_mul_f32_e32 v13, 0x38800000, v13
	v_bfe_u32 v14, v12, 16, 1
	v_add3_u32 v12, v12, v14, s17
	v_bfe_u32 v14, v13, 16, 1
	v_lshrrev_b32_e32 v12, 16, v12
	v_add3_u32 v13, v13, v14, s17
	v_and_or_b32 v12, v13, s6, v12
	global_store_dword v[8:9], v12, off
	v_lshrrev_b32_e32 v12, 9, v118
	v_or_b32_e32 v12, v16, v12
	v_sub_u32_e32 v12, 0, v12
	v_lshlrev_b32_e32 v13, 9, v12
	v_and_b32_e32 v13, 0x1e00, v13
	v_and_b32_e32 v14, 0x1f0, v12
	v_bfe_u32 v12, v12, 9, 4
	v_or3_b32 v14, v12, v14, v13
	v_lshrrev_b32_e32 v15, 4, v14
	v_add_lshl_u32 v17, v15, v14, 3
	ds_read_b64 v[12:13], v117 offset:28672
	v_add_u32_e32 v14, 0, v17
	ds_read_b64 v[14:15], v14
	ds_read_b64 v[18:19], v116
	v_add_u32_e32 v17, s33, v17
	ds_read_b64 v[22:23], v17
	s_mov_b32 s2, 0xc000
	s_waitcnt lgkmcnt(2)
	v_pk_add_f32 v[24:25], v[12:13], v[14:15]
	v_sub_f32_e32 v13, v13, v15
	v_mul_f32_e32 v17, 0x38800000, v24
	v_mul_f32_e32 v13, 0x38800000, v13
	v_bfe_u32 v15, v17, 16, 1
	v_add3_u32 v15, v17, v15, s17
	v_bfe_u32 v17, v13, 16, 1
	v_lshrrev_b32_e32 v15, 16, v15
	v_add3_u32 v13, v13, v17, s17
	v_and_or_b32 v13, v13, s6, v15
	global_store_dword v[10:11], v13, off offset:2048
	v_mul_f32_e32 v10, 0x38800000, v25
	v_sub_f32_e32 v11, v14, v12
	v_mul_f32_e32 v11, 0x38800000, v11
	v_bfe_u32 v12, v10, 16, 1
	v_add3_u32 v10, v10, v12, s17
	v_bfe_u32 v12, v11, 16, 1
	v_lshrrev_b32_e32 v10, 16, v10
	v_add3_u32 v11, v11, v12, s17
	v_and_or_b32 v10, v11, s6, v10
	global_store_dword v[2:3], v10, off offset:2048
	s_waitcnt lgkmcnt(0)
	v_pk_add_f32 v[2:3], v[18:19], v[22:23]
	v_sub_f32_e32 v10, v19, v23
	v_mul_f32_e32 v2, 0x38800000, v2
	v_mul_f32_e32 v10, 0x38800000, v10
	v_bfe_u32 v11, v2, 16, 1
	v_add3_u32 v2, v2, v11, s17
	v_bfe_u32 v11, v10, 16, 1
	v_lshrrev_b32_e32 v2, 16, v2
	v_add3_u32 v10, v10, v11, s17
	v_and_or_b32 v2, v10, s6, v2
	global_store_dword v[6:7], v2, off offset:2048
	v_mul_f32_e32 v2, 0x38800000, v3
	v_sub_f32_e32 v3, v22, v18
	v_mul_f32_e32 v3, 0x38800000, v3
	v_bfe_u32 v6, v2, 16, 1
	v_add3_u32 v2, v2, v6, s17
	v_bfe_u32 v6, v3, 16, 1
	v_lshrrev_b32_e32 v2, 16, v2
	v_add3_u32 v3, v3, v6, s17
	v_and_or_b32 v2, v3, s6, v2
	global_store_dword v[8:9], v2, off offset:2048
	v_lshrrev_b32_e32 v2, 9, v115
	v_or_b32_e32 v2, v16, v2
	v_sub_u32_e32 v2, 0, v2
	v_lshlrev_b32_e32 v3, 9, v2
	v_and_b32_e32 v3, 0x1e00, v3
	v_and_b32_e32 v6, 0x1f0, v2
	v_bfe_u32 v2, v2, 9, 4
	v_or3_b32 v6, v2, v6, v3
	v_lshrrev_b32_e32 v7, 4, v6
	v_add_lshl_u32 v10, v7, v6, 3
	ds_read_b64 v[2:3], v113 offset:32768
	v_add_u32_e32 v6, 0, v10
	ds_read_b64 v[6:7], v6
	ds_read_b64 v[8:9], v114
	v_add_u32_e32 v10, s33, v10
	ds_read_b64 v[14:15], v10
	s_waitcnt lgkmcnt(2)
; DEV unsigned pk2(float lo, float hi) { return (unsigned)f2bf(lo) | ((unsigned)f2bf(hi) << 16); }
; DEV int fpos(int k) { return ((k & 15) << 9) | (((k >> 4) & 31) << 4) | (k >> 9); }
; DEV int fnat(int p) { return (p >> 9) | (((p >> 4) & 31) << 4) | ((p & 15) << 9); }
; DEV void filt_channel_unit2(int c, const bf16_t* h2b, const float* w3, unsigned* KF, LAS unsigned char* lds, int tid) {
;     ...
;     const float sc = 0.5f / 8192.0f;
; #pragma unroll
;     for (int i = 0; i < 16; ++i) {
;         const int p = tid + 512 * i, k = fnat(p), p2 = fpos((8192 - k) & 8191);
;         const cf a0 = buf0[PADI(p)], b0 = buf0[PADI(p2)], a1 = buf1[PADI(p)], b1 = buf1[PADI(p2)];
;         KF[((size_t)c * 2 + 0) * 8192 + p] = pk2((a0.x + b0.x) * sc, (a0.y - b0.y) * sc);
;         KF[((size_t)c * 2 + 1) * 8192 + p] = pk2((a0.y + b0.y) * sc, (b0.x - a0.x) * sc);
;         KF[((size_t)c * 2 + 2) * 8192 + p] = pk2((a1.x + b1.x) * sc, (a1.y - b1.y) * sc);
;         KF[((size_t)c * 2 + 3) * 8192 + p] = pk2((a1.y + b1.y) * sc, (b1.x - a1.x) * sc);
;     }
	v_pk_add_f32 v[10:11], v[2:3], v[6:7]
	s_nop 0
	v_mul_f32_e32 v10, 0x38800000, v10
	v_sub_f32_e32 v3, v3, v7
	v_mul_f32_e32 v3, 0x38800000, v3
	v_bfe_u32 v7, v10, 16, 1
	v_add3_u32 v7, v10, v7, s17
	v_bfe_u32 v10, v3, 16, 1
	v_lshrrev_b32_e32 v7, 16, v7
	v_add3_u32 v3, v3, v10, s17
	v_and_or_b32 v3, v3, s6, v7
	global_store_dword v[4:5], v3, off
	v_mul_f32_e32 v3, 0x38800000, v11
	v_sub_f32_e32 v2, v6, v2
	v_mul_f32_e32 v2, 0x38800000, v2
	v_bfe_u32 v6, v3, 16, 1
	v_add3_u32 v3, v3, v6, s17
	v_bfe_u32 v6, v2, 16, 1
	v_add_co_u32_e32 v10, vcc, s2, v0
	v_lshrrev_b32_e32 v3, 16, v3
	v_add3_u32 v2, v2, v6, s17
	v_addc_co_u32_e32 v11, vcc, 0, v1, vcc
	s_mov_b32 s2, 0xd000
	v_and_or_b32 v6, v2, s6, v3
	v_add_co_u32_e32 v2, vcc, s2, v0
	s_waitcnt lgkmcnt(0)
	v_pk_add_f32 v[18:19], v[8:9], v[14:15]
	v_addc_co_u32_e32 v3, vcc, 0, v1, vcc
	global_store_dword v[2:3], v6, off offset:-4096
	v_mul_f32_e32 v6, 0x38800000, v18
	v_sub_f32_e32 v7, v9, v15
	v_mul_f32_e32 v7, 0x38800000, v7
	v_bfe_u32 v9, v6, 16, 1
	s_mov_b32 s2, 0x14000
	v_add3_u32 v6, v6, v9, s17
	v_bfe_u32 v9, v7, 16, 1
	v_add_co_u32_e32 v12, vcc, s2, v0
	v_lshrrev_b32_e32 v6, 16, v6
	v_add3_u32 v7, v7, v9, s17
	v_addc_co_u32_e32 v13, vcc, 0, v1, vcc
	s_mov_b32 s2, 0x15000
	v_and_or_b32 v9, v7, s6, v6
	v_add_co_u32_e32 v6, vcc, s2, v0
	v_sub_f32_e32 v8, v14, v8
	s_nop 0
	v_addc_co_u32_e32 v7, vcc, 0, v1, vcc
	global_store_dword v[6:7], v9, off offset:-4096
	v_mul_f32_e32 v9, 0x38800000, v19
	v_mul_f32_e32 v8, 0x38800000, v8
	v_bfe_u32 v14, v9, 16, 1
	v_add3_u32 v9, v9, v14, s17
	v_bfe_u32 v14, v8, 16, 1
	s_mov_b32 s2, 0x1c000
	v_add3_u32 v8, v8, v14, s17
	v_add_co_u32_e32 v14, vcc, s2, v0
	v_lshrrev_b32_e32 v9, 16, v9
	s_nop 0
	v_addc_co_u32_e32 v15, vcc, 0, v1, vcc
	s_mov_b32 s2, 0x1d000
	v_and_or_b32 v17, v8, s6, v9
	v_add_co_u32_e32 v8, vcc, s2, v0
	s_movk_i32 s2, 0x5000
	s_nop 0
	v_addc_co_u32_e32 v9, vcc, 0, v1, vcc
	global_store_dword v[8:9], v17, off offset:-4096
	v_lshrrev_b32_e32 v17, 9, v112
	v_or_b32_e32 v17, v16, v17
	v_sub_u32_e32 v17, 0, v17
	v_lshlrev_b32_e32 v18, 9, v17
	v_and_b32_e32 v18, 0x1e00, v18
	v_and_b32_e32 v19, 0x1f0, v17
	v_bfe_u32 v17, v17, 9, 4
	v_or3_b32 v17, v17, v19, v18
	v_lshrrev_b32_e32 v22, 4, v17
	v_add_lshl_u32 v17, v22, v17, 3
	ds_read_b64 v[18:19], v111 offset:36864
	v_add_u32_e32 v22, 0, v17
	ds_read_b64 v[22:23], v22
	ds_read_b64 v[24:25], v110
	v_add_u32_e32 v17, s33, v17
	ds_read_b64 v[26:27], v17
	s_waitcnt lgkmcnt(2)
	v_pk_add_f32 v[28:29], v[18:19], v[22:23]
	s_nop 0
	v_mul_f32_e32 v17, 0x38800000, v28
	v_sub_f32_e32 v19, v19, v23
	v_mul_f32_e32 v19, 0x38800000, v19
	v_bfe_u32 v23, v17, 16, 1
	v_add3_u32 v17, v17, v23, s17
	v_bfe_u32 v23, v19, 16, 1
	v_lshrrev_b32_e32 v17, 16, v17
	v_add3_u32 v19, v19, v23, s17
	v_and_or_b32 v17, v19, s6, v17
	global_store_dword v[4:5], v17, off offset:2048
	v_mul_f32_e32 v4, 0x38800000, v29
	v_sub_f32_e32 v5, v22, v18
	v_mul_f32_e32 v5, 0x38800000, v5
	v_bfe_u32 v17, v4, 16, 1
	v_add3_u32 v4, v4, v17, s17
	v_bfe_u32 v17, v5, 16, 1
	v_lshrrev_b32_e32 v4, 16, v4
	v_add3_u32 v5, v5, v17, s17
	v_and_or_b32 v4, v5, s6, v4
	global_store_dword v[10:11], v4, off offset:2048
	s_waitcnt lgkmcnt(0)
	v_pk_add_f32 v[4:5], v[24:25], v[26:27]
	v_sub_f32_e32 v10, v25, v27
	v_mul_f32_e32 v4, 0x38800000, v4
	v_mul_f32_e32 v10, 0x38800000, v10
	v_bfe_u32 v11, v4, 16, 1
	v_add3_u32 v4, v4, v11, s17
	v_bfe_u32 v11, v10, 16, 1
	v_lshrrev_b32_e32 v4, 16, v4
	v_add3_u32 v10, v10, v11, s17
	v_and_or_b32 v4, v10, s6, v4
	global_store_dword v[12:13], v4, off offset:2048
	v_mul_f32_e32 v4, 0x38800000, v5
	v_sub_f32_e32 v5, v26, v24
	v_mul_f32_e32 v5, 0x38800000, v5
	v_bfe_u32 v10, v4, 16, 1
	v_add3_u32 v4, v4, v10, s17
	v_bfe_u32 v10, v5, 16, 1
	v_lshrrev_b32_e32 v4, 16, v4
	v_add3_u32 v5, v5, v10, s17
	v_and_or_b32 v4, v5, s6, v4
	global_store_dword v[14:15], v4, off offset:2048
	v_lshrrev_b32_e32 v4, 9, v109
	v_or_b32_e32 v4, v16, v4
	v_sub_u32_e32 v4, 0, v4
	v_lshlrev_b32_e32 v5, 9, v4
	v_and_b32_e32 v5, 0x1e00, v5
	v_and_b32_e32 v10, 0x1f0, v4
	v_bfe_u32 v4, v4, 9, 4
	v_or3_b32 v4, v4, v10, v5
	v_lshrrev_b32_e32 v5, 4, v4
	v_add_lshl_u32 v4, v5, v4, 3
	ds_read_b64 v[12:13], v107 offset:40960
	v_add_u32_e32 v5, 0, v4
	ds_read_b64 v[14:15], v5
	ds_read_b64 v[18:19], v108
	v_add_u32_e32 v4, s33, v4
	ds_read_b64 v[22:23], v4
	s_waitcnt lgkmcnt(2)
	v_pk_add_f32 v[24:25], v[12:13], v[14:15]
	s_nop 0
	v_mul_f32_e32 v4, 0x38800000, v24
	v_sub_f32_e32 v5, v13, v15
	v_mul_f32_e32 v5, 0x38800000, v5
	v_bfe_u32 v10, v4, 16, 1
	v_add3_u32 v4, v4, v10, s17
	v_bfe_u32 v10, v5, 16, 1
	v_add3_u32 v5, v5, v10, s17
	v_add_co_u32_e32 v10, vcc, s2, v0
	v_lshrrev_b32_e32 v4, 16, v4
	s_nop 0
	v_addc_co_u32_e32 v11, vcc, 0, v1, vcc
	s_movk_i32 s2, 0x6000
	v_and_or_b32 v13, v5, s6, v4
	v_add_co_u32_e32 v4, vcc, s2, v0
	v_sub_f32_e32 v12, v14, v12
	s_nop 0
	v_addc_co_u32_e32 v5, vcc, 0, v1, vcc
	global_store_dword v[4:5], v13, off offset:-4096
	v_mul_f32_e32 v13, 0x38800000, v25
	v_mul_f32_e32 v12, 0x38800000, v12
	v_bfe_u32 v14, v13, 16, 1
	v_add3_u32 v13, v13, v14, s17
	v_bfe_u32 v14, v12, 16, 1
	v_lshrrev_b32_e32 v13, 16, v13
	v_add3_u32 v12, v12, v14, s17
	v_and_or_b32 v12, v12, s6, v13
	global_store_dword v[2:3], v12, off
	s_waitcnt lgkmcnt(0)
; DEV unsigned pk2(float lo, float hi) { return (unsigned)f2bf(lo) | ((unsigned)f2bf(hi) << 16); }
; DEV int fpos(int k) { return ((k & 15) << 9) | (((k >> 4) & 31) << 4) | (k >> 9); }
; DEV int fnat(int p) { return (p >> 9) | (((p >> 4) & 31) << 4) | ((p & 15) << 9); }
; DEV void filt_channel_unit2(int c, const bf16_t* h2b, const float* w3, unsigned* KF, LAS unsigned char* lds, int tid) {
;     ...
;     const float sc = 0.5f / 8192.0f;
; #pragma unroll
;     for (int i = 0; i < 16; ++i) {
;         const int p = tid + 512 * i, k = fnat(p), p2 = fpos((8192 - k) & 8191);
;         const cf a0 = buf0[PADI(p)], b0 = buf0[PADI(p2)], a1 = buf1[PADI(p)], b1 = buf1[PADI(p2)];
;         KF[((size_t)c * 2 + 0) * 8192 + p] = pk2((a0.x + b0.x) * sc, (a0.y - b0.y) * sc);
;         KF[((size_t)c * 2 + 1) * 8192 + p] = pk2((a0.y + b0.y) * sc, (b0.x - a0.x) * sc);
;         KF[((size_t)c * 2 + 2) * 8192 + p] = pk2((a1.x + b1.x) * sc, (a1.y - b1.y) * sc);
;         KF[((size_t)c * 2 + 3) * 8192 + p] = pk2((a1.y + b1.y) * sc, (b1.x - a1.x) * sc);
;     }
	v_pk_add_f32 v[12:13], v[18:19], v[22:23]
	v_sub_f32_e32 v14, v19, v23
	v_mul_f32_e32 v12, 0x38800000, v12
	v_mul_f32_e32 v14, 0x38800000, v14
	v_bfe_u32 v15, v12, 16, 1
	v_add3_u32 v12, v12, v15, s17
	v_bfe_u32 v15, v14, 16, 1
	v_lshrrev_b32_e32 v12, 16, v12
	v_add3_u32 v14, v14, v15, s17
	v_and_or_b32 v12, v14, s6, v12
	global_store_dword v[6:7], v12, off
	v_mul_f32_e32 v12, 0x38800000, v13
	v_sub_f32_e32 v13, v22, v18
	v_mul_f32_e32 v13, 0x38800000, v13
	v_bfe_u32 v14, v12, 16, 1
	v_add3_u32 v12, v12, v14, s17
	v_bfe_u32 v14, v13, 16, 1
	v_lshrrev_b32_e32 v12, 16, v12
	v_add3_u32 v13, v13, v14, s17
	v_and_or_b32 v12, v13, s6, v12
	global_store_dword v[8:9], v12, off
	v_lshrrev_b32_e32 v12, 9, v87
	v_or_b32_e32 v12, v16, v12
	v_sub_u32_e32 v12, 0, v12
	v_lshlrev_b32_e32 v13, 9, v12
	v_and_b32_e32 v13, 0x1e00, v13
	v_and_b32_e32 v14, 0x1f0, v12
	v_bfe_u32 v12, v12, 9, 4
	v_or3_b32 v14, v12, v14, v13
	v_lshrrev_b32_e32 v15, 4, v14
	v_add_lshl_u32 v17, v15, v14, 3
	ds_read_b64 v[12:13], v86 offset:45056
	v_add_u32_e32 v14, 0, v17
	ds_read_b64 v[14:15], v14
	ds_read_b64 v[18:19], v85
	v_add_u32_e32 v17, s33, v17
	ds_read_b64 v[22:23], v17
	s_mov_b32 s2, 0xe000
	s_waitcnt lgkmcnt(2)
	v_pk_add_f32 v[24:25], v[12:13], v[14:15]
	v_sub_f32_e32 v13, v13, v15
	v_mul_f32_e32 v17, 0x38800000, v24
	v_mul_f32_e32 v13, 0x38800000, v13
	v_bfe_u32 v15, v17, 16, 1
	v_add3_u32 v15, v17, v15, s17
	v_bfe_u32 v17, v13, 16, 1
	v_lshrrev_b32_e32 v15, 16, v15
	v_add3_u32 v13, v13, v17, s17
	v_and_or_b32 v13, v13, s6, v15
	global_store_dword v[10:11], v13, off offset:2048
	v_mul_f32_e32 v10, 0x38800000, v25
	v_sub_f32_e32 v11, v14, v12
	v_mul_f32_e32 v11, 0x38800000, v11
	v_bfe_u32 v12, v10, 16, 1
	v_add3_u32 v10, v10, v12, s17
	v_bfe_u32 v12, v11, 16, 1
	v_lshrrev_b32_e32 v10, 16, v10
	v_add3_u32 v11, v11, v12, s17
	v_and_or_b32 v10, v11, s6, v10
	global_store_dword v[2:3], v10, off offset:2048
	s_waitcnt lgkmcnt(0)
	v_pk_add_f32 v[2:3], v[18:19], v[22:23]
	v_sub_f32_e32 v10, v19, v23
	v_mul_f32_e32 v2, 0x38800000, v2
	v_mul_f32_e32 v10, 0x38800000, v10
	v_bfe_u32 v11, v2, 16, 1
	v_add3_u32 v2, v2, v11, s17
	v_bfe_u32 v11, v10, 16, 1
	v_lshrrev_b32_e32 v2, 16, v2
	v_add3_u32 v10, v10, v11, s17
	v_and_or_b32 v2, v10, s6, v2
	global_store_dword v[6:7], v2, off offset:2048
	v_mul_f32_e32 v2, 0x38800000, v3
	v_sub_f32_e32 v3, v22, v18
	v_mul_f32_e32 v3, 0x38800000, v3
	v_bfe_u32 v6, v2, 16, 1
	v_add3_u32 v2, v2, v6, s17
	v_bfe_u32 v6, v3, 16, 1
	v_lshrrev_b32_e32 v2, 16, v2
	v_add3_u32 v3, v3, v6, s17
	v_and_or_b32 v2, v3, s6, v2
	global_store_dword v[8:9], v2, off offset:2048
	v_lshrrev_b32_e32 v2, 9, v84
	v_or_b32_e32 v2, v16, v2
	v_sub_u32_e32 v2, 0, v2
	v_lshlrev_b32_e32 v3, 9, v2
	v_and_b32_e32 v3, 0x1e00, v3
	v_and_b32_e32 v6, 0x1f0, v2
	v_bfe_u32 v2, v2, 9, 4
	v_or3_b32 v6, v2, v6, v3
	v_lshrrev_b32_e32 v7, 4, v6
	v_add_lshl_u32 v10, v7, v6, 3
	ds_read_b64 v[2:3], v80 offset:49152
	v_add_u32_e32 v6, 0, v10
	ds_read_b64 v[6:7], v6
	ds_read_b64 v[8:9], v81
	v_add_u32_e32 v10, s33, v10
	ds_read_b64 v[14:15], v10
	s_waitcnt lgkmcnt(2)
	v_pk_add_f32 v[10:11], v[2:3], v[6:7]
	s_nop 0
	v_mul_f32_e32 v10, 0x38800000, v10
	v_sub_f32_e32 v3, v3, v7
	v_mul_f32_e32 v3, 0x38800000, v3
	v_bfe_u32 v7, v10, 16, 1
	v_add3_u32 v7, v10, v7, s17
	v_bfe_u32 v10, v3, 16, 1
	v_lshrrev_b32_e32 v7, 16, v7
	v_add3_u32 v3, v3, v10, s17
	v_and_or_b32 v3, v3, s6, v7
	global_store_dword v[4:5], v3, off
	v_mul_f32_e32 v3, 0x38800000, v11
	v_sub_f32_e32 v2, v6, v2
	v_mul_f32_e32 v2, 0x38800000, v2
	v_bfe_u32 v6, v3, 16, 1
	v_add3_u32 v3, v3, v6, s17
	v_bfe_u32 v6, v2, 16, 1
	v_add_co_u32_e32 v10, vcc, s2, v0
	v_lshrrev_b32_e32 v3, 16, v3
	v_add3_u32 v2, v2, v6, s17
	v_addc_co_u32_e32 v11, vcc, 0, v1, vcc
	s_mov_b32 s2, 0xf000
	v_and_or_b32 v6, v2, s6, v3
	v_add_co_u32_e32 v2, vcc, s2, v0
	s_waitcnt lgkmcnt(0)
	v_pk_add_f32 v[18:19], v[8:9], v[14:15]
	v_addc_co_u32_e32 v3, vcc, 0, v1, vcc
	global_store_dword v[2:3], v6, off offset:-4096
	v_mul_f32_e32 v6, 0x38800000, v18
	v_sub_f32_e32 v7, v9, v15
	v_mul_f32_e32 v7, 0x38800000, v7
	v_bfe_u32 v9, v6, 16, 1
	s_mov_b32 s2, 0x16000
	v_add3_u32 v6, v6, v9, s17
	v_bfe_u32 v9, v7, 16, 1
	v_add_co_u32_e32 v12, vcc, s2, v0
	v_lshrrev_b32_e32 v6, 16, v6
	v_add3_u32 v7, v7, v9, s17
	v_addc_co_u32_e32 v13, vcc, 0, v1, vcc
	s_mov_b32 s2, 0x17000
	v_and_or_b32 v9, v7, s6, v6
	v_add_co_u32_e32 v6, vcc, s2, v0
	v_sub_f32_e32 v8, v14, v8
	s_nop 0
	v_addc_co_u32_e32 v7, vcc, 0, v1, vcc
	global_store_dword v[6:7], v9, off offset:-4096
	v_mul_f32_e32 v9, 0x38800000, v19
	v_mul_f32_e32 v8, 0x38800000, v8
	v_bfe_u32 v14, v9, 16, 1
	v_add3_u32 v9, v9, v14, s17
	v_bfe_u32 v14, v8, 16, 1
	s_mov_b32 s2, 0x1e000
	v_add3_u32 v8, v8, v14, s17
	v_add_co_u32_e32 v14, vcc, s2, v0
	v_lshrrev_b32_e32 v9, 16, v9
	s_nop 0
	v_addc_co_u32_e32 v15, vcc, 0, v1, vcc
	s_mov_b32 s2, 0x1f000
	v_and_or_b32 v17, v8, s6, v9
	v_add_co_u32_e32 v8, vcc, s2, v0
	s_movk_i32 s2, 0x7000
	s_nop 0
	v_addc_co_u32_e32 v9, vcc, 0, v1, vcc
	global_store_dword v[8:9], v17, off offset:-4096
	v_lshrrev_b32_e32 v17, 9, v79
	v_or_b32_e32 v17, v16, v17
	v_sub_u32_e32 v17, 0, v17
	v_lshlrev_b32_e32 v18, 9, v17
	v_and_b32_e32 v18, 0x1e00, v18
	v_and_b32_e32 v19, 0x1f0, v17
	v_bfe_u32 v17, v17, 9, 4
	v_or3_b32 v17, v17, v19, v18
	v_lshrrev_b32_e32 v22, 4, v17
	v_add_lshl_u32 v17, v22, v17, 3
	ds_read_b64 v[18:19], v78 offset:53248
	v_add_u32_e32 v22, 0, v17
	ds_read_b64 v[22:23], v22
	ds_read_b64 v[24:25], v77
	v_add_u32_e32 v17, s33, v17
	ds_read_b64 v[26:27], v17
	v_add_co_u32_e32 v0, vcc, s2, v0
	s_waitcnt lgkmcnt(2)
; #define SYNC() __syncthreads()
; DEV unsigned pk2(float lo, float hi) { return (unsigned)f2bf(lo) | ((unsigned)f2bf(hi) << 16); }
; DEV int fpos(int k) { return ((k & 15) << 9) | (((k >> 4) & 31) << 4) | (k >> 9); }
; DEV int fnat(int p) { return (p >> 9) | (((p >> 4) & 31) << 4) | ((p & 15) << 9); }
; #define DUP(bit) for (int rep_ = 0; rep_ < (((DUP_MASK) & (bit)) ? (DUP_REP) : 1); (void)(((DUP_BAR) && ((DUP_MASK) & (bit)) && rep_ + 1 < (DUP_REP)) ? (xcd_barrier(bar, IS_T0()), 0) : 0), ++rep_)
; DEV void filt_channel_unit2(int c, const bf16_t* h2b, const float* w3, unsigned* KF, LAS unsigned char* lds, int tid) {
;     ...
;     const float sc = 0.5f / 8192.0f;
; #pragma unroll
;     for (int i = 0; i < 16; ++i) {
;         const int p = tid + 512 * i, k = fnat(p), p2 = fpos((8192 - k) & 8191);
;         const cf a0 = buf0[PADI(p)], b0 = buf0[PADI(p2)], a1 = buf1[PADI(p)], b1 = buf1[PADI(p2)];
;         KF[((size_t)c * 2 + 0) * 8192 + p] = pk2((a0.x + b0.x) * sc, (a0.y - b0.y) * sc);
;         KF[((size_t)c * 2 + 1) * 8192 + p] = pk2((a0.y + b0.y) * sc, (b0.x - a0.x) * sc);
;         KF[((size_t)c * 2 + 2) * 8192 + p] = pk2((a1.x + b1.x) * sc, (a1.y - b1.y) * sc);
;         KF[((size_t)c * 2 + 3) * 8192 + p] = pk2((a1.y + b1.y) * sc, (b1.x - a1.x) * sc);
;     }
;     SYNC();
; __global__ void __launch_bounds__(512, 2) mega_fwd(Args args) {
;     ...
;           if (PH_IN) DUP(2048) { PH_CTX int pvcu = vcu; asm volatile("" : "+s"(pvcu)); for (int c2 = pvcu; c2 < 512; c2 += G) filt_channel_unit2(2 * c2, WSP(const bf16_t, WS_H2F), ap->in[17] + (size_t)pl * 64 * 4096, WSP(unsigned, WS_KF), lds, ptid); }
	v_pk_add_f32 v[28:29], v[18:19], v[22:23]
	v_sub_f32_e32 v19, v19, v23
	v_mul_f32_e32 v17, 0x38800000, v28
	v_mul_f32_e32 v19, 0x38800000, v19
	v_bfe_u32 v23, v17, 16, 1
	v_add3_u32 v17, v17, v23, s17
	v_bfe_u32 v23, v19, 16, 1
	v_lshrrev_b32_e32 v17, 16, v17
	v_add3_u32 v19, v19, v23, s17
	v_and_or_b32 v17, v19, s6, v17
	global_store_dword v[4:5], v17, off offset:2048
	v_mul_f32_e32 v4, 0x38800000, v29
	v_sub_f32_e32 v5, v22, v18
	v_mul_f32_e32 v5, 0x38800000, v5
	v_bfe_u32 v17, v4, 16, 1
	v_add3_u32 v4, v4, v17, s17
	v_bfe_u32 v17, v5, 16, 1
	v_lshrrev_b32_e32 v4, 16, v4
	v_add3_u32 v5, v5, v17, s17
	v_and_or_b32 v4, v5, s6, v4
	global_store_dword v[10:11], v4, off offset:2048
	s_waitcnt lgkmcnt(0)
	v_pk_add_f32 v[4:5], v[24:25], v[26:27]
	v_sub_f32_e32 v10, v25, v27
	v_mul_f32_e32 v4, 0x38800000, v4
	v_mul_f32_e32 v10, 0x38800000, v10
	v_bfe_u32 v11, v4, 16, 1
	v_add3_u32 v4, v4, v11, s17
	v_bfe_u32 v11, v10, 16, 1
	v_lshrrev_b32_e32 v4, 16, v4
	v_add3_u32 v10, v10, v11, s17
	v_and_or_b32 v4, v10, s6, v4
	global_store_dword v[12:13], v4, off offset:2048
	v_mul_f32_e32 v4, 0x38800000, v5
	v_sub_f32_e32 v5, v26, v24
	v_mul_f32_e32 v5, 0x38800000, v5
	v_bfe_u32 v10, v4, 16, 1
	v_add3_u32 v4, v4, v10, s17
	v_bfe_u32 v10, v5, 16, 1
	v_lshrrev_b32_e32 v4, 16, v4
	v_add3_u32 v5, v5, v10, s17
	v_and_or_b32 v4, v5, s6, v4
	global_store_dword v[14:15], v4, off offset:2048
	v_lshrrev_b32_e32 v4, 9, v76
	v_or_b32_e32 v4, v16, v4
	v_sub_u32_e32 v4, 0, v4
	v_lshlrev_b32_e32 v5, 9, v4
	v_and_b32_e32 v5, 0x1e00, v5
	v_and_b32_e32 v10, 0x1f0, v4
	v_bfe_u32 v4, v4, 9, 4
	v_or3_b32 v10, v4, v10, v5
	v_lshrrev_b32_e32 v11, 4, v10
	v_add_lshl_u32 v14, v11, v10, 3
	ds_read_b64 v[4:5], v74 offset:57344
	v_add_u32_e32 v10, 0, v14
	ds_read_b64 v[10:11], v10
	ds_read_b64 v[12:13], v75
	v_add_u32_e32 v14, s33, v14
	v_addc_co_u32_e32 v1, vcc, 0, v1, vcc
	s_waitcnt lgkmcnt(1)
	v_pk_add_f32 v[18:19], v[4:5], v[10:11]
	v_sub_f32_e32 v5, v5, v11
	v_mul_f32_e32 v17, 0x38800000, v18
	v_mul_f32_e32 v5, 0x38800000, v5
	v_bfe_u32 v11, v17, 16, 1
	v_add3_u32 v11, v17, v11, s17
	v_bfe_u32 v17, v5, 16, 1
	v_lshrrev_b32_e32 v11, 16, v11
	v_add3_u32 v5, v5, v17, s17
	v_and_or_b32 v5, v5, s6, v11
	ds_read_b64 v[14:15], v14
	global_store_dword v[0:1], v5, off
	v_mul_f32_e32 v5, 0x38800000, v19
	v_sub_f32_e32 v4, v10, v4
	v_mul_f32_e32 v4, 0x38800000, v4
	v_bfe_u32 v10, v5, 16, 1
	v_add3_u32 v5, v5, v10, s17
	v_bfe_u32 v10, v4, 16, 1
	v_lshrrev_b32_e32 v5, 16, v5
	v_add3_u32 v4, v4, v10, s17
	v_and_or_b32 v4, v4, s6, v5
	global_store_dword v[2:3], v4, off
	s_waitcnt lgkmcnt(0)
	v_pk_add_f32 v[4:5], v[12:13], v[14:15]
	v_sub_f32_e32 v10, v13, v15
	v_mul_f32_e32 v4, 0x38800000, v4
	v_mul_f32_e32 v10, 0x38800000, v10
	v_bfe_u32 v11, v4, 16, 1
	v_add3_u32 v4, v4, v11, s17
	v_bfe_u32 v11, v10, 16, 1
	v_lshrrev_b32_e32 v4, 16, v4
	v_add3_u32 v10, v10, v11, s17
	v_and_or_b32 v4, v10, s6, v4
	global_store_dword v[6:7], v4, off
	v_mul_f32_e32 v4, 0x38800000, v5
	v_sub_f32_e32 v5, v14, v12
	v_mul_f32_e32 v5, 0x38800000, v5
	v_bfe_u32 v10, v4, 16, 1
	v_add3_u32 v4, v4, v10, s17
	v_bfe_u32 v10, v5, 16, 1
	v_lshrrev_b32_e32 v4, 16, v4
	v_add3_u32 v5, v5, v10, s17
	v_and_or_b32 v4, v5, s6, v4
	global_store_dword v[8:9], v4, off
	v_lshrrev_b32_e32 v4, 9, v73
	v_or_b32_e32 v4, v16, v4
	v_sub_u32_e32 v4, 0, v4
	v_lshlrev_b32_e32 v5, 9, v4
	v_and_b32_e32 v5, 0x1e00, v5
	v_and_b32_e32 v10, 0x1f0, v4
	v_bfe_u32 v4, v4, 9, 4
	v_or3_b32 v10, v4, v10, v5
	v_lshrrev_b32_e32 v11, 4, v10
	v_add_lshl_u32 v14, v11, v10, 3
	ds_read_b64 v[4:5], v72 offset:61440
	v_add_u32_e32 v10, 0, v14
	ds_read_b64 v[10:11], v10
	ds_read_b64 v[12:13], v21
	v_add_u32_e32 v14, s33, v14
	ds_read_b64 v[14:15], v14
	s_waitcnt lgkmcnt(2)
	v_pk_add_f32 v[16:17], v[4:5], v[10:11]
	s_nop 0
	v_mul_f32_e32 v16, 0x38800000, v16
	v_sub_f32_e32 v5, v5, v11
	v_mul_f32_e32 v5, 0x38800000, v5
	v_bfe_u32 v11, v16, 16, 1
	v_add3_u32 v11, v16, v11, s17
	v_bfe_u32 v16, v5, 16, 1
	v_lshrrev_b32_e32 v11, 16, v11
	v_add3_u32 v5, v5, v16, s17
	v_and_or_b32 v5, v5, s6, v11
	global_store_dword v[0:1], v5, off offset:2048
	v_mul_f32_e32 v0, 0x38800000, v17
	v_sub_f32_e32 v1, v10, v4
	v_mul_f32_e32 v1, 0x38800000, v1
	v_bfe_u32 v4, v0, 16, 1
	v_add3_u32 v0, v0, v4, s17
	v_bfe_u32 v4, v1, 16, 1
	v_lshrrev_b32_e32 v0, 16, v0
	v_add3_u32 v1, v1, v4, s17
	v_and_or_b32 v0, v1, s6, v0
	global_store_dword v[2:3], v0, off offset:2048
	s_waitcnt lgkmcnt(0)
	v_pk_add_f32 v[0:1], v[12:13], v[14:15]
	v_sub_f32_e32 v2, v13, v15
	v_mul_f32_e32 v0, 0x38800000, v0
	v_mul_f32_e32 v2, 0x38800000, v2
	v_bfe_u32 v3, v0, 16, 1
	v_add3_u32 v0, v0, v3, s17
	v_bfe_u32 v3, v2, 16, 1
	v_lshrrev_b32_e32 v0, 16, v0
	v_add3_u32 v2, v2, v3, s17
	v_and_or_b32 v0, v2, s6, v0
	global_store_dword v[6:7], v0, off offset:2048
	v_mul_f32_e32 v0, 0x38800000, v1
	v_sub_f32_e32 v1, v14, v12
	v_mul_f32_e32 v1, 0x38800000, v1
	v_bfe_u32 v2, v0, 16, 1
	v_add3_u32 v0, v0, v2, s17
	v_bfe_u32 v2, v1, 16, 1
	v_lshrrev_b32_e32 v0, 16, v0
	v_add3_u32 v1, v1, v2, s17
	v_and_or_b32 v0, v1, s6, v0
	global_store_dword v[8:9], v0, off offset:2048
	s_waitcnt vmcnt(63) expcnt(7) lgkmcnt(15)
	s_barrier
	s_cbranch_scc0 .LBB0_226

; #define LAS __attribute__((address_space(3)))
; #define OPAQUE_I(x) asm volatile("" : "+v"(x))
; template <int R, bool INV> DEV void dft_regs(cf (&v)[R]) {
; #pragma unroll
;     for (int s = R; s >= 2; s >>= 1) {
;         const int h = s >> 1;
; #pragma unroll
;         for (int b = 0; b < R; b += s) {
; #pragma unroll
;             for (int k = 0; k < h; ++k) {
;                 const cf a = v[b + k], c = v[b + k + h];
;                 v[b + k] = a + c;
;                 const cf d = a - c;
;                 const int m = k * (32 / s);
;                 const float wr = tw_cos(m), wi = INV ? tw_sin(m) : -tw_sin(m);
;                 v[b + k + h] = cf{d.x * wr - d.y * wi, d.x * wi + d.y * wr};
; DEV void fft_f1x2(LAS cf* buf0, LAS cf* buf1, const cf (&z0)[8], const cf (&z1)[8], int tid) {
;     OPAQUE_I(tid);
;     cf v[16], u[16];
; #pragma unroll
;     for (int q = 0; q < 8; ++q) { v[q] = z0[q]; v[q + 8] = cf{0.f, 0.f}; u[q] = z1[q]; u[q + 8] = cf{0.f, 0.f}; }
;     dft_regs<16, false>(v); dft_regs<16, false>(u);
.LBB0_519:
	v_pk_mul_f32 v[16:17], v[26:27], s[16:17] op_sel_hi:[1,0]
	v_pk_add_f32 v[0:1], v[24:25], 0 op_sel_hi:[1,0]
	v_pk_fma_f32 v[18:19], v[26:27], s[84:85], v[16:17] op_sel:[0,0,1] op_sel_hi:[1,0,0] neg_hi:[0,0,1]
	v_pk_add_f32 v[16:17], v[22:23], 0 op_sel_hi:[1,0]
	v_mov_b32_e32 v4, v24
	v_mov_b32_e32 v5, v25
	v_pk_add_f32 v[80:81], v[0:1], v[16:17]
	v_pk_add_f32 v[0:1], v[0:1], v[16:17] neg_lo:[0,1] neg_hi:[0,1]
	v_pk_fma_f32 v[66:67], v[22:23], 0, v[22:23] op_sel:[0,0,1] op_sel_hi:[1,0,0] neg_hi:[0,0,1]
	v_mov_b32_e32 v5, v25
	v_pk_add_f32 v[2:3], v[30:31], 0 op_sel_hi:[1,0]
	v_pk_mul_f32 v[6:7], v[30:31], s[84:85] op_sel_hi:[1,0]
	v_pk_add_f32 v[68:69], v[32:33], 0 op_sel_hi:[1,0]
	v_pk_fma_f32 v[8:9], v[30:31], s[16:17], v[6:7] op_sel:[0,0,1] op_sel_hi:[1,0,0] neg_hi:[0,0,1]
	v_pk_add_f32 v[82:83], v[2:3], v[68:69]
	v_pk_add_f32 v[2:3], v[2:3], v[68:69] neg_lo:[0,1] neg_hi:[0,1]
	v_pk_add_f32 v[6:7], v[28:29], 0 op_sel_hi:[1,0]
	v_pk_add_f32 v[72:73], v[34:35], 0 op_sel_hi:[1,0]
	v_pk_mul_f32 v[16:17], v[2:3], s[18:19] op_sel_hi:[1,0]
	v_pk_mul_f32 v[10:11], v[28:29], s[18:19] op_sel_hi:[1,0]
	v_pk_fma_f32 v[68:69], v[2:3], s[18:19], v[16:17] op_sel:[0,0,1] op_sel_hi:[1,0,0]
	v_pk_fma_f32 v[2:3], v[2:3], s[18:19], v[16:17] op_sel_hi:[1,0,0] neg_lo:[0,0,1] neg_hi:[0,0,1]
	v_pk_add_f32 v[16:17], v[6:7], v[72:73]
	v_pk_add_f32 v[6:7], v[6:7], v[72:73] neg_lo:[0,1] neg_hi:[0,1]
	v_pk_add_f32 v[14:15], v[26:27], 0 op_sel_hi:[1,0]
	v_pk_add_f32 v[76:77], v[36:37], 0 op_sel_hi:[1,0]
	v_pk_add_f32 v[72:73], v[6:7], 0 op_sel:[1,0] op_sel_hi:[0,0] neg_hi:[1,0]
	v_pk_fma_f32 v[12:13], v[28:29], s[18:19], v[10:11] op_sel:[0,0,1] op_sel_hi:[1,0,0]
	v_pk_fma_f32 v[10:11], v[28:29], s[18:19], v[10:11] op_sel_hi:[1,0,0] neg_lo:[0,0,1] neg_hi:[0,0,1]
	v_pk_add_f32 v[6:7], v[14:15], v[76:77]
	v_pk_add_f32 v[14:15], v[14:15], v[76:77] neg_lo:[0,1] neg_hi:[0,1]
	v_pk_add_f32 v[76:77], v[4:5], v[66:67]
	v_pk_add_f32 v[4:5], v[4:5], v[66:67] neg_lo:[0,1] neg_hi:[0,1]
	v_mov_b32_e32 v10, v33
	s_mov_b32 s30, s85
	s_mov_b32 s31, s0
	v_pk_mul_f32 v[70:71], v[32:33], s[84:85] op_sel_hi:[0,1]
	v_pk_fma_f32 v[70:71], v[10:11], s[30:31], v[70:71] op_sel_hi:[0,1,1] neg_lo:[0,0,1] neg_hi:[0,0,1]
	v_mul_f32_e32 v10, 0x3f3504f3, v34
	v_mov_b32_e32 v74, v35
	s_mov_b32 s28, s97
	s_mov_b32 s29, s96
	s_mov_b32 s24, s85
	s_mov_b32 s25, s84
	v_pk_add_f32 v[84:85], v[8:9], v[70:71]
	v_pk_add_f32 v[8:9], v[8:9], v[70:71] neg_lo:[0,1] neg_hi:[0,1]
	v_pk_fma_f32 v[74:75], v[74:75], s[28:29], v[10:11] op_sel_hi:[0,1,0] neg_lo:[0,0,1] neg_hi:[0,0,1]
	v_mov_b32_e32 v10, v37
	s_mov_b32 s34, s84
	s_mov_b32 s35, s88
	v_pk_mul_f32 v[78:79], v[36:37], s[24:25] op_sel_hi:[0,1]
	v_pk_mul_f32 v[66:67], v[8:9], s[18:19] op_sel_hi:[1,0]
	v_mov_b32_e32 v13, v11
	v_pk_fma_f32 v[78:79], v[10:11], s[34:35], v[78:79] op_sel_hi:[0,1,1] neg_lo:[0,0,1] neg_hi:[0,0,1]
	v_pk_fma_f32 v[70:71], v[8:9], s[18:19], v[66:67] op_sel:[0,0,1] op_sel_hi:[1,0,0] neg_hi:[0,0,1]
	v_pk_add_f32 v[10:11], v[12:13], v[74:75] neg_lo:[0,1] neg_hi:[0,1]
	v_pk_add_f32 v[66:67], v[80:81], v[16:17]
	v_pk_add_f32 v[16:17], v[80:81], v[16:17] neg_lo:[0,1] neg_hi:[0,1]
	v_pk_add_f32 v[8:9], v[12:13], v[74:75]
	v_pk_add_f32 v[12:13], v[10:11], 0 op_sel:[1,0] op_sel_hi:[0,0] neg_hi:[1,0]
	v_pk_add_f32 v[10:11], v[18:19], v[78:79]
	v_pk_add_f32 v[18:19], v[18:19], v[78:79] neg_lo:[0,1] neg_hi:[0,1]
	v_mul_f32_e32 v2, 0x3f3504f3, v14
	v_pk_add_f32 v[78:79], v[82:83], v[6:7]
	v_pk_add_f32 v[82:83], v[82:83], v[6:7] neg_lo:[0,1] neg_hi:[0,1]
	v_pk_add_f32 v[74:75], v[0:1], v[72:73]
	v_pk_add_f32 v[6:7], v[82:83], 0 op_sel:[1,0] op_sel_hi:[0,0] neg_hi:[1,0]
	v_pk_fma_f32 v[14:15], v[14:15], s[28:29], v[2:3] op_sel:[1,0,0] op_sel_hi:[1,1,0] neg_lo:[0,0,1] neg_hi:[0,0,1]
	v_pk_add_f32 v[82:83], v[0:1], v[72:73] neg_lo:[0,1] neg_hi:[0,1]
	v_mov_b32_e32 v69, v3
	v_mul_f32_e32 v2, 0x3f3504f3, v18
	v_mov_b32_e32 v80, v82
	v_mov_b32_e32 v81, v83
	v_pk_fma_f32 v[18:19], v[18:19], s[28:29], v[2:3] op_sel:[1,0,0] op_sel_hi:[1,1,0] neg_lo:[0,0,1] neg_hi:[0,0,1]
	v_pk_add_f32 v[0:1], v[68:69], v[14:15] neg_lo:[0,1] neg_hi:[0,1]
	v_pk_add_f32 v[2:3], v[68:69], v[14:15]
	v_pk_add_f32 v[14:15], v[0:1], 0 op_sel:[1,0] op_sel_hi:[0,0] neg_hi:[1,0]
	v_pk_add_f32 v[72:73], v[76:77], v[8:9]
	v_pk_add_f32 v[0:1], v[76:77], v[8:9] neg_lo:[0,1] neg_hi:[0,1]
	v_pk_add_f32 v[86:87], v[4:5], v[12:13]
	v_pk_add_f32 v[68:69], v[66:67], v[78:79]
	v_pk_add_f32 v[8:9], v[84:85], v[10:11]
	v_pk_add_f32 v[82:83], v[84:85], v[10:11] neg_lo:[0,1] neg_hi:[0,1]
	v_pk_add_f32 v[88:89], v[70:71], v[18:19]
	v_pk_add_f32 v[10:11], v[82:83], 0 op_sel:[1,0] op_sel_hi:[0,0] neg_hi:[1,0]
	v_pk_add_f32 v[76:77], v[72:73], v[8:9]
	v_pk_add_f32 v[82:83], v[4:5], v[12:13] neg_lo:[0,1] neg_hi:[0,1]
	v_pk_add_f32 v[8:9], v[72:73], v[8:9] neg_lo:[0,1] neg_hi:[0,1]
	v_pk_add_f32 v[72:73], v[0:1], v[10:11]
	v_mov_b32_e32 v4, v82
	v_mov_b32_e32 v5, v83
	v_pk_add_f32 v[10:11], v[0:1], v[10:11] neg_lo:[0,1] neg_hi:[0,1]
	v_pk_add_f32 v[0:1], v[70:71], v[18:19] neg_lo:[0,1] neg_hi:[0,1]
	v_pk_add_f32 v[70:71], v[74:75], v[2:3]
	v_pk_add_f32 v[90:91], v[0:1], 0 op_sel:[1,0] op_sel_hi:[0,0] neg_hi:[1,0]
	v_pk_add_f32 v[2:3], v[74:75], v[2:3] neg_lo:[0,1] neg_hi:[0,1]
	v_pk_add_f32 v[0:1], v[66:67], v[78:79] neg_lo:[0,1] neg_hi:[0,1]
	v_pk_add_f32 v[78:79], v[16:17], v[6:7]
	v_pk_add_f32 v[6:7], v[16:17], v[6:7] neg_lo:[0,1] neg_hi:[0,1]
	v_mov_b32_e32 v84, v0
	v_mov_b32_e32 v85, v1
	v_mov_b32_e32 v0, v6
	v_mov_b32_e32 v1, v7
	v_mov_b32_e32 v6, v2
	v_mov_b32_e32 v7, v3
	v_pk_add_f32 v[12:13], v[80:81], v[14:15] neg_lo:[0,1] neg_hi:[0,1]
	v_pk_add_f32 v[18:19], v[80:81], v[14:15]
; template <int R, bool INV> DEV void dft_regs(cf (&v)[R]) {
; #pragma unroll
;     for (int s = R; s >= 2; s >>= 1) {
;         const int h = s >> 1;
; #pragma unroll
;         for (int b = 0; b < R; b += s) {
; #pragma unroll
;             for (int k = 0; k < h; ++k) {
;                 const cf a = v[b + k], c = v[b + k + h];
;                 v[b + k] = a + c;
;                 const cf d = a - c;
;                 const int m = k * (32 / s);
;                 const float wr = tw_cos(m), wi = INV ? tw_sin(m) : -tw_sin(m);
;                 v[b + k + h] = cf{d.x * wr - d.y * wi, d.x * wi + d.y * wr};
; DEV void fft_f1x2(LAS cf* buf0, LAS cf* buf1, const cf (&z0)[8], const cf (&z1)[8], int tid) {
;     ...
;     for (int q = 0; q < 8; ++q) { v[q] = z0[q]; v[q + 8] = cf{0.f, 0.f}; u[q] = z1[q]; u[q + 8] = cf{0.f, 0.f}; }
;     dft_regs<16, false>(v); dft_regs<16, false>(u);
; DEV void fft_midx2(LAS cf* buf0, LAS cf* buf1, const unsigned* Kp, int blk) {
;     ...
;     u32x4 kw[4];
; #pragma unroll
;     for (int j = 0; j < 4; ++j) kw[j] = *(const u32x4*)(Kp + base + 4 * j);
	v_mov_b32_e32 v2, v12
	v_mov_b32_e32 v3, v13
	v_mov_b32_e32 v12, v8
	v_mov_b32_e32 v13, v9
	v_mov_b32_e32 v8, v10
	v_mov_b32_e32 v9, v11
	v_pk_mul_f32 v[92:93], v[50:51], s[16:17] op_sel_hi:[1,0]
	v_pk_add_f32 v[10:11], v[86:87], v[88:89] neg_lo:[0,1] neg_hi:[0,1]
	v_pk_fma_f32 v[94:95], v[50:51], s[84:85], v[92:93] op_sel:[0,0,1] op_sel_hi:[1,0,0] neg_hi:[0,0,1]
	v_mov_b32_e32 v14, v10
	v_mov_b32_e32 v15, v11
	v_pk_add_f32 v[66:67], v[4:5], v[90:91] neg_lo:[0,1] neg_hi:[0,1]
	v_mov_b32_e32 v10, v66
	v_mov_b32_e32 v11, v67
	v_pk_add_f32 v[92:93], v[46:47], 0 op_sel_hi:[1,0]
	v_pk_add_f32 v[66:67], v[38:39], 0 op_sel_hi:[1,0]
	v_mov_b32_e32 v108, v41
	v_pk_mul_f32 v[110:111], v[40:41], s[24:25] op_sel_hi:[0,1]
	v_pk_fma_f32 v[108:109], v[108:109], s[34:35], v[110:111] op_sel_hi:[0,1,1] neg_lo:[0,0,1] neg_hi:[0,0,1]
	v_pk_add_f32 v[110:111], v[66:67], v[92:93]
	v_pk_add_f32 v[66:67], v[66:67], v[92:93] neg_lo:[0,1] neg_hi:[0,1]
	v_mov_b32_e32 v82, v38
	v_mov_b32_e32 v83, v39
	v_pk_fma_f32 v[96:97], v[46:47], 0, v[46:47] op_sel:[0,0,1] op_sel_hi:[1,0,0] neg_hi:[0,0,1]
	v_mov_b32_e32 v83, v39
	v_pk_add_f32 v[80:81], v[42:43], 0 op_sel_hi:[1,0]
	v_pk_add_f32 v[98:99], v[48:49], 0 op_sel_hi:[1,0]
	v_mov_b32_e32 v112, v66
	v_mov_b32_e32 v113, v67
	v_pk_add_f32 v[74:75], v[4:5], v[90:91]
	v_pk_mul_f32 v[4:5], v[42:43], s[84:85] op_sel_hi:[1,0]
	v_pk_add_f32 v[66:67], v[80:81], v[98:99]
	v_pk_add_f32 v[80:81], v[80:81], v[98:99] neg_lo:[0,1] neg_hi:[0,1]
	v_pk_add_f32 v[16:17], v[86:87], v[88:89]
	v_pk_fma_f32 v[86:87], v[42:43], s[16:17], v[4:5] op_sel:[0,0,1] op_sel_hi:[1,0,0] neg_hi:[0,0,1]
	v_mov_b32_e32 v100, v49
	v_pk_mul_f32 v[102:103], v[48:49], s[84:85] op_sel_hi:[0,1]
	v_pk_mul_f32 v[92:93], v[80:81], s[18:19] op_sel_hi:[1,0]
	v_pk_add_f32 v[4:5], v[44:45], 0 op_sel_hi:[1,0]
	v_pk_mul_f32 v[88:89], v[44:45], s[18:19] op_sel_hi:[1,0]
	v_pk_fma_f32 v[100:101], v[100:101], s[30:31], v[102:103] op_sel_hi:[0,1,1] neg_lo:[0,0,1] neg_hi:[0,0,1]
	v_pk_add_f32 v[102:103], v[52:53], 0 op_sel_hi:[1,0]
	v_pk_fma_f32 v[98:99], v[80:81], s[18:19], v[92:93] op_sel:[0,0,1] op_sel_hi:[1,0,0] neg_hi:[0,0,1]
	v_pk_fma_f32 v[90:91], v[44:45], s[18:19], v[88:89] op_sel:[0,0,1] op_sel_hi:[1,0,0] neg_hi:[0,0,1]
	v_mul_f32_e32 v104, 0x3f3504f3, v52
	v_mov_b32_e32 v106, v53
	v_pk_add_f32 v[80:81], v[4:5], v[102:103]
	v_pk_add_f32 v[4:5], v[4:5], v[102:103] neg_lo:[0,1] neg_hi:[0,1]
	v_pk_add_f32 v[88:89], v[50:51], 0 op_sel_hi:[1,0]
	v_pk_fma_f32 v[104:105], v[106:107], s[28:29], v[104:105] op_sel_hi:[0,1,0] neg_lo:[0,0,1] neg_hi:[0,0,1]
	v_pk_add_f32 v[106:107], v[40:41], 0 op_sel_hi:[1,0]
	v_pk_add_f32 v[92:93], v[4:5], 0 op_sel:[1,0] op_sel_hi:[0,0] neg_hi:[1,0]
	v_mov_b32_e32 v114, v21
	v_pk_add_f32 v[4:5], v[88:89], v[106:107]
	v_pk_add_f32 v[88:89], v[88:89], v[106:107] neg_lo:[0,1] neg_hi:[0,1]
	s_mov_b32 s2, s86
	v_mul_f32_e32 v102, 0x3f3504f3, v88
	v_pk_fma_f32 v[88:89], v[88:89], s[28:29], v[102:103] op_sel:[1,0,0] op_sel_hi:[1,1,0] neg_lo:[0,0,1] neg_hi:[0,0,1]
	v_pk_add_f32 v[102:103], v[82:83], v[96:97]
	v_pk_add_f32 v[82:83], v[82:83], v[96:97] neg_lo:[0,1] neg_hi:[0,1]
	s_mov_b32 s3, s4
	s_mov_b32 s10, s4
	s_mov_b32 s6, s94
	v_pk_add_f32 v[106:107], v[86:87], v[100:101]
	v_pk_add_f32 v[86:87], v[86:87], v[100:101] neg_lo:[0,1] neg_hi:[0,1]
	s_mov_b32 s7, s82
	v_pk_mul_f32 v[96:97], v[86:87], s[18:19] op_sel_hi:[1,0]
	s_mov_b32 s8, s82
	v_pk_fma_f32 v[100:101], v[86:87], s[18:19], v[96:97] op_sel:[0,0,1] op_sel_hi:[1,0,0] neg_hi:[0,0,1]
	s_lshl_b32 s92, s19, 13
	v_lshl_add_u64 v[232:233], s[92:93], 2, v[54:55]
	global_load_dwordx4 v[170:173], v[232:233], off offset:48
	global_load_dwordx4 v[174:177], v[232:233], off offset:32
	global_load_dwordx4 v[178:181], v[232:233], off offset:16
	global_load_dwordx4 v[182:185], v[232:233], off
	v_pk_add_f32 v[86:87], v[90:91], v[104:105]
	v_pk_add_f32 v[90:91], v[90:91], v[104:105] neg_lo:[0,1] neg_hi:[0,1]
	s_mov_b32 s1, s85
	v_pk_add_f32 v[96:97], v[90:91], 0 op_sel:[1,0] op_sel_hi:[0,0] neg_hi:[1,0]
	s_mov_b32 s89, s84
	v_pk_add_f32 v[90:91], v[94:95], v[108:109]
	v_pk_add_f32 v[94:95], v[94:95], v[108:109] neg_lo:[0,1] neg_hi:[0,1]
	v_mul_f32_e32 v104, 0x3f3504f3, v94
	v_pk_fma_f32 v[94:95], v[94:95], s[28:29], v[104:105] op_sel:[1,0,0] op_sel_hi:[1,1,0] neg_lo:[0,0,1] neg_hi:[0,0,1]
	v_pk_add_f32 v[104:105], v[110:111], v[80:81]
	v_pk_add_f32 v[80:81], v[110:111], v[80:81] neg_lo:[0,1] neg_hi:[0,1]
	v_pk_add_f32 v[110:111], v[66:67], v[4:5]
	v_pk_add_f32 v[66:67], v[66:67], v[4:5] neg_lo:[0,1] neg_hi:[0,1]
	v_pk_add_f32 v[4:5], v[66:67], 0 op_sel:[1,0] op_sel_hi:[0,0] neg_hi:[1,0]
	v_pk_add_f32 v[66:67], v[112:113], v[92:93]
	v_pk_add_f32 v[92:93], v[112:113], v[92:93] neg_lo:[0,1] neg_hi:[0,1]
	v_pk_add_f32 v[112:113], v[98:99], v[88:89]
	v_pk_add_f32 v[88:89], v[98:99], v[88:89] neg_lo:[0,1] neg_hi:[0,1]
	v_pk_add_f32 v[98:99], v[88:89], 0 op_sel:[1,0] op_sel_hi:[0,0] neg_hi:[1,0]
	v_pk_add_f32 v[88:89], v[102:103], v[86:87]
	v_pk_add_f32 v[86:87], v[102:103], v[86:87] neg_lo:[0,1] neg_hi:[0,1]
	v_pk_add_f32 v[108:109], v[106:107], v[90:91]
	v_pk_add_f32 v[106:107], v[106:107], v[90:91] neg_lo:[0,1] neg_hi:[0,1]
	v_pk_add_f32 v[90:91], v[106:107], 0 op_sel:[1,0] op_sel_hi:[0,0] neg_hi:[1,0]
	v_pk_add_f32 v[106:107], v[82:83], v[96:97]
	v_pk_add_f32 v[96:97], v[82:83], v[96:97] neg_lo:[0,1] neg_hi:[0,1]
	v_pk_add_f32 v[82:83], v[100:101], v[94:95]
	v_pk_add_f32 v[94:95], v[100:101], v[94:95] neg_lo:[0,1] neg_hi:[0,1]
	v_pk_add_f32 v[100:101], v[94:95], 0 op_sel:[1,0] op_sel_hi:[0,0] neg_hi:[1,0]
	v_pk_add_f32 v[94:95], v[104:105], v[110:111]
	v_pk_add_f32 v[110:111], v[104:105], v[110:111] neg_lo:[0,1] neg_hi:[0,1]
; #define LAS __attribute__((address_space(3)))
; #define SINCOSPI(x, s, c) do { const float hx_ = 0.5f * (x); *(s) = __builtin_amdgcn_sinf(hx_); *(c) = __builtin_amdgcn_cosf(hx_); } while (0)
; DEV void fft_f1x2(LAS cf* buf0, LAS cf* buf1, const cf (&z0)[8], const cf (&z1)[8], int tid) {
;     ...
;     float sn, cs; SINCOSPI(-(float)tid * (2.0f / 8192.0f), &sn, &cs);
;     const cf w = cf{cs, sn}; cf wp = cf{1.f, 0.f};
;     LAS cf* p0 = buf0 + PADI(tid); LAS cf* p1 = buf1 + PADI(tid);
; #pragma unroll
;     for (int p = 0; p < 16; ++p) { p0[544 * p] = cmul(v[BR16[p]], wp); p1[544 * p] = cmul(u[BR16[p]], wp); wp = cmul(wp, w); }
	v_pk_add_f32 v[104:105], v[80:81], v[4:5]
	v_pk_add_f32 v[4:5], v[80:81], v[4:5] neg_lo:[0,1] neg_hi:[0,1]
	v_pk_add_f32 v[80:81], v[66:67], v[112:113]
	v_pk_add_f32 v[66:67], v[66:67], v[112:113] neg_lo:[0,1] neg_hi:[0,1]
	v_mov_b32_e32 v102, v66
	v_mov_b32_e32 v103, v67
	v_pk_add_f32 v[112:113], v[92:93], v[98:99]
	v_pk_add_f32 v[66:67], v[92:93], v[98:99] neg_lo:[0,1] neg_hi:[0,1]
	v_mov_b32_e32 v92, v66
	v_mov_b32_e32 v93, v67
	v_pk_add_f32 v[98:99], v[88:89], v[108:109]
	v_pk_add_f32 v[66:67], v[88:89], v[108:109] neg_lo:[0,1] neg_hi:[0,1]
	v_mov_b32_e32 v88, v66
	v_mov_b32_e32 v89, v67
	v_pk_add_f32 v[108:109], v[86:87], v[90:91]
	v_pk_add_f32 v[66:67], v[86:87], v[90:91] neg_lo:[0,1] neg_hi:[0,1]
	v_mov_b32_e32 v86, v66
	v_mov_b32_e32 v87, v67
	v_pk_add_f32 v[90:91], v[106:107], v[82:83]
	v_pk_add_f32 v[66:67], v[106:107], v[82:83] neg_lo:[0,1] neg_hi:[0,1]
	v_mov_b32_e32 v82, v66
	v_mov_b32_e32 v83, v67
	v_pk_add_f32 v[106:107], v[96:97], v[100:101]
	v_pk_add_f32 v[66:67], v[96:97], v[100:101] neg_lo:[0,1] neg_hi:[0,1]
	v_mov_b32_e32 v96, v66
	v_mov_b32_e32 v97, v67
	s_nop 0
	v_cvt_f32_i32_e32 v66, v114
	v_mul_f32_e32 v66, 0xb9800000, v66
	v_mul_f32_e32 v66, 0.5, v66
	v_sin_f32_e32 v101, v66
	v_cos_f32_e32 v100, v66
	v_ashrrev_i32_e32 v66, 4, v114
	v_add_lshl_u32 v66, v66, v114, 3
	v_add_u32_e32 v116, 0, v66
	v_add_u32_e32 v117, s33, v66
	v_mov_b64_e32 v[66:67], s[90:91]
	v_pk_mul_f32 v[114:115], v[68:69], v[66:67] op_sel:[1,1] op_sel_hi:[1,0] neg_lo:[1,0]
	v_pk_fma_f32 v[68:69], v[68:69], v[66:67], v[114:115] op_sel_hi:[0,1,1]
	ds_write_b64 v116, v[68:69]
	v_pk_mul_f32 v[114:115], v[94:95], v[66:67] op_sel:[1,1] op_sel_hi:[1,0] neg_lo:[1,0]
	v_pk_fma_f32 v[68:69], v[94:95], v[66:67], v[114:115] op_sel_hi:[0,1,1]
	ds_write_b64 v117, v[68:69]
	v_pk_mul_f32 v[68:69], v[66:67], v[100:101] op_sel:[1,1] op_sel_hi:[1,0] neg_lo:[1,0]
	v_pk_fma_f32 v[94:95], v[66:67], v[100:101], v[68:69] op_sel_hi:[0,1,1]
	v_pk_mul_f32 v[114:115], v[76:77], v[94:95] op_sel:[1,1] op_sel_hi:[1,0] neg_lo:[1,0]
	v_pk_fma_f32 v[68:69], v[76:77], v[94:95], v[114:115] op_sel_hi:[0,1,1]
	ds_write_b64 v116, v[68:69] offset:4352
	v_pk_mul_f32 v[76:77], v[98:99], v[94:95] op_sel:[1,1] op_sel_hi:[1,0] neg_lo:[1,0]
	v_pk_fma_f32 v[68:69], v[98:99], v[94:95], v[76:77] op_sel_hi:[0,1,1]
	ds_write_b64 v117, v[68:69] offset:4352
	v_pk_mul_f32 v[68:69], v[94:95], v[100:101] op_sel:[1,1] op_sel_hi:[1,0] neg_lo:[1,0]
	v_pk_fma_f32 v[76:77], v[94:95], v[100:101], v[68:69] op_sel_hi:[0,1,1]
	v_pk_mul_f32 v[94:95], v[70:71], v[76:77] op_sel:[1,1] op_sel_hi:[1,0] neg_lo:[1,0]
	v_pk_fma_f32 v[68:69], v[70:71], v[76:77], v[94:95] op_sel_hi:[0,1,1]
	ds_write_b64 v116, v[68:69] offset:8704
	v_pk_mul_f32 v[70:71], v[80:81], v[76:77] op_sel:[1,1] op_sel_hi:[1,0] neg_lo:[1,0]
	v_pk_fma_f32 v[68:69], v[80:81], v[76:77], v[70:71] op_sel_hi:[0,1,1]
	ds_write_b64 v117, v[68:69] offset:8704
	v_pk_mul_f32 v[68:69], v[76:77], v[100:101] op_sel:[1,1] op_sel_hi:[1,0] neg_lo:[1,0]
	v_pk_fma_f32 v[70:71], v[76:77], v[100:101], v[68:69] op_sel_hi:[0,1,1]
	v_pk_mul_f32 v[76:77], v[16:17], v[70:71] op_sel:[1,1] op_sel_hi:[1,0] neg_lo:[1,0]
	v_pk_fma_f32 v[68:69], v[16:17], v[70:71], v[76:77] op_sel_hi:[0,1,1]
	ds_write_b64 v116, v[68:69] offset:13056
	v_pk_mul_f32 v[76:77], v[90:91], v[70:71] op_sel:[1,1] op_sel_hi:[1,0] neg_lo:[1,0]
	v_pk_fma_f32 v[68:69], v[90:91], v[70:71], v[76:77] op_sel_hi:[0,1,1]
	ds_write_b64 v117, v[68:69] offset:13056
	v_pk_mul_f32 v[68:69], v[70:71], v[100:101] op_sel:[1,1] op_sel_hi:[1,0] neg_lo:[1,0]
	v_pk_fma_f32 v[70:71], v[70:71], v[100:101], v[68:69] op_sel_hi:[0,1,1]
	v_pk_mul_f32 v[68:69], v[78:79], v[70:71] op_sel:[1,1] op_sel_hi:[1,0] neg_lo:[1,0]
	v_pk_fma_f32 v[16:17], v[78:79], v[70:71], v[68:69] op_sel_hi:[0,1,1]
	ds_write_b64 v116, v[16:17] offset:17408
	v_pk_mul_f32 v[68:69], v[104:105], v[70:71] op_sel:[1,1] op_sel_hi:[1,0] neg_lo:[1,0]
	v_pk_fma_f32 v[16:17], v[104:105], v[70:71], v[68:69] op_sel_hi:[0,1,1]
	ds_write_b64 v117, v[16:17] offset:17408
	v_pk_mul_f32 v[16:17], v[70:71], v[100:101] op_sel:[1,1] op_sel_hi:[1,0] neg_lo:[1,0]
	v_pk_fma_f32 v[68:69], v[70:71], v[100:101], v[16:17] op_sel_hi:[0,1,1]
	v_pk_mul_f32 v[70:71], v[72:73], v[68:69] op_sel:[1,1] op_sel_hi:[1,0] neg_lo:[1,0]
	v_pk_fma_f32 v[16:17], v[72:73], v[68:69], v[70:71] op_sel_hi:[0,1,1]
	ds_write_b64 v116, v[16:17] offset:21760
	v_pk_mul_f32 v[70:71], v[108:109], v[68:69] op_sel:[1,1] op_sel_hi:[1,0] neg_lo:[1,0]
	v_pk_fma_f32 v[16:17], v[108:109], v[68:69], v[70:71] op_sel_hi:[0,1,1]
	ds_write_b64 v117, v[16:17] offset:21760
	v_pk_mul_f32 v[16:17], v[68:69], v[100:101] op_sel:[1,1] op_sel_hi:[1,0] neg_lo:[1,0]
	v_pk_fma_f32 v[68:69], v[68:69], v[100:101], v[16:17] op_sel_hi:[0,1,1]
	v_pk_mul_f32 v[70:71], v[18:19], v[68:69] op_sel:[1,1] op_sel_hi:[1,0] neg_lo:[1,0]
	v_pk_fma_f32 v[16:17], v[18:19], v[68:69], v[70:71] op_sel_hi:[0,1,1]
	ds_write_b64 v116, v[16:17] offset:26112
	v_pk_mul_f32 v[18:19], v[112:113], v[68:69] op_sel:[1,1] op_sel_hi:[1,0] neg_lo:[1,0]
	v_pk_fma_f32 v[16:17], v[112:113], v[68:69], v[18:19] op_sel_hi:[0,1,1]
	ds_write_b64 v117, v[16:17] offset:26112
	v_pk_mul_f32 v[16:17], v[68:69], v[100:101] op_sel:[1,1] op_sel_hi:[1,0] neg_lo:[1,0]
	v_pk_fma_f32 v[18:19], v[68:69], v[100:101], v[16:17] op_sel_hi:[0,1,1]
	v_pk_mul_f32 v[68:69], v[74:75], v[18:19] op_sel:[1,1] op_sel_hi:[1,0] neg_lo:[1,0]
	v_pk_fma_f32 v[16:17], v[74:75], v[18:19], v[68:69] op_sel_hi:[0,1,1]
	ds_write_b64 v116, v[16:17] offset:30464
	v_pk_mul_f32 v[68:69], v[106:107], v[18:19] op_sel:[1,1] op_sel_hi:[1,0] neg_lo:[1,0]
	v_pk_fma_f32 v[16:17], v[106:107], v[18:19], v[68:69] op_sel_hi:[0,1,1]
; #define LAS __attribute__((address_space(3)))
; DEV void fft_f1x2(LAS cf* buf0, LAS cf* buf1, const cf (&z0)[8], const cf (&z1)[8], int tid) {
;     ...
;     const cf w = cf{cs, sn}; cf wp = cf{1.f, 0.f};
;     LAS cf* p0 = buf0 + PADI(tid); LAS cf* p1 = buf1 + PADI(tid);
; #pragma unroll
;     for (int p = 0; p < 16; ++p) { p0[544 * p] = cmul(v[BR16[p]], wp); p1[544 * p] = cmul(u[BR16[p]], wp); wp = cmul(wp, w); }
	ds_write_b64 v117, v[16:17] offset:30464
	v_pk_mul_f32 v[16:17], v[18:19], v[100:101] op_sel:[1,1] op_sel_hi:[1,0] neg_lo:[1,0]
	v_pk_fma_f32 v[18:19], v[18:19], v[100:101], v[16:17] op_sel_hi:[0,1,1]
	v_pk_mul_f32 v[16:17], v[84:85], v[18:19] op_sel:[1,1] op_sel_hi:[1,0] neg_lo:[1,0]
	v_pk_fma_f32 v[80:81], v[84:85], v[18:19], v[16:17] op_sel_hi:[0,1,1]
	ds_write_b64 v116, v[80:81] offset:34816
	v_pk_mul_f32 v[16:17], v[110:111], v[18:19] op_sel:[1,1] op_sel_hi:[1,0] neg_lo:[1,0]
	v_pk_fma_f32 v[80:81], v[110:111], v[18:19], v[16:17] op_sel_hi:[0,1,1]
	ds_write_b64 v117, v[80:81] offset:34816
	v_pk_mul_f32 v[80:81], v[18:19], v[100:101] op_sel:[1,1] op_sel_hi:[1,0] neg_lo:[1,0]
	v_pk_fma_f32 v[16:17], v[18:19], v[100:101], v[80:81] op_sel_hi:[0,1,1]
	v_pk_mul_f32 v[18:19], v[12:13], v[16:17] op_sel:[1,1] op_sel_hi:[1,0] neg_lo:[1,0]
	v_pk_fma_f32 v[80:81], v[12:13], v[16:17], v[18:19] op_sel_hi:[0,1,1]
	ds_write_b64 v116, v[80:81] offset:39168
	v_pk_mul_f32 v[12:13], v[88:89], v[16:17] op_sel:[1,1] op_sel_hi:[1,0] neg_lo:[1,0]
	v_pk_fma_f32 v[80:81], v[88:89], v[16:17], v[12:13] op_sel_hi:[0,1,1]
	ds_write_b64 v117, v[80:81] offset:39168
	v_pk_mul_f32 v[80:81], v[16:17], v[100:101] op_sel:[1,1] op_sel_hi:[1,0] neg_lo:[1,0]
	v_pk_fma_f32 v[12:13], v[16:17], v[100:101], v[80:81] op_sel_hi:[0,1,1]
	v_pk_mul_f32 v[16:17], v[6:7], v[12:13] op_sel:[1,1] op_sel_hi:[1,0] neg_lo:[1,0]
	v_pk_fma_f32 v[80:81], v[6:7], v[12:13], v[16:17] op_sel_hi:[0,1,1]
	ds_write_b64 v116, v[80:81] offset:43520
	v_pk_mul_f32 v[6:7], v[102:103], v[12:13] op_sel:[1,1] op_sel_hi:[1,0] neg_lo:[1,0]
	v_pk_fma_f32 v[80:81], v[102:103], v[12:13], v[6:7] op_sel_hi:[0,1,1]
	ds_write_b64 v117, v[80:81] offset:43520
	v_pk_mul_f32 v[80:81], v[12:13], v[100:101] op_sel:[1,1] op_sel_hi:[1,0] neg_lo:[1,0]
	v_pk_fma_f32 v[6:7], v[12:13], v[100:101], v[80:81] op_sel_hi:[0,1,1]
	v_pk_mul_f32 v[12:13], v[14:15], v[6:7] op_sel:[1,1] op_sel_hi:[1,0] neg_lo:[1,0]
	v_pk_fma_f32 v[80:81], v[14:15], v[6:7], v[12:13] op_sel_hi:[0,1,1]
	ds_write_b64 v116, v[80:81] offset:47872
	v_pk_mul_f32 v[12:13], v[82:83], v[6:7] op_sel:[1,1] op_sel_hi:[1,0] neg_lo:[1,0]
	v_pk_fma_f32 v[80:81], v[82:83], v[6:7], v[12:13] op_sel_hi:[0,1,1]
	ds_write_b64 v117, v[80:81] offset:47872
	v_pk_mul_f32 v[80:81], v[6:7], v[100:101] op_sel:[1,1] op_sel_hi:[1,0] neg_lo:[1,0]
	v_pk_fma_f32 v[6:7], v[6:7], v[100:101], v[80:81] op_sel_hi:[0,1,1]
	v_pk_mul_f32 v[80:81], v[0:1], v[6:7] op_sel:[1,1] op_sel_hi:[1,0] neg_lo:[1,0]
	v_pk_fma_f32 v[0:1], v[0:1], v[6:7], v[80:81] op_sel_hi:[0,1,1]
	ds_write_b64 v116, v[0:1] offset:52224
	v_pk_mul_f32 v[80:81], v[4:5], v[6:7] op_sel:[1,1] op_sel_hi:[1,0] neg_lo:[1,0]
	v_pk_fma_f32 v[0:1], v[4:5], v[6:7], v[80:81] op_sel_hi:[0,1,1]
	ds_write_b64 v117, v[0:1] offset:52224
	v_pk_mul_f32 v[0:1], v[6:7], v[100:101] op_sel:[1,1] op_sel_hi:[1,0] neg_lo:[1,0]
	v_pk_fma_f32 v[4:5], v[6:7], v[100:101], v[0:1] op_sel_hi:[0,1,1]
	v_pk_mul_f32 v[6:7], v[8:9], v[4:5] op_sel:[1,1] op_sel_hi:[1,0] neg_lo:[1,0]
	v_pk_fma_f32 v[0:1], v[8:9], v[4:5], v[6:7] op_sel_hi:[0,1,1]
	ds_write_b64 v116, v[0:1] offset:56576
	v_pk_mul_f32 v[6:7], v[86:87], v[4:5] op_sel:[1,1] op_sel_hi:[1,0] neg_lo:[1,0]
	v_pk_fma_f32 v[0:1], v[86:87], v[4:5], v[6:7] op_sel_hi:[0,1,1]
	ds_write_b64 v117, v[0:1] offset:56576
	v_pk_mul_f32 v[0:1], v[4:5], v[100:101] op_sel:[1,1] op_sel_hi:[1,0] neg_lo:[1,0]
	v_pk_fma_f32 v[4:5], v[4:5], v[100:101], v[0:1] op_sel_hi:[0,1,1]
	v_pk_mul_f32 v[6:7], v[2:3], v[4:5] op_sel:[1,1] op_sel_hi:[1,0] neg_lo:[1,0]
	v_pk_fma_f32 v[0:1], v[2:3], v[4:5], v[6:7] op_sel_hi:[0,1,1]
	ds_write_b64 v116, v[0:1] offset:60928
	v_pk_mul_f32 v[2:3], v[92:93], v[4:5] op_sel:[1,1] op_sel_hi:[1,0] neg_lo:[1,0]
	v_pk_fma_f32 v[0:1], v[92:93], v[4:5], v[2:3] op_sel_hi:[0,1,1]
	ds_write_b64 v117, v[0:1] offset:60928
	v_pk_mul_f32 v[0:1], v[4:5], v[100:101] op_sel:[1,1] op_sel_hi:[1,0] neg_lo:[1,0]
	v_pk_fma_f32 v[2:3], v[4:5], v[100:101], v[0:1] op_sel_hi:[0,1,1]
	v_pk_mul_f32 v[4:5], v[10:11], v[2:3] op_sel:[1,1] op_sel_hi:[1,0] neg_lo:[1,0]
	v_pk_fma_f32 v[0:1], v[10:11], v[2:3], v[4:5] op_sel_hi:[0,1,1]
	ds_write_b64 v116, v[0:1] offset:65280
	v_pk_mul_f32 v[4:5], v[96:97], v[2:3] op_sel:[1,1] op_sel_hi:[1,0] neg_lo:[1,0]
	v_pk_fma_f32 v[0:1], v[96:97], v[2:3], v[4:5] op_sel_hi:[0,1,1]
	ds_write_b64 v117, v[0:1] offset:65280
	v_mov_b32_e32 v0, v160
	s_waitcnt lgkmcnt(0)
	s_barrier
; #define LAS __attribute__((address_space(3)))
; #define SINCOSPI(x, s, c) do { const float hx_ = 0.5f * (x); *(s) = __builtin_amdgcn_sinf(hx_); *(c) = __builtin_amdgcn_cosf(hx_); } while (0)
; #define OPAQUE_I(x) asm volatile("" : "+v"(x))
; template <int R, bool INV> DEV void dft_regs(cf (&v)[R]) {
; #pragma unroll
;     for (int s = R; s >= 2; s >>= 1) {
;         const int h = s >> 1;
; #pragma unroll
;         for (int b = 0; b < R; b += s) {
; #pragma unroll
;             for (int k = 0; k < h; ++k) {
;                 const cf a = v[b + k], c = v[b + k + h];
;                 v[b + k] = a + c;
;                 const cf d = a - c;
;                 const int m = k * (32 / s);
;                 const float wr = tw_cos(m), wi = INV ? tw_sin(m) : -tw_sin(m);
;                 v[b + k + h] = cf{d.x * wr - d.y * wi, d.x * wi + d.y * wr};
; DEV void fft_f2(LAS cf* buf, int t8) {
;     OPAQUE_I(t8);
;     LAS cf* pb = buf + (t8 >> 4) * 544 + (t8 & 15);
;     cf v[32];
; #pragma unroll
;     for (int q = 0; q < 32; ++q) v[q] = pb[17 * q];
;     dft_regs<32, false>(v);
;     float sn, cs; SINCOSPI(-(float)(t8 & 15) * (2.0f / 512.0f), &sn, &cs);
	s_nop 0
	v_lshrrev_b32_e32 v1, 4, v0
	v_and_b32_e32 v3, 15, v0
	v_mul_lo_u32 v1, v1, s15
	v_lshlrev_b32_e32 v0, 3, v3
	v_add3_u32 v2, v159, v1, v0
	ds_read2_b64 v[4:7], v2 offset1:17
	ds_read2_b64 v[8:11], v2 offset0:34 offset1:51
	ds_read2_b64 v[12:15], v2 offset0:68 offset1:85
	ds_read2_b64 v[16:19], v2 offset0:102 offset1:119
	ds_read2_b64 v[68:71], v2 offset0:136 offset1:153
	ds_read2_b64 v[72:75], v2 offset0:170 offset1:187
	ds_read2_b64 v[76:79], v2 offset0:204 offset1:221
	ds_read2_b64 v[80:83], v2 offset0:238 offset1:255
	v_add_u32_e32 v0, 0x800, v2
	ds_read2_b64 v[84:87], v0 offset0:16 offset1:33
	ds_read2_b64 v[88:91], v0 offset0:50 offset1:67
	ds_read2_b64 v[92:95], v0 offset0:84 offset1:101
	ds_read2_b64 v[96:99], v0 offset0:118 offset1:135
	ds_read2_b64 v[100:103], v0 offset0:152 offset1:169
	ds_read2_b64 v[104:107], v0 offset0:186 offset1:203
	ds_read2_b64 v[108:111], v0 offset0:220 offset1:237
	s_waitcnt lgkmcnt(6)
	v_pk_add_f32 v[116:117], v[4:5], v[84:85]
	v_pk_add_f32 v[4:5], v[4:5], v[84:85] neg_lo:[0,1] neg_hi:[0,1]
	v_add_u32_e32 v1, 0xc00, v2
	ds_read2_b64 v[112:115], v1 offset0:126 offset1:143
	v_cvt_f32_ubyte0_e32 v3, v3
	v_pk_add_f32 v[118:119], v[6:7], v[86:87]
	v_pk_add_f32 v[6:7], v[6:7], v[86:87] neg_lo:[0,1] neg_hi:[0,1]
	v_mul_f32_e32 v3, 0xbb800000, v3
	v_pk_mul_f32 v[84:85], v[6:7], s[82:83] op_sel_hi:[1,0]
	v_mul_f32_e32 v3, 0.5, v3
	v_pk_fma_f32 v[86:87], v[6:7], s[94:95], v[84:85] op_sel:[0,0,1] op_sel_hi:[1,0,0] neg_hi:[0,0,1]
	s_waitcnt lgkmcnt(6)
	v_pk_add_f32 v[6:7], v[8:9], v[88:89]
	v_pk_add_f32 v[8:9], v[8:9], v[88:89] neg_lo:[0,1] neg_hi:[0,1]
	v_pk_mul_f32 v[84:85], v[8:9], s[84:85] op_sel_hi:[1,0]
	v_pk_fma_f32 v[88:89], v[8:9], s[16:17], v[84:85] op_sel:[0,0,1] op_sel_hi:[1,0,0] neg_hi:[0,0,1]
	v_pk_add_f32 v[8:9], v[10:11], v[90:91]
	v_pk_add_f32 v[10:11], v[10:11], v[90:91] neg_lo:[0,1] neg_hi:[0,1]
	v_pk_mul_f32 v[84:85], v[10:11], s[4:5] op_sel_hi:[1,0]
	v_pk_fma_f32 v[90:91], v[10:11], s[86:87], v[84:85] op_sel:[0,0,1] op_sel_hi:[1,0,0] neg_hi:[0,0,1]
	s_waitcnt lgkmcnt(5)
	v_pk_add_f32 v[10:11], v[12:13], v[92:93]
	v_pk_add_f32 v[12:13], v[12:13], v[92:93] neg_lo:[0,1] neg_hi:[0,1]
	v_pk_mul_f32 v[84:85], v[12:13], s[18:19] op_sel_hi:[1,0]
	v_pk_fma_f32 v[92:93], v[12:13], s[18:19], v[84:85] op_sel:[0,0,1] op_sel_hi:[1,0,0] neg_hi:[0,0,1]
	v_pk_add_f32 v[12:13], v[14:15], v[94:95]
	v_pk_add_f32 v[14:15], v[14:15], v[94:95] neg_lo:[0,1] neg_hi:[0,1]
	v_pk_mul_f32 v[84:85], v[14:15], s[86:87] op_sel_hi:[1,0]
	v_pk_fma_f32 v[94:95], v[14:15], s[4:5], v[84:85] op_sel:[0,0,1] op_sel_hi:[1,0,0] neg_hi:[0,0,1]
	s_mov_b32 s5, s86
	s_waitcnt lgkmcnt(4)
	v_pk_add_f32 v[14:15], v[16:17], v[96:97]
	v_pk_add_f32 v[16:17], v[16:17], v[96:97] neg_lo:[0,1] neg_hi:[0,1]
	v_pk_mul_f32 v[84:85], v[16:17], s[16:17] op_sel_hi:[1,0]
	v_pk_fma_f32 v[96:97], v[16:17], s[84:85], v[84:85] op_sel:[0,0,1] op_sel_hi:[1,0,0] neg_hi:[0,0,1]
	v_pk_add_f32 v[16:17], v[18:19], v[98:99]
	v_pk_add_f32 v[18:19], v[18:19], v[98:99] neg_lo:[0,1] neg_hi:[0,1]
	v_pk_mul_f32 v[84:85], v[18:19], s[94:95] op_sel_hi:[1,0]
	v_pk_fma_f32 v[98:99], v[18:19], s[82:83], v[84:85] op_sel:[0,0,1] op_sel_hi:[1,0,0] neg_hi:[0,0,1]
	s_mov_b32 s83, s94
	s_waitcnt lgkmcnt(3)
	v_pk_add_f32 v[18:19], v[68:69], v[100:101]
	v_pk_add_f32 v[68:69], v[68:69], v[100:101] neg_lo:[0,1] neg_hi:[0,1]
	v_pk_add_f32 v[84:85], v[68:69], 0 op_sel:[1,0] op_sel_hi:[0,0] neg_hi:[1,0]
	v_pk_add_f32 v[68:69], v[70:71], v[102:103]
	v_pk_add_f32 v[70:71], v[70:71], v[102:103] neg_lo:[0,1] neg_hi:[0,1]
	v_pk_mul_f32 v[100:101], v[70:71], s[82:83] op_sel_hi:[0,1]
	v_pk_fma_f32 v[70:71], v[70:71], s[94:95], v[100:101] op_sel:[1,0,0] neg_lo:[0,0,1] neg_hi:[0,0,1]
	s_waitcnt lgkmcnt(2)
	v_pk_add_f32 v[100:101], v[72:73], v[104:105]
	v_pk_add_f32 v[72:73], v[72:73], v[104:105] neg_lo:[0,1] neg_hi:[0,1]
	v_pk_mul_f32 v[102:103], v[72:73], s[84:85] op_sel_hi:[0,1]
	v_pk_fma_f32 v[72:73], v[72:73], s[30:31], v[102:103] op_sel:[1,0,0] neg_lo:[0,0,1] neg_hi:[0,0,1]
	v_pk_add_f32 v[102:103], v[74:75], v[106:107]
	v_pk_add_f32 v[74:75], v[74:75], v[106:107] neg_lo:[0,1] neg_hi:[0,1]
	v_pk_mul_f32 v[104:105], v[74:75], s[4:5] op_sel_hi:[0,1]
	v_pk_fma_f32 v[74:75], v[74:75], s[86:87], v[104:105] op_sel:[1,0,0] neg_lo:[0,0,1] neg_hi:[0,0,1]
	s_waitcnt lgkmcnt(1)
	v_pk_add_f32 v[104:105], v[76:77], v[108:109]
	v_pk_add_f32 v[76:77], v[76:77], v[108:109] neg_lo:[0,1] neg_hi:[0,1]
	v_mul_f32_e32 v106, 0x3f3504f3, v76
	v_pk_fma_f32 v[76:77], v[76:77], s[28:29], v[106:107] op_sel:[1,0,0] op_sel_hi:[1,1,0] neg_lo:[0,0,1] neg_hi:[0,0,1]
	v_pk_add_f32 v[106:107], v[78:79], v[110:111]
	v_pk_add_f32 v[78:79], v[78:79], v[110:111] neg_lo:[0,1] neg_hi:[0,1]
	v_pk_mul_f32 v[108:109], v[78:79], s[2:3] op_sel_hi:[0,1]
	v_pk_fma_f32 v[78:79], v[78:79], s[10:11], v[108:109] op_sel:[1,0,0] neg_lo:[0,0,1] neg_hi:[0,0,1]
	s_waitcnt lgkmcnt(0)
; template <int R, bool INV> DEV void dft_regs(cf (&v)[R]) {
;     ...
;     for (int s = R; s >= 2; s >>= 1) {
;         const int h = s >> 1;
; #pragma unroll
;         for (int b = 0; b < R; b += s) {
; #pragma unroll
;             for (int k = 0; k < h; ++k) {
;                 const cf a = v[b + k], c = v[b + k + h];
;                 v[b + k] = a + c;
;                 const cf d = a - c;
;                 const int m = k * (32 / s);
;                 const float wr = tw_cos(m), wi = INV ? tw_sin(m) : -tw_sin(m);
;                 v[b + k + h] = cf{d.x * wr - d.y * wi, d.x * wi + d.y * wr};
;             }
;         }
;     }
; DEV void fft_f2(LAS cf* buf, int t8) {
;     ...
;     dft_regs<32, false>(v);
	v_pk_add_f32 v[108:109], v[80:81], v[112:113]
	v_pk_add_f32 v[80:81], v[80:81], v[112:113] neg_lo:[0,1] neg_hi:[0,1]
	v_pk_mul_f32 v[110:111], v[80:81], s[24:25] op_sel_hi:[0,1]
	v_pk_fma_f32 v[80:81], v[80:81], s[34:35], v[110:111] op_sel:[1,0,0] neg_lo:[0,0,1] neg_hi:[0,0,1]
	v_pk_add_f32 v[110:111], v[82:83], v[114:115]
	v_pk_add_f32 v[82:83], v[82:83], v[114:115] neg_lo:[0,1] neg_hi:[0,1]
	v_pk_mul_f32 v[112:113], v[82:83], s[6:7] op_sel_hi:[0,1]
	v_pk_fma_f32 v[82:83], v[82:83], s[8:9], v[112:113] op_sel:[1,0,0] neg_lo:[0,0,1] neg_hi:[0,0,1]
	v_pk_add_f32 v[112:113], v[116:117], v[18:19]
	v_pk_add_f32 v[18:19], v[116:117], v[18:19] neg_lo:[0,1] neg_hi:[0,1]
	v_pk_add_f32 v[116:117], v[118:119], v[68:69]
	v_pk_add_f32 v[118:119], v[118:119], v[68:69] neg_lo:[0,1] neg_hi:[0,1]
	v_pk_mul_f32 v[68:69], v[118:119], s[84:85] op_sel_hi:[1,0]
	v_pk_fma_f32 v[114:115], v[118:119], s[16:17], v[68:69] op_sel:[0,0,1] op_sel_hi:[1,0,0] neg_hi:[0,0,1]
	v_pk_add_f32 v[118:119], v[6:7], v[100:101]
	v_pk_add_f32 v[6:7], v[6:7], v[100:101] neg_lo:[0,1] neg_hi:[0,1]
	v_pk_mul_f32 v[68:69], v[6:7], s[18:19] op_sel_hi:[1,0]
	v_pk_fma_f32 v[100:101], v[6:7], s[18:19], v[68:69] op_sel:[0,0,1] op_sel_hi:[1,0,0] neg_hi:[0,0,1]
	v_pk_add_f32 v[6:7], v[8:9], v[102:103]
	v_pk_add_f32 v[8:9], v[8:9], v[102:103] neg_lo:[0,1] neg_hi:[0,1]
	v_pk_mul_f32 v[68:69], v[8:9], s[16:17] op_sel_hi:[1,0]
	v_pk_fma_f32 v[102:103], v[8:9], s[84:85], v[68:69] op_sel:[0,0,1] op_sel_hi:[1,0,0] neg_hi:[0,0,1]
	v_pk_add_f32 v[8:9], v[10:11], v[104:105]
	v_pk_add_f32 v[10:11], v[10:11], v[104:105] neg_lo:[0,1] neg_hi:[0,1]
	v_pk_add_f32 v[68:69], v[10:11], 0 op_sel:[1,0] op_sel_hi:[0,0] neg_hi:[1,0]
	v_pk_add_f32 v[10:11], v[12:13], v[106:107]
	v_pk_add_f32 v[12:13], v[12:13], v[106:107] neg_lo:[0,1] neg_hi:[0,1]
	v_pk_mul_f32 v[104:105], v[12:13], s[84:85] op_sel_hi:[0,1]
	v_pk_fma_f32 v[12:13], v[12:13], s[30:31], v[104:105] op_sel:[1,0,0] neg_lo:[0,0,1] neg_hi:[0,0,1]
	v_pk_add_f32 v[104:105], v[14:15], v[108:109]
	v_pk_add_f32 v[14:15], v[14:15], v[108:109] neg_lo:[0,1] neg_hi:[0,1]
	v_mul_f32_e32 v106, 0x3f3504f3, v14
	v_pk_fma_f32 v[14:15], v[14:15], s[28:29], v[106:107] op_sel:[1,0,0] op_sel_hi:[1,1,0] neg_lo:[0,0,1] neg_hi:[0,0,1]
	v_pk_add_f32 v[106:107], v[16:17], v[110:111]
	v_pk_add_f32 v[16:17], v[16:17], v[110:111] neg_lo:[0,1] neg_hi:[0,1]
	v_pk_mul_f32 v[108:109], v[16:17], s[24:25] op_sel_hi:[0,1]
	v_pk_fma_f32 v[16:17], v[16:17], s[34:35], v[108:109] op_sel:[1,0,0] neg_lo:[0,0,1] neg_hi:[0,0,1]
	v_pk_add_f32 v[108:109], v[4:5], v[84:85]
	v_pk_add_f32 v[84:85], v[4:5], v[84:85] neg_lo:[0,1] neg_hi:[0,1]
	v_pk_add_f32 v[4:5], v[86:87], v[70:71]
	v_pk_add_f32 v[70:71], v[86:87], v[70:71] neg_lo:[0,1] neg_hi:[0,1]
	v_pk_mul_f32 v[86:87], v[70:71], s[84:85] op_sel_hi:[1,0]
	v_pk_fma_f32 v[110:111], v[70:71], s[16:17], v[86:87] op_sel:[0,0,1] op_sel_hi:[1,0,0] neg_hi:[0,0,1]
	v_pk_add_f32 v[70:71], v[88:89], v[72:73]
	v_pk_add_f32 v[72:73], v[88:89], v[72:73] neg_lo:[0,1] neg_hi:[0,1]
	v_pk_mul_f32 v[86:87], v[72:73], s[18:19] op_sel_hi:[1,0]
	v_pk_fma_f32 v[88:89], v[72:73], s[18:19], v[86:87] op_sel:[0,0,1] op_sel_hi:[1,0,0] neg_hi:[0,0,1]
	v_pk_add_f32 v[72:73], v[90:91], v[74:75]
	v_pk_add_f32 v[74:75], v[90:91], v[74:75] neg_lo:[0,1] neg_hi:[0,1]
	v_pk_mul_f32 v[86:87], v[74:75], s[16:17] op_sel_hi:[1,0]
	v_pk_fma_f32 v[90:91], v[74:75], s[84:85], v[86:87] op_sel:[0,0,1] op_sel_hi:[1,0,0] neg_hi:[0,0,1]
	v_pk_add_f32 v[74:75], v[92:93], v[76:77]
	v_pk_add_f32 v[76:77], v[92:93], v[76:77] neg_lo:[0,1] neg_hi:[0,1]
	v_pk_add_f32 v[86:87], v[76:77], 0 op_sel:[1,0] op_sel_hi:[0,0] neg_hi:[1,0]
	v_pk_add_f32 v[76:77], v[94:95], v[78:79]
	v_pk_add_f32 v[78:79], v[94:95], v[78:79] neg_lo:[0,1] neg_hi:[0,1]
	v_pk_mul_f32 v[92:93], v[78:79], s[84:85] op_sel_hi:[0,1]
	v_pk_fma_f32 v[78:79], v[78:79], s[30:31], v[92:93] op_sel:[1,0,0] neg_lo:[0,0,1] neg_hi:[0,0,1]
	v_pk_add_f32 v[92:93], v[96:97], v[80:81]
	v_pk_add_f32 v[80:81], v[96:97], v[80:81] neg_lo:[0,1] neg_hi:[0,1]
	v_mul_f32_e32 v94, 0x3f3504f3, v80
	v_pk_fma_f32 v[80:81], v[80:81], s[28:29], v[94:95] op_sel:[1,0,0] op_sel_hi:[1,1,0] neg_lo:[0,0,1] neg_hi:[0,0,1]
	v_pk_add_f32 v[94:95], v[98:99], v[82:83]
	v_pk_add_f32 v[82:83], v[98:99], v[82:83] neg_lo:[0,1] neg_hi:[0,1]
	v_pk_mul_f32 v[96:97], v[82:83], s[24:25] op_sel_hi:[0,1]
	v_pk_fma_f32 v[82:83], v[82:83], s[34:35], v[96:97] op_sel:[1,0,0] neg_lo:[0,0,1] neg_hi:[0,0,1]
	v_pk_add_f32 v[96:97], v[112:113], v[8:9]
	v_pk_add_f32 v[8:9], v[112:113], v[8:9] neg_lo:[0,1] neg_hi:[0,1]
	v_pk_add_f32 v[112:113], v[116:117], v[10:11]
	v_pk_add_f32 v[10:11], v[116:117], v[10:11] neg_lo:[0,1] neg_hi:[0,1]
	v_pk_mul_f32 v[116:117], v[10:11], s[18:19] op_sel_hi:[1,0]
	v_pk_fma_f32 v[98:99], v[10:11], s[18:19], v[116:117] op_sel:[0,0,1] op_sel_hi:[1,0,0] neg_hi:[0,0,1]
	v_pk_add_f32 v[10:11], v[118:119], v[104:105]
	v_pk_add_f32 v[118:119], v[118:119], v[104:105] neg_lo:[0,1] neg_hi:[0,1]
	v_pk_add_f32 v[116:117], v[118:119], 0 op_sel:[1,0] op_sel_hi:[0,0] neg_hi:[1,0]
	v_pk_add_f32 v[118:119], v[6:7], v[106:107]
	v_pk_add_f32 v[6:7], v[6:7], v[106:107] neg_lo:[0,1] neg_hi:[0,1]
	v_mul_f32_e32 v104, 0x3f3504f3, v6
	v_pk_fma_f32 v[6:7], v[6:7], s[28:29], v[104:105] op_sel:[1,0,0] op_sel_hi:[1,1,0] neg_lo:[0,0,1] neg_hi:[0,0,1]
	v_pk_add_f32 v[104:105], v[18:19], v[68:69]
	v_pk_add_f32 v[68:69], v[18:19], v[68:69] neg_lo:[0,1] neg_hi:[0,1]
	v_pk_add_f32 v[18:19], v[114:115], v[12:13]
	v_pk_add_f32 v[12:13], v[114:115], v[12:13] neg_lo:[0,1] neg_hi:[0,1]
	v_pk_mul_f32 v[106:107], v[12:13], s[18:19] op_sel_hi:[1,0]
	v_pk_fma_f32 v[114:115], v[12:13], s[18:19], v[106:107] op_sel:[0,0,1] op_sel_hi:[1,0,0] neg_hi:[0,0,1]
; template <int R, bool INV> DEV void dft_regs(cf (&v)[R]) {
;     ...
;     for (int s = R; s >= 2; s >>= 1) {
;         const int h = s >> 1;
; #pragma unroll
;         for (int b = 0; b < R; b += s) {
; #pragma unroll
;             for (int k = 0; k < h; ++k) {
;                 const cf a = v[b + k], c = v[b + k + h];
;                 v[b + k] = a + c;
;                 const cf d = a - c;
;                 const int m = k * (32 / s);
;                 const float wr = tw_cos(m), wi = INV ? tw_sin(m) : -tw_sin(m);
;                 v[b + k + h] = cf{d.x * wr - d.y * wi, d.x * wi + d.y * wr};
;             }
;         }
;     }
; DEV void fft_f2(LAS cf* buf, int t8) {
;     ...
;     dft_regs<32, false>(v);
	v_pk_add_f32 v[12:13], v[100:101], v[14:15]
	v_pk_add_f32 v[14:15], v[100:101], v[14:15] neg_lo:[0,1] neg_hi:[0,1]
	v_pk_add_f32 v[100:101], v[14:15], 0 op_sel:[1,0] op_sel_hi:[0,0] neg_hi:[1,0]
	v_pk_add_f32 v[14:15], v[102:103], v[16:17]
	v_pk_add_f32 v[16:17], v[102:103], v[16:17] neg_lo:[0,1] neg_hi:[0,1]
	v_mul_f32_e32 v102, 0x3f3504f3, v16
	v_pk_fma_f32 v[16:17], v[16:17], s[28:29], v[102:103] op_sel:[1,0,0] op_sel_hi:[1,1,0] neg_lo:[0,0,1] neg_hi:[0,0,1]
	v_pk_add_f32 v[102:103], v[108:109], v[74:75]
	v_pk_add_f32 v[74:75], v[108:109], v[74:75] neg_lo:[0,1] neg_hi:[0,1]
	v_pk_add_f32 v[108:109], v[4:5], v[76:77]
	v_pk_add_f32 v[76:77], v[4:5], v[76:77] neg_lo:[0,1] neg_hi:[0,1]
	v_pk_mul_f32 v[4:5], v[76:77], s[18:19] op_sel_hi:[1,0]
	v_pk_fma_f32 v[106:107], v[76:77], s[18:19], v[4:5] op_sel:[0,0,1] op_sel_hi:[1,0,0] neg_hi:[0,0,1]
	v_pk_add_f32 v[76:77], v[70:71], v[92:93]
	v_pk_add_f32 v[70:71], v[70:71], v[92:93] neg_lo:[0,1] neg_hi:[0,1]
	v_pk_add_f32 v[4:5], v[70:71], 0 op_sel:[1,0] op_sel_hi:[0,0] neg_hi:[1,0]
	v_pk_add_f32 v[70:71], v[72:73], v[94:95]
	v_pk_add_f32 v[72:73], v[72:73], v[94:95] neg_lo:[0,1] neg_hi:[0,1]
	v_mul_f32_e32 v92, 0x3f3504f3, v72
	v_pk_fma_f32 v[72:73], v[72:73], s[28:29], v[92:93] op_sel:[1,0,0] op_sel_hi:[1,1,0] neg_lo:[0,0,1] neg_hi:[0,0,1]
	v_pk_add_f32 v[92:93], v[84:85], v[86:87]
	v_pk_add_f32 v[86:87], v[84:85], v[86:87] neg_lo:[0,1] neg_hi:[0,1]
	v_mov_b32_e32 v84, v86
	v_mov_b32_e32 v85, v87
	v_pk_add_f32 v[86:87], v[110:111], v[78:79]
	v_pk_add_f32 v[78:79], v[110:111], v[78:79] neg_lo:[0,1] neg_hi:[0,1]
	v_pk_mul_f32 v[94:95], v[78:79], s[18:19] op_sel_hi:[1,0]
	v_pk_fma_f32 v[110:111], v[78:79], s[18:19], v[94:95] op_sel:[0,0,1] op_sel_hi:[1,0,0] neg_hi:[0,0,1]
	v_pk_add_f32 v[78:79], v[88:89], v[80:81]
	v_pk_add_f32 v[80:81], v[88:89], v[80:81] neg_lo:[0,1] neg_hi:[0,1]
	v_pk_add_f32 v[88:89], v[80:81], 0 op_sel:[1,0] op_sel_hi:[0,0] neg_hi:[1,0]
	v_pk_add_f32 v[80:81], v[90:91], v[82:83]
	v_pk_add_f32 v[82:83], v[90:91], v[82:83] neg_lo:[0,1] neg_hi:[0,1]
	v_mul_f32_e32 v90, 0x3f3504f3, v82
	v_pk_fma_f32 v[82:83], v[82:83], s[28:29], v[90:91] op_sel:[1,0,0] op_sel_hi:[1,1,0] neg_lo:[0,0,1] neg_hi:[0,0,1]
	v_pk_add_f32 v[90:91], v[96:97], v[10:11]
	v_pk_add_f32 v[10:11], v[96:97], v[10:11] neg_lo:[0,1] neg_hi:[0,1]
	v_pk_add_f32 v[96:97], v[112:113], v[118:119]
	v_pk_add_f32 v[118:119], v[112:113], v[118:119] neg_lo:[0,1] neg_hi:[0,1]
	v_pk_add_f32 v[112:113], v[118:119], 0 op_sel:[1,0] op_sel_hi:[0,0] neg_hi:[1,0]
	v_pk_add_f32 v[118:119], v[8:9], v[116:117]
	v_pk_add_f32 v[116:117], v[8:9], v[116:117] neg_lo:[0,1] neg_hi:[0,1]
	v_pk_add_f32 v[8:9], v[98:99], v[6:7]
	v_pk_add_f32 v[6:7], v[98:99], v[6:7] neg_lo:[0,1] neg_hi:[0,1]
	v_pk_add_f32 v[94:95], v[6:7], 0 op_sel:[1,0] op_sel_hi:[0,0] neg_hi:[1,0]
	v_pk_add_f32 v[6:7], v[104:105], v[12:13]
	v_pk_add_f32 v[12:13], v[104:105], v[12:13] neg_lo:[0,1] neg_hi:[0,1]
	v_pk_add_f32 v[98:99], v[68:69], v[100:101] neg_lo:[0,1] neg_hi:[0,1]
	v_pk_add_f32 v[104:105], v[18:19], v[14:15]
	v_pk_add_f32 v[14:15], v[18:19], v[14:15] neg_lo:[0,1] neg_hi:[0,1]
	v_pk_add_f32 v[18:19], v[14:15], 0 op_sel:[1,0] op_sel_hi:[0,0] neg_hi:[1,0]
	v_pk_add_f32 v[14:15], v[68:69], v[100:101]
	v_pk_add_f32 v[68:69], v[114:115], v[16:17]
	v_pk_add_f32 v[16:17], v[114:115], v[16:17] neg_lo:[0,1] neg_hi:[0,1]
	v_pk_add_f32 v[100:101], v[16:17], 0 op_sel:[1,0] op_sel_hi:[0,0] neg_hi:[1,0]
	v_pk_add_f32 v[16:17], v[102:103], v[76:77]
	v_pk_add_f32 v[76:77], v[102:103], v[76:77] neg_lo:[0,1] neg_hi:[0,1]
	v_pk_add_f32 v[114:115], v[108:109], v[70:71]
	v_pk_add_f32 v[70:71], v[108:109], v[70:71] neg_lo:[0,1] neg_hi:[0,1]
	v_pk_add_f32 v[108:109], v[70:71], 0 op_sel:[1,0] op_sel_hi:[0,0] neg_hi:[1,0]
	v_pk_add_f32 v[70:71], v[74:75], v[4:5]
	v_pk_add_f32 v[4:5], v[74:75], v[4:5] neg_lo:[0,1] neg_hi:[0,1]
	v_pk_add_f32 v[74:75], v[106:107], v[72:73]
	v_pk_add_f32 v[72:73], v[106:107], v[72:73] neg_lo:[0,1] neg_hi:[0,1]
	v_pk_add_f32 v[102:103], v[72:73], 0 op_sel:[1,0] op_sel_hi:[0,0] neg_hi:[1,0]
	v_pk_add_f32 v[72:73], v[92:93], v[78:79]
	v_pk_add_f32 v[78:79], v[92:93], v[78:79] neg_lo:[0,1] neg_hi:[0,1]
	v_pk_add_f32 v[106:107], v[86:87], v[80:81]
	v_pk_add_f32 v[80:81], v[86:87], v[80:81] neg_lo:[0,1] neg_hi:[0,1]
	v_pk_add_f32 v[86:87], v[80:81], 0 op_sel:[1,0] op_sel_hi:[0,0] neg_hi:[1,0]
	v_pk_add_f32 v[80:81], v[84:85], v[88:89]
	v_pk_add_f32 v[88:89], v[84:85], v[88:89] neg_lo:[0,1] neg_hi:[0,1]
	v_pk_add_f32 v[84:85], v[110:111], v[82:83]
	v_pk_add_f32 v[82:83], v[110:111], v[82:83] neg_lo:[0,1] neg_hi:[0,1]
	v_pk_add_f32 v[92:93], v[82:83], 0 op_sel:[1,0] op_sel_hi:[0,0] neg_hi:[1,0]
	v_pk_add_f32 v[82:83], v[90:91], v[96:97]
	v_pk_add_f32 v[96:97], v[90:91], v[96:97] neg_lo:[0,1] neg_hi:[0,1]
	v_pk_add_f32 v[110:111], v[10:11], v[112:113]
	v_pk_add_f32 v[112:113], v[10:11], v[112:113] neg_lo:[0,1] neg_hi:[0,1]
	v_pk_add_f32 v[10:11], v[118:119], v[8:9]
	v_pk_add_f32 v[118:119], v[118:119], v[8:9] neg_lo:[0,1] neg_hi:[0,1]
	v_pk_add_f32 v[8:9], v[116:117], v[94:95] neg_lo:[0,1] neg_hi:[0,1]
	v_pk_add_f32 v[90:91], v[116:117], v[94:95]
	v_pk_add_f32 v[116:117], v[6:7], v[104:105]
	v_pk_add_f32 v[6:7], v[6:7], v[104:105] neg_lo:[0,1] neg_hi:[0,1]
	v_pk_add_f32 v[104:105], v[12:13], v[18:19] neg_lo:[0,1] neg_hi:[0,1]
	v_pk_add_f32 v[94:95], v[12:13], v[18:19]
	v_pk_add_f32 v[12:13], v[14:15], v[68:69]
	v_pk_add_f32 v[14:15], v[14:15], v[68:69] neg_lo:[0,1] neg_hi:[0,1]
	v_pk_add_f32 v[18:19], v[98:99], v[100:101] neg_lo:[0,1] neg_hi:[0,1]
	v_pk_add_f32 v[68:69], v[98:99], v[100:101]
	v_pk_add_f32 v[98:99], v[16:17], v[114:115]
; #define SINCOSPI(x, s, c) do { const float hx_ = 0.5f * (x); *(s) = __builtin_amdgcn_sinf(hx_); *(c) = __builtin_amdgcn_cosf(hx_); } while (0)
; DEV void fft_f2(LAS cf* buf, int t8) {
;     ...
;     float sn, cs; SINCOSPI(-(float)(t8 & 15) * (2.0f / 512.0f), &sn, &cs);
;     const cf w = cf{cs, sn}; cf wp = cf{1.f, 0.f};
; #pragma unroll
;     for (int p = 0; p < 32; ++p) { pb[17 * p] = cmul(v[BR32[p]], wp); wp = cmul(wp, w); }
	v_pk_add_f32 v[16:17], v[16:17], v[114:115] neg_lo:[0,1] neg_hi:[0,1]
	v_pk_add_f32 v[100:101], v[76:77], v[108:109]
	v_pk_add_f32 v[108:109], v[76:77], v[108:109] neg_lo:[0,1] neg_hi:[0,1]
	v_pk_add_f32 v[76:77], v[70:71], v[74:75]
	v_pk_add_f32 v[70:71], v[70:71], v[74:75] neg_lo:[0,1] neg_hi:[0,1]
	v_pk_add_f32 v[114:115], v[4:5], v[102:103] neg_lo:[0,1] neg_hi:[0,1]
	v_pk_add_f32 v[74:75], v[4:5], v[102:103]
	v_pk_add_f32 v[4:5], v[72:73], v[106:107]
	v_pk_add_f32 v[72:73], v[72:73], v[106:107] neg_lo:[0,1] neg_hi:[0,1]
	v_pk_add_f32 v[106:107], v[78:79], v[86:87] neg_lo:[0,1] neg_hi:[0,1]
	v_pk_add_f32 v[102:103], v[78:79], v[86:87]
	v_pk_add_f32 v[78:79], v[80:81], v[84:85]
	v_pk_add_f32 v[80:81], v[80:81], v[84:85] neg_lo:[0,1] neg_hi:[0,1]
	v_pk_add_f32 v[86:87], v[88:89], v[92:93] neg_lo:[0,1] neg_hi:[0,1]
	v_pk_add_f32 v[84:85], v[88:89], v[92:93]
	v_mov_b32_e32 v88, v86
	v_mov_b32_e32 v89, v87
	v_pk_mul_f32 v[92:93], v[82:83], v[66:67] op_sel:[1,1] op_sel_hi:[1,0] neg_lo:[1,0]
	v_pk_fma_f32 v[82:83], v[82:83], v[66:67], v[92:93] op_sel_hi:[0,1,1]
	v_sin_f32_e32 v87, v3
	v_cos_f32_e32 v86, v3
	v_pk_mul_f32 v[92:93], v[66:67], v[86:87] op_sel:[1,1] op_sel_hi:[1,0] neg_lo:[1,0]
	v_pk_fma_f32 v[120:121], v[66:67], v[86:87], v[92:93] op_sel_hi:[0,1,1]
	v_pk_mul_f32 v[92:93], v[98:99], v[120:121] op_sel:[1,1] op_sel_hi:[1,0] neg_lo:[1,0]
	v_pk_fma_f32 v[98:99], v[98:99], v[120:121], v[92:93] op_sel_hi:[0,1,1]
	ds_write2_b64 v2, v[82:83], v[98:99] offset1:17
	v_pk_mul_f32 v[98:99], v[120:121], v[86:87] op_sel:[1,1] op_sel_hi:[1,0] neg_lo:[1,0]
	v_pk_fma_f32 v[82:83], v[120:121], v[86:87], v[98:99] op_sel_hi:[0,1,1]
	v_pk_mul_f32 v[98:99], v[116:117], v[82:83] op_sel:[1,1] op_sel_hi:[1,0] neg_lo:[1,0]
	v_pk_fma_f32 v[116:117], v[116:117], v[82:83], v[98:99] op_sel_hi:[0,1,1]
	v_pk_mul_f32 v[98:99], v[82:83], v[86:87] op_sel:[1,1] op_sel_hi:[1,0] neg_lo:[1,0]
	v_pk_fma_f32 v[82:83], v[82:83], v[86:87], v[98:99] op_sel_hi:[0,1,1]
	v_pk_mul_f32 v[92:93], v[4:5], v[82:83] op_sel:[1,1] op_sel_hi:[1,0] neg_lo:[1,0]
	v_pk_fma_f32 v[98:99], v[4:5], v[82:83], v[92:93] op_sel_hi:[0,1,1]
	ds_write2_b64 v2, v[116:117], v[98:99] offset0:34 offset1:51
	v_pk_mul_f32 v[116:117], v[82:83], v[86:87] op_sel:[1,1] op_sel_hi:[1,0] neg_lo:[1,0]
	v_pk_fma_f32 v[98:99], v[82:83], v[86:87], v[116:117] op_sel_hi:[0,1,1]
	v_pk_mul_f32 v[116:117], v[10:11], v[98:99] op_sel:[1,1] op_sel_hi:[1,0] neg_lo:[1,0]
	v_pk_fma_f32 v[10:11], v[10:11], v[98:99], v[116:117] op_sel_hi:[0,1,1]
	v_pk_mul_f32 v[116:117], v[98:99], v[86:87] op_sel:[1,1] op_sel_hi:[1,0] neg_lo:[1,0]
	v_pk_fma_f32 v[98:99], v[98:99], v[86:87], v[116:117] op_sel_hi:[0,1,1]
	v_pk_mul_f32 v[4:5], v[76:77], v[98:99] op_sel:[1,1] op_sel_hi:[1,0] neg_lo:[1,0]
	v_pk_fma_f32 v[116:117], v[76:77], v[98:99], v[4:5] op_sel_hi:[0,1,1]
	ds_write2_b64 v2, v[10:11], v[116:117] offset0:68 offset1:85
	v_pk_mul_f32 v[10:11], v[98:99], v[86:87] op_sel:[1,1] op_sel_hi:[1,0] neg_lo:[1,0]
	v_pk_fma_f32 v[116:117], v[98:99], v[86:87], v[10:11] op_sel_hi:[0,1,1]
	v_pk_mul_f32 v[98:99], v[12:13], v[116:117] op_sel:[1,1] op_sel_hi:[1,0] neg_lo:[1,0]
	v_pk_fma_f32 v[10:11], v[12:13], v[116:117], v[98:99] op_sel_hi:[0,1,1]
	v_pk_mul_f32 v[12:13], v[116:117], v[86:87] op_sel:[1,1] op_sel_hi:[1,0] neg_lo:[1,0]
	v_pk_fma_f32 v[116:117], v[116:117], v[86:87], v[12:13] op_sel_hi:[0,1,1]
	v_pk_mul_f32 v[98:99], v[78:79], v[116:117] op_sel:[1,1] op_sel_hi:[1,0] neg_lo:[1,0]
	v_pk_fma_f32 v[12:13], v[78:79], v[116:117], v[98:99] op_sel_hi:[0,1,1]
	ds_write2_b64 v2, v[10:11], v[12:13] offset0:102 offset1:119
	v_pk_mul_f32 v[10:11], v[116:117], v[86:87] op_sel:[1,1] op_sel_hi:[1,0] neg_lo:[1,0]
	v_pk_fma_f32 v[12:13], v[116:117], v[86:87], v[10:11] op_sel_hi:[0,1,1]
	v_pk_mul_f32 v[116:117], v[110:111], v[12:13] op_sel:[1,1] op_sel_hi:[1,0] neg_lo:[1,0]
	v_pk_fma_f32 v[10:11], v[110:111], v[12:13], v[116:117] op_sel_hi:[0,1,1]
	v_pk_mul_f32 v[110:111], v[12:13], v[86:87] op_sel:[1,1] op_sel_hi:[1,0] neg_lo:[1,0]
	v_pk_fma_f32 v[12:13], v[12:13], v[86:87], v[110:111] op_sel_hi:[0,1,1]
	v_pk_mul_f32 v[116:117], v[100:101], v[12:13] op_sel:[1,1] op_sel_hi:[1,0] neg_lo:[1,0]
	v_pk_fma_f32 v[110:111], v[100:101], v[12:13], v[116:117] op_sel_hi:[0,1,1]
	ds_write2_b64 v2, v[10:11], v[110:111] offset0:136 offset1:153
	v_pk_mul_f32 v[10:11], v[12:13], v[86:87] op_sel:[1,1] op_sel_hi:[1,0] neg_lo:[1,0]
	v_pk_fma_f32 v[110:111], v[12:13], v[86:87], v[10:11] op_sel_hi:[0,1,1]
	v_pk_mul_f32 v[10:11], v[94:95], v[110:111] op_sel:[1,1] op_sel_hi:[1,0] neg_lo:[1,0]
	v_pk_fma_f32 v[94:95], v[94:95], v[110:111], v[10:11] op_sel_hi:[0,1,1]
	v_pk_mul_f32 v[10:11], v[110:111], v[86:87] op_sel:[1,1] op_sel_hi:[1,0] neg_lo:[1,0]
	v_pk_fma_f32 v[110:111], v[110:111], v[86:87], v[10:11] op_sel_hi:[0,1,1]
	v_pk_mul_f32 v[12:13], v[102:103], v[110:111] op_sel:[1,1] op_sel_hi:[1,0] neg_lo:[1,0]
	v_pk_fma_f32 v[10:11], v[102:103], v[110:111], v[12:13] op_sel_hi:[0,1,1]
	ds_write2_b64 v2, v[94:95], v[10:11] offset0:170 offset1:187
	v_pk_mul_f32 v[94:95], v[110:111], v[86:87] op_sel:[1,1] op_sel_hi:[1,0] neg_lo:[1,0]
	v_pk_fma_f32 v[10:11], v[110:111], v[86:87], v[94:95] op_sel_hi:[0,1,1]
	v_pk_mul_f32 v[94:95], v[90:91], v[10:11] op_sel:[1,1] op_sel_hi:[1,0] neg_lo:[1,0]
	v_pk_fma_f32 v[90:91], v[90:91], v[10:11], v[94:95] op_sel_hi:[0,1,1]
	v_pk_mul_f32 v[94:95], v[10:11], v[86:87] op_sel:[1,1] op_sel_hi:[1,0] neg_lo:[1,0]
	v_pk_fma_f32 v[10:11], v[10:11], v[86:87], v[94:95] op_sel_hi:[0,1,1]
	v_pk_mul_f32 v[110:111], v[74:75], v[10:11] op_sel:[1,1] op_sel_hi:[1,0] neg_lo:[1,0]
	v_pk_fma_f32 v[94:95], v[74:75], v[10:11], v[110:111] op_sel_hi:[0,1,1]
; #define SINCOSPI(x, s, c) do { const float hx_ = 0.5f * (x); *(s) = __builtin_amdgcn_sinf(hx_); *(c) = __builtin_amdgcn_cosf(hx_); } while (0)
; DEV void fft_f2(LAS cf* buf, int t8) {
;     ...
;     float sn, cs; SINCOSPI(-(float)(t8 & 15) * (2.0f / 512.0f), &sn, &cs);
;     const cf w = cf{cs, sn}; cf wp = cf{1.f, 0.f};
; #pragma unroll
;     for (int p = 0; p < 32; ++p) { pb[17 * p] = cmul(v[BR32[p]], wp); wp = cmul(wp, w); }
	ds_write2_b64 v2, v[90:91], v[94:95] offset0:204 offset1:221
	v_pk_mul_f32 v[90:91], v[10:11], v[86:87] op_sel:[1,1] op_sel_hi:[1,0] neg_lo:[1,0]
	v_pk_fma_f32 v[94:95], v[10:11], v[86:87], v[90:91] op_sel_hi:[0,1,1]
	v_pk_mul_f32 v[10:11], v[68:69], v[94:95] op_sel:[1,1] op_sel_hi:[1,0] neg_lo:[1,0]
	v_pk_fma_f32 v[90:91], v[68:69], v[94:95], v[10:11] op_sel_hi:[0,1,1]
	v_pk_mul_f32 v[10:11], v[94:95], v[86:87] op_sel:[1,1] op_sel_hi:[1,0] neg_lo:[1,0]
	v_pk_fma_f32 v[94:95], v[94:95], v[86:87], v[10:11] op_sel_hi:[0,1,1]
	v_pk_mul_f32 v[110:111], v[84:85], v[94:95] op_sel:[1,1] op_sel_hi:[1,0] neg_lo:[1,0]
	v_pk_fma_f32 v[10:11], v[84:85], v[94:95], v[110:111] op_sel_hi:[0,1,1]
	ds_write2_b64 v2, v[90:91], v[10:11] offset0:238 offset1:255
	v_pk_mul_f32 v[2:3], v[94:95], v[86:87] op_sel:[1,1] op_sel_hi:[1,0] neg_lo:[1,0]
	v_pk_fma_f32 v[90:91], v[94:95], v[86:87], v[2:3] op_sel_hi:[0,1,1]
	v_pk_mul_f32 v[94:95], v[96:97], v[90:91] op_sel:[1,1] op_sel_hi:[1,0] neg_lo:[1,0]
	v_pk_fma_f32 v[2:3], v[96:97], v[90:91], v[94:95] op_sel_hi:[0,1,1]
	v_pk_mul_f32 v[94:95], v[90:91], v[86:87] op_sel:[1,1] op_sel_hi:[1,0] neg_lo:[1,0]
	v_pk_fma_f32 v[90:91], v[90:91], v[86:87], v[94:95] op_sel_hi:[0,1,1]
	v_pk_mul_f32 v[10:11], v[16:17], v[90:91] op_sel:[1,1] op_sel_hi:[1,0] neg_lo:[1,0]
	v_pk_fma_f32 v[94:95], v[16:17], v[90:91], v[10:11] op_sel_hi:[0,1,1]
	ds_write2_b64 v0, v[2:3], v[94:95] offset0:16 offset1:33
	v_pk_mul_f32 v[2:3], v[90:91], v[86:87] op_sel:[1,1] op_sel_hi:[1,0] neg_lo:[1,0]
	v_pk_fma_f32 v[90:91], v[90:91], v[86:87], v[2:3] op_sel_hi:[0,1,1]
	v_pk_mul_f32 v[94:95], v[6:7], v[90:91] op_sel:[1,1] op_sel_hi:[1,0] neg_lo:[1,0]
	v_pk_fma_f32 v[2:3], v[6:7], v[90:91], v[94:95] op_sel_hi:[0,1,1]
	v_pk_mul_f32 v[6:7], v[90:91], v[86:87] op_sel:[1,1] op_sel_hi:[1,0] neg_lo:[1,0]
	v_pk_fma_f32 v[90:91], v[90:91], v[86:87], v[6:7] op_sel_hi:[0,1,1]
	v_pk_mul_f32 v[10:11], v[72:73], v[90:91] op_sel:[1,1] op_sel_hi:[1,0] neg_lo:[1,0]
	v_pk_fma_f32 v[6:7], v[72:73], v[90:91], v[10:11] op_sel_hi:[0,1,1]
	ds_write2_b64 v0, v[2:3], v[6:7] offset0:50 offset1:67
	v_pk_mul_f32 v[2:3], v[90:91], v[86:87] op_sel:[1,1] op_sel_hi:[1,0] neg_lo:[1,0]
	v_pk_fma_f32 v[90:91], v[90:91], v[86:87], v[2:3] op_sel_hi:[0,1,1]
	v_pk_mul_f32 v[6:7], v[118:119], v[90:91] op_sel:[1,1] op_sel_hi:[1,0] neg_lo:[1,0]
	v_pk_fma_f32 v[2:3], v[118:119], v[90:91], v[6:7] op_sel_hi:[0,1,1]
	v_pk_mul_f32 v[6:7], v[90:91], v[86:87] op_sel:[1,1] op_sel_hi:[1,0] neg_lo:[1,0]
	v_pk_fma_f32 v[118:119], v[90:91], v[86:87], v[6:7] op_sel_hi:[0,1,1]
	v_pk_mul_f32 v[10:11], v[70:71], v[118:119] op_sel:[1,1] op_sel_hi:[1,0] neg_lo:[1,0]
	v_pk_fma_f32 v[6:7], v[70:71], v[118:119], v[10:11] op_sel_hi:[0,1,1]
	ds_write2_b64 v0, v[2:3], v[6:7] offset0:84 offset1:101
	v_pk_mul_f32 v[2:3], v[118:119], v[86:87] op_sel:[1,1] op_sel_hi:[1,0] neg_lo:[1,0]
	v_pk_fma_f32 v[118:119], v[118:119], v[86:87], v[2:3] op_sel_hi:[0,1,1]
	v_pk_mul_f32 v[6:7], v[14:15], v[118:119] op_sel:[1,1] op_sel_hi:[1,0] neg_lo:[1,0]
	v_pk_fma_f32 v[2:3], v[14:15], v[118:119], v[6:7] op_sel_hi:[0,1,1]
	v_pk_mul_f32 v[6:7], v[118:119], v[86:87] op_sel:[1,1] op_sel_hi:[1,0] neg_lo:[1,0]
	v_pk_fma_f32 v[118:119], v[118:119], v[86:87], v[6:7] op_sel_hi:[0,1,1]
	v_pk_mul_f32 v[10:11], v[80:81], v[118:119] op_sel:[1,1] op_sel_hi:[1,0] neg_lo:[1,0]
	v_pk_fma_f32 v[6:7], v[80:81], v[118:119], v[10:11] op_sel_hi:[0,1,1]
	ds_write2_b64 v0, v[2:3], v[6:7] offset0:118 offset1:135
	v_pk_mul_f32 v[2:3], v[118:119], v[86:87] op_sel:[1,1] op_sel_hi:[1,0] neg_lo:[1,0]
	v_pk_fma_f32 v[118:119], v[118:119], v[86:87], v[2:3] op_sel_hi:[0,1,1]
	v_pk_mul_f32 v[6:7], v[112:113], v[118:119] op_sel:[1,1] op_sel_hi:[1,0] neg_lo:[1,0]
	v_pk_fma_f32 v[2:3], v[112:113], v[118:119], v[6:7] op_sel_hi:[0,1,1]
	v_pk_mul_f32 v[6:7], v[118:119], v[86:87] op_sel:[1,1] op_sel_hi:[1,0] neg_lo:[1,0]
	v_pk_fma_f32 v[118:119], v[118:119], v[86:87], v[6:7] op_sel_hi:[0,1,1]
	v_pk_mul_f32 v[112:113], v[108:109], v[118:119] op_sel:[1,1] op_sel_hi:[1,0] neg_lo:[1,0]
	v_pk_fma_f32 v[6:7], v[108:109], v[118:119], v[112:113] op_sel_hi:[0,1,1]
	ds_write2_b64 v0, v[2:3], v[6:7] offset0:152 offset1:169
	v_pk_mul_f32 v[2:3], v[118:119], v[86:87] op_sel:[1,1] op_sel_hi:[1,0] neg_lo:[1,0]
	v_pk_fma_f32 v[118:119], v[118:119], v[86:87], v[2:3] op_sel_hi:[0,1,1]
	v_pk_mul_f32 v[6:7], v[104:105], v[118:119] op_sel:[1,1] op_sel_hi:[1,0] neg_lo:[1,0]
	v_pk_fma_f32 v[2:3], v[104:105], v[118:119], v[6:7] op_sel_hi:[0,1,1]
	v_pk_mul_f32 v[6:7], v[118:119], v[86:87] op_sel:[1,1] op_sel_hi:[1,0] neg_lo:[1,0]
	v_pk_fma_f32 v[118:119], v[118:119], v[86:87], v[6:7] op_sel_hi:[0,1,1]
	v_pk_mul_f32 v[112:113], v[106:107], v[118:119] op_sel:[1,1] op_sel_hi:[1,0] neg_lo:[1,0]
	v_pk_fma_f32 v[6:7], v[106:107], v[118:119], v[112:113] op_sel_hi:[0,1,1]
	ds_write2_b64 v0, v[2:3], v[6:7] offset0:186 offset1:203
	v_pk_mul_f32 v[2:3], v[118:119], v[86:87] op_sel:[1,1] op_sel_hi:[1,0] neg_lo:[1,0]
	v_pk_fma_f32 v[118:119], v[118:119], v[86:87], v[2:3] op_sel_hi:[0,1,1]
	v_pk_mul_f32 v[6:7], v[8:9], v[118:119] op_sel:[1,1] op_sel_hi:[1,0] neg_lo:[1,0]
	v_pk_fma_f32 v[2:3], v[8:9], v[118:119], v[6:7] op_sel_hi:[0,1,1]
	v_pk_mul_f32 v[6:7], v[118:119], v[86:87] op_sel:[1,1] op_sel_hi:[1,0] neg_lo:[1,0]
	v_pk_fma_f32 v[118:119], v[118:119], v[86:87], v[6:7] op_sel_hi:[0,1,1]
	v_pk_mul_f32 v[8:9], v[114:115], v[118:119] op_sel:[1,1] op_sel_hi:[1,0] neg_lo:[1,0]
	v_pk_fma_f32 v[6:7], v[114:115], v[118:119], v[8:9] op_sel_hi:[0,1,1]
	ds_write2_b64 v0, v[2:3], v[6:7] offset0:220 offset1:237
	v_pk_mul_f32 v[2:3], v[118:119], v[86:87] op_sel:[1,1] op_sel_hi:[1,0] neg_lo:[1,0]
	v_pk_fma_f32 v[118:119], v[118:119], v[86:87], v[2:3] op_sel_hi:[0,1,1]
	v_pk_mul_f32 v[6:7], v[18:19], v[118:119] op_sel:[1,1] op_sel_hi:[1,0] neg_lo:[1,0]
	v_pk_fma_f32 v[2:3], v[18:19], v[118:119], v[6:7] op_sel_hi:[0,1,1]
	v_pk_mul_f32 v[6:7], v[118:119], v[86:87] op_sel:[1,1] op_sel_hi:[1,0] neg_lo:[1,0]
	v_pk_fma_f32 v[118:119], v[118:119], v[86:87], v[6:7] op_sel_hi:[0,1,1]
	v_pk_mul_f32 v[6:7], v[88:89], v[118:119] op_sel:[1,1] op_sel_hi:[1,0] neg_lo:[1,0]
	v_pk_fma_f32 v[118:119], v[88:89], v[118:119], v[6:7] op_sel_hi:[0,1,1]
	ds_write2_b64 v1, v[2:3], v[118:119] offset0:126 offset1:143
	s_waitcnt lgkmcnt(0)
	s_barrier
; #define LAS __attribute__((address_space(3)))
; template <int R, bool INV> DEV void dft_regs(cf (&v)[R]) {
;     ...
;     for (int s = R; s >= 2; s >>= 1) {
;         const int h = s >> 1;
; #pragma unroll
;         for (int b = 0; b < R; b += s) {
; #pragma unroll
;             for (int k = 0; k < h; ++k) {
;                 const cf a = v[b + k], c = v[b + k + h];
;                 v[b + k] = a + c;
;                 const cf d = a - c;
;                 const int m = k * (32 / s);
;                 const float wr = tw_cos(m), wi = INV ? tw_sin(m) : -tw_sin(m);
;                 v[b + k + h] = cf{d.x * wr - d.y * wi, d.x * wi + d.y * wr};
;             }
;         }
;     }
; DEV void fft_midx2(LAS cf* buf0, LAS cf* buf1, const unsigned* Kp, int blk) {
;     ...
;     LAS cf* p0 = buf0 + 17 * blk; LAS cf* p1 = buf1 + 17 * blk;
;     cf v[16], u[16];
; #pragma unroll
;     for (int q = 0; q < 16; ++q) { v[q] = p0[q]; u[q] = p1[q]; }
;     dft_regs<16, false>(v); dft_regs<16, false>(u);
	ds_read2_b64 v[68:71], v161 offset1:1
	ds_read2_b64 v[8:11], v162 offset1:1
	ds_read2_b64 v[72:75], v161 offset0:2 offset1:3
	ds_read2_b64 v[12:15], v162 offset0:2 offset1:3
	ds_read2_b64 v[76:79], v161 offset0:4 offset1:5
	ds_read2_b64 v[0:3], v162 offset0:4 offset1:5
	ds_read2_b64 v[80:83], v161 offset0:6 offset1:7
	ds_read2_b64 v[4:7], v162 offset0:6 offset1:7
	ds_read2_b64 v[84:87], v161 offset0:8 offset1:9
	ds_read2_b64 v[100:103], v162 offset0:8 offset1:9
	ds_read2_b64 v[88:91], v161 offset0:10 offset1:11
	ds_read2_b64 v[104:107], v162 offset0:10 offset1:11
	ds_read2_b64 v[92:95], v161 offset0:12 offset1:13
	ds_read2_b64 v[16:19], v162 offset0:12 offset1:13
	ds_read2_b64 v[96:99], v161 offset0:14 offset1:15
	ds_read2_b64 v[108:111], v162 offset0:14 offset1:15
	s_waitcnt lgkmcnt(7)
	v_pk_add_f32 v[112:113], v[68:69], v[84:85]
	v_pk_add_f32 v[68:69], v[68:69], v[84:85] neg_lo:[0,1] neg_hi:[0,1]
	v_pk_add_f32 v[114:115], v[70:71], v[86:87]
	v_pk_add_f32 v[70:71], v[70:71], v[86:87] neg_lo:[0,1] neg_hi:[0,1]
	v_pk_mul_f32 v[84:85], v[70:71], s[84:85] op_sel_hi:[1,0]
	v_pk_fma_f32 v[86:87], v[70:71], s[16:17], v[84:85] op_sel:[0,0,1] op_sel_hi:[1,0,0] neg_hi:[0,0,1]
	s_waitcnt lgkmcnt(5)
	v_pk_add_f32 v[70:71], v[72:73], v[88:89]
	v_pk_add_f32 v[72:73], v[72:73], v[88:89] neg_lo:[0,1] neg_hi:[0,1]
	v_pk_mul_f32 v[84:85], v[72:73], s[18:19] op_sel_hi:[1,0]
	v_pk_fma_f32 v[88:89], v[72:73], s[18:19], v[84:85] op_sel:[0,0,1] op_sel_hi:[1,0,0]
	v_pk_fma_f32 v[72:73], v[72:73], s[18:19], v[84:85] op_sel_hi:[1,0,0] neg_lo:[0,0,1] neg_hi:[0,0,1]
	v_pk_add_f32 v[84:85], v[74:75], v[90:91]
	v_pk_add_f32 v[74:75], v[74:75], v[90:91] neg_lo:[0,1] neg_hi:[0,1]
	v_mov_b32_e32 v89, v73
	v_pk_mul_f32 v[90:91], v[74:75], s[16:17] op_sel_hi:[1,0]
	v_pk_fma_f32 v[116:117], v[74:75], s[84:85], v[90:91] op_sel:[0,0,1] op_sel_hi:[1,0,0] neg_hi:[0,0,1]
	s_waitcnt lgkmcnt(3)
	v_pk_add_f32 v[74:75], v[76:77], v[92:93]
	v_pk_add_f32 v[76:77], v[76:77], v[92:93] neg_lo:[0,1] neg_hi:[0,1]
	v_pk_add_f32 v[90:91], v[76:77], 0 op_sel:[1,0] op_sel_hi:[0,0] neg_hi:[1,0]
	v_pk_add_f32 v[76:77], v[78:79], v[94:95]
	v_pk_add_f32 v[78:79], v[78:79], v[94:95] neg_lo:[0,1] neg_hi:[0,1]
	s_waitcnt lgkmcnt(1)
	v_pk_add_f32 v[94:95], v[82:83], v[98:99]
	v_pk_mul_f32 v[92:93], v[78:79], s[84:85] op_sel_hi:[0,1]
	v_pk_add_f32 v[82:83], v[82:83], v[98:99] neg_lo:[0,1] neg_hi:[0,1]
	v_pk_fma_f32 v[78:79], v[78:79], s[30:31], v[92:93] op_sel:[1,0,0] neg_lo:[0,0,1] neg_hi:[0,0,1]
	v_pk_add_f32 v[92:93], v[80:81], v[96:97]
	v_pk_add_f32 v[80:81], v[80:81], v[96:97] neg_lo:[0,1] neg_hi:[0,1]
	v_pk_mul_f32 v[96:97], v[82:83], s[24:25] op_sel_hi:[0,1]
	v_pk_fma_f32 v[82:83], v[82:83], s[34:35], v[96:97] op_sel:[1,0,0] neg_lo:[0,0,1] neg_hi:[0,0,1]
	v_pk_add_f32 v[96:97], v[112:113], v[74:75]
	v_pk_add_f32 v[74:75], v[112:113], v[74:75] neg_lo:[0,1] neg_hi:[0,1]
	v_mul_f32_e32 v72, 0x3f3504f3, v80
	v_pk_fma_f32 v[80:81], v[80:81], s[28:29], v[72:73] op_sel:[1,0,0] op_sel_hi:[1,1,0] neg_lo:[0,0,1] neg_hi:[0,0,1]
	v_pk_add_f32 v[72:73], v[88:89], v[80:81]
	v_pk_add_f32 v[112:113], v[114:115], v[76:77]
	v_pk_add_f32 v[114:115], v[114:115], v[76:77] neg_lo:[0,1] neg_hi:[0,1]
	v_pk_mul_f32 v[76:77], v[114:115], s[18:19] op_sel_hi:[1,0]
	v_pk_fma_f32 v[98:99], v[114:115], s[18:19], v[76:77] op_sel:[0,0,1] op_sel_hi:[1,0,0]
	v_pk_fma_f32 v[114:115], v[114:115], s[18:19], v[76:77] op_sel_hi:[1,0,0] neg_lo:[0,0,1] neg_hi:[0,0,1]
	v_pk_add_f32 v[76:77], v[70:71], v[92:93]
	v_pk_add_f32 v[70:71], v[70:71], v[92:93] neg_lo:[0,1] neg_hi:[0,1]
	v_mov_b32_e32 v99, v115
	v_pk_add_f32 v[92:93], v[70:71], 0 op_sel:[1,0] op_sel_hi:[0,0] neg_hi:[1,0]
	v_pk_add_f32 v[70:71], v[84:85], v[94:95]
	v_pk_add_f32 v[84:85], v[84:85], v[94:95] neg_lo:[0,1] neg_hi:[0,1]
	v_pk_add_f32 v[94:95], v[68:69], v[90:91]
	v_pk_add_f32 v[90:91], v[68:69], v[90:91] neg_lo:[0,1] neg_hi:[0,1]
	v_mul_f32_e32 v114, 0x3f3504f3, v84
	v_pk_fma_f32 v[84:85], v[84:85], s[28:29], v[114:115] op_sel:[1,0,0] op_sel_hi:[1,1,0] neg_lo:[0,0,1] neg_hi:[0,0,1]
	v_pk_add_f32 v[118:119], v[86:87], v[78:79]
	v_pk_add_f32 v[78:79], v[86:87], v[78:79] neg_lo:[0,1] neg_hi:[0,1]
	v_pk_mul_f32 v[86:87], v[78:79], s[18:19] op_sel_hi:[1,0]
	v_pk_fma_f32 v[68:69], v[78:79], s[18:19], v[86:87] op_sel:[0,0,1] op_sel_hi:[1,0,0] neg_hi:[0,0,1]
	v_pk_add_f32 v[78:79], v[88:89], v[80:81] neg_lo:[0,1] neg_hi:[0,1]
	v_pk_add_f32 v[88:89], v[96:97], v[76:77]
	v_pk_add_f32 v[76:77], v[96:97], v[76:77] neg_lo:[0,1] neg_hi:[0,1]
	v_pk_add_f32 v[80:81], v[78:79], 0 op_sel:[1,0] op_sel_hi:[0,0] neg_hi:[1,0]
	v_pk_add_f32 v[96:97], v[112:113], v[70:71]
	v_pk_add_f32 v[70:71], v[112:113], v[70:71] neg_lo:[0,1] neg_hi:[0,1]
	v_pk_add_f32 v[78:79], v[116:117], v[82:83]
	v_pk_add_f32 v[112:113], v[70:71], 0 op_sel:[1,0] op_sel_hi:[0,0] neg_hi:[1,0]
	v_pk_add_f32 v[82:83], v[116:117], v[82:83] neg_lo:[0,1] neg_hi:[0,1]
	v_pk_add_f32 v[70:71], v[74:75], v[92:93] neg_lo:[0,1] neg_hi:[0,1]
	v_pk_add_f32 v[116:117], v[74:75], v[92:93]
	v_mul_f32_e32 v114, 0x3f3504f3, v82
	v_pk_fma_f32 v[82:83], v[82:83], s[28:29], v[114:115] op_sel:[1,0,0] op_sel_hi:[1,1,0] neg_lo:[0,0,1] neg_hi:[0,0,1]
	v_pk_add_f32 v[92:93], v[98:99], v[84:85] neg_lo:[0,1] neg_hi:[0,1]
	v_pk_add_f32 v[114:115], v[98:99], v[84:85]
	v_pk_add_f32 v[98:99], v[92:93], 0 op_sel:[1,0] op_sel_hi:[0,0] neg_hi:[1,0]
	v_pk_add_f32 v[74:75], v[94:95], v[72:73]
	v_pk_add_f32 v[92:93], v[94:95], v[72:73] neg_lo:[0,1] neg_hi:[0,1]
	v_pk_add_f32 v[122:123], v[90:91], v[80:81]
	v_pk_add_f32 v[124:125], v[68:69], v[82:83]
	v_pk_add_f32 v[72:73], v[118:119], v[78:79]
	v_pk_add_f32 v[120:121], v[118:119], v[78:79] neg_lo:[0,1] neg_hi:[0,1]
; template <int R, bool INV> DEV void dft_regs(cf (&v)[R]) {
;     ...
;     for (int s = R; s >= 2; s >>= 1) {
;         const int h = s >> 1;
; #pragma unroll
;         for (int b = 0; b < R; b += s) {
; #pragma unroll
;             for (int k = 0; k < h; ++k) {
;                 const cf a = v[b + k], c = v[b + k + h];
;                 v[b + k] = a + c;
;                 const cf d = a - c;
;                 const int m = k * (32 / s);
;                 const float wr = tw_cos(m), wi = INV ? tw_sin(m) : -tw_sin(m);
;                 v[b + k + h] = cf{d.x * wr - d.y * wi, d.x * wi + d.y * wr};
;             }
;         }
;     }
; DEV void fft_midx2(LAS cf* buf0, LAS cf* buf1, const unsigned* Kp, int blk) {
;     ...
;     dft_regs<16, false>(v); dft_regs<16, false>(u);
	v_pk_add_f32 v[86:87], v[88:89], v[96:97]
	v_pk_add_f32 v[78:79], v[120:121], 0 op_sel:[1,0] op_sel_hi:[0,0] neg_hi:[1,0]
	v_pk_add_f32 v[94:95], v[74:75], v[72:73]
	v_pk_add_f32 v[120:121], v[90:91], v[80:81] neg_lo:[0,1] neg_hi:[0,1]
	v_pk_add_f32 v[72:73], v[74:75], v[72:73] neg_lo:[0,1] neg_hi:[0,1]
	v_pk_add_f32 v[84:85], v[70:71], v[98:99]
	v_pk_add_f32 v[74:75], v[8:9], v[100:101]
	v_pk_add_f32 v[90:91], v[68:69], v[82:83] neg_lo:[0,1] neg_hi:[0,1]
	v_pk_add_f32 v[82:83], v[76:77], v[112:113]
	v_pk_add_f32 v[68:69], v[90:91], 0 op_sel:[1,0] op_sel_hi:[0,0] neg_hi:[1,0]
	v_pk_add_f32 v[112:113], v[76:77], v[112:113] neg_lo:[0,1] neg_hi:[0,1]
	v_pk_add_f32 v[90:91], v[88:89], v[96:97] neg_lo:[0,1] neg_hi:[0,1]
	v_pk_add_f32 v[88:89], v[116:117], v[114:115]
	v_pk_add_f32 v[114:115], v[116:117], v[114:115] neg_lo:[0,1] neg_hi:[0,1]
	v_mov_b32_e32 v96, v90
	v_mov_b32_e32 v97, v91
	v_mov_b32_e32 v90, v112
	v_mov_b32_e32 v91, v113
	v_mov_b32_e32 v112, v114
	v_mov_b32_e32 v113, v115
	v_pk_add_f32 v[80:81], v[70:71], v[98:99] neg_lo:[0,1] neg_hi:[0,1]
	v_pk_add_f32 v[8:9], v[8:9], v[100:101] neg_lo:[0,1] neg_hi:[0,1]
	v_mov_b32_e32 v114, v80
	v_mov_b32_e32 v115, v81
	v_mov_b32_e32 v80, v72
	v_mov_b32_e32 v81, v73
	v_pk_add_f32 v[118:119], v[92:93], v[78:79]
	v_pk_add_f32 v[78:79], v[92:93], v[78:79] neg_lo:[0,1] neg_hi:[0,1]
	v_mov_b32_e32 v72, v78
	v_mov_b32_e32 v73, v79
	v_pk_add_f32 v[70:71], v[122:123], v[124:125] neg_lo:[0,1] neg_hi:[0,1]
	v_pk_add_f32 v[76:77], v[122:123], v[124:125]
	v_pk_add_f32 v[98:99], v[120:121], v[68:69] neg_lo:[0,1] neg_hi:[0,1]
	v_pk_add_f32 v[78:79], v[120:121], v[68:69]
	v_pk_add_f32 v[68:69], v[10:11], v[102:103]
	v_pk_add_f32 v[10:11], v[10:11], v[102:103] neg_lo:[0,1] neg_hi:[0,1]
	v_pk_mul_f32 v[100:101], v[10:11], s[84:85] op_sel_hi:[1,0]
	v_pk_fma_f32 v[102:103], v[10:11], s[16:17], v[100:101] op_sel:[0,0,1] op_sel_hi:[1,0,0] neg_hi:[0,0,1]
	v_pk_add_f32 v[10:11], v[12:13], v[104:105]
	v_pk_add_f32 v[12:13], v[12:13], v[104:105] neg_lo:[0,1] neg_hi:[0,1]
	v_pk_mul_f32 v[100:101], v[12:13], s[18:19] op_sel_hi:[1,0]
	v_pk_fma_f32 v[104:105], v[12:13], s[18:19], v[100:101] op_sel:[0,0,1] op_sel_hi:[1,0,0] neg_hi:[0,0,1]
	v_pk_add_f32 v[12:13], v[14:15], v[106:107]
	v_pk_add_f32 v[14:15], v[14:15], v[106:107] neg_lo:[0,1] neg_hi:[0,1]
	v_pk_mul_f32 v[100:101], v[14:15], s[16:17] op_sel_hi:[1,0]
	v_pk_fma_f32 v[106:107], v[14:15], s[84:85], v[100:101] op_sel:[0,0,1] op_sel_hi:[1,0,0] neg_hi:[0,0,1]
	v_pk_add_f32 v[14:15], v[0:1], v[16:17]
	v_pk_add_f32 v[0:1], v[0:1], v[16:17] neg_lo:[0,1] neg_hi:[0,1]
	v_pk_add_f32 v[16:17], v[0:1], 0 op_sel:[1,0] op_sel_hi:[0,0] neg_hi:[1,0]
	v_pk_add_f32 v[0:1], v[2:3], v[18:19]
	v_pk_add_f32 v[2:3], v[2:3], v[18:19] neg_lo:[0,1] neg_hi:[0,1]
	v_pk_mul_f32 v[18:19], v[2:3], s[84:85] op_sel_hi:[0,1]
	v_pk_fma_f32 v[2:3], v[2:3], s[30:31], v[18:19] op_sel:[1,0,0] neg_lo:[0,0,1] neg_hi:[0,0,1]
	s_waitcnt lgkmcnt(0)
	v_pk_add_f32 v[18:19], v[4:5], v[108:109]
	v_pk_add_f32 v[4:5], v[4:5], v[108:109] neg_lo:[0,1] neg_hi:[0,1]
	v_mul_f32_e32 v100, 0x3f3504f3, v4
	v_pk_fma_f32 v[4:5], v[4:5], s[28:29], v[100:101] op_sel:[1,0,0] op_sel_hi:[1,1,0] neg_lo:[0,0,1] neg_hi:[0,0,1]
	v_pk_add_f32 v[100:101], v[6:7], v[110:111]
	v_pk_add_f32 v[6:7], v[6:7], v[110:111] neg_lo:[0,1] neg_hi:[0,1]
	v_pk_mul_f32 v[108:109], v[6:7], s[24:25] op_sel_hi:[0,1]
	v_pk_fma_f32 v[6:7], v[6:7], s[34:35], v[108:109] op_sel:[1,0,0] neg_lo:[0,0,1] neg_hi:[0,0,1]
	v_pk_add_f32 v[108:109], v[74:75], v[14:15]
	v_pk_add_f32 v[14:15], v[74:75], v[14:15] neg_lo:[0,1] neg_hi:[0,1]
	v_pk_add_f32 v[74:75], v[68:69], v[0:1]
	v_pk_add_f32 v[0:1], v[68:69], v[0:1] neg_lo:[0,1] neg_hi:[0,1]
	v_pk_mul_f32 v[68:69], v[0:1], s[18:19] op_sel_hi:[1,0]
	v_pk_fma_f32 v[110:111], v[0:1], s[18:19], v[68:69] op_sel:[0,0,1] op_sel_hi:[1,0,0] neg_hi:[0,0,1]
	v_pk_add_f32 v[68:69], v[10:11], v[18:19] neg_lo:[0,1] neg_hi:[0,1]
	v_pk_add_f32 v[0:1], v[10:11], v[18:19]
	v_pk_add_f32 v[10:11], v[68:69], 0 op_sel:[1,0] op_sel_hi:[0,0] neg_hi:[1,0]
	v_pk_add_f32 v[68:69], v[12:13], v[100:101]
	v_pk_add_f32 v[12:13], v[12:13], v[100:101] neg_lo:[0,1] neg_hi:[0,1]
	v_mul_f32_e32 v18, 0x3f3504f3, v12
	v_pk_fma_f32 v[12:13], v[12:13], s[28:29], v[18:19] op_sel:[1,0,0] op_sel_hi:[1,1,0] neg_lo:[0,0,1] neg_hi:[0,0,1]
	v_pk_add_f32 v[18:19], v[8:9], v[16:17]
	v_pk_add_f32 v[16:17], v[8:9], v[16:17] neg_lo:[0,1] neg_hi:[0,1]
	v_pk_add_f32 v[8:9], v[102:103], v[2:3]
	v_pk_add_f32 v[2:3], v[102:103], v[2:3] neg_lo:[0,1] neg_hi:[0,1]
	v_pk_mul_f32 v[100:101], v[2:3], s[18:19] op_sel_hi:[1,0]
	v_pk_fma_f32 v[102:103], v[2:3], s[18:19], v[100:101] op_sel:[0,0,1] op_sel_hi:[1,0,0] neg_hi:[0,0,1]
	v_pk_add_f32 v[2:3], v[104:105], v[4:5]
	v_pk_add_f32 v[4:5], v[104:105], v[4:5] neg_lo:[0,1] neg_hi:[0,1]
	v_pk_add_f32 v[100:101], v[4:5], 0 op_sel:[1,0] op_sel_hi:[0,0] neg_hi:[1,0]
	v_pk_add_f32 v[4:5], v[106:107], v[6:7]
	v_pk_add_f32 v[6:7], v[106:107], v[6:7] neg_lo:[0,1] neg_hi:[0,1]
	v_mul_f32_e32 v104, 0x3f3504f3, v6
	v_pk_fma_f32 v[6:7], v[6:7], s[28:29], v[104:105] op_sel:[1,0,0] op_sel_hi:[1,1,0] neg_lo:[0,0,1] neg_hi:[0,0,1]
	v_pk_add_f32 v[104:105], v[108:109], v[0:1]
	v_pk_add_f32 v[0:1], v[108:109], v[0:1] neg_lo:[0,1] neg_hi:[0,1]
	v_pk_add_f32 v[166:167], v[102:103], v[6:7]
	v_pk_add_f32 v[6:7], v[102:103], v[6:7] neg_lo:[0,1] neg_hi:[0,1]
	v_pk_add_f32 v[168:169], v[6:7], 0 op_sel:[1,0] op_sel_hi:[0,0] neg_hi:[1,0]
	v_pk_add_f32 v[108:109], v[74:75], v[68:69]
	v_pk_add_f32 v[68:69], v[74:75], v[68:69] neg_lo:[0,1] neg_hi:[0,1]
	v_pk_add_f32 v[74:75], v[68:69], 0 op_sel:[1,0] op_sel_hi:[0,0] neg_hi:[1,0]
	v_pk_add_f32 v[122:123], v[104:105], v[108:109]
; #define U2F(x) __uint_as_float(x)
; DEV cf kunpack(unsigned w) { return cf{U2F(w << 16), U2F(w & 0xffff0000u)}; }
; DEV void fft_midx2(LAS cf* buf0, LAS cf* buf1, const unsigned* Kp, int blk) {
;     ...
;     u32x4 kw[4];
; #pragma unroll
;     for (int j = 0; j < 4; ++j) kw[j] = *(const u32x4*)(Kp + base + 4 * j);
; #pragma unroll
;     for (int p = 0; p < 16; ++p) { const cf k = kunpack(kw[p >> 2][p & 3]); w[p] = cmul(v[BR16[p]], k); x[p] = cmul(u[BR16[p]], k); }
	v_pk_add_f32 v[68:69], v[14:15], v[10:11]
	v_pk_add_f32 v[10:11], v[14:15], v[10:11] neg_lo:[0,1] neg_hi:[0,1]
	v_pk_add_f32 v[108:109], v[104:105], v[108:109] neg_lo:[0,1] neg_hi:[0,1]
	v_pk_add_f32 v[116:117], v[110:111], v[12:13]
	v_pk_add_f32 v[12:13], v[110:111], v[12:13] neg_lo:[0,1] neg_hi:[0,1]
	v_pk_add_f32 v[110:111], v[12:13], 0 op_sel:[1,0] op_sel_hi:[0,0] neg_hi:[1,0]
	v_pk_add_f32 v[12:13], v[18:19], v[2:3]
	v_pk_add_f32 v[2:3], v[18:19], v[2:3] neg_lo:[0,1] neg_hi:[0,1]
	v_pk_add_f32 v[106:107], v[0:1], v[74:75] neg_lo:[0,1] neg_hi:[0,1]
	v_pk_add_f32 v[124:125], v[8:9], v[4:5]
	v_pk_add_f32 v[4:5], v[8:9], v[4:5] neg_lo:[0,1] neg_hi:[0,1]
	v_pk_add_f32 v[8:9], v[16:17], v[100:101] neg_lo:[0,1] neg_hi:[0,1]
	v_pk_add_f32 v[164:165], v[4:5], 0 op_sel:[1,0] op_sel_hi:[0,0] neg_hi:[1,0]
	v_pk_add_f32 v[4:5], v[16:17], v[100:101]
	v_pk_add_f32 v[18:19], v[68:69], v[116:117] neg_lo:[0,1] neg_hi:[0,1]
	v_pk_add_f32 v[126:127], v[12:13], v[124:125]
	v_pk_add_f32 v[14:15], v[10:11], v[110:111]
	v_mov_b32_e32 v104, v18
	v_mov_b32_e32 v105, v19
	v_pk_add_f32 v[100:101], v[0:1], v[74:75]
	v_pk_add_f32 v[0:1], v[10:11], v[110:111] neg_lo:[0,1] neg_hi:[0,1]
	v_pk_add_f32 v[10:11], v[8:9], v[168:169]
	v_pk_add_f32 v[92:93], v[68:69], v[116:117]
	v_pk_add_f32 v[120:121], v[2:3], v[164:165]
	v_pk_add_f32 v[16:17], v[12:13], v[124:125] neg_lo:[0,1] neg_hi:[0,1]
	s_mov_b32 s28, s95
	s_mov_b32 s29, s94
	v_pk_add_f32 v[110:111], v[2:3], v[164:165] neg_lo:[0,1] neg_hi:[0,1]
	v_pk_add_f32 v[124:125], v[4:5], v[166:167]
	v_pk_add_f32 v[102:103], v[4:5], v[166:167] neg_lo:[0,1] neg_hi:[0,1]
	v_mov_b32_e32 v166, v98
	v_mov_b32_e32 v167, v99
	v_pk_add_f32 v[18:19], v[8:9], v[168:169] neg_lo:[0,1] neg_hi:[0,1]
	s_nop 0
	s_waitcnt vmcnt(0)
	v_lshlrev_b32_e32 v98, 16, v182
	v_and_b32_e32 v99, 0xffff0000, v182
	v_lshlrev_b32_e32 v12, 16, v183
	v_and_b32_e32 v13, 0xffff0000, v183
	v_pk_mul_f32 v[168:169], v[86:87], v[98:99] op_sel:[1,1] op_sel_hi:[1,0] neg_lo:[1,0]
	v_pk_fma_f32 v[164:165], v[86:87], v[98:99], v[168:169] op_sel_hi:[0,1,1]
	v_pk_mul_f32 v[168:169], v[122:123], v[98:99] op_sel:[1,1] op_sel_hi:[1,0] neg_lo:[1,0]
	v_pk_fma_f32 v[86:87], v[122:123], v[98:99], v[168:169] op_sel_hi:[0,1,1]
	v_pk_mul_f32 v[98:99], v[94:95], v[12:13] op_sel:[1,1] op_sel_hi:[1,0] neg_lo:[1,0]
	v_pk_fma_f32 v[94:95], v[94:95], v[12:13], v[98:99] op_sel_hi:[0,1,1]
	v_pk_mul_f32 v[98:99], v[126:127], v[12:13] op_sel:[1,1] op_sel_hi:[1,0] neg_lo:[1,0]
	v_pk_fma_f32 v[12:13], v[126:127], v[12:13], v[98:99] op_sel_hi:[0,1,1]
	v_lshlrev_b32_e32 v98, 16, v184
	v_and_b32_e32 v99, 0xffff0000, v184
	v_lshlrev_b32_e32 v74, 16, v185
	v_and_b32_e32 v75, 0xffff0000, v185
	v_pk_mul_f32 v[126:127], v[88:89], v[98:99] op_sel:[1,1] op_sel_hi:[1,0] neg_lo:[1,0]
	v_pk_fma_f32 v[122:123], v[88:89], v[98:99], v[126:127] op_sel_hi:[0,1,1]
	v_pk_mul_f32 v[126:127], v[92:93], v[98:99] op_sel:[1,1] op_sel_hi:[1,0] neg_lo:[1,0]
	v_pk_fma_f32 v[88:89], v[92:93], v[98:99], v[126:127] op_sel_hi:[0,1,1]
	v_pk_mul_f32 v[98:99], v[76:77], v[74:75] op_sel:[1,1] op_sel_hi:[1,0] neg_lo:[1,0]
	v_pk_fma_f32 v[76:77], v[76:77], v[74:75], v[98:99] op_sel_hi:[0,1,1]
	v_pk_mul_f32 v[98:99], v[124:125], v[74:75] op_sel:[1,1] op_sel_hi:[1,0] neg_lo:[1,0]
	v_pk_fma_f32 v[74:75], v[124:125], v[74:75], v[98:99] op_sel_hi:[0,1,1]
	v_lshlrev_b32_e32 v98, 16, v178
	v_and_b32_e32 v99, 0xffff0000, v178
	v_lshlrev_b32_e32 v68, 16, v179
	v_and_b32_e32 v69, 0xffff0000, v179
	v_pk_mul_f32 v[124:125], v[82:83], v[98:99] op_sel:[1,1] op_sel_hi:[1,0] neg_lo:[1,0]
	v_pk_fma_f32 v[92:93], v[82:83], v[98:99], v[124:125] op_sel_hi:[0,1,1]
	v_pk_mul_f32 v[124:125], v[100:101], v[98:99] op_sel:[1,1] op_sel_hi:[1,0] neg_lo:[1,0]
	v_pk_fma_f32 v[82:83], v[100:101], v[98:99], v[124:125] op_sel_hi:[0,1,1]
	v_pk_mul_f32 v[98:99], v[118:119], v[68:69] op_sel:[1,1] op_sel_hi:[1,0] neg_lo:[1,0]
	v_pk_fma_f32 v[118:119], v[118:119], v[68:69], v[98:99] op_sel_hi:[0,1,1]
	v_pk_mul_f32 v[98:99], v[120:121], v[68:69] op_sel:[1,1] op_sel_hi:[1,0] neg_lo:[1,0]
	v_pk_fma_f32 v[100:101], v[120:121], v[68:69], v[98:99] op_sel_hi:[0,1,1]
	v_lshlrev_b32_e32 v98, 16, v180
	v_and_b32_e32 v99, 0xffff0000, v180
	v_lshlrev_b32_e32 v116, 16, v181
	v_and_b32_e32 v117, 0xffff0000, v181
	v_pk_mul_f32 v[120:121], v[84:85], v[98:99] op_sel:[1,1] op_sel_hi:[1,0] neg_lo:[1,0]
	v_pk_fma_f32 v[68:69], v[84:85], v[98:99], v[120:121] op_sel_hi:[0,1,1]
	v_pk_mul_f32 v[120:121], v[14:15], v[98:99] op_sel:[1,1] op_sel_hi:[1,0] neg_lo:[1,0]
	v_pk_fma_f32 v[84:85], v[14:15], v[98:99], v[120:121] op_sel_hi:[0,1,1]
	v_pk_mul_f32 v[98:99], v[78:79], v[116:117] op_sel:[1,1] op_sel_hi:[1,0] neg_lo:[1,0]
	v_pk_fma_f32 v[78:79], v[78:79], v[116:117], v[98:99] op_sel_hi:[0,1,1]
	v_pk_mul_f32 v[98:99], v[10:11], v[116:117] op_sel:[1,1] op_sel_hi:[1,0] neg_lo:[1,0]
	v_pk_fma_f32 v[116:117], v[10:11], v[116:117], v[98:99] op_sel_hi:[0,1,1]
	v_lshlrev_b32_e32 v98, 16, v174
	v_and_b32_e32 v99, 0xffff0000, v174
	v_pk_mul_f32 v[14:15], v[96:97], v[98:99] op_sel:[1,1] op_sel_hi:[1,0] neg_lo:[1,0]
	v_pk_fma_f32 v[96:97], v[96:97], v[98:99], v[14:15] op_sel_hi:[0,1,1]
	v_lshlrev_b32_e32 v4, 16, v175
	v_pk_mul_f32 v[14:15], v[108:109], v[98:99] op_sel:[1,1] op_sel_hi:[1,0] neg_lo:[1,0]
	v_pk_fma_f32 v[98:99], v[108:109], v[98:99], v[14:15] op_sel_hi:[0,1,1]
	v_and_b32_e32 v5, 0xffff0000, v175
	v_pk_mul_f32 v[108:109], v[80:81], v[4:5] op_sel:[1,1] op_sel_hi:[1,0] neg_lo:[1,0]
	v_pk_fma_f32 v[80:81], v[80:81], v[4:5], v[108:109] op_sel_hi:[0,1,1]
	v_pk_mul_f32 v[14:15], v[16:17], v[4:5] op_sel:[1,1] op_sel_hi:[1,0] neg_lo:[1,0]
	v_pk_fma_f32 v[108:109], v[16:17], v[4:5], v[14:15] op_sel_hi:[0,1,1]
; DEV cf kunpack(unsigned w) { return cf{U2F(w << 16), U2F(w & 0xffff0000u)}; }
; template <int R, bool INV> DEV void dft_regs(cf (&v)[R]) {
;     ...
;     for (int s = R; s >= 2; s >>= 1) {
;         const int h = s >> 1;
; #pragma unroll
;         for (int b = 0; b < R; b += s) {
; #pragma unroll
;             for (int k = 0; k < h; ++k) {
;                 const cf a = v[b + k], c = v[b + k + h];
;                 v[b + k] = a + c;
;                 const cf d = a - c;
;                 const int m = k * (32 / s);
;                 const float wr = tw_cos(m), wi = INV ? tw_sin(m) : -tw_sin(m);
;                 v[b + k + h] = cf{d.x * wr - d.y * wi, d.x * wi + d.y * wr};
;             }
;         }
;     }
; DEV void fft_midx2(LAS cf* buf0, LAS cf* buf1, const unsigned* Kp, int blk) {
;     ...
;     for (int p = 0; p < 16; ++p) { const cf k = kunpack(kw[p >> 2][p & 3]); w[p] = cmul(v[BR16[p]], k); x[p] = cmul(u[BR16[p]], k); }
;     dft_regs<16, true>(w); dft_regs<16, true>(x);
	v_lshlrev_b32_e32 v4, 16, v176
	v_and_b32_e32 v5, 0xffff0000, v176
	v_pk_mul_f32 v[8:9], v[112:113], v[4:5] op_sel:[1,1] op_sel_hi:[1,0] neg_lo:[1,0]
	v_pk_fma_f32 v[14:15], v[112:113], v[4:5], v[8:9] op_sel_hi:[0,1,1]
	v_pk_mul_f32 v[8:9], v[104:105], v[4:5] op_sel:[1,1] op_sel_hi:[1,0] neg_lo:[1,0]
	v_pk_fma_f32 v[104:105], v[104:105], v[4:5], v[8:9] op_sel_hi:[0,1,1]
	v_lshlrev_b32_e32 v4, 16, v177
	v_and_b32_e32 v5, 0xffff0000, v177
	v_pk_mul_f32 v[8:9], v[70:71], v[4:5] op_sel:[1,1] op_sel_hi:[1,0] neg_lo:[1,0]
	v_pk_fma_f32 v[6:7], v[70:71], v[4:5], v[8:9] op_sel_hi:[0,1,1]
	v_pk_mul_f32 v[70:71], v[102:103], v[4:5] op_sel:[1,1] op_sel_hi:[1,0] neg_lo:[1,0]
	v_pk_fma_f32 v[8:9], v[102:103], v[4:5], v[70:71] op_sel_hi:[0,1,1]
	v_lshlrev_b32_e32 v4, 16, v170
	v_and_b32_e32 v5, 0xffff0000, v170
	v_lshlrev_b32_e32 v16, 16, v171
	v_and_b32_e32 v17, 0xffff0000, v171
	v_pk_mul_f32 v[70:71], v[90:91], v[4:5] op_sel:[1,1] op_sel_hi:[1,0] neg_lo:[1,0]
	v_pk_fma_f32 v[120:121], v[90:91], v[4:5], v[70:71] op_sel_hi:[0,1,1]
	v_pk_mul_f32 v[70:71], v[106:107], v[4:5] op_sel:[1,1] op_sel_hi:[1,0] neg_lo:[1,0]
	v_pk_fma_f32 v[102:103], v[106:107], v[4:5], v[70:71] op_sel_hi:[0,1,1]
	v_pk_mul_f32 v[106:107], v[72:73], v[16:17] op_sel:[1,1] op_sel_hi:[1,0] neg_lo:[1,0]
	v_pk_fma_f32 v[4:5], v[72:73], v[16:17], v[106:107] op_sel_hi:[0,1,1]
	v_pk_mul_f32 v[106:107], v[110:111], v[16:17] op_sel:[1,1] op_sel_hi:[1,0] neg_lo:[1,0]
	v_pk_fma_f32 v[110:111], v[110:111], v[16:17], v[106:107] op_sel_hi:[0,1,1]
	v_lshlrev_b32_e32 v16, 16, v172
	v_and_b32_e32 v17, 0xffff0000, v172
	v_pk_mul_f32 v[72:73], v[114:115], v[16:17] op_sel:[1,1] op_sel_hi:[1,0] neg_lo:[1,0]
	v_pk_fma_f32 v[106:107], v[114:115], v[16:17], v[72:73] op_sel_hi:[0,1,1]
	v_pk_mul_f32 v[114:115], v[0:1], v[16:17] op_sel:[1,1] op_sel_hi:[1,0] neg_lo:[1,0]
	v_pk_fma_f32 v[112:113], v[0:1], v[16:17], v[114:115] op_sel_hi:[0,1,1]
	v_lshlrev_b32_e32 v16, 16, v173
	v_and_b32_e32 v17, 0xffff0000, v173
	v_pk_mul_f32 v[0:1], v[166:167], v[16:17] op_sel:[1,1] op_sel_hi:[1,0] neg_lo:[1,0]
	v_pk_fma_f32 v[2:3], v[166:167], v[16:17], v[0:1] op_sel_hi:[0,1,1]
	v_pk_mul_f32 v[0:1], v[18:19], v[16:17] op_sel:[1,1] op_sel_hi:[1,0] neg_lo:[1,0]
	v_pk_fma_f32 v[18:19], v[18:19], v[16:17], v[0:1] op_sel_hi:[0,1,1]
	v_pk_add_f32 v[0:1], v[164:165], v[96:97]
	v_pk_add_f32 v[16:17], v[164:165], v[96:97] neg_lo:[0,1] neg_hi:[0,1]
	v_pk_add_f32 v[114:115], v[94:95], v[80:81] neg_lo:[0,1] neg_hi:[0,1]
	v_pk_mul_f32 v[96:97], v[114:115], s[84:85] op_sel_hi:[1,0]
	v_pk_add_f32 v[72:73], v[94:95], v[80:81]
	v_pk_fma_f32 v[70:71], v[114:115], s[16:17], v[96:97] op_sel:[0,0,1] op_sel_hi:[1,0,0] neg_lo:[0,0,1]
	v_pk_add_f32 v[114:115], v[122:123], v[14:15]
	v_pk_add_f32 v[14:15], v[122:123], v[14:15] neg_lo:[0,1] neg_hi:[0,1]
	v_pk_mul_f32 v[96:97], v[14:15], s[18:19] op_sel_hi:[1,0]
	v_pk_fma_f32 v[80:81], v[14:15], s[18:19], v[96:97] op_sel:[0,0,1] op_sel_hi:[1,0,0] neg_lo:[0,0,1]
	v_pk_add_f32 v[14:15], v[76:77], v[6:7]
	v_pk_add_f32 v[6:7], v[76:77], v[6:7] neg_lo:[0,1] neg_hi:[0,1]
	v_pk_mul_f32 v[96:97], v[6:7], s[16:17] op_sel_hi:[1,0]
	v_pk_fma_f32 v[94:95], v[6:7], s[84:85], v[96:97] op_sel:[0,0,1] op_sel_hi:[1,0,0] neg_lo:[0,0,1]
	v_pk_add_f32 v[6:7], v[92:93], v[120:121]
	v_pk_add_f32 v[120:121], v[92:93], v[120:121] neg_lo:[0,1] neg_hi:[0,1]
	v_pk_add_f32 v[96:97], v[120:121], 0 op_sel:[1,0] op_sel_hi:[0,0] neg_lo:[1,0]
	v_pk_add_f32 v[92:93], v[118:119], v[4:5]
	v_pk_add_f32 v[4:5], v[118:119], v[4:5] neg_lo:[0,1] neg_hi:[0,1]
	v_pk_mul_f32 v[90:91], v[4:5], s[24:25] op_sel:[1,0]
	v_pk_fma_f32 v[4:5], v[4:5], s[0:1], v[90:91] op_sel_hi:[0,1,1] neg_lo:[0,0,1] neg_hi:[0,0,1]
	v_pk_add_f32 v[90:91], v[68:69], v[106:107]
	v_pk_add_f32 v[106:107], v[68:69], v[106:107] neg_lo:[0,1] neg_hi:[0,1]
	v_mul_f32_e32 v76, 0x3f3504f3, v107
	v_pk_fma_f32 v[106:107], v[106:107], s[96:97], v[76:77] op_sel_hi:[0,1,0] neg_lo:[0,0,1] neg_hi:[0,0,1]
	v_pk_add_f32 v[76:77], v[78:79], v[2:3]
	v_pk_add_f32 v[2:3], v[78:79], v[2:3] neg_lo:[0,1] neg_hi:[0,1]
	v_pk_mul_f32 v[78:79], v[2:3], s[84:85] op_sel:[1,0]
	v_pk_fma_f32 v[2:3], v[2:3], s[88:89], v[78:79] op_sel_hi:[0,1,1] neg_lo:[0,0,1] neg_hi:[0,0,1]
	v_pk_add_f32 v[78:79], v[0:1], v[6:7]
	v_pk_add_f32 v[0:1], v[0:1], v[6:7] neg_lo:[0,1] neg_hi:[0,1]
	v_pk_add_f32 v[6:7], v[72:73], v[92:93] neg_lo:[0,1] neg_hi:[0,1]
	v_pk_add_f32 v[68:69], v[72:73], v[92:93]
	v_pk_mul_f32 v[72:73], v[6:7], s[18:19] op_sel_hi:[1,0]
	v_pk_fma_f32 v[92:93], v[6:7], s[18:19], v[72:73] op_sel:[0,0,1] op_sel_hi:[1,0,0] neg_lo:[0,0,1]
	v_pk_add_f32 v[72:73], v[114:115], v[90:91] neg_lo:[0,1] neg_hi:[0,1]
	v_pk_add_f32 v[6:7], v[114:115], v[90:91]
	v_pk_add_f32 v[114:115], v[72:73], 0 op_sel:[1,0] op_sel_hi:[0,0] neg_lo:[1,0]
	v_pk_add_f32 v[72:73], v[14:15], v[76:77]
	v_pk_add_f32 v[14:15], v[14:15], v[76:77] neg_lo:[0,1] neg_hi:[0,1]
	v_mul_f32_e32 v90, 0x3f3504f3, v15
	v_pk_fma_f32 v[14:15], v[14:15], s[96:97], v[90:91] op_sel_hi:[0,1,0] neg_lo:[0,0,1] neg_hi:[0,0,1]
	v_pk_add_f32 v[90:91], v[16:17], v[96:97]
	v_pk_add_f32 v[16:17], v[16:17], v[96:97] neg_lo:[0,1] neg_hi:[0,1]
	v_pk_add_f32 v[76:77], v[70:71], v[4:5]
	v_pk_add_f32 v[4:5], v[70:71], v[4:5] neg_lo:[0,1] neg_hi:[0,1]
	v_pk_mul_f32 v[96:97], v[4:5], s[18:19] op_sel_hi:[1,0]
	v_pk_fma_f32 v[70:71], v[4:5], s[18:19], v[96:97] op_sel:[0,0,1] op_sel_hi:[1,0,0] neg_lo:[0,0,1]
	v_pk_add_f32 v[4:5], v[80:81], v[106:107]
	v_pk_add_f32 v[106:107], v[80:81], v[106:107] neg_lo:[0,1] neg_hi:[0,1]
	v_pk_add_f32 v[10:11], v[90:91], v[4:5]
	v_pk_add_f32 v[96:97], v[106:107], 0 op_sel:[1,0] op_sel_hi:[0,0] neg_lo:[1,0]
; template <int R, bool INV> DEV void dft_regs(cf (&v)[R]) {
;     ...
;     for (int s = R; s >= 2; s >>= 1) {
;         const int h = s >> 1;
; #pragma unroll
;         for (int b = 0; b < R; b += s) {
; #pragma unroll
;             for (int k = 0; k < h; ++k) {
;                 const cf a = v[b + k], c = v[b + k + h];
;                 v[b + k] = a + c;
;                 const cf d = a - c;
;                 const int m = k * (32 / s);
;                 const float wr = tw_cos(m), wi = INV ? tw_sin(m) : -tw_sin(m);
;                 v[b + k + h] = cf{d.x * wr - d.y * wi, d.x * wi + d.y * wr};
;             }
;         }
;     }
; DEV void fft_midx2(LAS cf* buf0, LAS cf* buf1, const unsigned* Kp, int blk) {
;     ...
;     dft_regs<16, true>(w); dft_regs<16, true>(x);
	v_pk_add_f32 v[4:5], v[90:91], v[4:5] neg_lo:[0,1] neg_hi:[0,1]
	v_pk_add_f32 v[106:107], v[94:95], v[2:3]
	v_pk_add_f32 v[2:3], v[94:95], v[2:3] neg_lo:[0,1] neg_hi:[0,1]
	v_pk_add_f32 v[118:119], v[76:77], v[106:107]
	v_mul_f32_e32 v80, 0x3f3504f3, v3
	v_pk_fma_f32 v[2:3], v[2:3], s[96:97], v[80:81] op_sel_hi:[0,1,0] neg_lo:[0,0,1] neg_hi:[0,0,1]
	v_pk_add_f32 v[80:81], v[78:79], v[6:7]
	v_pk_add_f32 v[6:7], v[78:79], v[6:7] neg_lo:[0,1] neg_hi:[0,1]
	v_pk_add_f32 v[122:123], v[70:71], v[2:3]
	v_pk_add_f32 v[2:3], v[70:71], v[2:3] neg_lo:[0,1] neg_hi:[0,1]
	v_pk_add_f32 v[78:79], v[2:3], 0 op_sel:[1,0] op_sel_hi:[0,0] neg_lo:[1,0]
	v_pk_add_f32 v[94:95], v[68:69], v[72:73]
	v_pk_add_f32 v[68:69], v[68:69], v[72:73] neg_lo:[0,1] neg_hi:[0,1]
	v_pk_add_f32 v[72:73], v[68:69], 0 op_sel:[1,0] op_sel_hi:[0,0] neg_lo:[1,0]
	v_pk_add_f32 v[120:121], v[16:17], v[96:97]
	v_pk_add_f32 v[68:69], v[0:1], v[114:115]
	v_pk_add_f32 v[114:115], v[0:1], v[114:115] neg_lo:[0,1] neg_hi:[0,1]
	v_pk_add_f32 v[2:3], v[80:81], v[94:95] neg_lo:[0,1] neg_hi:[0,1]
	v_pk_add_f32 v[70:71], v[92:93], v[14:15]
	v_pk_add_f32 v[0:1], v[92:93], v[14:15] neg_lo:[0,1] neg_hi:[0,1]
	v_pk_add_f32 v[124:125], v[80:81], v[94:95]
	v_pk_add_f32 v[14:15], v[0:1], 0 op_sel:[1,0] op_sel_hi:[0,0] neg_lo:[1,0]
	v_pk_add_f32 v[80:81], v[6:7], v[72:73]
	v_pk_add_f32 v[90:91], v[76:77], v[106:107] neg_lo:[0,1] neg_hi:[0,1]
	v_pk_add_f32 v[76:77], v[90:91], 0 op_sel:[1,0] op_sel_hi:[0,0] neg_lo:[1,0]
	v_pk_add_f32 v[90:91], v[16:17], v[96:97] neg_lo:[0,1] neg_hi:[0,1]
	v_pk_add_f32 v[126:127], v[4:5], v[76:77]
	v_pk_add_f32 v[16:17], v[4:5], v[76:77] neg_lo:[0,1] neg_hi:[0,1]
	v_pk_add_f32 v[76:77], v[120:121], v[122:123]
	v_pk_add_f32 v[164:165], v[90:91], v[78:79]
	v_mov_b32_e32 v106, v2
	v_mov_b32_e32 v107, v3
	v_mov_b32_e32 v0, v2
	v_mov_b32_e32 v1, v3
	v_pk_add_f32 v[4:5], v[6:7], v[72:73] neg_lo:[0,1] neg_hi:[0,1]
	v_pk_add_f32 v[94:95], v[68:69], v[70:71]
	v_pk_add_f32 v[68:69], v[68:69], v[70:71] neg_lo:[0,1] neg_hi:[0,1]
	v_mov_b32_e32 v2, v4
	v_mov_b32_e32 v3, v5
	v_pk_add_f32 v[92:93], v[114:115], v[14:15]
	v_mov_b32_e32 v70, v68
	v_mov_b32_e32 v71, v69
	v_pk_add_f32 v[6:7], v[114:115], v[14:15] neg_lo:[0,1] neg_hi:[0,1]
	v_pk_add_f32 v[72:73], v[10:11], v[118:119]
	v_pk_add_f32 v[78:79], v[90:91], v[78:79] neg_lo:[0,1] neg_hi:[0,1]
	v_mov_b32_e32 v114, v6
	v_mov_b32_e32 v115, v7
	v_pk_add_f32 v[14:15], v[10:11], v[118:119] neg_lo:[0,1] neg_hi:[0,1]
	v_mov_b32_e32 v10, v14
	v_mov_b32_e32 v11, v15
	v_mov_b32_e32 v118, v14
	v_mov_b32_e32 v119, v15
	v_mov_b32_e32 v107, v1
	v_mov_b32_e32 v96, v16
	v_mov_b32_e32 v97, v17
	v_pk_add_f32 v[14:15], v[120:121], v[122:123] neg_lo:[0,1] neg_hi:[0,1]
	v_mov_b32_e32 v11, v119
	v_mov_b32_e32 v69, v71
	v_mov_b32_e32 v122, v14
	v_mov_b32_e32 v123, v15
	v_mov_b32_e32 v120, v14
	v_mov_b32_e32 v121, v15
	v_pk_add_f32 v[90:91], v[86:87], v[98:99]
	v_pk_add_f32 v[86:87], v[86:87], v[98:99] neg_lo:[0,1] neg_hi:[0,1]
	v_mov_b32_e32 v123, v121
	v_mov_b32_e32 v166, v86
	v_mov_b32_e32 v167, v87
	v_pk_add_f32 v[86:87], v[12:13], v[108:109]
	v_pk_add_f32 v[12:13], v[12:13], v[108:109] neg_lo:[0,1] neg_hi:[0,1]
	v_mov_b32_e32 v17, v97
	v_pk_mul_f32 v[98:99], v[12:13], s[84:85] op_sel_hi:[1,0]
	v_pk_fma_f32 v[108:109], v[12:13], s[16:17], v[98:99] op_sel:[0,0,1] op_sel_hi:[1,0,0] neg_lo:[0,0,1]
	v_pk_add_f32 v[12:13], v[88:89], v[104:105]
	v_pk_add_f32 v[88:89], v[88:89], v[104:105] neg_lo:[0,1] neg_hi:[0,1]
	v_pk_mul_f32 v[98:99], v[88:89], s[18:19] op_sel_hi:[1,0]
	v_pk_fma_f32 v[104:105], v[88:89], s[18:19], v[98:99] op_sel:[0,0,1] op_sel_hi:[1,0,0] neg_lo:[0,0,1]
	v_pk_add_f32 v[88:89], v[74:75], v[8:9]
	v_pk_add_f32 v[74:75], v[74:75], v[8:9] neg_lo:[0,1] neg_hi:[0,1]
	v_pk_mul_f32 v[98:99], v[74:75], s[16:17] op_sel_hi:[1,0]
	v_pk_fma_f32 v[8:9], v[74:75], s[84:85], v[98:99] op_sel:[0,0,1] op_sel_hi:[1,0,0] neg_lo:[0,0,1]
	v_pk_add_f32 v[74:75], v[82:83], v[102:103]
	v_pk_add_f32 v[82:83], v[82:83], v[102:103] neg_lo:[0,1] neg_hi:[0,1]
	v_pk_add_f32 v[102:103], v[116:117], v[18:19]
	v_pk_add_f32 v[116:117], v[116:117], v[18:19] neg_lo:[0,1] neg_hi:[0,1]
	v_pk_add_f32 v[98:99], v[82:83], 0 op_sel:[1,0] op_sel_hi:[0,0] neg_lo:[1,0]
	v_pk_mul_f32 v[18:19], v[116:117], s[84:85] op_sel:[1,0]
	v_pk_add_f32 v[82:83], v[100:101], v[110:111]
	v_pk_add_f32 v[100:101], v[100:101], v[110:111] neg_lo:[0,1] neg_hi:[0,1]
	v_pk_fma_f32 v[116:117], v[116:117], s[88:89], v[18:19] op_sel_hi:[0,1,1] neg_lo:[0,0,1] neg_hi:[0,0,1]
	v_pk_add_f32 v[18:19], v[90:91], v[74:75]
	v_pk_add_f32 v[74:75], v[90:91], v[74:75] neg_lo:[0,1] neg_hi:[0,1]
	v_pk_mul_f32 v[110:111], v[100:101], s[24:25] op_sel:[1,0]
	v_pk_fma_f32 v[100:101], v[100:101], s[0:1], v[110:111] op_sel_hi:[0,1,1] neg_lo:[0,0,1] neg_hi:[0,0,1]
	v_pk_add_f32 v[110:111], v[84:85], v[112:113]
	v_pk_add_f32 v[84:85], v[84:85], v[112:113] neg_lo:[0,1] neg_hi:[0,1]
	v_mul_f32_e32 v4, 0x3f3504f3, v85
	v_pk_add_f32 v[112:113], v[86:87], v[82:83]
	v_pk_add_f32 v[82:83], v[86:87], v[82:83] neg_lo:[0,1] neg_hi:[0,1]
	v_pk_fma_f32 v[84:85], v[84:85], s[96:97], v[4:5] op_sel_hi:[0,1,0] neg_lo:[0,0,1] neg_hi:[0,0,1]
	v_pk_mul_f32 v[86:87], v[82:83], s[18:19] op_sel_hi:[1,0]
	v_pk_fma_f32 v[96:97], v[82:83], s[18:19], v[86:87] op_sel:[0,0,1] op_sel_hi:[1,0,0] neg_lo:[0,0,1]
	v_pk_add_f32 v[82:83], v[12:13], v[110:111]
	v_pk_add_f32 v[12:13], v[12:13], v[110:111] neg_lo:[0,1] neg_hi:[0,1]
	v_pk_add_f32 v[110:111], v[166:167], v[98:99]
	v_pk_add_f32 v[86:87], v[12:13], 0 op_sel:[1,0] op_sel_hi:[0,0] neg_lo:[1,0]
	v_pk_add_f32 v[98:99], v[166:167], v[98:99] neg_lo:[0,1] neg_hi:[0,1]
	v_pk_add_f32 v[12:13], v[88:89], v[102:103]
; #define LAS __attribute__((address_space(3)))
; #define SINCOSPI(x, s, c) do { const float hx_ = 0.5f * (x); *(s) = __builtin_amdgcn_sinf(hx_); *(c) = __builtin_amdgcn_cosf(hx_); } while (0)
; #define OPAQUE_I(x) asm volatile("" : "+v"(x))
; DEV void fft_midx2(LAS cf* buf0, LAS cf* buf1, const unsigned* Kp, int blk) {
;     ...
;     dft_regs<16, true>(w); dft_regs<16, true>(x);
; #pragma unroll
;     for (int q = 0; q < 16; ++q) { p0[q] = w[BR16[q]]; p1[q] = x[BR16[q]]; }
; }
; DEV void fft_i2(LAS cf* buf, int t8) {
;     OPAQUE_I(t8);
;     LAS cf* pb = buf + (t8 >> 4) * 544 + (t8 & 15);
;     float sn, cs; SINCOSPI(-(float)(t8 & 15) * (2.0f / 512.0f), &sn, &cs);
;     const cf w = cf{cs, sn}; cf wp = cf{1.f, 0.f};
; DEV void hyena_issue_rows(const bf16_t* UT, int s, int c, u32x4 (&r)[4], int tid) {
; #pragma unroll
;     for (int b = 0; b < 4; ++b) r[b] = *(const u32x4*)(UT + ((size_t)(b * 3072 + s * 1024 + c)) * 4096 + tid * 8);
; }
	v_pk_add_f32 v[88:89], v[88:89], v[102:103] neg_lo:[0,1] neg_hi:[0,1]
	v_mul_f32_e32 v4, 0x3f3504f3, v89
	v_pk_fma_f32 v[88:89], v[88:89], s[96:97], v[4:5] op_sel_hi:[0,1,0] neg_lo:[0,0,1] neg_hi:[0,0,1]
	v_pk_add_f32 v[166:167], v[108:109], v[100:101]
	v_pk_add_f32 v[100:101], v[108:109], v[100:101] neg_lo:[0,1] neg_hi:[0,1]
	v_pk_mul_f32 v[108:109], v[100:101], s[18:19] op_sel_hi:[1,0]
	v_pk_fma_f32 v[102:103], v[100:101], s[18:19], v[108:109] op_sel:[0,0,1] op_sel_hi:[1,0,0] neg_lo:[0,0,1]
	v_pk_add_f32 v[108:109], v[18:19], v[82:83]
	v_pk_add_f32 v[100:101], v[104:105], v[84:85]
	v_pk_add_f32 v[84:85], v[104:105], v[84:85] neg_lo:[0,1] neg_hi:[0,1]
	v_pk_add_f32 v[82:83], v[18:19], v[82:83] neg_lo:[0,1] neg_hi:[0,1]
	v_pk_add_f32 v[104:105], v[84:85], 0 op_sel:[1,0] op_sel_hi:[0,0] neg_lo:[1,0]
	v_pk_add_f32 v[84:85], v[8:9], v[116:117]
	v_pk_add_f32 v[116:117], v[8:9], v[116:117] neg_lo:[0,1] neg_hi:[0,1]
	v_mul_f32_e32 v4, 0x3f3504f3, v117
	v_pk_add_f32 v[8:9], v[112:113], v[12:13]
	v_pk_add_f32 v[12:13], v[112:113], v[12:13] neg_lo:[0,1] neg_hi:[0,1]
	v_pk_fma_f32 v[116:117], v[116:117], s[96:97], v[4:5] op_sel_hi:[0,1,0] neg_lo:[0,0,1] neg_hi:[0,0,1]
	v_pk_add_f32 v[112:113], v[12:13], 0 op_sel:[1,0] op_sel_hi:[0,0] neg_lo:[1,0]
	v_pk_add_f32 v[12:13], v[74:75], v[86:87]
	v_pk_add_f32 v[86:87], v[74:75], v[86:87] neg_lo:[0,1] neg_hi:[0,1]
	v_pk_add_f32 v[74:75], v[96:97], v[88:89]
	v_pk_add_f32 v[88:89], v[96:97], v[88:89] neg_lo:[0,1] neg_hi:[0,1]
	v_pk_add_f32 v[96:97], v[88:89], 0 op_sel:[1,0] op_sel_hi:[0,0] neg_lo:[1,0]
	v_pk_add_f32 v[88:89], v[110:111], v[100:101]
	v_pk_add_f32 v[18:19], v[110:111], v[100:101] neg_lo:[0,1] neg_hi:[0,1]
	v_pk_add_f32 v[100:101], v[98:99], v[104:105] neg_lo:[0,1] neg_hi:[0,1]
	v_pk_add_f32 v[110:111], v[166:167], v[84:85]
	v_pk_add_f32 v[84:85], v[166:167], v[84:85] neg_lo:[0,1] neg_hi:[0,1]
	v_pk_add_f32 v[166:167], v[84:85], 0 op_sel:[1,0] op_sel_hi:[0,0] neg_lo:[1,0]
	v_pk_add_f32 v[84:85], v[98:99], v[104:105]
	v_pk_add_f32 v[98:99], v[102:103], v[116:117]
	v_pk_add_f32 v[116:117], v[102:103], v[116:117] neg_lo:[0,1] neg_hi:[0,1]
	v_pk_add_f32 v[104:105], v[116:117], 0 op_sel:[1,0] op_sel_hi:[0,0] neg_lo:[1,0]
	v_pk_add_f32 v[116:117], v[108:109], v[8:9]
	v_pk_add_f32 v[8:9], v[108:109], v[8:9] neg_lo:[0,1] neg_hi:[0,1]
	v_pk_add_f32 v[108:109], v[82:83], v[112:113]
	v_pk_add_f32 v[112:113], v[82:83], v[112:113] neg_lo:[0,1] neg_hi:[0,1]
	v_pk_add_f32 v[102:103], v[12:13], v[74:75]
	v_pk_add_f32 v[12:13], v[12:13], v[74:75] neg_lo:[0,1] neg_hi:[0,1]
	v_pk_add_f32 v[74:75], v[86:87], v[96:97]
	v_pk_add_f32 v[96:97], v[86:87], v[96:97] neg_lo:[0,1] neg_hi:[0,1]
	v_pk_add_f32 v[168:169], v[88:89], v[110:111]
	v_pk_add_f32 v[110:111], v[88:89], v[110:111] neg_lo:[0,1] neg_hi:[0,1]
	v_pk_add_f32 v[88:89], v[18:19], v[166:167]
	v_pk_add_f32 v[166:167], v[18:19], v[166:167] neg_lo:[0,1] neg_hi:[0,1]
	v_mov_b32_e32 v176, v166
	v_mov_b32_e32 v177, v167
	v_pk_add_f32 v[174:175], v[84:85], v[98:99]
	v_pk_add_f32 v[84:85], v[84:85], v[98:99] neg_lo:[0,1] neg_hi:[0,1]
	v_pk_add_f32 v[98:99], v[100:101], v[104:105]
	v_pk_add_f32 v[104:105], v[100:101], v[104:105] neg_lo:[0,1] neg_hi:[0,1]
	ds_write2_b64 v161, v[124:125], v[72:73] offset1:1
	ds_write2_b64 v162, v[116:117], v[168:169] offset1:1
	ds_write2_b64 v161, v[94:95], v[76:77] offset0:2 offset1:3
	ds_write2_b64 v162, v[102:103], v[174:175] offset0:2 offset1:3
	ds_write2_b64 v161, v[80:81], v[126:127] offset0:4 offset1:5
	ds_write2_b64 v162, v[108:109], v[88:89] offset0:4 offset1:5
	ds_write2_b64 v161, v[92:93], v[164:165] offset0:6 offset1:7
	ds_write2_b64 v162, v[74:75], v[98:99] offset0:6 offset1:7
	ds_write2_b64 v161, v[114:115], v[78:79] offset0:14 offset1:15
	v_mov_b32_e32 v114, v160
	ds_write2_b64 v161, v[106:107], v[10:11] offset0:8 offset1:9
	ds_write2_b64 v162, v[8:9], v[110:111] offset0:8 offset1:9
	ds_write2_b64 v161, v[68:69], v[122:123] offset0:10 offset1:11
	ds_write2_b64 v162, v[12:13], v[84:85] offset0:10 offset1:11
	ds_write2_b64 v161, v[2:3], v[16:17] offset0:12 offset1:13
	ds_write2_b64 v162, v[112:113], v[176:177] offset0:12 offset1:13
	ds_write2_b64 v162, v[96:97], v[104:105] offset0:14 offset1:15
	s_waitcnt lgkmcnt(0)
	s_barrier
	s_lshl_b32 s100, s19, 10
	s_add_i32 s100, s79, s100
	s_ashr_i32 s101, s100, 31
	s_lshl_b64 s[100:101], s[100:101], 13
	v_lshl_add_u64 v[218:219], v[56:57], 0, s[100:101]
	global_load_dwordx4 v[222:225], v[218:219], off
	s_add_u32 s100, s100, 0x1800000
	s_addc_u32 s101, s101, 0
	v_lshl_add_u64 v[220:221], v[56:57], 0, s[100:101]
	global_load_dwordx4 v[226:229], v[220:221], off
	s_add_u32 s100, s100, 0x1800000
	s_addc_u32 s101, s101, 0
	v_lshl_add_u64 v[218:219], v[56:57], 0, s[100:101]
	global_load_dwordx4 v[236:239], v[218:219], off
	s_add_u32 s100, s100, 0x1800000
	s_addc_u32 s101, s101, 0
	v_lshl_add_u64 v[220:221], v[56:57], 0, s[100:101]
	global_load_dwordx4 v[240:243], v[220:221], off
	s_nop 0
	v_lshrrev_b32_e32 v115, 4, v114
	v_and_b32_e32 v114, 15, v114
	v_mul_lo_u32 v115, v115, s15
	v_lshlrev_b32_e32 v2, 3, v114
	v_cvt_f32_ubyte0_e32 v114, v114
	v_add3_u32 v74, v159, v115, v2
	v_mul_f32_e32 v114, 0xbb800000, v114
	v_mul_f32_e32 v114, 0.5, v114
	v_add_u32_e32 v232, 0x800, v74
	v_add_u32_e32 v233, 0xc00, v74
	ds_read2_b64 v[166:169], v74 offset1:17
	ds_read2_b64 v[170:173], v74 offset0:34 offset1:51
	ds_read2_b64 v[174:177], v74 offset0:68 offset1:85
	ds_read2_b64 v[178:181], v74 offset0:102 offset1:119
	ds_read2_b64 v[182:185], v74 offset0:136 offset1:153
	ds_read2_b64 v[186:189], v74 offset0:170 offset1:187
	ds_read2_b64 v[190:193], v74 offset0:204 offset1:221
	ds_read2_b64 v[194:197], v74 offset0:238 offset1:255
	ds_read2_b64 v[198:201], v232 offset0:16 offset1:33
	ds_read2_b64 v[202:205], v232 offset0:50 offset1:67
	ds_read2_b64 v[208:211], v232 offset0:84 offset1:101
	ds_read2_b64 v[214:217], v232 offset0:118 offset1:135
	ds_read2_b64 v[218:221], v232 offset0:152 offset1:169
	v_sin_f32_e32 v115, v114
	v_cos_f32_e32 v114, v114
	s_waitcnt lgkmcnt(12)
; #define SINCOSPI(x, s, c) do { const float hx_ = 0.5f * (x); *(s) = __builtin_amdgcn_sinf(hx_); *(c) = __builtin_amdgcn_cosf(hx_); } while (0)
; DEV void fft_i2(LAS cf* buf, int t8) {
;     ...
;     float sn, cs; SINCOSPI(-(float)(t8 & 15) * (2.0f / 512.0f), &sn, &cs);
;     const cf w = cf{cs, sn}; cf wp = cf{1.f, 0.f};
;     cf v[32];
; #pragma unroll
;     for (int p = 0; p < 32; ++p) { v[p] = cmulc(pb[17 * p], wp); wp = cmul(wp, w); }
	v_pk_mul_f32 v[2:3], v[166:167], v[66:67] op_sel:[1,1] op_sel_hi:[1,0]
	v_pk_fma_f32 v[4:5], v[166:167], v[66:67], v[2:3] op_sel_hi:[0,1,1] neg_hi:[1,0,0]
	v_add_u32_e32 v75, 0x800, v74
	v_pk_mul_f32 v[2:3], v[66:67], v[114:115] op_sel:[1,1] op_sel_hi:[1,0] neg_lo:[1,0]
	v_pk_fma_f32 v[8:9], v[66:67], v[114:115], v[2:3] op_sel_hi:[0,1,1]
	v_pk_mul_f32 v[10:11], v[168:169], v[8:9] op_sel:[1,1] op_sel_hi:[1,0]
	v_pk_fma_f32 v[2:3], v[168:169], v[8:9], v[10:11] op_sel_hi:[0,1,1] neg_hi:[1,0,0]
	v_pk_mul_f32 v[6:7], v[8:9], v[114:115] op_sel:[1,1] op_sel_hi:[1,0] neg_lo:[1,0]
	v_pk_fma_f32 v[12:13], v[8:9], v[114:115], v[6:7] op_sel_hi:[0,1,1]
	ds_read2_b64 v[166:169], v232 offset0:186 offset1:203
	s_waitcnt lgkmcnt(12)
	v_pk_mul_f32 v[14:15], v[170:171], v[12:13] op_sel:[1,1] op_sel_hi:[1,0]
	v_pk_fma_f32 v[10:11], v[170:171], v[12:13], v[14:15] op_sel_hi:[0,1,1] neg_hi:[1,0,0]
	v_pk_mul_f32 v[6:7], v[12:13], v[114:115] op_sel:[1,1] op_sel_hi:[1,0] neg_lo:[1,0]
	v_pk_fma_f32 v[12:13], v[12:13], v[114:115], v[6:7] op_sel_hi:[0,1,1]
	v_pk_mul_f32 v[14:15], v[172:173], v[12:13] op_sel:[1,1] op_sel_hi:[1,0]
	v_pk_fma_f32 v[6:7], v[172:173], v[12:13], v[14:15] op_sel_hi:[0,1,1] neg_hi:[1,0,0]
	v_pk_mul_f32 v[8:9], v[12:13], v[114:115] op_sel:[1,1] op_sel_hi:[1,0] neg_lo:[1,0]
	v_pk_fma_f32 v[16:17], v[12:13], v[114:115], v[8:9] op_sel_hi:[0,1,1]
	ds_read2_b64 v[170:173], v232 offset0:220 offset1:237
	s_waitcnt lgkmcnt(12)
	v_pk_mul_f32 v[8:9], v[174:175], v[16:17] op_sel:[1,1] op_sel_hi:[1,0]
	v_pk_fma_f32 v[12:13], v[174:175], v[16:17], v[8:9] op_sel_hi:[0,1,1] neg_hi:[1,0,0]
	v_pk_mul_f32 v[8:9], v[16:17], v[114:115] op_sel:[1,1] op_sel_hi:[1,0] neg_lo:[1,0]
	v_pk_fma_f32 v[16:17], v[16:17], v[114:115], v[8:9] op_sel_hi:[0,1,1]
	v_pk_mul_f32 v[18:19], v[176:177], v[16:17] op_sel:[1,1] op_sel_hi:[1,0]
	v_pk_fma_f32 v[8:9], v[176:177], v[16:17], v[18:19] op_sel_hi:[0,1,1] neg_hi:[1,0,0]
	v_pk_mul_f32 v[14:15], v[16:17], v[114:115] op_sel:[1,1] op_sel_hi:[1,0] neg_lo:[1,0]
	v_pk_fma_f32 v[68:69], v[16:17], v[114:115], v[14:15] op_sel_hi:[0,1,1]
	ds_read2_b64 v[174:177], v233 offset0:126 offset1:143
	s_waitcnt lgkmcnt(12)
	v_pk_mul_f32 v[14:15], v[178:179], v[68:69] op_sel:[1,1] op_sel_hi:[1,0]
	v_pk_fma_f32 v[16:17], v[178:179], v[68:69], v[14:15] op_sel_hi:[0,1,1] neg_hi:[1,0,0]
	v_pk_mul_f32 v[14:15], v[68:69], v[114:115] op_sel:[1,1] op_sel_hi:[1,0] neg_lo:[1,0]
	v_pk_fma_f32 v[68:69], v[68:69], v[114:115], v[14:15] op_sel_hi:[0,1,1]
	v_pk_mul_f32 v[70:71], v[180:181], v[68:69] op_sel:[1,1] op_sel_hi:[1,0]
	v_pk_fma_f32 v[14:15], v[180:181], v[68:69], v[70:71] op_sel_hi:[0,1,1] neg_hi:[1,0,0]
	v_pk_mul_f32 v[18:19], v[68:69], v[114:115] op_sel:[1,1] op_sel_hi:[1,0] neg_lo:[1,0]
	v_pk_fma_f32 v[72:73], v[68:69], v[114:115], v[18:19] op_sel_hi:[0,1,1]
	s_waitcnt lgkmcnt(11)
	v_pk_mul_f32 v[18:19], v[182:183], v[72:73] op_sel:[1,1] op_sel_hi:[1,0]
	v_pk_fma_f32 v[68:69], v[182:183], v[72:73], v[18:19] op_sel_hi:[0,1,1] neg_hi:[1,0,0]
	v_pk_mul_f32 v[18:19], v[72:73], v[114:115] op_sel:[1,1] op_sel_hi:[1,0] neg_lo:[1,0]
	v_pk_fma_f32 v[72:73], v[72:73], v[114:115], v[18:19] op_sel_hi:[0,1,1]
	v_pk_mul_f32 v[86:87], v[184:185], v[72:73] op_sel:[1,1] op_sel_hi:[1,0]
	v_pk_fma_f32 v[18:19], v[184:185], v[72:73], v[86:87] op_sel_hi:[0,1,1] neg_hi:[1,0,0]
	v_pk_mul_f32 v[70:71], v[72:73], v[114:115] op_sel:[1,1] op_sel_hi:[1,0] neg_lo:[1,0]
	v_pk_fma_f32 v[76:77], v[72:73], v[114:115], v[70:71] op_sel_hi:[0,1,1]
	s_waitcnt lgkmcnt(10)
	v_pk_mul_f32 v[70:71], v[186:187], v[76:77] op_sel:[1,1] op_sel_hi:[1,0]
	v_pk_fma_f32 v[72:73], v[186:187], v[76:77], v[70:71] op_sel_hi:[0,1,1] neg_hi:[1,0,0]
	v_pk_mul_f32 v[70:71], v[76:77], v[114:115] op_sel:[1,1] op_sel_hi:[1,0] neg_lo:[1,0]
	v_pk_fma_f32 v[76:77], v[76:77], v[114:115], v[70:71] op_sel_hi:[0,1,1]
	v_pk_mul_f32 v[78:79], v[188:189], v[76:77] op_sel:[1,1] op_sel_hi:[1,0]
	v_pk_fma_f32 v[70:71], v[188:189], v[76:77], v[78:79] op_sel_hi:[0,1,1] neg_hi:[1,0,0]
	v_pk_mul_f32 v[86:87], v[76:77], v[114:115] op_sel:[1,1] op_sel_hi:[1,0] neg_lo:[1,0]
	v_pk_fma_f32 v[80:81], v[76:77], v[114:115], v[86:87] op_sel_hi:[0,1,1]
	s_waitcnt lgkmcnt(9)
	v_pk_mul_f32 v[86:87], v[190:191], v[80:81] op_sel:[1,1] op_sel_hi:[1,0]
	v_pk_fma_f32 v[76:77], v[190:191], v[80:81], v[86:87] op_sel_hi:[0,1,1] neg_hi:[1,0,0]
	v_pk_mul_f32 v[86:87], v[80:81], v[114:115] op_sel:[1,1] op_sel_hi:[1,0] neg_lo:[1,0]
	v_pk_fma_f32 v[80:81], v[80:81], v[114:115], v[86:87] op_sel_hi:[0,1,1]
	v_pk_mul_f32 v[82:83], v[192:193], v[80:81] op_sel:[1,1] op_sel_hi:[1,0]
	v_pk_fma_f32 v[86:87], v[192:193], v[80:81], v[82:83] op_sel_hi:[0,1,1] neg_hi:[1,0,0]
	v_pk_mul_f32 v[78:79], v[80:81], v[114:115] op_sel:[1,1] op_sel_hi:[1,0] neg_lo:[1,0]
	v_pk_fma_f32 v[84:85], v[80:81], v[114:115], v[78:79] op_sel_hi:[0,1,1]
	s_waitcnt lgkmcnt(8)
	v_pk_mul_f32 v[78:79], v[194:195], v[84:85] op_sel:[1,1] op_sel_hi:[1,0]
	v_pk_fma_f32 v[80:81], v[194:195], v[84:85], v[78:79] op_sel_hi:[0,1,1] neg_hi:[1,0,0]
	v_pk_mul_f32 v[78:79], v[84:85], v[114:115] op_sel:[1,1] op_sel_hi:[1,0] neg_lo:[1,0]
	v_pk_fma_f32 v[84:85], v[84:85], v[114:115], v[78:79] op_sel_hi:[0,1,1]
	v_pk_mul_f32 v[88:89], v[196:197], v[84:85] op_sel:[1,1] op_sel_hi:[1,0]
	v_pk_fma_f32 v[78:79], v[196:197], v[84:85], v[88:89] op_sel_hi:[0,1,1] neg_hi:[1,0,0]
	v_pk_mul_f32 v[82:83], v[84:85], v[114:115] op_sel:[1,1] op_sel_hi:[1,0] neg_lo:[1,0]
	v_pk_fma_f32 v[92:93], v[84:85], v[114:115], v[82:83] op_sel_hi:[0,1,1]
	s_waitcnt lgkmcnt(7)
; DEV void fft_i2(LAS cf* buf, int t8) {
;     ...
;     cf v[32];
; #pragma unroll
;     for (int p = 0; p < 32; ++p) { v[p] = cmulc(pb[17 * p], wp); wp = cmul(wp, w); }
	v_pk_mul_f32 v[82:83], v[198:199], v[92:93] op_sel:[1,1] op_sel_hi:[1,0]
	v_pk_fma_f32 v[84:85], v[198:199], v[92:93], v[82:83] op_sel_hi:[0,1,1] neg_hi:[1,0,0]
	v_pk_mul_f32 v[82:83], v[92:93], v[114:115] op_sel:[1,1] op_sel_hi:[1,0] neg_lo:[1,0]
	v_pk_fma_f32 v[88:89], v[92:93], v[114:115], v[82:83] op_sel_hi:[0,1,1]
	v_pk_mul_f32 v[92:93], v[200:201], v[88:89] op_sel:[1,1] op_sel_hi:[1,0]
	v_pk_fma_f32 v[82:83], v[200:201], v[88:89], v[92:93] op_sel_hi:[0,1,1] neg_hi:[1,0,0]
	v_pk_mul_f32 v[90:91], v[88:89], v[114:115] op_sel:[1,1] op_sel_hi:[1,0] neg_lo:[1,0]
	v_pk_fma_f32 v[92:93], v[88:89], v[114:115], v[90:91] op_sel_hi:[0,1,1]
	s_waitcnt lgkmcnt(6)
	v_pk_mul_f32 v[96:97], v[202:203], v[92:93] op_sel:[1,1] op_sel_hi:[1,0]
	v_pk_fma_f32 v[94:95], v[202:203], v[92:93], v[96:97] op_sel_hi:[0,1,1] neg_hi:[1,0,0]
	v_pk_mul_f32 v[88:89], v[92:93], v[114:115] op_sel:[1,1] op_sel_hi:[1,0] neg_lo:[1,0]
	v_pk_fma_f32 v[92:93], v[92:93], v[114:115], v[88:89] op_sel_hi:[0,1,1]
	v_pk_mul_f32 v[88:89], v[204:205], v[92:93] op_sel:[1,1] op_sel_hi:[1,0]
	v_pk_fma_f32 v[96:97], v[204:205], v[92:93], v[88:89] op_sel_hi:[0,1,1] neg_hi:[1,0,0]
	v_pk_mul_f32 v[88:89], v[92:93], v[114:115] op_sel:[1,1] op_sel_hi:[1,0] neg_lo:[1,0]
	v_pk_fma_f32 v[92:93], v[92:93], v[114:115], v[88:89] op_sel_hi:[0,1,1]
	s_waitcnt lgkmcnt(5)
	v_pk_mul_f32 v[100:101], v[208:209], v[92:93] op_sel:[1,1] op_sel_hi:[1,0]
	v_pk_fma_f32 v[98:99], v[208:209], v[92:93], v[100:101] op_sel_hi:[0,1,1] neg_hi:[1,0,0]
	v_pk_mul_f32 v[88:89], v[92:93], v[114:115] op_sel:[1,1] op_sel_hi:[1,0] neg_lo:[1,0]
	v_pk_fma_f32 v[92:93], v[92:93], v[114:115], v[88:89] op_sel_hi:[0,1,1]
	v_pk_mul_f32 v[88:89], v[210:211], v[92:93] op_sel:[1,1] op_sel_hi:[1,0]
	v_pk_fma_f32 v[100:101], v[210:211], v[92:93], v[88:89] op_sel_hi:[0,1,1] neg_hi:[1,0,0]
	v_pk_mul_f32 v[88:89], v[92:93], v[114:115] op_sel:[1,1] op_sel_hi:[1,0] neg_lo:[1,0]
	v_pk_fma_f32 v[92:93], v[92:93], v[114:115], v[88:89] op_sel_hi:[0,1,1]
	s_waitcnt lgkmcnt(4)
	v_pk_mul_f32 v[104:105], v[214:215], v[92:93] op_sel:[1,1] op_sel_hi:[1,0]
	v_pk_fma_f32 v[102:103], v[214:215], v[92:93], v[104:105] op_sel_hi:[0,1,1] neg_hi:[1,0,0]
	v_pk_mul_f32 v[88:89], v[92:93], v[114:115] op_sel:[1,1] op_sel_hi:[1,0] neg_lo:[1,0]
	v_pk_fma_f32 v[92:93], v[92:93], v[114:115], v[88:89] op_sel_hi:[0,1,1]
	v_pk_mul_f32 v[88:89], v[216:217], v[92:93] op_sel:[1,1] op_sel_hi:[1,0]
	v_pk_fma_f32 v[104:105], v[216:217], v[92:93], v[88:89] op_sel_hi:[0,1,1] neg_hi:[1,0,0]
	v_pk_mul_f32 v[88:89], v[92:93], v[114:115] op_sel:[1,1] op_sel_hi:[1,0] neg_lo:[1,0]
	v_pk_fma_f32 v[92:93], v[92:93], v[114:115], v[88:89] op_sel_hi:[0,1,1]
	s_waitcnt lgkmcnt(3)
	v_pk_mul_f32 v[108:109], v[218:219], v[92:93] op_sel:[1,1] op_sel_hi:[1,0]
	v_pk_fma_f32 v[106:107], v[218:219], v[92:93], v[108:109] op_sel_hi:[0,1,1] neg_hi:[1,0,0]
	v_pk_mul_f32 v[88:89], v[92:93], v[114:115] op_sel:[1,1] op_sel_hi:[1,0] neg_lo:[1,0]
	v_pk_fma_f32 v[92:93], v[92:93], v[114:115], v[88:89] op_sel_hi:[0,1,1]
	v_pk_mul_f32 v[88:89], v[220:221], v[92:93] op_sel:[1,1] op_sel_hi:[1,0]
	v_pk_fma_f32 v[108:109], v[220:221], v[92:93], v[88:89] op_sel_hi:[0,1,1] neg_hi:[1,0,0]
	v_pk_mul_f32 v[88:89], v[92:93], v[114:115] op_sel:[1,1] op_sel_hi:[1,0] neg_lo:[1,0]
	v_pk_fma_f32 v[92:93], v[92:93], v[114:115], v[88:89] op_sel_hi:[0,1,1]
	s_waitcnt lgkmcnt(2)
	v_pk_mul_f32 v[112:113], v[166:167], v[92:93] op_sel:[1,1] op_sel_hi:[1,0]
	v_pk_fma_f32 v[110:111], v[166:167], v[92:93], v[112:113] op_sel_hi:[0,1,1] neg_hi:[1,0,0]
	v_pk_mul_f32 v[88:89], v[92:93], v[114:115] op_sel:[1,1] op_sel_hi:[1,0] neg_lo:[1,0]
	v_pk_fma_f32 v[92:93], v[92:93], v[114:115], v[88:89] op_sel_hi:[0,1,1]
	v_pk_mul_f32 v[88:89], v[168:169], v[92:93] op_sel:[1,1] op_sel_hi:[1,0]
	v_pk_fma_f32 v[112:113], v[168:169], v[92:93], v[88:89] op_sel_hi:[0,1,1] neg_hi:[1,0,0]
	v_pk_mul_f32 v[88:89], v[92:93], v[114:115] op_sel:[1,1] op_sel_hi:[1,0] neg_lo:[1,0]
	v_pk_fma_f32 v[92:93], v[92:93], v[114:115], v[88:89] op_sel_hi:[0,1,1]
	s_waitcnt lgkmcnt(1)
	v_pk_mul_f32 v[116:117], v[170:171], v[92:93] op_sel:[1,1] op_sel_hi:[1,0]
	v_pk_fma_f32 v[0:1], v[170:171], v[92:93], v[116:117] op_sel_hi:[0,1,1] neg_hi:[1,0,0]
	v_pk_mul_f32 v[88:89], v[92:93], v[114:115] op_sel:[1,1] op_sel_hi:[1,0] neg_lo:[1,0]
	v_pk_fma_f32 v[92:93], v[92:93], v[114:115], v[88:89] op_sel_hi:[0,1,1]
	v_pk_mul_f32 v[88:89], v[172:173], v[92:93] op_sel:[1,1] op_sel_hi:[1,0]
	v_pk_fma_f32 v[116:117], v[172:173], v[92:93], v[88:89] op_sel_hi:[0,1,1] neg_hi:[1,0,0]
	v_pk_mul_f32 v[88:89], v[92:93], v[114:115] op_sel:[1,1] op_sel_hi:[1,0] neg_lo:[1,0]
	v_pk_fma_f32 v[118:119], v[92:93], v[114:115], v[88:89] op_sel_hi:[0,1,1]
	v_add_u32_e32 v88, 0xc00, v74
	v_pk_mul_f32 v[120:121], v[118:119], v[114:115] op_sel:[1,1] op_sel_hi:[1,0] neg_lo:[1,0]
	v_pk_fma_f32 v[114:115], v[118:119], v[114:115], v[120:121] op_sel_hi:[0,1,1]
	s_waitcnt lgkmcnt(0)
; template <int R, bool INV> DEV void dft_regs(cf (&v)[R]) {
;     ...
;     for (int s = R; s >= 2; s >>= 1) {
;         const int h = s >> 1;
; #pragma unroll
;         for (int b = 0; b < R; b += s) {
; #pragma unroll
;             for (int k = 0; k < h; ++k) {
;                 const cf a = v[b + k], c = v[b + k + h];
;                 v[b + k] = a + c;
;                 const cf d = a - c;
;                 const int m = k * (32 / s);
;                 const float wr = tw_cos(m), wi = INV ? tw_sin(m) : -tw_sin(m);
;                 v[b + k + h] = cf{d.x * wr - d.y * wi, d.x * wi + d.y * wr};
;             }
;         }
;     }
; DEV void fft_i2(LAS cf* buf, int t8) {
;     ...
;     dft_regs<32, true>(v);
	v_pk_mul_f32 v[120:121], v[174:175], v[118:119] op_sel:[1,1] op_sel_hi:[1,0]
	v_pk_fma_f32 v[90:91], v[174:175], v[118:119], v[120:121] op_sel_hi:[0,1,1] neg_hi:[1,0,0]
	v_pk_mul_f32 v[118:119], v[176:177], v[114:115] op_sel:[1,1] op_sel_hi:[1,0]
	v_pk_fma_f32 v[114:115], v[176:177], v[114:115], v[118:119] op_sel_hi:[0,1,1] neg_hi:[1,0,0]
	v_pk_add_f32 v[92:93], v[4:5], v[84:85]
	v_pk_add_f32 v[4:5], v[4:5], v[84:85] neg_lo:[0,1] neg_hi:[0,1]
	v_mov_b32_e32 v118, v4
	v_mov_b32_e32 v119, v5
	v_pk_add_f32 v[4:5], v[2:3], v[82:83]
	v_pk_add_f32 v[2:3], v[2:3], v[82:83] neg_lo:[0,1] neg_hi:[0,1]
	v_pk_mul_f32 v[82:83], v[2:3], s[82:83] op_sel_hi:[1,0]
	v_pk_fma_f32 v[84:85], v[2:3], s[94:95], v[82:83] op_sel:[0,0,1] op_sel_hi:[1,0,0] neg_lo:[0,0,1]
	v_pk_add_f32 v[2:3], v[10:11], v[94:95]
	v_pk_add_f32 v[10:11], v[10:11], v[94:95] neg_lo:[0,1] neg_hi:[0,1]
	v_pk_mul_f32 v[82:83], v[10:11], s[84:85] op_sel_hi:[1,0]
	v_pk_fma_f32 v[94:95], v[10:11], s[16:17], v[82:83] op_sel:[0,0,1] op_sel_hi:[1,0,0] neg_lo:[0,0,1]
	v_pk_add_f32 v[10:11], v[6:7], v[96:97]
	v_pk_add_f32 v[6:7], v[6:7], v[96:97] neg_lo:[0,1] neg_hi:[0,1]
	v_pk_mul_f32 v[82:83], v[6:7], s[4:5] op_sel_hi:[1,0]
	v_pk_fma_f32 v[96:97], v[6:7], s[86:87], v[82:83] op_sel:[0,0,1] op_sel_hi:[1,0,0] neg_lo:[0,0,1]
	v_pk_add_f32 v[6:7], v[12:13], v[98:99]
	v_pk_add_f32 v[12:13], v[12:13], v[98:99] neg_lo:[0,1] neg_hi:[0,1]
	v_pk_mul_f32 v[82:83], v[12:13], s[18:19] op_sel_hi:[1,0]
	v_pk_fma_f32 v[98:99], v[12:13], s[18:19], v[82:83] op_sel:[0,0,1] op_sel_hi:[1,0,0] neg_lo:[0,0,1]
	v_pk_add_f32 v[12:13], v[8:9], v[100:101]
	v_pk_add_f32 v[8:9], v[8:9], v[100:101] neg_lo:[0,1] neg_hi:[0,1]
	v_pk_mul_f32 v[82:83], v[8:9], s[86:87] op_sel_hi:[1,0]
	v_pk_fma_f32 v[100:101], v[8:9], s[4:5], v[82:83] op_sel:[0,0,1] op_sel_hi:[1,0,0] neg_lo:[0,0,1]
	v_pk_add_f32 v[8:9], v[16:17], v[102:103]
	v_pk_add_f32 v[16:17], v[16:17], v[102:103] neg_lo:[0,1] neg_hi:[0,1]
	v_pk_mul_f32 v[82:83], v[16:17], s[16:17] op_sel_hi:[1,0]
	v_pk_fma_f32 v[102:103], v[16:17], s[84:85], v[82:83] op_sel:[0,0,1] op_sel_hi:[1,0,0] neg_lo:[0,0,1]
	v_pk_add_f32 v[16:17], v[14:15], v[104:105]
	v_pk_add_f32 v[14:15], v[14:15], v[104:105] neg_lo:[0,1] neg_hi:[0,1]
	v_pk_mul_f32 v[82:83], v[14:15], s[94:95] op_sel_hi:[1,0]
	v_pk_fma_f32 v[104:105], v[14:15], s[82:83], v[82:83] op_sel:[0,0,1] op_sel_hi:[1,0,0] neg_lo:[0,0,1]
	v_pk_add_f32 v[14:15], v[68:69], v[106:107]
	v_pk_add_f32 v[68:69], v[68:69], v[106:107] neg_lo:[0,1] neg_hi:[0,1]
	v_pk_add_f32 v[82:83], v[68:69], 0 op_sel:[1,0] op_sel_hi:[0,0] neg_lo:[1,0]
	v_pk_add_f32 v[68:69], v[18:19], v[108:109]
	v_pk_add_f32 v[18:19], v[18:19], v[108:109] neg_lo:[0,1] neg_hi:[0,1]
	v_pk_mul_f32 v[106:107], v[18:19], s[6:7] op_sel:[1,0]
	s_mov_b32 s6, s87
	v_pk_fma_f32 v[18:19], v[18:19], s[28:29], v[106:107] op_sel_hi:[0,1,1] neg_lo:[0,0,1] neg_hi:[0,0,1]
	v_pk_add_f32 v[106:107], v[72:73], v[110:111]
	v_pk_add_f32 v[72:73], v[72:73], v[110:111] neg_lo:[0,1] neg_hi:[0,1]
	s_mov_b32 s7, s86
	v_pk_mul_f32 v[108:109], v[72:73], s[24:25] op_sel:[1,0]
	v_pk_fma_f32 v[72:73], v[72:73], s[0:1], v[108:109] op_sel_hi:[0,1,1] neg_lo:[0,0,1] neg_hi:[0,0,1]
	v_pk_add_f32 v[108:109], v[70:71], v[112:113]
	v_pk_add_f32 v[70:71], v[70:71], v[112:113] neg_lo:[0,1] neg_hi:[0,1]
	v_pk_mul_f32 v[110:111], v[70:71], s[2:3] op_sel:[1,0]
	s_mov_b32 s2, s11
	v_pk_fma_f32 v[70:71], v[70:71], s[6:7], v[110:111] op_sel_hi:[0,1,1] neg_lo:[0,0,1] neg_hi:[0,0,1]
	v_pk_add_f32 v[110:111], v[76:77], v[0:1]
	v_pk_add_f32 v[76:77], v[76:77], v[0:1] neg_lo:[0,1] neg_hi:[0,1]
	v_mul_f32_e32 v112, 0x3f3504f3, v77
	v_pk_fma_f32 v[76:77], v[76:77], s[96:97], v[112:113] op_sel_hi:[0,1,0] neg_lo:[0,0,1] neg_hi:[0,0,1]
	v_pk_add_f32 v[112:113], v[86:87], v[116:117]
	v_pk_add_f32 v[86:87], v[86:87], v[116:117] neg_lo:[0,1] neg_hi:[0,1]
	v_pk_mul_f32 v[0:1], v[86:87], s[4:5] op_sel:[1,0]
	s_lshl_b32 s5, s19, 10
	v_pk_fma_f32 v[86:87], v[86:87], s[2:3], v[0:1] op_sel_hi:[0,1,1] neg_lo:[0,0,1] neg_hi:[0,0,1]
	v_pk_add_f32 v[0:1], v[80:81], v[90:91]
	v_pk_add_f32 v[80:81], v[80:81], v[90:91] neg_lo:[0,1] neg_hi:[0,1]
	s_mov_b32 s2, s9
	v_pk_mul_f32 v[90:91], v[80:81], s[84:85] op_sel:[1,0]
	s_mov_b32 s3, s82
	v_pk_fma_f32 v[80:81], v[80:81], s[88:89], v[90:91] op_sel_hi:[0,1,1] neg_lo:[0,0,1] neg_hi:[0,0,1]
	v_pk_add_f32 v[90:91], v[78:79], v[114:115]
	v_pk_add_f32 v[114:115], v[78:79], v[114:115] neg_lo:[0,1] neg_hi:[0,1]
	s_add_i32 s6, s79, s5
	v_pk_mul_f32 v[78:79], v[114:115], s[82:83] op_sel:[1,0]
	s_ashr_i32 s7, s6, 31
	v_pk_fma_f32 v[114:115], v[114:115], s[2:3], v[78:79] op_sel_hi:[0,1,1] neg_lo:[0,0,1] neg_hi:[0,0,1]
	v_pk_add_f32 v[78:79], v[92:93], v[14:15]
	v_pk_add_f32 v[14:15], v[92:93], v[14:15] neg_lo:[0,1] neg_hi:[0,1]
	s_lshl_b64 s[2:3], s[6:7], 13
	v_mov_b32_e32 v116, v14
	v_mov_b32_e32 v117, v15
	v_pk_add_f32 v[14:15], v[4:5], v[68:69]
	v_pk_add_f32 v[4:5], v[4:5], v[68:69] neg_lo:[0,1] neg_hi:[0,1]
	v_pk_mul_f32 v[68:69], v[4:5], s[84:85] op_sel_hi:[1,0]
	v_pk_fma_f32 v[92:93], v[4:5], s[16:17], v[68:69] op_sel:[0,0,1] op_sel_hi:[1,0,0] neg_lo:[0,0,1]
	v_pk_add_f32 v[4:5], v[2:3], v[106:107]
	v_pk_add_f32 v[2:3], v[2:3], v[106:107] neg_lo:[0,1] neg_hi:[0,1]
	v_pk_mul_f32 v[68:69], v[2:3], s[18:19] op_sel_hi:[1,0]
	v_pk_fma_f32 v[106:107], v[2:3], s[18:19], v[68:69] op_sel:[0,0,1] op_sel_hi:[1,0,0] neg_lo:[0,0,1]
	v_pk_add_f32 v[2:3], v[10:11], v[108:109]
	v_pk_add_f32 v[10:11], v[10:11], v[108:109] neg_lo:[0,1] neg_hi:[0,1]
	v_pk_mul_f32 v[68:69], v[10:11], s[16:17] op_sel_hi:[1,0]
	v_pk_fma_f32 v[108:109], v[10:11], s[84:85], v[68:69] op_sel:[0,0,1] op_sel_hi:[1,0,0] neg_lo:[0,0,1]
; template <int R, bool INV> DEV void dft_regs(cf (&v)[R]) {
;     ...
;     for (int s = R; s >= 2; s >>= 1) {
;         const int h = s >> 1;
; #pragma unroll
;         for (int b = 0; b < R; b += s) {
; #pragma unroll
;             for (int k = 0; k < h; ++k) {
;                 const cf a = v[b + k], c = v[b + k + h];
;                 v[b + k] = a + c;
;                 const cf d = a - c;
;                 const int m = k * (32 / s);
;                 const float wr = tw_cos(m), wi = INV ? tw_sin(m) : -tw_sin(m);
;                 v[b + k + h] = cf{d.x * wr - d.y * wi, d.x * wi + d.y * wr};
;             }
;         }
;     }
; DEV void fft_i2(LAS cf* buf, int t8) {
;     ...
;     dft_regs<32, true>(v);
	v_pk_add_f32 v[10:11], v[6:7], v[110:111]
	v_pk_add_f32 v[6:7], v[6:7], v[110:111] neg_lo:[0,1] neg_hi:[0,1]
	v_pk_add_f32 v[68:69], v[6:7], 0 op_sel:[1,0] op_sel_hi:[0,0] neg_lo:[1,0]
	v_pk_add_f32 v[6:7], v[12:13], v[112:113]
	v_pk_add_f32 v[12:13], v[12:13], v[112:113] neg_lo:[0,1] neg_hi:[0,1]
	v_pk_mul_f32 v[110:111], v[12:13], s[24:25] op_sel:[1,0]
	v_pk_fma_f32 v[12:13], v[12:13], s[0:1], v[110:111] op_sel_hi:[0,1,1] neg_lo:[0,0,1] neg_hi:[0,0,1]
	v_pk_add_f32 v[110:111], v[8:9], v[0:1]
	v_pk_add_f32 v[8:9], v[8:9], v[0:1] neg_lo:[0,1] neg_hi:[0,1]
	v_mul_f32_e32 v112, 0x3f3504f3, v9
	v_pk_fma_f32 v[8:9], v[8:9], s[96:97], v[112:113] op_sel_hi:[0,1,0] neg_lo:[0,0,1] neg_hi:[0,0,1]
	v_pk_add_f32 v[112:113], v[16:17], v[90:91]
	v_pk_add_f32 v[16:17], v[16:17], v[90:91] neg_lo:[0,1] neg_hi:[0,1]
	v_pk_mul_f32 v[90:91], v[16:17], s[84:85] op_sel:[1,0]
	v_pk_fma_f32 v[16:17], v[16:17], s[88:89], v[90:91] op_sel_hi:[0,1,1] neg_lo:[0,0,1] neg_hi:[0,0,1]
	v_pk_add_f32 v[90:91], v[118:119], v[82:83]
	v_pk_add_f32 v[82:83], v[118:119], v[82:83] neg_lo:[0,1] neg_hi:[0,1]
	v_pk_add_f32 v[118:119], v[84:85], v[18:19]
	v_pk_add_f32 v[18:19], v[84:85], v[18:19] neg_lo:[0,1] neg_hi:[0,1]
	v_pk_mul_f32 v[84:85], v[18:19], s[84:85] op_sel_hi:[1,0]
	v_pk_fma_f32 v[0:1], v[18:19], s[16:17], v[84:85] op_sel:[0,0,1] op_sel_hi:[1,0,0] neg_lo:[0,0,1]
	v_pk_add_f32 v[18:19], v[94:95], v[72:73]
	v_pk_add_f32 v[72:73], v[94:95], v[72:73] neg_lo:[0,1] neg_hi:[0,1]
	v_pk_mul_f32 v[84:85], v[72:73], s[18:19] op_sel_hi:[1,0]
	v_pk_fma_f32 v[94:95], v[72:73], s[18:19], v[84:85] op_sel:[0,0,1] op_sel_hi:[1,0,0] neg_lo:[0,0,1]
	v_pk_add_f32 v[72:73], v[96:97], v[70:71]
	v_pk_add_f32 v[70:71], v[96:97], v[70:71] neg_lo:[0,1] neg_hi:[0,1]
	v_pk_mul_f32 v[84:85], v[70:71], s[16:17] op_sel_hi:[1,0]
	v_pk_fma_f32 v[96:97], v[70:71], s[84:85], v[84:85] op_sel:[0,0,1] op_sel_hi:[1,0,0] neg_lo:[0,0,1]
	v_pk_add_f32 v[70:71], v[98:99], v[76:77]
	v_pk_add_f32 v[76:77], v[98:99], v[76:77] neg_lo:[0,1] neg_hi:[0,1]
	v_pk_add_f32 v[84:85], v[76:77], 0 op_sel:[1,0] op_sel_hi:[0,0] neg_lo:[1,0]
	v_pk_add_f32 v[76:77], v[100:101], v[86:87]
	v_pk_add_f32 v[86:87], v[100:101], v[86:87] neg_lo:[0,1] neg_hi:[0,1]
	v_pk_mul_f32 v[98:99], v[86:87], s[24:25] op_sel:[1,0]
	v_pk_fma_f32 v[86:87], v[86:87], s[0:1], v[98:99] op_sel_hi:[0,1,1] neg_lo:[0,0,1] neg_hi:[0,0,1]
	v_pk_add_f32 v[98:99], v[102:103], v[80:81]
	v_pk_add_f32 v[80:81], v[102:103], v[80:81] neg_lo:[0,1] neg_hi:[0,1]
	v_mul_f32_e32 v100, 0x3f3504f3, v81
	v_pk_fma_f32 v[80:81], v[80:81], s[96:97], v[100:101] op_sel_hi:[0,1,0] neg_lo:[0,0,1] neg_hi:[0,0,1]
	v_pk_add_f32 v[100:101], v[104:105], v[114:115]
	v_pk_add_f32 v[114:115], v[104:105], v[114:115] neg_lo:[0,1] neg_hi:[0,1]
	v_pk_mul_f32 v[102:103], v[114:115], s[84:85] op_sel:[1,0]
	v_pk_fma_f32 v[114:115], v[114:115], s[88:89], v[102:103] op_sel_hi:[0,1,1] neg_lo:[0,0,1] neg_hi:[0,0,1]
	v_pk_add_f32 v[102:103], v[78:79], v[10:11]
	v_pk_add_f32 v[10:11], v[78:79], v[10:11] neg_lo:[0,1] neg_hi:[0,1]
	v_mov_b32_e32 v104, v10
	v_mov_b32_e32 v105, v11
	v_pk_add_f32 v[10:11], v[14:15], v[6:7]
	v_pk_add_f32 v[6:7], v[14:15], v[6:7] neg_lo:[0,1] neg_hi:[0,1]
	v_pk_mul_f32 v[14:15], v[6:7], s[18:19] op_sel_hi:[1,0]
	v_pk_fma_f32 v[78:79], v[6:7], s[18:19], v[14:15] op_sel:[0,0,1] op_sel_hi:[1,0,0] neg_lo:[0,0,1]
	v_pk_add_f32 v[6:7], v[4:5], v[110:111]
	v_pk_add_f32 v[4:5], v[4:5], v[110:111] neg_lo:[0,1] neg_hi:[0,1]
	v_pk_add_f32 v[14:15], v[4:5], 0 op_sel:[1,0] op_sel_hi:[0,0] neg_lo:[1,0]
	v_pk_add_f32 v[4:5], v[2:3], v[112:113]
	v_pk_add_f32 v[2:3], v[2:3], v[112:113] neg_lo:[0,1] neg_hi:[0,1]
	v_mul_f32_e32 v110, 0x3f3504f3, v3
	v_pk_fma_f32 v[2:3], v[2:3], s[96:97], v[110:111] op_sel_hi:[0,1,0] neg_lo:[0,0,1] neg_hi:[0,0,1]
	v_pk_add_f32 v[110:111], v[116:117], v[68:69]
	v_pk_add_f32 v[68:69], v[116:117], v[68:69] neg_lo:[0,1] neg_hi:[0,1]
	v_pk_add_f32 v[116:117], v[92:93], v[12:13]
	v_pk_add_f32 v[12:13], v[92:93], v[12:13] neg_lo:[0,1] neg_hi:[0,1]
	v_pk_mul_f32 v[92:93], v[12:13], s[18:19] op_sel_hi:[1,0]
	v_pk_fma_f32 v[112:113], v[12:13], s[18:19], v[92:93] op_sel:[0,0,1] op_sel_hi:[1,0,0] neg_lo:[0,0,1]
	v_pk_add_f32 v[12:13], v[106:107], v[8:9]
	v_pk_add_f32 v[8:9], v[106:107], v[8:9] neg_lo:[0,1] neg_hi:[0,1]
	v_pk_add_f32 v[92:93], v[8:9], 0 op_sel:[1,0] op_sel_hi:[0,0] neg_lo:[1,0]
	v_pk_add_f32 v[8:9], v[108:109], v[16:17]
	v_pk_add_f32 v[16:17], v[108:109], v[16:17] neg_lo:[0,1] neg_hi:[0,1]
	v_mul_f32_e32 v106, 0x3f3504f3, v17
	v_pk_fma_f32 v[16:17], v[16:17], s[96:97], v[106:107] op_sel_hi:[0,1,0] neg_lo:[0,0,1] neg_hi:[0,0,1]
	v_pk_add_f32 v[106:107], v[90:91], v[70:71]
	v_pk_add_f32 v[70:71], v[90:91], v[70:71] neg_lo:[0,1] neg_hi:[0,1]
	v_pk_add_f32 v[108:109], v[118:119], v[76:77]
	v_pk_add_f32 v[76:77], v[118:119], v[76:77] neg_lo:[0,1] neg_hi:[0,1]
	v_pk_mul_f32 v[118:119], v[76:77], s[18:19] op_sel_hi:[1,0]
	v_pk_fma_f32 v[90:91], v[76:77], s[18:19], v[118:119] op_sel:[0,0,1] op_sel_hi:[1,0,0] neg_lo:[0,0,1]
	v_pk_add_f32 v[76:77], v[18:19], v[98:99]
	v_pk_add_f32 v[18:19], v[18:19], v[98:99] neg_lo:[0,1] neg_hi:[0,1]
	v_pk_add_f32 v[118:119], v[18:19], 0 op_sel:[1,0] op_sel_hi:[0,0] neg_lo:[1,0]
	v_pk_add_f32 v[18:19], v[72:73], v[100:101]
	v_pk_add_f32 v[72:73], v[72:73], v[100:101] neg_lo:[0,1] neg_hi:[0,1]
	v_mul_f32_e32 v98, 0x3f3504f3, v73
	v_pk_fma_f32 v[72:73], v[72:73], s[96:97], v[98:99] op_sel_hi:[0,1,0] neg_lo:[0,0,1] neg_hi:[0,0,1]
	v_pk_add_f32 v[98:99], v[82:83], v[84:85]
	v_pk_add_f32 v[84:85], v[82:83], v[84:85] neg_lo:[0,1] neg_hi:[0,1]
	v_pk_add_f32 v[82:83], v[0:1], v[86:87]
	v_pk_add_f32 v[86:87], v[0:1], v[86:87] neg_lo:[0,1] neg_hi:[0,1]
; template <int R, bool INV> DEV void dft_regs(cf (&v)[R]) {
;     ...
;     for (int s = R; s >= 2; s >>= 1) {
;         const int h = s >> 1;
; #pragma unroll
;         for (int b = 0; b < R; b += s) {
; #pragma unroll
;             for (int k = 0; k < h; ++k) {
;                 const cf a = v[b + k], c = v[b + k + h];
;                 v[b + k] = a + c;
;                 const cf d = a - c;
;                 const int m = k * (32 / s);
;                 const float wr = tw_cos(m), wi = INV ? tw_sin(m) : -tw_sin(m);
;                 v[b + k + h] = cf{d.x * wr - d.y * wi, d.x * wi + d.y * wr};
;             }
;         }
;     }
; DEV void fft_i2(LAS cf* buf, int t8) {
;     ...
;     dft_regs<32, true>(v);
; #pragma unroll
;     for (int q = 0; q < 32; ++q) pb[17 * q] = v[BR32[q]];
	v_pk_mul_f32 v[100:101], v[86:87], s[18:19] op_sel_hi:[1,0]
	v_pk_fma_f32 v[0:1], v[86:87], s[18:19], v[100:101] op_sel:[0,0,1] op_sel_hi:[1,0,0] neg_lo:[0,0,1]
	v_pk_add_f32 v[86:87], v[94:95], v[80:81]
	v_pk_add_f32 v[80:81], v[94:95], v[80:81] neg_lo:[0,1] neg_hi:[0,1]
	v_pk_add_f32 v[94:95], v[80:81], 0 op_sel:[1,0] op_sel_hi:[0,0] neg_lo:[1,0]
	v_pk_add_f32 v[80:81], v[96:97], v[114:115]
	v_pk_add_f32 v[114:115], v[96:97], v[114:115] neg_lo:[0,1] neg_hi:[0,1]
	v_mul_f32_e32 v96, 0x3f3504f3, v115
	v_pk_fma_f32 v[114:115], v[114:115], s[96:97], v[96:97] op_sel_hi:[0,1,0] neg_lo:[0,0,1] neg_hi:[0,0,1]
	v_pk_add_f32 v[96:97], v[102:103], v[6:7]
	v_pk_add_f32 v[6:7], v[102:103], v[6:7] neg_lo:[0,1] neg_hi:[0,1]
	v_mov_b32_e32 v102, v6
	v_mov_b32_e32 v103, v7
	v_pk_add_f32 v[6:7], v[10:11], v[4:5]
	v_pk_add_f32 v[4:5], v[10:11], v[4:5] neg_lo:[0,1] neg_hi:[0,1]
	v_pk_add_f32 v[10:11], v[4:5], 0 op_sel:[1,0] op_sel_hi:[0,0] neg_lo:[1,0]
	v_pk_add_f32 v[4:5], v[104:105], v[14:15]
	v_pk_add_f32 v[14:15], v[104:105], v[14:15] neg_lo:[0,1] neg_hi:[0,1]
	v_mov_b32_e32 v104, v14
	v_mov_b32_e32 v105, v15
	v_pk_add_f32 v[14:15], v[78:79], v[2:3]
	v_pk_add_f32 v[2:3], v[78:79], v[2:3] neg_lo:[0,1] neg_hi:[0,1]
	v_pk_add_f32 v[78:79], v[2:3], 0 op_sel:[1,0] op_sel_hi:[0,0] neg_lo:[1,0]
	v_pk_add_f32 v[2:3], v[110:111], v[12:13]
	v_pk_add_f32 v[12:13], v[110:111], v[12:13] neg_lo:[0,1] neg_hi:[0,1]
	v_mov_b32_e32 v110, v12
	v_mov_b32_e32 v111, v13
	v_pk_add_f32 v[12:13], v[116:117], v[8:9]
	v_pk_add_f32 v[8:9], v[116:117], v[8:9] neg_lo:[0,1] neg_hi:[0,1]
	v_pk_add_f32 v[116:117], v[8:9], 0 op_sel:[1,0] op_sel_hi:[0,0] neg_lo:[1,0]
	v_pk_add_f32 v[8:9], v[68:69], v[92:93]
	v_pk_add_f32 v[92:93], v[68:69], v[92:93] neg_lo:[0,1] neg_hi:[0,1]
	v_mov_b32_e32 v68, v92
	v_mov_b32_e32 v69, v93
	v_pk_add_f32 v[92:93], v[112:113], v[16:17]
	v_pk_add_f32 v[16:17], v[112:113], v[16:17] neg_lo:[0,1] neg_hi:[0,1]
	v_pk_add_f32 v[100:101], v[16:17], 0 op_sel:[1,0] op_sel_hi:[0,0] neg_lo:[1,0]
	v_pk_add_f32 v[16:17], v[106:107], v[76:77]
	v_pk_add_f32 v[76:77], v[106:107], v[76:77] neg_lo:[0,1] neg_hi:[0,1]
	v_pk_add_f32 v[112:113], v[108:109], v[18:19]
	v_pk_add_f32 v[18:19], v[108:109], v[18:19] neg_lo:[0,1] neg_hi:[0,1]
	v_pk_add_f32 v[108:109], v[18:19], 0 op_sel:[1,0] op_sel_hi:[0,0] neg_lo:[1,0]
	v_pk_add_f32 v[18:19], v[70:71], v[118:119]
	v_pk_add_f32 v[118:119], v[70:71], v[118:119] neg_lo:[0,1] neg_hi:[0,1]
	v_pk_add_f32 v[70:71], v[90:91], v[72:73]
	v_pk_add_f32 v[72:73], v[90:91], v[72:73] neg_lo:[0,1] neg_hi:[0,1]
	v_pk_add_f32 v[90:91], v[72:73], 0 op_sel:[1,0] op_sel_hi:[0,0] neg_lo:[1,0]
	v_pk_add_f32 v[72:73], v[98:99], v[86:87]
	v_pk_add_f32 v[86:87], v[98:99], v[86:87] neg_lo:[0,1] neg_hi:[0,1]
	v_pk_add_f32 v[106:107], v[82:83], v[80:81]
	v_pk_add_f32 v[80:81], v[82:83], v[80:81] neg_lo:[0,1] neg_hi:[0,1]
	v_pk_add_f32 v[82:83], v[80:81], 0 op_sel:[1,0] op_sel_hi:[0,0] neg_lo:[1,0]
	v_pk_add_f32 v[80:81], v[84:85], v[94:95]
	v_pk_add_f32 v[94:95], v[84:85], v[94:95] neg_lo:[0,1] neg_hi:[0,1]
	v_pk_add_f32 v[84:85], v[0:1], v[114:115]
	v_pk_add_f32 v[114:115], v[0:1], v[114:115] neg_lo:[0,1] neg_hi:[0,1]
	v_pk_add_f32 v[98:99], v[114:115], 0 op_sel:[1,0] op_sel_hi:[0,0] neg_lo:[1,0]
	v_pk_add_f32 v[0:1], v[96:97], v[6:7]
	v_pk_add_f32 v[6:7], v[96:97], v[6:7] neg_lo:[0,1] neg_hi:[0,1]
	v_mov_b32_e32 v114, v6
	v_mov_b32_e32 v115, v7
	v_pk_add_f32 v[6:7], v[102:103], v[10:11]
	v_pk_add_f32 v[10:11], v[102:103], v[10:11] neg_lo:[0,1] neg_hi:[0,1]
	v_mov_b32_e32 v102, v10
	v_mov_b32_e32 v103, v11
	v_pk_add_f32 v[10:11], v[4:5], v[14:15]
	v_pk_add_f32 v[4:5], v[4:5], v[14:15] neg_lo:[0,1] neg_hi:[0,1]
	v_mov_b32_e32 v96, v4
	v_mov_b32_e32 v97, v5
	v_pk_add_f32 v[14:15], v[104:105], v[78:79] neg_lo:[0,1] neg_hi:[0,1]
	v_pk_add_f32 v[4:5], v[104:105], v[78:79]
	v_mov_b32_e32 v104, v14
	v_mov_b32_e32 v105, v15
	v_pk_add_f32 v[14:15], v[2:3], v[12:13]
	v_pk_add_f32 v[2:3], v[2:3], v[12:13] neg_lo:[0,1] neg_hi:[0,1]
	v_mov_b32_e32 v78, v2
	v_mov_b32_e32 v79, v3
	v_pk_add_f32 v[12:13], v[110:111], v[116:117] neg_lo:[0,1] neg_hi:[0,1]
	v_pk_add_f32 v[2:3], v[110:111], v[116:117]
	v_mov_b32_e32 v110, v12
	v_mov_b32_e32 v111, v13
	v_pk_add_f32 v[12:13], v[8:9], v[92:93]
	v_pk_add_f32 v[8:9], v[8:9], v[92:93] neg_lo:[0,1] neg_hi:[0,1]
	v_mov_b32_e32 v92, v8
	v_mov_b32_e32 v93, v9
	v_pk_add_f32 v[116:117], v[68:69], v[100:101] neg_lo:[0,1] neg_hi:[0,1]
	v_pk_add_f32 v[8:9], v[68:69], v[100:101]
	v_pk_add_f32 v[68:69], v[16:17], v[112:113]
	v_pk_add_f32 v[16:17], v[16:17], v[112:113] neg_lo:[0,1] neg_hi:[0,1]
	v_pk_add_f32 v[100:101], v[76:77], v[108:109]
	v_pk_add_f32 v[108:109], v[76:77], v[108:109] neg_lo:[0,1] neg_hi:[0,1]
	v_pk_add_f32 v[76:77], v[18:19], v[70:71]
	v_pk_add_f32 v[18:19], v[18:19], v[70:71] neg_lo:[0,1] neg_hi:[0,1]
	v_pk_add_f32 v[112:113], v[118:119], v[90:91] neg_lo:[0,1] neg_hi:[0,1]
	v_pk_add_f32 v[70:71], v[118:119], v[90:91]
	v_pk_add_f32 v[118:119], v[72:73], v[106:107]
	v_pk_add_f32 v[72:73], v[72:73], v[106:107] neg_lo:[0,1] neg_hi:[0,1]
	v_pk_add_f32 v[106:107], v[86:87], v[82:83] neg_lo:[0,1] neg_hi:[0,1]
	v_pk_add_f32 v[90:91], v[86:87], v[82:83]
	v_pk_add_f32 v[86:87], v[80:81], v[84:85]
	v_pk_add_f32 v[80:81], v[80:81], v[84:85] neg_lo:[0,1] neg_hi:[0,1]
	v_pk_add_f32 v[82:83], v[94:95], v[98:99] neg_lo:[0,1] neg_hi:[0,1]
	v_pk_add_f32 v[84:85], v[94:95], v[98:99]
	v_mov_b32_e32 v94, v82
	v_mov_b32_e32 v95, v83
	ds_write2_b64 v74, v[0:1], v[68:69] offset1:17
	ds_write2_b64 v74, v[14:15], v[118:119] offset0:34 offset1:51
	ds_write2_b64 v74, v[10:11], v[76:77] offset0:68 offset1:85
	ds_write2_b64 v74, v[12:13], v[86:87] offset0:102 offset1:119
	ds_write2_b64 v74, v[6:7], v[100:101] offset0:136 offset1:153
	ds_write2_b64 v74, v[2:3], v[90:91] offset0:170 offset1:187
	ds_write2_b64 v74, v[4:5], v[70:71] offset0:204 offset1:221
	ds_write2_b64 v74, v[8:9], v[84:85] offset0:238 offset1:255
	ds_write2_b64 v75, v[114:115], v[16:17] offset0:16 offset1:33
	ds_write2_b64 v75, v[78:79], v[72:73] offset0:50 offset1:67
	ds_write2_b64 v75, v[96:97], v[18:19] offset0:84 offset1:101
	ds_write2_b64 v75, v[92:93], v[80:81] offset0:118 offset1:135
	ds_write2_b64 v75, v[102:103], v[108:109] offset0:152 offset1:169
	ds_write2_b64 v75, v[110:111], v[106:107] offset0:186 offset1:203
	ds_write2_b64 v75, v[104:105], v[112:113] offset0:220 offset1:237
	ds_write2_b64 v88, v[116:117], v[94:95] offset0:126 offset1:143
	s_mov_b32 s2, 0x1800000
	s_mov_b32 s2, 0x3000000
	s_nop 0
	s_mov_b32 s2, 0x4800000
	s_nop 0
	s_waitcnt lgkmcnt(0)
	s_barrier
; #define LAS __attribute__((address_space(3)))
; #define SINCOSPI(x, s, c) do { const float hx_ = 0.5f * (x); *(s) = __builtin_amdgcn_sinf(hx_); *(c) = __builtin_amdgcn_cosf(hx_); } while (0)
; #define OPAQUE_I(x) asm volatile("" : "+v"(x))
; DEV void fft_i1x2(LAS cf* buf0, LAS cf* buf1, cf (&y0)[8], cf (&y1)[8], int tid) {
;     OPAQUE_I(tid);
;     float sn, cs; SINCOSPI(-(float)tid * (2.0f / 8192.0f), &sn, &cs);
;     const cf w = cf{cs, sn}; cf wp = cf{1.f, 0.f};
;     cf v[16], u[16];
;     const LAS cf* p0 = buf0 + PADI(tid); const LAS cf* p1 = buf1 + PADI(tid);
; #pragma unroll
;     for (int p = 0; p < 16; ++p) { v[p] = cmulc(p0[544 * p], wp); u[p] = cmulc(p1[544 * p], wp); wp = cmul(wp, w); }
	s_nop 0
	v_mov_b32_e32 v100, v21
	s_andn2_b64 vcc, exec, s[26:27]
	v_cvt_f32_i32_e32 v101, v100
	v_mul_f32_e32 v101, 0xb9800000, v101
	v_mul_f32_e32 v101, 0.5, v101
	v_sin_f32_e32 v93, v101
	v_cos_f32_e32 v92, v101
	v_ashrrev_i32_e32 v101, 4, v100
	v_add_lshl_u32 v100, v101, v100, 3
	v_add_u32_e32 v163, 0, v100
	v_add_u32_e32 v164, s33, v100
	ds_read_b64 v[166:167], v163
	ds_read_b64 v[168:169], v164
	ds_read_b64 v[170:171], v163 offset:4352
	ds_read_b64 v[172:173], v164 offset:4352
	ds_read_b64 v[174:175], v163 offset:8704
	ds_read_b64 v[176:177], v164 offset:8704
	ds_read_b64 v[178:179], v163 offset:13056
	ds_read_b64 v[180:181], v164 offset:13056
	ds_read_b64 v[182:183], v163 offset:17408
	ds_read_b64 v[184:185], v164 offset:17408
	ds_read_b64 v[186:187], v163 offset:21760
	ds_read_b64 v[188:189], v164 offset:21760
	ds_read_b64 v[190:191], v163 offset:26112
	s_waitcnt lgkmcnt(12)
	v_pk_mul_f32 v[18:19], v[166:167], v[66:67] op_sel:[1,1] op_sel_hi:[1,0]
	v_pk_fma_f32 v[76:77], v[166:167], v[66:67], v[18:19] op_sel_hi:[0,1,1] neg_hi:[1,0,0]
	ds_read_b64 v[166:167], v164 offset:26112
	s_waitcnt lgkmcnt(12)
	v_pk_mul_f32 v[18:19], v[168:169], v[66:67] op_sel:[1,1] op_sel_hi:[1,0]
	v_pk_fma_f32 v[16:17], v[168:169], v[66:67], v[18:19] op_sel_hi:[0,1,1] neg_hi:[1,0,0]
	v_pk_mul_f32 v[18:19], v[66:67], v[92:93] op_sel:[1,1] op_sel_hi:[1,0] neg_lo:[1,0]
	v_pk_fma_f32 v[66:67], v[66:67], v[92:93], v[18:19] op_sel_hi:[0,1,1]
	ds_read_b64 v[168:169], v163 offset:30464
	s_waitcnt lgkmcnt(12)
	v_pk_mul_f32 v[68:69], v[170:171], v[66:67] op_sel:[1,1] op_sel_hi:[1,0]
	v_pk_fma_f32 v[78:79], v[170:171], v[66:67], v[68:69] op_sel_hi:[0,1,1] neg_hi:[1,0,0]
	ds_read_b64 v[170:171], v164 offset:30464
	s_waitcnt lgkmcnt(12)
	v_pk_mul_f32 v[68:69], v[172:173], v[66:67] op_sel:[1,1] op_sel_hi:[1,0]
	v_pk_fma_f32 v[18:19], v[172:173], v[66:67], v[68:69] op_sel_hi:[0,1,1] neg_hi:[1,0,0]
	v_pk_mul_f32 v[68:69], v[66:67], v[92:93] op_sel:[1,1] op_sel_hi:[1,0] neg_lo:[1,0]
	v_pk_fma_f32 v[70:71], v[66:67], v[92:93], v[68:69] op_sel_hi:[0,1,1]
	ds_read_b64 v[172:173], v163 offset:34816
	s_waitcnt lgkmcnt(12)
	v_pk_mul_f32 v[68:69], v[174:175], v[70:71] op_sel:[1,1] op_sel_hi:[1,0]
	v_pk_fma_f32 v[82:83], v[174:175], v[70:71], v[68:69] op_sel_hi:[0,1,1] neg_hi:[1,0,0]
	ds_read_b64 v[174:175], v164 offset:34816
	s_waitcnt lgkmcnt(12)
	v_pk_mul_f32 v[68:69], v[176:177], v[70:71] op_sel:[1,1] op_sel_hi:[1,0]
	v_pk_fma_f32 v[66:67], v[176:177], v[70:71], v[68:69] op_sel_hi:[0,1,1] neg_hi:[1,0,0]
	v_pk_mul_f32 v[68:69], v[70:71], v[92:93] op_sel:[1,1] op_sel_hi:[1,0] neg_lo:[1,0]
	v_pk_fma_f32 v[70:71], v[70:71], v[92:93], v[68:69] op_sel_hi:[0,1,1]
	ds_read_b64 v[176:177], v163 offset:39168
	s_waitcnt lgkmcnt(12)
	v_pk_mul_f32 v[72:73], v[178:179], v[70:71] op_sel:[1,1] op_sel_hi:[1,0]
	v_pk_fma_f32 v[84:85], v[178:179], v[70:71], v[72:73] op_sel_hi:[0,1,1] neg_hi:[1,0,0]
	ds_read_b64 v[178:179], v164 offset:39168
	s_waitcnt lgkmcnt(12)
	v_pk_mul_f32 v[72:73], v[180:181], v[70:71] op_sel:[1,1] op_sel_hi:[1,0]
	v_pk_fma_f32 v[68:69], v[180:181], v[70:71], v[72:73] op_sel_hi:[0,1,1] neg_hi:[1,0,0]
	v_pk_mul_f32 v[72:73], v[70:71], v[92:93] op_sel:[1,1] op_sel_hi:[1,0] neg_lo:[1,0]
	v_pk_fma_f32 v[74:75], v[70:71], v[92:93], v[72:73] op_sel_hi:[0,1,1]
	ds_read_b64 v[180:181], v163 offset:43520
	s_waitcnt lgkmcnt(12)
	v_pk_mul_f32 v[72:73], v[182:183], v[74:75] op_sel:[1,1] op_sel_hi:[1,0]
	v_pk_fma_f32 v[86:87], v[182:183], v[74:75], v[72:73] op_sel_hi:[0,1,1] neg_hi:[1,0,0]
	ds_read_b64 v[182:183], v164 offset:43520
	s_waitcnt lgkmcnt(12)
	v_pk_mul_f32 v[72:73], v[184:185], v[74:75] op_sel:[1,1] op_sel_hi:[1,0]
	v_pk_fma_f32 v[70:71], v[184:185], v[74:75], v[72:73] op_sel_hi:[0,1,1] neg_hi:[1,0,0]
	v_pk_mul_f32 v[72:73], v[74:75], v[92:93] op_sel:[1,1] op_sel_hi:[1,0] neg_lo:[1,0]
	v_pk_fma_f32 v[74:75], v[74:75], v[92:93], v[72:73] op_sel_hi:[0,1,1]
	ds_read_b64 v[184:185], v163 offset:47872
	s_waitcnt lgkmcnt(12)
	v_pk_mul_f32 v[80:81], v[186:187], v[74:75] op_sel:[1,1] op_sel_hi:[1,0]
	v_pk_fma_f32 v[90:91], v[186:187], v[74:75], v[80:81] op_sel_hi:[0,1,1] neg_hi:[1,0,0]
	ds_read_b64 v[186:187], v164 offset:47872
	s_waitcnt lgkmcnt(12)
	v_pk_mul_f32 v[80:81], v[188:189], v[74:75] op_sel:[1,1] op_sel_hi:[1,0]
	v_pk_fma_f32 v[72:73], v[188:189], v[74:75], v[80:81] op_sel_hi:[0,1,1] neg_hi:[1,0,0]
	v_pk_mul_f32 v[80:81], v[74:75], v[92:93] op_sel:[1,1] op_sel_hi:[1,0] neg_lo:[1,0]
	v_pk_fma_f32 v[88:89], v[74:75], v[92:93], v[80:81] op_sel_hi:[0,1,1]
	ds_read_b64 v[188:189], v163 offset:52224
	s_waitcnt lgkmcnt(12)
	v_pk_mul_f32 v[80:81], v[190:191], v[88:89] op_sel:[1,1] op_sel_hi:[1,0]
	v_pk_fma_f32 v[94:95], v[190:191], v[88:89], v[80:81] op_sel_hi:[0,1,1] neg_hi:[1,0,0]
	ds_read_b64 v[190:191], v164 offset:52224
	s_waitcnt lgkmcnt(12)
	v_pk_mul_f32 v[80:81], v[166:167], v[88:89] op_sel:[1,1] op_sel_hi:[1,0]
	v_pk_fma_f32 v[74:75], v[166:167], v[88:89], v[80:81] op_sel_hi:[0,1,1] neg_hi:[1,0,0]
	v_pk_mul_f32 v[80:81], v[88:89], v[92:93] op_sel:[1,1] op_sel_hi:[1,0] neg_lo:[1,0]
	v_pk_fma_f32 v[88:89], v[88:89], v[92:93], v[80:81] op_sel_hi:[0,1,1]
	ds_read_b64 v[166:167], v163 offset:56576
	s_waitcnt lgkmcnt(12)
	v_pk_mul_f32 v[96:97], v[168:169], v[88:89] op_sel:[1,1] op_sel_hi:[1,0]
	v_pk_fma_f32 v[98:99], v[168:169], v[88:89], v[96:97] op_sel_hi:[0,1,1] neg_hi:[1,0,0]
	ds_read_b64 v[168:169], v164 offset:56576
	s_waitcnt lgkmcnt(12)
; #define LAS __attribute__((address_space(3)))
; #define SYNC() __syncthreads()
; DEV void fft_i1x2(LAS cf* buf0, LAS cf* buf1, cf (&y0)[8], cf (&y1)[8], int tid) {
;     ...
;     const LAS cf* p0 = buf0 + PADI(tid); const LAS cf* p1 = buf1 + PADI(tid);
; #pragma unroll
;     for (int p = 0; p < 16; ++p) { v[p] = cmulc(p0[544 * p], wp); u[p] = cmulc(p1[544 * p], wp); wp = cmul(wp, w); }
; DEV void hyena_units(int c0, int cstride, const bf16_t* UT, bf16_t* YHT, const unsigned* KF, const float* convw  , const float* convb  , const float* hyb  , LAS unsigned char* lds, int tid, bool abl = false) {
;     ...
;             SYNC();
;             hyena_commit_rows(lds, r, tid);
;             if (o == 1 && c + cstride < 1024) hyena_issue_rows(UT, 0, c + cstride, r, tid);
	v_pk_mul_f32 v[96:97], v[170:171], v[88:89] op_sel:[1,1] op_sel_hi:[1,0]
	v_pk_fma_f32 v[80:81], v[170:171], v[88:89], v[96:97] op_sel_hi:[0,1,1] neg_hi:[1,0,0]
	v_pk_mul_f32 v[96:97], v[88:89], v[92:93] op_sel:[1,1] op_sel_hi:[1,0] neg_lo:[1,0]
	v_pk_fma_f32 v[102:103], v[88:89], v[92:93], v[96:97] op_sel_hi:[0,1,1]
	ds_read_b64 v[170:171], v163 offset:60928
	s_waitcnt lgkmcnt(12)
	v_pk_mul_f32 v[96:97], v[172:173], v[102:103] op_sel:[1,1] op_sel_hi:[1,0]
	v_pk_fma_f32 v[100:101], v[172:173], v[102:103], v[96:97] op_sel_hi:[0,1,1] neg_hi:[1,0,0]
	ds_read_b64 v[172:173], v164 offset:60928
	s_waitcnt lgkmcnt(12)
	v_pk_mul_f32 v[96:97], v[174:175], v[102:103] op_sel:[1,1] op_sel_hi:[1,0]
	v_pk_fma_f32 v[88:89], v[174:175], v[102:103], v[96:97] op_sel_hi:[0,1,1] neg_hi:[1,0,0]
	v_pk_mul_f32 v[96:97], v[102:103], v[92:93] op_sel:[1,1] op_sel_hi:[1,0] neg_lo:[1,0]
	v_pk_fma_f32 v[102:103], v[102:103], v[92:93], v[96:97] op_sel_hi:[0,1,1]
	ds_read_b64 v[174:175], v163 offset:65280
	s_waitcnt lgkmcnt(12)
	v_pk_mul_f32 v[104:105], v[176:177], v[102:103] op_sel:[1,1] op_sel_hi:[1,0]
	v_pk_fma_f32 v[112:113], v[176:177], v[102:103], v[104:105] op_sel_hi:[0,1,1] neg_hi:[1,0,0]
	ds_read_b64 v[176:177], v164 offset:65280
	s_waitcnt lgkmcnt(12)
	v_pk_mul_f32 v[104:105], v[178:179], v[102:103] op_sel:[1,1] op_sel_hi:[1,0]
	v_pk_fma_f32 v[96:97], v[178:179], v[102:103], v[104:105] op_sel_hi:[0,1,1] neg_hi:[1,0,0]
	v_pk_mul_f32 v[104:105], v[102:103], v[92:93] op_sel:[1,1] op_sel_hi:[1,0] neg_lo:[1,0]
	v_pk_fma_f32 v[106:107], v[102:103], v[92:93], v[104:105] op_sel_hi:[0,1,1]
	s_waitcnt lgkmcnt(11)
	v_pk_mul_f32 v[104:105], v[180:181], v[106:107] op_sel:[1,1] op_sel_hi:[1,0]
	v_pk_fma_f32 v[116:117], v[180:181], v[106:107], v[104:105] op_sel_hi:[0,1,1] neg_hi:[1,0,0]
	s_waitcnt lgkmcnt(10)
	v_pk_mul_f32 v[104:105], v[182:183], v[106:107] op_sel:[1,1] op_sel_hi:[1,0]
	v_pk_fma_f32 v[102:103], v[182:183], v[106:107], v[104:105] op_sel_hi:[0,1,1] neg_hi:[1,0,0]
	v_pk_mul_f32 v[104:105], v[106:107], v[92:93] op_sel:[1,1] op_sel_hi:[1,0] neg_lo:[1,0]
	v_pk_fma_f32 v[106:107], v[106:107], v[92:93], v[104:105] op_sel_hi:[0,1,1]
	s_waitcnt lgkmcnt(9)
	v_pk_mul_f32 v[108:109], v[184:185], v[106:107] op_sel:[1,1] op_sel_hi:[1,0]
	v_pk_fma_f32 v[118:119], v[184:185], v[106:107], v[108:109] op_sel_hi:[0,1,1] neg_hi:[1,0,0]
	s_waitcnt lgkmcnt(8)
	v_pk_mul_f32 v[108:109], v[186:187], v[106:107] op_sel:[1,1] op_sel_hi:[1,0]
	v_pk_fma_f32 v[104:105], v[186:187], v[106:107], v[108:109] op_sel_hi:[0,1,1] neg_hi:[1,0,0]
	v_pk_mul_f32 v[108:109], v[106:107], v[92:93] op_sel:[1,1] op_sel_hi:[1,0] neg_lo:[1,0]
	v_pk_fma_f32 v[110:111], v[106:107], v[92:93], v[108:109] op_sel_hi:[0,1,1]
	s_waitcnt lgkmcnt(7)
	v_pk_mul_f32 v[108:109], v[188:189], v[110:111] op_sel:[1,1] op_sel_hi:[1,0]
	v_pk_fma_f32 v[120:121], v[188:189], v[110:111], v[108:109] op_sel_hi:[0,1,1] neg_hi:[1,0,0]
	s_waitcnt lgkmcnt(6)
	v_pk_mul_f32 v[108:109], v[190:191], v[110:111] op_sel:[1,1] op_sel_hi:[1,0]
	v_pk_fma_f32 v[106:107], v[190:191], v[110:111], v[108:109] op_sel_hi:[0,1,1] neg_hi:[1,0,0]
	v_pk_mul_f32 v[108:109], v[110:111], v[92:93] op_sel:[1,1] op_sel_hi:[1,0] neg_lo:[1,0]
	v_pk_fma_f32 v[110:111], v[110:111], v[92:93], v[108:109] op_sel_hi:[0,1,1]
	s_waitcnt lgkmcnt(5)
	v_pk_mul_f32 v[114:115], v[166:167], v[110:111] op_sel:[1,1] op_sel_hi:[1,0]
	v_pk_fma_f32 v[122:123], v[166:167], v[110:111], v[114:115] op_sel_hi:[0,1,1] neg_hi:[1,0,0]
	s_waitcnt lgkmcnt(4)
	v_pk_mul_f32 v[114:115], v[168:169], v[110:111] op_sel:[1,1] op_sel_hi:[1,0]
	v_pk_fma_f32 v[108:109], v[168:169], v[110:111], v[114:115] op_sel_hi:[0,1,1] neg_hi:[1,0,0]
	v_pk_mul_f32 v[114:115], v[110:111], v[92:93] op_sel:[1,1] op_sel_hi:[1,0] neg_lo:[1,0]
	v_pk_fma_f32 v[126:127], v[110:111], v[92:93], v[114:115] op_sel_hi:[0,1,1]
	s_waitcnt lgkmcnt(3)
	v_pk_mul_f32 v[114:115], v[170:171], v[126:127] op_sel:[1,1] op_sel_hi:[1,0]
	v_pk_fma_f32 v[124:125], v[170:171], v[126:127], v[114:115] op_sel_hi:[0,1,1] neg_hi:[1,0,0]
	s_waitcnt lgkmcnt(2)
	v_pk_mul_f32 v[114:115], v[172:173], v[126:127] op_sel:[1,1] op_sel_hi:[1,0]
	v_pk_fma_f32 v[110:111], v[172:173], v[126:127], v[114:115] op_sel_hi:[0,1,1] neg_hi:[1,0,0]
	v_pk_mul_f32 v[114:115], v[126:127], v[92:93] op_sel:[1,1] op_sel_hi:[1,0] neg_lo:[1,0]
	v_pk_fma_f32 v[126:127], v[126:127], v[92:93], v[114:115] op_sel_hi:[0,1,1]
	s_waitcnt lgkmcnt(1)
	v_pk_mul_f32 v[114:115], v[174:175], v[126:127] op_sel:[1,1] op_sel_hi:[1,0]
	v_pk_fma_f32 v[92:93], v[174:175], v[126:127], v[114:115] op_sel_hi:[0,1,1] neg_hi:[1,0,0]
	s_waitcnt lgkmcnt(0)
	v_pk_mul_f32 v[164:165], v[176:177], v[126:127] op_sel:[1,1] op_sel_hi:[1,0]
	v_pk_fma_f32 v[114:115], v[176:177], v[126:127], v[164:165] op_sel_hi:[0,1,1] neg_hi:[1,0,0]
	s_barrier
	s_waitcnt vmcnt(3)
	ds_write_b128 v128, v[222:225]
	s_waitcnt vmcnt(2)
	ds_write_b128 v128, v[226:229] offset:8192
	s_waitcnt vmcnt(1)
	ds_write_b128 v128, v[236:239] offset:16384
	s_waitcnt vmcnt(0)
	ds_write_b128 v128, v[240:243] offset:24576
	s_cbranch_vccnz .LBB0_518
	s_andn2_b64 vcc, exec, s[20:21]
	s_cbranch_vccnz .LBB0_518
	global_load_dwordx4 v[0:3], v[58:59], off
	global_load_dwordx4 v[4:7], v[60:61], off
	global_load_dwordx4 v[8:11], v[62:63], off
	global_load_dwordx4 v[12:15], v[64:65], off
	s_branch .LBB0_518
